# v34
# speedup vs baseline: 1.0099x; 1.0012x over previous
.LBB0_189:
	s_add_u32 s36, s34, 0xfffc0080
	s_addc_u32 s37, s35, -1
	s_add_i32 s75, 0, 0x10000
	v_add_u32_e32 v140, s75, v161
	ds_read_b128 v[164:167], v140
	ds_read_b128 v[168:171], v140 offset:1024
	ds_read_b128 v[172:175], v140 offset:2048
	ds_read_b128 v[176:179], v140 offset:3072
	s_cmp_eq_u32 s74, 12
	s_cselect_b32 s39, s25, s37
	s_cselect_b32 s38, s69, s36
	s_cselect_b32 s37, s23, s73
	s_cselect_b32 s36, s70, s71
	s_add_i32 m0, s31, 0xc000
	ds_read_b128 v[180:183], v163
	ds_read_b128 v[184:187], v163 offset:1024
	ds_read_b128 v[188:191], v163 offset:2048
	ds_read_b128 v[192:195], v163 offset:3072
	ds_read_b128 v[196:199], v163 offset:4096
	ds_read_b128 v[200:203], v163 offset:5120
	ds_read_b128 v[204:207], v163 offset:6144
	ds_read_b128 v[208:211], v163 offset:7168
	global_load_lds_dwordx4 v136, s[34:35]
	s_add_i32 m0, s31, 0xe000
	s_nop 0
	global_load_lds_dwordx4 v138, s[34:35]
	s_waitcnt lgkmcnt(8)
	s_barrier
	s_waitcnt lgkmcnt(0)
	s_setprio 1
	v_mfma_f32_16x16x32_bf16 v[124:127], v[164:167], v[180:183], v[124:127]
	v_mfma_f32_16x16x32_bf16 v[120:123], v[172:175], v[180:183], v[120:123]
	v_mfma_f32_16x16x32_bf16 v[116:119], v[164:167], v[188:191], v[116:119]
	v_mfma_f32_16x16x32_bf16 v[108:111], v[172:175], v[188:191], v[108:111]
	v_mfma_f32_16x16x32_bf16 v[100:103], v[164:167], v[196:199], v[100:103]
	v_mfma_f32_16x16x32_bf16 v[92:95], v[172:175], v[196:199], v[92:95]
	v_mfma_f32_16x16x32_bf16 v[84:87], v[164:167], v[204:207], v[84:87]
	v_mfma_f32_16x16x32_bf16 v[76:79], v[172:175], v[204:207], v[76:79]
	v_mfma_f32_16x16x32_bf16 v[124:127], v[168:171], v[184:187], v[124:127]
	v_mfma_f32_16x16x32_bf16 v[120:123], v[176:179], v[184:187], v[120:123]
	v_mfma_f32_16x16x32_bf16 v[116:119], v[168:171], v[192:195], v[116:119]
	v_mfma_f32_16x16x32_bf16 v[108:111], v[176:179], v[192:195], v[108:111]
	v_mfma_f32_16x16x32_bf16 v[100:103], v[168:171], v[200:203], v[100:103]
	v_mfma_f32_16x16x32_bf16 v[92:95], v[176:179], v[200:203], v[92:95]
	v_mfma_f32_16x16x32_bf16 v[84:87], v[168:171], v[208:211], v[84:87]
	v_mfma_f32_16x16x32_bf16 v[76:79], v[176:179], v[208:211], v[76:79]
	s_setprio 0
	s_barrier
	s_add_i32 s78, 0, 0x14000
	v_add_u32_e32 v140, s78, v161
	s_add_i32 s75, s75, s57
	ds_read_b128 v[212:215], v140
	ds_read_b128 v[216:219], v140 offset:1024
	ds_read_b128 v[220:223], v140 offset:2048
	ds_read_b128 v[224:227], v140 offset:3072
	s_add_u32 s98, s36, s14
	s_addc_u32 s99, s37, s15
	s_mov_b32 m0, s75
	s_nop 0
	global_load_lds_dwordx4 v128, s[36:37]
	s_add_i32 m0, s75, 0x2000
	s_nop 0
	global_load_lds_dwordx4 v130, s[36:37]
	s_barrier
	s_waitcnt lgkmcnt(0)
	s_setprio 1
	v_mfma_f32_16x16x32_bf16 v[112:115], v[212:215], v[180:183], v[112:115]
	v_mfma_f32_16x16x32_bf16 v[104:107], v[220:223], v[180:183], v[104:107]
	v_mfma_f32_16x16x32_bf16 v[96:99], v[212:215], v[188:191], v[96:99]
	v_mfma_f32_16x16x32_bf16 v[88:91], v[220:223], v[188:191], v[88:91]
	v_mfma_f32_16x16x32_bf16 v[80:83], v[212:215], v[196:199], v[80:83]
	v_mfma_f32_16x16x32_bf16 v[72:75], v[220:223], v[196:199], v[72:75]
	v_mfma_f32_16x16x32_bf16 v[68:71], v[212:215], v[204:207], v[68:71]
	v_mfma_f32_16x16x32_bf16 v[64:67], v[220:223], v[204:207], v[64:67]
	v_mfma_f32_16x16x32_bf16 v[112:115], v[216:219], v[184:187], v[112:115]
	v_mfma_f32_16x16x32_bf16 v[104:107], v[224:227], v[184:187], v[104:107]
	v_mfma_f32_16x16x32_bf16 v[96:99], v[216:219], v[192:195], v[96:99]
	v_mfma_f32_16x16x32_bf16 v[88:91], v[224:227], v[192:195], v[88:91]
	v_mfma_f32_16x16x32_bf16 v[80:83], v[216:219], v[200:203], v[80:83]
	v_mfma_f32_16x16x32_bf16 v[72:75], v[224:227], v[200:203], v[72:75]
	v_mfma_f32_16x16x32_bf16 v[68:71], v[216:219], v[208:211], v[68:71]
	v_mfma_f32_16x16x32_bf16 v[64:67], v[224:227], v[208:211], v[64:67]
	s_setprio 0
	s_mov_b32 m0, s31
	s_add_u32 s100, s38, s14
	s_addc_u32 s101, s39, s15
	s_barrier
	ds_read_b128 v[180:183], v163 offset:16384
	ds_read_b128 v[184:187], v163 offset:17408
	ds_read_b128 v[188:191], v163 offset:18432
	ds_read_b128 v[192:195], v163 offset:19456
	ds_read_b128 v[196:199], v163 offset:20480
	ds_read_b128 v[200:203], v163 offset:21504
	ds_read_b128 v[204:207], v163 offset:22528
	ds_read_b128 v[208:211], v163 offset:23552
	global_load_lds_dwordx4 v134, s[38:39]
	s_mov_b32 m0, s60
	s_nop 0
	global_load_lds_dwordx4 v132, s[38:39]
	s_barrier
	s_waitcnt lgkmcnt(0)
	s_setprio 1
	v_mfma_f32_16x16x32_bf16 v[60:63], v[164:167], v[180:183], v[60:63]
	v_mfma_f32_16x16x32_bf16 v[56:59], v[172:175], v[180:183], v[56:59]
	v_mfma_f32_16x16x32_bf16 v[52:55], v[164:167], v[188:191], v[52:55]
	v_mfma_f32_16x16x32_bf16 v[44:47], v[172:175], v[188:191], v[44:47]
	v_mfma_f32_16x16x32_bf16 v[36:39], v[164:167], v[196:199], v[36:39]
	v_mfma_f32_16x16x32_bf16 v[28:31], v[172:175], v[196:199], v[28:31]
	v_mfma_f32_16x16x32_bf16 v[20:23], v[164:167], v[204:207], v[20:23]
	v_mfma_f32_16x16x32_bf16 v[12:15], v[172:175], v[204:207], v[12:15]
	v_mfma_f32_16x16x32_bf16 v[60:63], v[168:171], v[184:187], v[60:63]
	v_mfma_f32_16x16x32_bf16 v[56:59], v[176:179], v[184:187], v[56:59]
	v_mfma_f32_16x16x32_bf16 v[52:55], v[168:171], v[192:195], v[52:55]
	v_mfma_f32_16x16x32_bf16 v[44:47], v[176:179], v[192:195], v[44:47]
	v_mfma_f32_16x16x32_bf16 v[36:39], v[168:171], v[200:203], v[36:39]
	v_mfma_f32_16x16x32_bf16 v[28:31], v[176:179], v[200:203], v[28:31]
	v_mfma_f32_16x16x32_bf16 v[20:23], v[168:171], v[208:211], v[20:23]
	v_mfma_f32_16x16x32_bf16 v[12:15], v[176:179], v[208:211], v[12:15]
	s_setprio 0
	s_barrier
	s_add_u32 s76, s36, 0x40000
	s_addc_u32 s77, s37, 0
	s_add_i32 s75, s78, s57
	s_mov_b32 m0, s75
	s_nop 0
	global_load_lds_dwordx4 v128, s[76:77]
	s_add_i32 m0, s75, 0x2000
	s_nop 0
	global_load_lds_dwordx4 v130, s[76:77]
	s_waitcnt vmcnt(6)
	s_barrier
	s_setprio 1
	v_mfma_f32_16x16x32_bf16 v[48:51], v[212:215], v[180:183], v[48:51]
	v_mfma_f32_16x16x32_bf16 v[40:43], v[220:223], v[180:183], v[40:43]
	v_mfma_f32_16x16x32_bf16 v[32:35], v[212:215], v[188:191], v[32:35]
	v_mfma_f32_16x16x32_bf16 v[24:27], v[220:223], v[188:191], v[24:27]
	v_mfma_f32_16x16x32_bf16 v[16:19], v[212:215], v[196:199], v[16:19]
	v_mfma_f32_16x16x32_bf16 v[8:11], v[220:223], v[196:199], v[8:11]
	v_mfma_f32_16x16x32_bf16 v[4:7], v[212:215], v[204:207], v[4:7]
	v_mfma_f32_16x16x32_bf16 v[0:3], v[220:223], v[204:207], v[0:3]
	v_mfma_f32_16x16x32_bf16 v[48:51], v[216:219], v[184:187], v[48:51]
	v_mfma_f32_16x16x32_bf16 v[40:43], v[224:227], v[184:187], v[40:43]
	v_mfma_f32_16x16x32_bf16 v[32:35], v[216:219], v[192:195], v[32:35]
	v_mfma_f32_16x16x32_bf16 v[24:27], v[224:227], v[192:195], v[24:27]
	v_mfma_f32_16x16x32_bf16 v[16:19], v[216:219], v[200:203], v[16:19]
	v_mfma_f32_16x16x32_bf16 v[8:11], v[224:227], v[200:203], v[8:11]
	v_mfma_f32_16x16x32_bf16 v[4:7], v[216:219], v[208:211], v[4:7]
	v_mfma_f32_16x16x32_bf16 v[0:3], v[224:227], v[208:211], v[0:3]
	s_setprio 0
	s_add_i32 s75, 0, 0x18000
	v_add_u32_e32 v176, s75, v161
	s_barrier
	ds_read_b128 v[164:167], v176
	ds_read_b128 v[168:171], v176 offset:1024
	ds_read_b128 v[172:175], v176 offset:2048
	ds_read_b128 v[176:179], v176 offset:3072
	s_add_u32 s38, s38, 0x40000
	s_addc_u32 s39, s39, 0
	s_mov_b32 m0, s61
	ds_read_b128 v[180:183], v163 offset:32768
	ds_read_b128 v[184:187], v163 offset:33792
	ds_read_b128 v[188:191], v163 offset:34816
	ds_read_b128 v[192:195], v163 offset:35840
	ds_read_b128 v[196:199], v163 offset:36864
	ds_read_b128 v[200:203], v163 offset:37888
	ds_read_b128 v[204:207], v163 offset:38912
	ds_read_b128 v[208:211], v163 offset:39936
	global_load_lds_dwordx4 v134, s[38:39]
	s_mov_b32 m0, s62
	s_nop 0
	global_load_lds_dwordx4 v132, s[38:39]
	s_waitcnt lgkmcnt(8)
	s_barrier
	s_waitcnt lgkmcnt(0)
	s_setprio 1
	v_mfma_f32_16x16x32_bf16 v[124:127], v[164:167], v[180:183], v[124:127]
	v_mfma_f32_16x16x32_bf16 v[120:123], v[172:175], v[180:183], v[120:123]
	v_mfma_f32_16x16x32_bf16 v[116:119], v[164:167], v[188:191], v[116:119]
	v_mfma_f32_16x16x32_bf16 v[108:111], v[172:175], v[188:191], v[108:111]
	v_mfma_f32_16x16x32_bf16 v[100:103], v[164:167], v[196:199], v[100:103]
	v_mfma_f32_16x16x32_bf16 v[92:95], v[172:175], v[196:199], v[92:95]
	v_mfma_f32_16x16x32_bf16 v[84:87], v[164:167], v[204:207], v[84:87]
	v_mfma_f32_16x16x32_bf16 v[76:79], v[172:175], v[204:207], v[76:79]
	v_mfma_f32_16x16x32_bf16 v[124:127], v[168:171], v[184:187], v[124:127]
	v_mfma_f32_16x16x32_bf16 v[120:123], v[176:179], v[184:187], v[120:123]
	v_mfma_f32_16x16x32_bf16 v[116:119], v[168:171], v[192:195], v[116:119]
	v_mfma_f32_16x16x32_bf16 v[108:111], v[176:179], v[192:195], v[108:111]
	v_mfma_f32_16x16x32_bf16 v[100:103], v[168:171], v[200:203], v[100:103]
	v_mfma_f32_16x16x32_bf16 v[92:95], v[176:179], v[200:203], v[92:95]
	v_mfma_f32_16x16x32_bf16 v[84:87], v[168:171], v[208:211], v[84:87]
	v_mfma_f32_16x16x32_bf16 v[76:79], v[176:179], v[208:211], v[76:79]
	s_setprio 0
	s_barrier
	s_add_i32 s38, 0, 0x1c000
	s_add_i32 s39, s75, s57
	v_add_u32_e32 v224, s38, v161
	s_mov_b32 m0, s39
	ds_read_b128 v[212:215], v224
	ds_read_b128 v[216:219], v224 offset:1024
	ds_read_b128 v[220:223], v224 offset:2048
	ds_read_b128 v[224:227], v224 offset:3072
	global_load_lds_dwordx4 v128, s[98:99]
	s_add_i32 m0, s39, 0x2000
	s_nop 0
	global_load_lds_dwordx4 v130, s[98:99]
	s_barrier
	s_waitcnt lgkmcnt(0)
	s_setprio 1
	v_mfma_f32_16x16x32_bf16 v[112:115], v[212:215], v[180:183], v[112:115]
	v_mfma_f32_16x16x32_bf16 v[104:107], v[220:223], v[180:183], v[104:107]
	v_mfma_f32_16x16x32_bf16 v[96:99], v[212:215], v[188:191], v[96:99]
	v_mfma_f32_16x16x32_bf16 v[88:91], v[220:223], v[188:191], v[88:91]
	v_mfma_f32_16x16x32_bf16 v[80:83], v[212:215], v[196:199], v[80:83]
	v_mfma_f32_16x16x32_bf16 v[72:75], v[220:223], v[196:199], v[72:75]
	v_mfma_f32_16x16x32_bf16 v[68:71], v[212:215], v[204:207], v[68:71]
	v_mfma_f32_16x16x32_bf16 v[64:67], v[220:223], v[204:207], v[64:67]
	v_mfma_f32_16x16x32_bf16 v[112:115], v[216:219], v[184:187], v[112:115]
	v_mfma_f32_16x16x32_bf16 v[104:107], v[224:227], v[184:187], v[104:107]
	v_mfma_f32_16x16x32_bf16 v[96:99], v[216:219], v[192:195], v[96:99]
	v_mfma_f32_16x16x32_bf16 v[88:91], v[224:227], v[192:195], v[88:91]
	v_mfma_f32_16x16x32_bf16 v[80:83], v[216:219], v[200:203], v[80:83]
	v_mfma_f32_16x16x32_bf16 v[72:75], v[224:227], v[200:203], v[72:75]
	v_mfma_f32_16x16x32_bf16 v[68:71], v[216:219], v[208:211], v[68:71]
	v_mfma_f32_16x16x32_bf16 v[64:67], v[224:227], v[208:211], v[64:67]
	s_setprio 0
	s_mov_b32 m0, s63
	s_barrier
	ds_read_b128 v[180:183], v163 offset:49152
	ds_read_b128 v[184:187], v163 offset:50176
	ds_read_b128 v[188:191], v163 offset:51200
	ds_read_b128 v[192:195], v163 offset:52224
	ds_read_b128 v[196:199], v163 offset:53248
	ds_read_b128 v[200:203], v163 offset:54272
	ds_read_b128 v[204:207], v163 offset:55296
	ds_read_b128 v[208:211], v163 offset:56320
	global_load_lds_dwordx4 v134, s[100:101]
	s_mov_b32 m0, s64
	s_nop 0
	global_load_lds_dwordx4 v132, s[100:101]
	s_barrier
	s_waitcnt lgkmcnt(0)
	s_setprio 1
	v_mfma_f32_16x16x32_bf16 v[60:63], v[164:167], v[180:183], v[60:63]
	v_mfma_f32_16x16x32_bf16 v[56:59], v[172:175], v[180:183], v[56:59]
	v_mfma_f32_16x16x32_bf16 v[52:55], v[164:167], v[188:191], v[52:55]
	v_mfma_f32_16x16x32_bf16 v[44:47], v[172:175], v[188:191], v[44:47]
	v_mfma_f32_16x16x32_bf16 v[36:39], v[164:167], v[196:199], v[36:39]
	v_mfma_f32_16x16x32_bf16 v[28:31], v[172:175], v[196:199], v[28:31]
	v_mfma_f32_16x16x32_bf16 v[20:23], v[164:167], v[204:207], v[20:23]
	v_mfma_f32_16x16x32_bf16 v[12:15], v[172:175], v[204:207], v[12:15]
	v_mfma_f32_16x16x32_bf16 v[60:63], v[168:171], v[184:187], v[60:63]
	v_mfma_f32_16x16x32_bf16 v[56:59], v[176:179], v[184:187], v[56:59]
	v_mfma_f32_16x16x32_bf16 v[52:55], v[168:171], v[192:195], v[52:55]
	v_mfma_f32_16x16x32_bf16 v[44:47], v[176:179], v[192:195], v[44:47]
	v_mfma_f32_16x16x32_bf16 v[36:39], v[168:171], v[200:203], v[36:39]
	v_mfma_f32_16x16x32_bf16 v[28:31], v[176:179], v[200:203], v[28:31]
	v_mfma_f32_16x16x32_bf16 v[20:23], v[168:171], v[208:211], v[20:23]
	v_mfma_f32_16x16x32_bf16 v[12:15], v[176:179], v[208:211], v[12:15]
	s_setprio 0
	s_barrier
	s_add_u32 s36, s36, 0x40080
	s_addc_u32 s37, s37, 0
	s_add_i32 s38, s38, s57
	s_mov_b32 m0, s38
	s_nop 0
	global_load_lds_dwordx4 v128, s[36:37]
	s_add_i32 m0, s38, 0x2000
	s_nop 0
	global_load_lds_dwordx4 v130, s[36:37]
	s_waitcnt vmcnt(6)
	s_barrier
	s_setprio 1
	v_mfma_f32_16x16x32_bf16 v[48:51], v[212:215], v[180:183], v[48:51]
	v_mfma_f32_16x16x32_bf16 v[40:43], v[220:223], v[180:183], v[40:43]
	v_mfma_f32_16x16x32_bf16 v[32:35], v[212:215], v[188:191], v[32:35]
	v_mfma_f32_16x16x32_bf16 v[24:27], v[220:223], v[188:191], v[24:27]
	v_mfma_f32_16x16x32_bf16 v[16:19], v[212:215], v[196:199], v[16:19]
	v_mfma_f32_16x16x32_bf16 v[8:11], v[220:223], v[196:199], v[8:11]
	v_mfma_f32_16x16x32_bf16 v[4:7], v[212:215], v[204:207], v[4:7]
	v_mfma_f32_16x16x32_bf16 v[0:3], v[220:223], v[204:207], v[0:3]
	v_mfma_f32_16x16x32_bf16 v[48:51], v[216:219], v[184:187], v[48:51]
	v_mfma_f32_16x16x32_bf16 v[40:43], v[224:227], v[184:187], v[40:43]
	v_mfma_f32_16x16x32_bf16 v[32:35], v[216:219], v[192:195], v[32:35]
	v_mfma_f32_16x16x32_bf16 v[24:27], v[224:227], v[192:195], v[24:27]
	v_mfma_f32_16x16x32_bf16 v[16:19], v[216:219], v[200:203], v[16:19]
	v_mfma_f32_16x16x32_bf16 v[8:11], v[224:227], v[200:203], v[8:11]
	v_mfma_f32_16x16x32_bf16 v[4:7], v[216:219], v[208:211], v[4:7]
	v_mfma_f32_16x16x32_bf16 v[0:3], v[224:227], v[208:211], v[0:3]
	s_setprio 0
	s_add_i32 s74, s74, 2
	s_add_u32 s34, s34, 0x100
	s_addc_u32 s35, s35, 0
	s_add_u32 s71, s71, 0x100
	s_addc_u32 s73, s73, 0
	s_cmp_gt_u32 s74, 13
	s_barrier
	s_cbranch_scc0 .LBB0_189
	v_lshl_or_b32 v140, s68, 8, v162
	v_lshl_add_u32 v166, s30, 8, v159
	v_ashrrev_i32_e32 v141, 31, v140
	v_lshl_add_u64 v[140:141], v[140:141], 1, s[20:21]
	v_mad_i64_i32 v[164:165], s[34:35], v166, s52, 0
	v_lshl_add_u64 v[164:165], v[164:165], 1, v[140:141]
	v_cvt_pk_bf16_f32 v124, v124, v125
	v_cvt_pk_bf16_f32 v125, v126, v127
	v_cvt_pk_bf16_f32 v126, v120, v121
	v_cvt_pk_bf16_f32 v127, v122, v123
	global_store_dwordx4 v[164:165], v[124:127], off
	v_cvt_pk_bf16_f32 v112, v112, v113
	v_cvt_pk_bf16_f32 v113, v114, v115
	v_cvt_pk_bf16_f32 v114, v104, v105
	v_or_b32_e32 v104, 16, v166
	v_mad_i64_i32 v[104:105], s[34:35], v104, s52, 0
	v_cvt_pk_bf16_f32 v115, v106, v107
	global_store_dwordx4 v[164:165], v[112:115], off offset:256
	s_and_b64 vcc, exec, s[4:5]
	s_mov_b32 s68, s22
	v_lshl_add_u64 v[112:113], v[104:105], 1, v[140:141]
	v_cvt_pk_bf16_f32 v104, v116, v117
	v_cvt_pk_bf16_f32 v105, v118, v119
	v_cvt_pk_bf16_f32 v106, v108, v109
	v_cvt_pk_bf16_f32 v107, v110, v111
	global_store_dwordx4 v[112:113], v[104:107], off
	v_cvt_pk_bf16_f32 v96, v96, v97
	v_cvt_pk_bf16_f32 v97, v98, v99
	v_cvt_pk_bf16_f32 v98, v88, v89
	v_or_b32_e32 v88, 32, v166
	v_mad_i64_i32 v[88:89], s[34:35], v88, s52, 0
	v_cvt_pk_bf16_f32 v99, v90, v91
	global_store_dwordx4 v[112:113], v[96:99], off offset:256
	s_mov_b32 s30, s24
	s_mov_b64 s[36:37], s[28:29]
	v_lshl_add_u64 v[96:97], v[88:89], 1, v[140:141]
	v_cvt_pk_bf16_f32 v88, v100, v101
	v_cvt_pk_bf16_f32 v89, v102, v103
	v_cvt_pk_bf16_f32 v90, v92, v93
	v_cvt_pk_bf16_f32 v91, v94, v95
	global_store_dwordx4 v[96:97], v[88:91], off
	v_cvt_pk_bf16_f32 v80, v80, v81
	v_cvt_pk_bf16_f32 v81, v82, v83
	v_cvt_pk_bf16_f32 v82, v72, v73
	v_or_b32_e32 v72, 48, v166
	v_mad_i64_i32 v[72:73], s[34:35], v72, s52, 0
	v_cvt_pk_bf16_f32 v83, v74, v75
	global_store_dwordx4 v[96:97], v[80:83], off offset:256
	s_nop 1
	v_lshl_add_u64 v[80:81], v[72:73], 1, v[140:141]
	v_cvt_pk_bf16_f32 v72, v84, v85
	v_cvt_pk_bf16_f32 v73, v86, v87
	v_cvt_pk_bf16_f32 v74, v76, v77
	v_cvt_pk_bf16_f32 v75, v78, v79
	global_store_dwordx4 v[80:81], v[72:75], off
	v_cvt_pk_bf16_f32 v68, v68, v69
	v_cvt_pk_bf16_f32 v69, v70, v71
	v_cvt_pk_bf16_f32 v70, v64, v65
	v_add_u32_e32 v64, 0x80, v166
	v_mad_i64_i32 v[64:65], s[34:35], v64, s52, 0
	v_lshl_add_u64 v[64:65], v[64:65], 1, v[140:141]
	v_cvt_pk_bf16_f32 v71, v66, v67
	global_store_dwordx4 v[80:81], v[68:71], off offset:256
	v_cvt_pk_bf16_f32 v60, v60, v61
	v_cvt_pk_bf16_f32 v61, v62, v63
	v_cvt_pk_bf16_f32 v62, v56, v57
	v_cvt_pk_bf16_f32 v63, v58, v59
	global_store_dwordx4 v[64:65], v[60:63], off
	v_cvt_pk_bf16_f32 v48, v48, v49
	v_cvt_pk_bf16_f32 v49, v50, v51
	v_cvt_pk_bf16_f32 v50, v40, v41
	v_add_u32_e32 v40, 0x90, v166
	v_mad_i64_i32 v[40:41], s[34:35], v40, s52, 0
	v_cvt_pk_bf16_f32 v51, v42, v43
	global_store_dwordx4 v[64:65], v[48:51], off offset:256
	s_nop 1
	v_lshl_add_u64 v[48:49], v[40:41], 1, v[140:141]
	v_cvt_pk_bf16_f32 v40, v52, v53
	v_cvt_pk_bf16_f32 v41, v54, v55
	v_cvt_pk_bf16_f32 v42, v44, v45
	v_cvt_pk_bf16_f32 v43, v46, v47
	global_store_dwordx4 v[48:49], v[40:43], off
	v_cvt_pk_bf16_f32 v32, v32, v33
	v_cvt_pk_bf16_f32 v33, v34, v35
	v_cvt_pk_bf16_f32 v34, v24, v25
	v_add_u32_e32 v24, 0xa0, v166
	v_mad_i64_i32 v[24:25], s[34:35], v24, s52, 0
	v_cvt_pk_bf16_f32 v35, v26, v27
	global_store_dwordx4 v[48:49], v[32:35], off offset:256
	s_nop 1
	v_lshl_add_u64 v[32:33], v[24:25], 1, v[140:141]
	v_cvt_pk_bf16_f32 v24, v36, v37
	v_cvt_pk_bf16_f32 v25, v38, v39
	v_cvt_pk_bf16_f32 v26, v28, v29
	v_cvt_pk_bf16_f32 v27, v30, v31
	global_store_dwordx4 v[32:33], v[24:27], off
	v_cvt_pk_bf16_f32 v16, v16, v17
	v_cvt_pk_bf16_f32 v17, v18, v19
	v_cvt_pk_bf16_f32 v18, v8, v9
	v_add_u32_e32 v8, 0xb0, v166
	v_mad_i64_i32 v[8:9], s[34:35], v8, s52, 0
	v_cvt_pk_bf16_f32 v19, v10, v11
	global_store_dwordx4 v[32:33], v[16:19], off offset:256
	s_mov_b64 s[34:35], s[26:27]
	s_nop 0
	v_lshl_add_u64 v[16:17], v[8:9], 1, v[140:141]
	v_cvt_pk_bf16_f32 v8, v20, v21
	v_cvt_pk_bf16_f32 v9, v22, v23
	v_cvt_pk_bf16_f32 v10, v12, v13
	v_cvt_pk_bf16_f32 v11, v14, v15
	global_store_dwordx4 v[16:17], v[8:11], off
	v_cvt_pk_bf16_f32 v4, v4, v5
	v_cvt_pk_bf16_f32 v5, v6, v7
	v_cvt_pk_bf16_f32 v6, v0, v1
	v_cvt_pk_bf16_f32 v7, v2, v3
	global_store_dwordx4 v[16:17], v[4:7], off offset:256
	s_cbranch_vccz .LBB0_186
	s_waitcnt vmcnt(0)
	s_cmpk_gt_u32 s56, 0xff
	s_cbranch_scc1 .LBB0_174
	s_barrier
	s_branch .LBB0_174

.LBB0_203:
	ds_read_b128 v[144:147], v153
	ds_read_b128 v[156:159], v153 offset:1024
	ds_read_b128 v[162:165], v153 offset:2048
	ds_read_b128 v[166:169], v153 offset:3072
	s_add_u32 s26, s24, 0xfffc0080
	s_addc_u32 s27, s25, -1
	s_cmp_eq_u32 s54, 12
	s_cselect_b32 s29, s5, s27
	s_cselect_b32 s28, s17, s26
	s_cselect_b32 s27, s15, s53
	s_cselect_b32 s26, s23, s52
	s_add_i32 m0, s36, 0xc000
	ds_read_b128 v[170:173], v154
	ds_read_b128 v[174:177], v154 offset:1024
	ds_read_b128 v[178:181], v154 offset:2048
	ds_read_b128 v[182:185], v154 offset:3072
	ds_read_b128 v[186:189], v154 offset:4096
	ds_read_b128 v[190:193], v154 offset:5120
	ds_read_b128 v[194:197], v154 offset:6144
	ds_read_b128 v[198:201], v154 offset:7168
	global_load_lds_dwordx4 v136, s[24:25]
	s_add_i32 m0, s36, 0xe000
	s_nop 0
	global_load_lds_dwordx4 v138, s[24:25]
	s_waitcnt lgkmcnt(8)
	s_barrier
	s_waitcnt lgkmcnt(0)
	s_setprio 1
	v_mfma_f32_16x16x32_bf16 v[124:127], v[144:147], v[170:173], v[124:127]
	v_mfma_f32_16x16x32_bf16 v[120:123], v[162:165], v[170:173], v[120:123]
	v_mfma_f32_16x16x32_bf16 v[108:111], v[144:147], v[178:181], v[108:111]
	v_mfma_f32_16x16x32_bf16 v[104:107], v[162:165], v[178:181], v[104:107]
	v_mfma_f32_16x16x32_bf16 v[92:95], v[144:147], v[186:189], v[92:95]
	v_mfma_f32_16x16x32_bf16 v[88:91], v[162:165], v[186:189], v[88:91]
	v_mfma_f32_16x16x32_bf16 v[76:79], v[144:147], v[194:197], v[76:79]
	v_mfma_f32_16x16x32_bf16 v[72:75], v[162:165], v[194:197], v[72:75]
	v_mfma_f32_16x16x32_bf16 v[124:127], v[156:159], v[174:177], v[124:127]
	v_mfma_f32_16x16x32_bf16 v[120:123], v[166:169], v[174:177], v[120:123]
	v_mfma_f32_16x16x32_bf16 v[108:111], v[156:159], v[182:185], v[108:111]
	v_mfma_f32_16x16x32_bf16 v[104:107], v[166:169], v[182:185], v[104:107]
	v_mfma_f32_16x16x32_bf16 v[92:95], v[156:159], v[190:193], v[92:95]
	v_mfma_f32_16x16x32_bf16 v[88:91], v[166:169], v[190:193], v[88:91]
	v_mfma_f32_16x16x32_bf16 v[76:79], v[156:159], v[198:201], v[76:79]
	v_mfma_f32_16x16x32_bf16 v[72:75], v[166:169], v[198:201], v[72:75]
	s_setprio 0
	s_barrier
	s_add_i32 s55, s48, s35
	s_add_u32 s98, s26, s12
	s_addc_u32 s99, s27, s13
	s_mov_b32 m0, s55
	ds_read_b128 v[202:205], v155
	ds_read_b128 v[206:209], v155 offset:1024
	ds_read_b128 v[210:213], v155 offset:2048
	ds_read_b128 v[214:217], v155 offset:3072
	global_load_lds_dwordx4 v130, s[26:27]
	s_add_i32 m0, s55, 0x2000
	s_nop 0
	global_load_lds_dwordx4 v134, s[26:27]
	s_barrier
	s_waitcnt lgkmcnt(0)
	s_setprio 1
	v_mfma_f32_16x16x32_bf16 v[116:119], v[202:205], v[170:173], v[116:119]
	v_mfma_f32_16x16x32_bf16 v[112:115], v[210:213], v[170:173], v[112:115]
	v_mfma_f32_16x16x32_bf16 v[100:103], v[202:205], v[178:181], v[100:103]
	v_mfma_f32_16x16x32_bf16 v[96:99], v[210:213], v[178:181], v[96:99]
	v_mfma_f32_16x16x32_bf16 v[84:87], v[202:205], v[186:189], v[84:87]
	v_mfma_f32_16x16x32_bf16 v[80:83], v[210:213], v[186:189], v[80:83]
	v_mfma_f32_16x16x32_bf16 v[68:71], v[202:205], v[194:197], v[68:71]
	v_mfma_f32_16x16x32_bf16 v[64:67], v[210:213], v[194:197], v[64:67]
	v_mfma_f32_16x16x32_bf16 v[116:119], v[206:209], v[174:177], v[116:119]
	v_mfma_f32_16x16x32_bf16 v[112:115], v[214:217], v[174:177], v[112:115]
	v_mfma_f32_16x16x32_bf16 v[100:103], v[206:209], v[182:185], v[100:103]
	v_mfma_f32_16x16x32_bf16 v[96:99], v[214:217], v[182:185], v[96:99]
	v_mfma_f32_16x16x32_bf16 v[84:87], v[206:209], v[190:193], v[84:87]
	v_mfma_f32_16x16x32_bf16 v[80:83], v[214:217], v[190:193], v[80:83]
	v_mfma_f32_16x16x32_bf16 v[68:71], v[206:209], v[198:201], v[68:71]
	v_mfma_f32_16x16x32_bf16 v[64:67], v[214:217], v[198:201], v[64:67]
	s_setprio 0
	s_mov_b32 m0, s36
	s_add_u32 s100, s28, s12
	s_addc_u32 s101, s29, s13
	s_barrier
	ds_read_b128 v[170:173], v154 offset:16384
	ds_read_b128 v[174:177], v154 offset:17408
	ds_read_b128 v[178:181], v154 offset:18432
	ds_read_b128 v[182:185], v154 offset:19456
	ds_read_b128 v[186:189], v154 offset:20480
	ds_read_b128 v[190:193], v154 offset:21504
	ds_read_b128 v[194:197], v154 offset:22528
	ds_read_b128 v[198:201], v154 offset:23552
	global_load_lds_dwordx4 v128, s[28:29]
	s_mov_b32 m0, s37
	s_nop 0
	global_load_lds_dwordx4 v132, s[28:29]
	s_barrier
	s_waitcnt lgkmcnt(0)
	s_setprio 1
	v_mfma_f32_16x16x32_bf16 v[60:63], v[144:147], v[170:173], v[60:63]
	v_mfma_f32_16x16x32_bf16 v[56:59], v[162:165], v[170:173], v[56:59]
	v_mfma_f32_16x16x32_bf16 v[44:47], v[144:147], v[178:181], v[44:47]
	v_mfma_f32_16x16x32_bf16 v[40:43], v[162:165], v[178:181], v[40:43]
	v_mfma_f32_16x16x32_bf16 v[28:31], v[144:147], v[186:189], v[28:31]
	v_mfma_f32_16x16x32_bf16 v[24:27], v[162:165], v[186:189], v[24:27]
	v_mfma_f32_16x16x32_bf16 v[12:15], v[144:147], v[194:197], v[12:15]
	v_mfma_f32_16x16x32_bf16 v[8:11], v[162:165], v[194:197], v[8:11]
	v_mfma_f32_16x16x32_bf16 v[60:63], v[156:159], v[174:177], v[60:63]
	v_mfma_f32_16x16x32_bf16 v[56:59], v[166:169], v[174:177], v[56:59]
	v_mfma_f32_16x16x32_bf16 v[44:47], v[156:159], v[182:185], v[44:47]
	v_mfma_f32_16x16x32_bf16 v[40:43], v[166:169], v[182:185], v[40:43]
	v_mfma_f32_16x16x32_bf16 v[28:31], v[156:159], v[190:193], v[28:31]
	v_mfma_f32_16x16x32_bf16 v[24:27], v[166:169], v[190:193], v[24:27]
	v_mfma_f32_16x16x32_bf16 v[12:15], v[156:159], v[198:201], v[12:15]
	v_mfma_f32_16x16x32_bf16 v[8:11], v[166:169], v[198:201], v[8:11]
	s_setprio 0
	s_barrier
	s_add_u32 s56, s26, 0x40000
	s_addc_u32 s57, s27, 0
	s_add_i32 s55, s49, s35
	s_mov_b32 m0, s55
	s_nop 0
	global_load_lds_dwordx4 v130, s[56:57]
	s_add_i32 m0, s55, 0x2000
	s_nop 0
	global_load_lds_dwordx4 v134, s[56:57]
	s_waitcnt vmcnt(6)
	s_barrier
	s_setprio 1
	v_mfma_f32_16x16x32_bf16 v[52:55], v[202:205], v[170:173], v[52:55]
	v_mfma_f32_16x16x32_bf16 v[48:51], v[210:213], v[170:173], v[48:51]
	v_mfma_f32_16x16x32_bf16 v[36:39], v[202:205], v[178:181], v[36:39]
	v_mfma_f32_16x16x32_bf16 v[32:35], v[210:213], v[178:181], v[32:35]
	v_mfma_f32_16x16x32_bf16 v[20:23], v[202:205], v[186:189], v[20:23]
	v_mfma_f32_16x16x32_bf16 v[16:19], v[210:213], v[186:189], v[16:19]
	v_mfma_f32_16x16x32_bf16 v[4:7], v[202:205], v[194:197], v[4:7]
	v_mfma_f32_16x16x32_bf16 v[0:3], v[210:213], v[194:197], v[0:3]
	v_mfma_f32_16x16x32_bf16 v[52:55], v[206:209], v[174:177], v[52:55]
	v_mfma_f32_16x16x32_bf16 v[48:51], v[214:217], v[174:177], v[48:51]
	v_mfma_f32_16x16x32_bf16 v[36:39], v[206:209], v[182:185], v[36:39]
	v_mfma_f32_16x16x32_bf16 v[32:35], v[214:217], v[182:185], v[32:35]
	v_mfma_f32_16x16x32_bf16 v[20:23], v[206:209], v[190:193], v[20:23]
	v_mfma_f32_16x16x32_bf16 v[16:19], v[214:217], v[190:193], v[16:19]
	v_mfma_f32_16x16x32_bf16 v[4:7], v[206:209], v[198:201], v[4:7]
	v_mfma_f32_16x16x32_bf16 v[0:3], v[214:217], v[198:201], v[0:3]
	s_setprio 0
	s_add_i32 s55, 0, 0x18000
	v_add_u32_e32 v161, s55, v151
	s_barrier
	ds_read_b128 v[144:147], v161
	ds_read_b128 v[156:159], v161 offset:1024
	ds_read_b128 v[162:165], v161 offset:2048
	ds_read_b128 v[166:169], v161 offset:3072
	s_add_u32 s28, s28, 0x40000
	s_addc_u32 s29, s29, 0
	s_mov_b32 m0, s38
	ds_read_b128 v[170:173], v154 offset:32768
	ds_read_b128 v[174:177], v154 offset:33792
	ds_read_b128 v[178:181], v154 offset:34816
	ds_read_b128 v[182:185], v154 offset:35840
	ds_read_b128 v[186:189], v154 offset:36864
	ds_read_b128 v[190:193], v154 offset:37888
	ds_read_b128 v[194:197], v154 offset:38912
	ds_read_b128 v[198:201], v154 offset:39936
	global_load_lds_dwordx4 v128, s[28:29]
	s_mov_b32 m0, s39
	s_nop 0
	global_load_lds_dwordx4 v132, s[28:29]
	s_waitcnt lgkmcnt(8)
	s_barrier
	s_waitcnt lgkmcnt(0)
	s_setprio 1
	v_mfma_f32_16x16x32_bf16 v[124:127], v[144:147], v[170:173], v[124:127]
	v_mfma_f32_16x16x32_bf16 v[120:123], v[162:165], v[170:173], v[120:123]
	v_mfma_f32_16x16x32_bf16 v[108:111], v[144:147], v[178:181], v[108:111]
	v_mfma_f32_16x16x32_bf16 v[104:107], v[162:165], v[178:181], v[104:107]
	v_mfma_f32_16x16x32_bf16 v[92:95], v[144:147], v[186:189], v[92:95]
	v_mfma_f32_16x16x32_bf16 v[88:91], v[162:165], v[186:189], v[88:91]
	v_mfma_f32_16x16x32_bf16 v[76:79], v[144:147], v[194:197], v[76:79]
	v_mfma_f32_16x16x32_bf16 v[72:75], v[162:165], v[194:197], v[72:75]
	v_mfma_f32_16x16x32_bf16 v[124:127], v[156:159], v[174:177], v[124:127]
	v_mfma_f32_16x16x32_bf16 v[120:123], v[166:169], v[174:177], v[120:123]
	v_mfma_f32_16x16x32_bf16 v[108:111], v[156:159], v[182:185], v[108:111]
	v_mfma_f32_16x16x32_bf16 v[104:107], v[166:169], v[182:185], v[104:107]
	v_mfma_f32_16x16x32_bf16 v[92:95], v[156:159], v[190:193], v[92:95]
	v_mfma_f32_16x16x32_bf16 v[88:91], v[166:169], v[190:193], v[88:91]
	v_mfma_f32_16x16x32_bf16 v[76:79], v[156:159], v[198:201], v[76:79]
	v_mfma_f32_16x16x32_bf16 v[72:75], v[166:169], v[198:201], v[72:75]
	s_setprio 0
	s_barrier
	s_add_i32 s28, 0, 0x1c000
	s_add_i32 s29, s55, s35
	v_add_u32_e32 v161, s28, v151
	s_mov_b32 m0, s29
	ds_read_b128 v[202:205], v161
	ds_read_b128 v[206:209], v161 offset:1024
	ds_read_b128 v[210:213], v161 offset:2048
	ds_read_b128 v[214:217], v161 offset:3072
	global_load_lds_dwordx4 v130, s[98:99]
	s_add_i32 m0, s29, 0x2000
	s_nop 0
	global_load_lds_dwordx4 v134, s[98:99]
	s_barrier
	s_waitcnt lgkmcnt(0)
	s_setprio 1
	v_mfma_f32_16x16x32_bf16 v[116:119], v[202:205], v[170:173], v[116:119]
	v_mfma_f32_16x16x32_bf16 v[112:115], v[210:213], v[170:173], v[112:115]
	v_mfma_f32_16x16x32_bf16 v[100:103], v[202:205], v[178:181], v[100:103]
	v_mfma_f32_16x16x32_bf16 v[96:99], v[210:213], v[178:181], v[96:99]
	v_mfma_f32_16x16x32_bf16 v[84:87], v[202:205], v[186:189], v[84:87]
	v_mfma_f32_16x16x32_bf16 v[80:83], v[210:213], v[186:189], v[80:83]
	v_mfma_f32_16x16x32_bf16 v[68:71], v[202:205], v[194:197], v[68:71]
	v_mfma_f32_16x16x32_bf16 v[64:67], v[210:213], v[194:197], v[64:67]
	v_mfma_f32_16x16x32_bf16 v[116:119], v[206:209], v[174:177], v[116:119]
	v_mfma_f32_16x16x32_bf16 v[112:115], v[214:217], v[174:177], v[112:115]
	v_mfma_f32_16x16x32_bf16 v[100:103], v[206:209], v[182:185], v[100:103]
	v_mfma_f32_16x16x32_bf16 v[96:99], v[214:217], v[182:185], v[96:99]
	v_mfma_f32_16x16x32_bf16 v[84:87], v[206:209], v[190:193], v[84:87]
	v_mfma_f32_16x16x32_bf16 v[80:83], v[214:217], v[190:193], v[80:83]
	v_mfma_f32_16x16x32_bf16 v[68:71], v[206:209], v[198:201], v[68:71]
	v_mfma_f32_16x16x32_bf16 v[64:67], v[214:217], v[198:201], v[64:67]
	s_setprio 0
	s_mov_b32 m0, s44
	s_barrier
	ds_read_b128 v[170:173], v154 offset:49152
	ds_read_b128 v[174:177], v154 offset:50176
	ds_read_b128 v[178:181], v154 offset:51200
	ds_read_b128 v[182:185], v154 offset:52224
	ds_read_b128 v[186:189], v154 offset:53248
	ds_read_b128 v[190:193], v154 offset:54272
	ds_read_b128 v[194:197], v154 offset:55296
	ds_read_b128 v[198:201], v154 offset:56320
	global_load_lds_dwordx4 v128, s[100:101]
	s_mov_b32 m0, s46
	s_nop 0
	global_load_lds_dwordx4 v132, s[100:101]
	s_barrier
	s_waitcnt lgkmcnt(0)
	s_setprio 1
	v_mfma_f32_16x16x32_bf16 v[60:63], v[144:147], v[170:173], v[60:63]
	v_mfma_f32_16x16x32_bf16 v[56:59], v[162:165], v[170:173], v[56:59]
	v_mfma_f32_16x16x32_bf16 v[44:47], v[144:147], v[178:181], v[44:47]
	v_mfma_f32_16x16x32_bf16 v[40:43], v[162:165], v[178:181], v[40:43]
	v_mfma_f32_16x16x32_bf16 v[28:31], v[144:147], v[186:189], v[28:31]
	v_mfma_f32_16x16x32_bf16 v[24:27], v[162:165], v[186:189], v[24:27]
	v_mfma_f32_16x16x32_bf16 v[12:15], v[144:147], v[194:197], v[12:15]
	v_mfma_f32_16x16x32_bf16 v[8:11], v[162:165], v[194:197], v[8:11]
	v_mfma_f32_16x16x32_bf16 v[60:63], v[156:159], v[174:177], v[60:63]
	v_mfma_f32_16x16x32_bf16 v[56:59], v[166:169], v[174:177], v[56:59]
	v_mfma_f32_16x16x32_bf16 v[44:47], v[156:159], v[182:185], v[44:47]
	v_mfma_f32_16x16x32_bf16 v[40:43], v[166:169], v[182:185], v[40:43]
	v_mfma_f32_16x16x32_bf16 v[28:31], v[156:159], v[190:193], v[28:31]
	v_mfma_f32_16x16x32_bf16 v[24:27], v[166:169], v[190:193], v[24:27]
	v_mfma_f32_16x16x32_bf16 v[12:15], v[156:159], v[198:201], v[12:15]
	v_mfma_f32_16x16x32_bf16 v[8:11], v[166:169], v[198:201], v[8:11]
	s_setprio 0
	s_barrier
	s_add_u32 s26, s26, 0x40080
	s_addc_u32 s27, s27, 0
	s_add_i32 s28, s28, s35
	s_mov_b32 m0, s28
	s_nop 0
	global_load_lds_dwordx4 v130, s[26:27]
	s_add_i32 m0, s28, 0x2000
	s_nop 0
	global_load_lds_dwordx4 v134, s[26:27]
	s_waitcnt vmcnt(6)
	s_barrier
	s_setprio 1
	v_mfma_f32_16x16x32_bf16 v[52:55], v[202:205], v[170:173], v[52:55]
	v_mfma_f32_16x16x32_bf16 v[48:51], v[210:213], v[170:173], v[48:51]
	v_mfma_f32_16x16x32_bf16 v[36:39], v[202:205], v[178:181], v[36:39]
	v_mfma_f32_16x16x32_bf16 v[32:35], v[210:213], v[178:181], v[32:35]
	v_mfma_f32_16x16x32_bf16 v[20:23], v[202:205], v[186:189], v[20:23]
	v_mfma_f32_16x16x32_bf16 v[16:19], v[210:213], v[186:189], v[16:19]
	v_mfma_f32_16x16x32_bf16 v[4:7], v[202:205], v[194:197], v[4:7]
	v_mfma_f32_16x16x32_bf16 v[0:3], v[210:213], v[194:197], v[0:3]
	v_mfma_f32_16x16x32_bf16 v[52:55], v[206:209], v[174:177], v[52:55]
	v_mfma_f32_16x16x32_bf16 v[48:51], v[214:217], v[174:177], v[48:51]
	v_mfma_f32_16x16x32_bf16 v[36:39], v[206:209], v[182:185], v[36:39]
	v_mfma_f32_16x16x32_bf16 v[32:35], v[214:217], v[182:185], v[32:35]
	v_mfma_f32_16x16x32_bf16 v[20:23], v[206:209], v[190:193], v[20:23]
	v_mfma_f32_16x16x32_bf16 v[16:19], v[214:217], v[190:193], v[16:19]
	v_mfma_f32_16x16x32_bf16 v[4:7], v[206:209], v[198:201], v[4:7]
	v_mfma_f32_16x16x32_bf16 v[0:3], v[214:217], v[198:201], v[0:3]
	s_setprio 0
	s_add_i32 s54, s54, 2
	s_add_u32 s24, s24, 0x100
	s_addc_u32 s25, s25, 0
	s_add_u32 s52, s52, 0x100
	s_addc_u32 s53, s53, 0
	s_cmp_gt_u32 s54, 13
	s_barrier
	s_cbranch_scc0 .LBB0_203
	v_lshl_or_b32 v148, s22, 8, v152
	v_cmp_lt_i32_e32 vcc, s50, v148
	s_and_saveexec_b64 s[22:23], vcc
	s_cbranch_execz .LBB0_206
	v_mul_f32_e32 v149, 0x3d372713, v126
	v_mul_f32_e32 v145, 0x3d372713, v120
	v_mul_f32_e32 v149, v126, v149
	v_mul_f32_e32 v156, 0x3d372713, v122
	v_mul_f32_e32 v145, v120, v145
	v_mul_f32_e32 v146, 0x3d372713, v125
	v_fma_f32 v149, v126, v149, v126
	v_mul_f32_e32 v156, v122, v156
	v_fma_f32 v145, v120, v145, v120
	v_mul_f32_e32 v146, v125, v146
	v_mul_f32_e32 v149, 0xc0135761, v149
	v_fma_f32 v156, v122, v156, v122
	v_mul_f32_e32 v145, 0xc0135761, v145
	v_fma_f32 v146, v125, v146, v125
	v_exp_f32_e32 v149, v149
	v_mul_f32_e32 v156, 0xc0135761, v156
	v_exp_f32_e32 v145, v145
	v_mul_f32_e32 v146, 0xc0135761, v146
	v_exp_f32_e32 v157, v156
	v_exp_f32_e32 v147, v146
	v_add_f32_e32 v149, 1.0, v149
	v_add_f32_e32 v145, 1.0, v145
	v_rcp_f32_e32 v156, v149
	v_add_f32_e32 v149, 1.0, v157
	v_mul_f32_e32 v157, 0x3d372713, v127
	v_mul_f32_e32 v144, 0x3d372713, v124
	v_rcp_f32_e32 v146, v145
	v_add_f32_e32 v145, 1.0, v147
	v_mul_f32_e32 v147, 0x3d372713, v121
	v_mul_f32_e32 v157, v127, v157
	v_mul_f32_e32 v158, 0x3d372713, v123
	v_mul_f32_e32 v144, v124, v144
	v_mul_f32_e32 v147, v121, v147
	v_fma_f32 v157, v127, v157, v127
	v_mul_f32_e32 v158, v123, v158
	v_fma_f32 v144, v124, v144, v124
	v_fma_f32 v147, v121, v147, v121
	v_mul_f32_e32 v157, 0xc0135761, v157
	v_fma_f32 v158, v123, v158, v123
	v_mul_f32_e32 v144, 0xc0135761, v144
	v_mul_f32_e32 v147, 0xc0135761, v147
	v_exp_f32_e32 v157, v157
	v_mul_f32_e32 v158, 0xc0135761, v158
	v_exp_f32_e32 v144, v144
	v_exp_f32_e32 v147, v147
	v_exp_f32_e32 v159, v158
	v_rcp_f32_e32 v158, v149
	v_add_f32_e32 v149, 1.0, v157
	v_add_f32_e32 v144, 1.0, v144
	v_add_f32_e32 v147, 1.0, v147
	v_rcp_f32_e32 v157, v149
	v_add_f32_e32 v149, 1.0, v159
	v_rcp_f32_e32 v144, v144
	v_rcp_f32_e32 v145, v145
	v_rcp_f32_e32 v159, v149
	v_rcp_f32_e32 v147, v147
	v_pk_mul_f32 v[126:127], v[126:127], v[156:157]
	v_pk_mul_f32 v[124:125], v[124:125], v[144:145]
	v_pk_mul_f32 v[122:123], v[122:123], v[158:159]
	v_pk_mul_f32 v[120:121], v[120:121], v[146:147]

.LBB0_321:
	ds_read_b128 v[144:147], v157
	ds_read_b128 v[148:151], v157 offset:1024
	ds_read_b128 v[164:167], v157 offset:2048
	ds_read_b128 v[168:171], v157 offset:3072
	s_add_u32 s4, s8, 0x100
	s_addc_u32 s5, s9, 0
	s_cmp_eq_u32 s60, 2
	s_cselect_b32 s11, s29, s5
	s_cselect_b32 s10, s28, s4
	s_cselect_b32 s7, s31, s37
	s_cselect_b32 s6, s30, s35
	v_lshl_add_u64 v[152:153], s[8:9], 0, v[136:137]
	s_add_i32 m0, s46, 0xc000
	ds_read_b128 v[172:175], v158
	ds_read_b128 v[176:179], v158 offset:1024
	ds_read_b128 v[180:183], v158 offset:2048
	ds_read_b128 v[184:187], v158 offset:3072
	ds_read_b128 v[188:191], v158 offset:4096
	ds_read_b128 v[192:195], v158 offset:5120
	ds_read_b128 v[196:199], v158 offset:6144
	ds_read_b128 v[200:203], v158 offset:7168
	global_load_lds_dwordx4 v[152:153], off
	v_lshl_add_u64 v[152:153], s[8:9], 0, v[138:139]
	s_add_i32 m0, s46, 0xe000
	s_nop 0
	global_load_lds_dwordx4 v[152:153], off
	s_waitcnt lgkmcnt(8)
	s_barrier
	s_waitcnt lgkmcnt(0)
	s_setprio 1
	v_mfma_f32_16x16x32_bf16 v[124:127], v[144:147], v[172:175], v[124:127]
	v_mfma_f32_16x16x32_bf16 v[120:123], v[164:167], v[172:175], v[120:123]
	v_mfma_f32_16x16x32_bf16 v[116:119], v[144:147], v[180:183], v[116:119]
	v_mfma_f32_16x16x32_bf16 v[112:115], v[164:167], v[180:183], v[112:115]
	v_mfma_f32_16x16x32_bf16 v[108:111], v[144:147], v[188:191], v[108:111]
	v_mfma_f32_16x16x32_bf16 v[104:107], v[164:167], v[188:191], v[104:107]
	v_mfma_f32_16x16x32_bf16 v[100:103], v[144:147], v[196:199], v[100:103]
	v_mfma_f32_16x16x32_bf16 v[96:99], v[164:167], v[196:199], v[96:99]
	v_mfma_f32_16x16x32_bf16 v[124:127], v[148:151], v[176:179], v[124:127]
	v_mfma_f32_16x16x32_bf16 v[120:123], v[168:171], v[176:179], v[120:123]
	v_mfma_f32_16x16x32_bf16 v[116:119], v[148:151], v[184:187], v[116:119]
	v_mfma_f32_16x16x32_bf16 v[112:115], v[168:171], v[184:187], v[112:115]
	v_mfma_f32_16x16x32_bf16 v[108:111], v[148:151], v[192:195], v[108:111]
	v_mfma_f32_16x16x32_bf16 v[104:107], v[168:171], v[192:195], v[104:107]
	v_mfma_f32_16x16x32_bf16 v[100:103], v[148:151], v[200:203], v[100:103]
	v_mfma_f32_16x16x32_bf16 v[96:99], v[168:171], v[200:203], v[96:99]
	s_setprio 0
	s_barrier
	s_add_i32 s8, s54, s44
	s_add_u32 s98, s6, s26
	s_addc_u32 s99, s7, s27
	s_mov_b32 m0, s8
	ds_read_b128 v[204:207], v159
	ds_read_b128 v[208:211], v159 offset:1024
	ds_read_b128 v[212:215], v159 offset:2048
	ds_read_b128 v[216:219], v159 offset:3072
	global_load_lds_dwordx4 v130, s[6:7]
	s_add_i32 m0, s8, 0x2000
	s_nop 0
	global_load_lds_dwordx4 v134, s[6:7]
	s_barrier
	s_waitcnt lgkmcnt(0)
	s_setprio 1
	v_mfma_f32_16x16x32_bf16 v[60:63], v[204:207], v[172:175], v[60:63]
	v_mfma_f32_16x16x32_bf16 v[56:59], v[212:215], v[172:175], v[56:59]
	v_mfma_f32_16x16x32_bf16 v[52:55], v[204:207], v[180:183], v[52:55]
	v_mfma_f32_16x16x32_bf16 v[48:51], v[212:215], v[180:183], v[48:51]
	v_mfma_f32_16x16x32_bf16 v[44:47], v[204:207], v[188:191], v[44:47]
	v_mfma_f32_16x16x32_bf16 v[40:43], v[212:215], v[188:191], v[40:43]
	v_mfma_f32_16x16x32_bf16 v[36:39], v[204:207], v[196:199], v[36:39]
	v_mfma_f32_16x16x32_bf16 v[32:35], v[212:215], v[196:199], v[32:35]
	v_mfma_f32_16x16x32_bf16 v[60:63], v[208:211], v[176:179], v[60:63]
	v_mfma_f32_16x16x32_bf16 v[56:59], v[216:219], v[176:179], v[56:59]
	v_mfma_f32_16x16x32_bf16 v[52:55], v[208:211], v[184:187], v[52:55]
	v_mfma_f32_16x16x32_bf16 v[48:51], v[216:219], v[184:187], v[48:51]
	v_mfma_f32_16x16x32_bf16 v[44:47], v[208:211], v[192:195], v[44:47]
	v_mfma_f32_16x16x32_bf16 v[40:43], v[216:219], v[192:195], v[40:43]
	v_mfma_f32_16x16x32_bf16 v[36:39], v[208:211], v[200:203], v[36:39]
	v_mfma_f32_16x16x32_bf16 v[32:35], v[216:219], v[200:203], v[32:35]
	s_setprio 0
	s_mov_b32 m0, s46
	s_add_u32 s100, s10, s26
	s_addc_u32 s101, s11, s27
	s_barrier
	ds_read_b128 v[172:175], v158 offset:16384
	ds_read_b128 v[176:179], v158 offset:17408
	ds_read_b128 v[180:183], v158 offset:18432
	ds_read_b128 v[184:187], v158 offset:19456
	ds_read_b128 v[188:191], v158 offset:20480
	ds_read_b128 v[192:195], v158 offset:21504
	ds_read_b128 v[196:199], v158 offset:22528
	ds_read_b128 v[200:203], v158 offset:23552
	global_load_lds_dwordx4 v128, s[10:11]
	s_mov_b32 m0, s47
	s_nop 0
	global_load_lds_dwordx4 v132, s[10:11]
	s_barrier
	s_waitcnt lgkmcnt(0)
	s_setprio 1
	v_mfma_f32_16x16x32_bf16 v[92:95], v[144:147], v[172:175], v[92:95]
	v_mfma_f32_16x16x32_bf16 v[88:91], v[164:167], v[172:175], v[88:91]
	v_mfma_f32_16x16x32_bf16 v[84:87], v[144:147], v[180:183], v[84:87]
	v_mfma_f32_16x16x32_bf16 v[80:83], v[164:167], v[180:183], v[80:83]
	v_mfma_f32_16x16x32_bf16 v[76:79], v[144:147], v[188:191], v[76:79]
	v_mfma_f32_16x16x32_bf16 v[72:75], v[164:167], v[188:191], v[72:75]
	v_mfma_f32_16x16x32_bf16 v[68:71], v[144:147], v[196:199], v[68:71]
	v_mfma_f32_16x16x32_bf16 v[64:67], v[164:167], v[196:199], v[64:67]
	v_mfma_f32_16x16x32_bf16 v[92:95], v[148:151], v[176:179], v[92:95]
	v_mfma_f32_16x16x32_bf16 v[88:91], v[168:171], v[176:179], v[88:91]
	v_mfma_f32_16x16x32_bf16 v[84:87], v[148:151], v[184:187], v[84:87]
	v_mfma_f32_16x16x32_bf16 v[80:83], v[168:171], v[184:187], v[80:83]
	v_mfma_f32_16x16x32_bf16 v[76:79], v[148:151], v[192:195], v[76:79]
	v_mfma_f32_16x16x32_bf16 v[72:75], v[168:171], v[192:195], v[72:75]
	v_mfma_f32_16x16x32_bf16 v[68:71], v[148:151], v[200:203], v[68:71]
	v_mfma_f32_16x16x32_bf16 v[64:67], v[168:171], v[200:203], v[64:67]
	s_setprio 0
	s_barrier
	s_add_u32 s8, s6, 0x18000
	s_addc_u32 s9, s7, 0
	s_add_i32 s61, s55, s44
	s_mov_b32 m0, s61
	s_nop 0
	global_load_lds_dwordx4 v130, s[8:9]
	s_add_i32 m0, s61, 0x2000
	s_nop 0
	global_load_lds_dwordx4 v134, s[8:9]
	s_waitcnt vmcnt(6)
	s_barrier
	s_setprio 1
	v_mfma_f32_16x16x32_bf16 v[28:31], v[204:207], v[172:175], v[28:31]
	v_mfma_f32_16x16x32_bf16 v[24:27], v[212:215], v[172:175], v[24:27]
	v_mfma_f32_16x16x32_bf16 v[20:23], v[204:207], v[180:183], v[20:23]
	v_mfma_f32_16x16x32_bf16 v[16:19], v[212:215], v[180:183], v[16:19]
	v_mfma_f32_16x16x32_bf16 v[12:15], v[204:207], v[188:191], v[12:15]
	v_mfma_f32_16x16x32_bf16 v[8:11], v[212:215], v[188:191], v[8:11]
	v_mfma_f32_16x16x32_bf16 v[4:7], v[204:207], v[196:199], v[4:7]
	v_mfma_f32_16x16x32_bf16 v[0:3], v[212:215], v[196:199], v[0:3]
	v_mfma_f32_16x16x32_bf16 v[28:31], v[208:211], v[176:179], v[28:31]
	v_mfma_f32_16x16x32_bf16 v[24:27], v[216:219], v[176:179], v[24:27]
	v_mfma_f32_16x16x32_bf16 v[20:23], v[208:211], v[184:187], v[20:23]
	v_mfma_f32_16x16x32_bf16 v[16:19], v[216:219], v[184:187], v[16:19]
	v_mfma_f32_16x16x32_bf16 v[12:15], v[208:211], v[192:195], v[12:15]
	v_mfma_f32_16x16x32_bf16 v[8:11], v[216:219], v[192:195], v[8:11]
	v_mfma_f32_16x16x32_bf16 v[4:7], v[208:211], v[200:203], v[4:7]
	v_mfma_f32_16x16x32_bf16 v[0:3], v[216:219], v[200:203], v[0:3]
	s_setprio 0
	s_add_i32 s61, 0, 0x18000
	v_add_u32_e32 v163, s61, v155
	s_barrier
	ds_read_b128 v[144:147], v163
	ds_read_b128 v[148:151], v163 offset:1024
	ds_read_b128 v[164:167], v163 offset:2048
	ds_read_b128 v[168:171], v163 offset:3072
	s_add_u32 s8, s10, 0x18000
	s_addc_u32 s9, s11, 0
	s_mov_b32 m0, s48
	ds_read_b128 v[172:175], v158 offset:32768
	ds_read_b128 v[176:179], v158 offset:33792
	ds_read_b128 v[180:183], v158 offset:34816
	ds_read_b128 v[184:187], v158 offset:35840
	ds_read_b128 v[188:191], v158 offset:36864
	ds_read_b128 v[192:195], v158 offset:37888
	ds_read_b128 v[196:199], v158 offset:38912
	ds_read_b128 v[200:203], v158 offset:39936
	global_load_lds_dwordx4 v128, s[8:9]
	s_mov_b32 m0, s49
	s_nop 0
	global_load_lds_dwordx4 v132, s[8:9]
	s_waitcnt lgkmcnt(8)
	s_barrier
	s_waitcnt lgkmcnt(0)
	s_setprio 1
	v_mfma_f32_16x16x32_bf16 v[124:127], v[144:147], v[172:175], v[124:127]
	v_mfma_f32_16x16x32_bf16 v[120:123], v[164:167], v[172:175], v[120:123]
	v_mfma_f32_16x16x32_bf16 v[116:119], v[144:147], v[180:183], v[116:119]
	v_mfma_f32_16x16x32_bf16 v[112:115], v[164:167], v[180:183], v[112:115]
	v_mfma_f32_16x16x32_bf16 v[108:111], v[144:147], v[188:191], v[108:111]
	v_mfma_f32_16x16x32_bf16 v[104:107], v[164:167], v[188:191], v[104:107]
	v_mfma_f32_16x16x32_bf16 v[100:103], v[144:147], v[196:199], v[100:103]
	v_mfma_f32_16x16x32_bf16 v[96:99], v[164:167], v[196:199], v[96:99]
	v_mfma_f32_16x16x32_bf16 v[124:127], v[148:151], v[176:179], v[124:127]
	v_mfma_f32_16x16x32_bf16 v[120:123], v[168:171], v[176:179], v[120:123]
	v_mfma_f32_16x16x32_bf16 v[116:119], v[148:151], v[184:187], v[116:119]
	v_mfma_f32_16x16x32_bf16 v[112:115], v[168:171], v[184:187], v[112:115]
	v_mfma_f32_16x16x32_bf16 v[108:111], v[148:151], v[192:195], v[108:111]
	v_mfma_f32_16x16x32_bf16 v[104:107], v[168:171], v[192:195], v[104:107]
	v_mfma_f32_16x16x32_bf16 v[100:103], v[148:151], v[200:203], v[100:103]
	v_mfma_f32_16x16x32_bf16 v[96:99], v[168:171], v[200:203], v[96:99]
	s_setprio 0
	s_barrier
	s_add_i32 s8, 0, 0x1c000
	s_add_i32 s9, s61, s44
	v_add_u32_e32 v163, s8, v155
	s_mov_b32 m0, s9
	ds_read_b128 v[204:207], v163
	ds_read_b128 v[208:211], v163 offset:1024
	ds_read_b128 v[212:215], v163 offset:2048
	ds_read_b128 v[216:219], v163 offset:3072
	global_load_lds_dwordx4 v130, s[98:99]
	s_add_i32 m0, s9, 0x2000
	s_nop 0
	global_load_lds_dwordx4 v134, s[98:99]
	s_barrier
	s_waitcnt lgkmcnt(0)
	s_setprio 1
	v_mfma_f32_16x16x32_bf16 v[60:63], v[204:207], v[172:175], v[60:63]
	v_mfma_f32_16x16x32_bf16 v[56:59], v[212:215], v[172:175], v[56:59]
	v_mfma_f32_16x16x32_bf16 v[52:55], v[204:207], v[180:183], v[52:55]
	v_mfma_f32_16x16x32_bf16 v[48:51], v[212:215], v[180:183], v[48:51]
	v_mfma_f32_16x16x32_bf16 v[44:47], v[204:207], v[188:191], v[44:47]
	v_mfma_f32_16x16x32_bf16 v[40:43], v[212:215], v[188:191], v[40:43]
	v_mfma_f32_16x16x32_bf16 v[36:39], v[204:207], v[196:199], v[36:39]
	v_mfma_f32_16x16x32_bf16 v[32:35], v[212:215], v[196:199], v[32:35]
	v_mfma_f32_16x16x32_bf16 v[60:63], v[208:211], v[176:179], v[60:63]
	v_mfma_f32_16x16x32_bf16 v[56:59], v[216:219], v[176:179], v[56:59]
	v_mfma_f32_16x16x32_bf16 v[52:55], v[208:211], v[184:187], v[52:55]
	v_mfma_f32_16x16x32_bf16 v[48:51], v[216:219], v[184:187], v[48:51]
	v_mfma_f32_16x16x32_bf16 v[44:47], v[208:211], v[192:195], v[44:47]
	v_mfma_f32_16x16x32_bf16 v[40:43], v[216:219], v[192:195], v[40:43]
	v_mfma_f32_16x16x32_bf16 v[36:39], v[208:211], v[200:203], v[36:39]
	v_mfma_f32_16x16x32_bf16 v[32:35], v[216:219], v[200:203], v[32:35]
	s_setprio 0
	s_mov_b32 m0, s51
	s_barrier
	ds_read_b128 v[172:175], v158 offset:49152
	ds_read_b128 v[176:179], v158 offset:50176
	ds_read_b128 v[180:183], v158 offset:51200
	ds_read_b128 v[184:187], v158 offset:52224
	ds_read_b128 v[188:191], v158 offset:53248
	ds_read_b128 v[192:195], v158 offset:54272
	ds_read_b128 v[196:199], v158 offset:55296
	ds_read_b128 v[200:203], v158 offset:56320
	global_load_lds_dwordx4 v128, s[100:101]
	s_mov_b32 m0, s52
	s_nop 0
	global_load_lds_dwordx4 v132, s[100:101]
	s_barrier
	s_waitcnt lgkmcnt(0)
	s_setprio 1
	v_mfma_f32_16x16x32_bf16 v[92:95], v[144:147], v[172:175], v[92:95]
	v_mfma_f32_16x16x32_bf16 v[88:91], v[164:167], v[172:175], v[88:91]
	v_mfma_f32_16x16x32_bf16 v[84:87], v[144:147], v[180:183], v[84:87]
	v_mfma_f32_16x16x32_bf16 v[80:83], v[164:167], v[180:183], v[80:83]
	v_mfma_f32_16x16x32_bf16 v[76:79], v[144:147], v[188:191], v[76:79]
	v_mfma_f32_16x16x32_bf16 v[72:75], v[164:167], v[188:191], v[72:75]
	v_mfma_f32_16x16x32_bf16 v[68:71], v[144:147], v[196:199], v[68:71]
	v_mfma_f32_16x16x32_bf16 v[64:67], v[164:167], v[196:199], v[64:67]
	v_mfma_f32_16x16x32_bf16 v[92:95], v[148:151], v[176:179], v[92:95]
	v_mfma_f32_16x16x32_bf16 v[88:91], v[168:171], v[176:179], v[88:91]
	v_mfma_f32_16x16x32_bf16 v[84:87], v[148:151], v[184:187], v[84:87]
	v_mfma_f32_16x16x32_bf16 v[80:83], v[168:171], v[184:187], v[80:83]
	v_mfma_f32_16x16x32_bf16 v[76:79], v[148:151], v[192:195], v[76:79]
	v_mfma_f32_16x16x32_bf16 v[72:75], v[168:171], v[192:195], v[72:75]
	v_mfma_f32_16x16x32_bf16 v[68:71], v[148:151], v[200:203], v[68:71]
	v_mfma_f32_16x16x32_bf16 v[64:67], v[168:171], v[200:203], v[64:67]
	s_setprio 0
	s_barrier
	s_add_u32 s6, s6, 0x18080
	s_addc_u32 s7, s7, 0
	s_add_i32 s8, s8, s44
	s_mov_b32 m0, s8
	s_nop 0
	global_load_lds_dwordx4 v130, s[6:7]
	s_add_i32 m0, s8, 0x2000
	s_nop 0
	global_load_lds_dwordx4 v134, s[6:7]
	s_waitcnt vmcnt(6)
	s_barrier
	s_setprio 1
	v_mfma_f32_16x16x32_bf16 v[28:31], v[204:207], v[172:175], v[28:31]
	v_mfma_f32_16x16x32_bf16 v[24:27], v[212:215], v[172:175], v[24:27]
	v_mfma_f32_16x16x32_bf16 v[20:23], v[204:207], v[180:183], v[20:23]
	v_mfma_f32_16x16x32_bf16 v[16:19], v[212:215], v[180:183], v[16:19]
	v_mfma_f32_16x16x32_bf16 v[12:15], v[204:207], v[188:191], v[12:15]
	v_mfma_f32_16x16x32_bf16 v[8:11], v[212:215], v[188:191], v[8:11]
	v_mfma_f32_16x16x32_bf16 v[4:7], v[204:207], v[196:199], v[4:7]
	v_mfma_f32_16x16x32_bf16 v[0:3], v[212:215], v[196:199], v[0:3]
	v_mfma_f32_16x16x32_bf16 v[28:31], v[208:211], v[176:179], v[28:31]
	v_mfma_f32_16x16x32_bf16 v[24:27], v[216:219], v[176:179], v[24:27]
	v_mfma_f32_16x16x32_bf16 v[20:23], v[208:211], v[184:187], v[20:23]
	v_mfma_f32_16x16x32_bf16 v[16:19], v[216:219], v[184:187], v[16:19]
	v_mfma_f32_16x16x32_bf16 v[12:15], v[208:211], v[192:195], v[12:15]
	v_mfma_f32_16x16x32_bf16 v[8:11], v[216:219], v[192:195], v[8:11]
	v_mfma_f32_16x16x32_bf16 v[4:7], v[208:211], v[200:203], v[4:7]
	v_mfma_f32_16x16x32_bf16 v[0:3], v[216:219], v[200:203], v[0:3]
	s_setprio 0
	s_add_i32 s60, s60, 2
	s_add_u32 s35, s35, 0x100
	s_addc_u32 s37, s37, 0
	s_cmp_gt_u32 s60, 3
	s_mov_b64 s[8:9], s[4:5]
	s_barrier
	s_cbranch_scc0 .LBB0_321
	s_lshl_b32 s37, s34, 8
	s_ashr_i32 s6, s34, 1
	s_cmp_lt_i32 s6, 2
	s_cselect_b64 s[8:9], -1, 0
	s_cmp_gt_i32 s6, 1
	s_cselect_b64 s[34:35], -1, 0
	s_lshl_b32 s60, s6, 9
	s_add_i32 s61, s60, 0xfffffc00
	v_bitop3_b32 v144, s37, v161, v156 bitop3:0xc8
	v_or_b32_e32 v146, s61, v144
	v_or_b32_e32 v144, s60, v144
	v_mov_b32_e32 v145, 0
	s_cmp_lt_i32 s6, 4
	v_cndmask_b32_e64 v152, v146, v144, s[8:9]
	s_cselect_b64 s[4:5], -1, 0
	s_cmp_gt_i32 s6, 3
	v_ashrrev_i32_e32 v153, 31, v152
	v_mov_b32_e32 v144, v145
	s_cbranch_scc1 .LBB0_330
	s_and_b64 s[10:11], s[8:9], exec
	s_cselect_b32 s7, s21, s23
	s_cselect_b32 s10, s20, s22
	v_mov_b32_e32 v146, s10
	v_mov_b32_e32 v147, s7
	v_lshl_add_u64 v[146:147], v[152:153], 2, v[146:147]
	global_load_dword v144, v[146:147], off
	v_cndmask_b32_e64 v146, 0, 1, s[4:5]
	v_cmp_ne_u32_e64 s[10:11], 1, v146
	s_andn2_b64 vcc, exec, s[4:5]
	s_cbranch_vccz .LBB0_331

.LBB0_583:
	ds_read_b128 v[128:131], v164
	ds_read_b128 v[132:135], v164 offset:1024
	ds_read_b128 v[152:155], v164 offset:2048
	ds_read_b128 v[156:159], v164 offset:3072
	s_add_u32 s38, s36, 0xfffc0080
	s_addc_u32 s39, s37, -1
	s_cmp_eq_u32 s63, 12
	s_cselect_b32 s41, s9, s39
	s_cselect_b32 s40, s29, s38
	s_cselect_b32 s39, s27, s62
	s_cselect_b32 s38, s60, s61
	s_add_i32 m0, s50, 0xc000
	ds_read_b128 v[168:171], v165
	ds_read_b128 v[172:175], v165 offset:1024
	ds_read_b128 v[176:179], v165 offset:2048
	ds_read_b128 v[180:183], v165 offset:3072
	ds_read_b128 v[184:187], v165 offset:4096
	ds_read_b128 v[188:191], v165 offset:5120
	ds_read_b128 v[192:195], v165 offset:6144
	ds_read_b128 v[196:199], v165 offset:7168
	global_load_lds_dwordx4 v144, s[36:37]
	s_add_i32 m0, s50, 0xe000
	s_nop 0
	global_load_lds_dwordx4 v146, s[36:37]
	s_waitcnt lgkmcnt(8)
	s_barrier
	s_waitcnt lgkmcnt(0)
	s_setprio 1
	v_mfma_f32_16x16x32_bf16 v[120:123], v[128:131], v[168:171], v[120:123]
	v_mfma_f32_16x16x32_bf16 v[124:127], v[152:155], v[168:171], v[124:127]
	v_mfma_f32_16x16x32_bf16 v[104:107], v[128:131], v[176:179], v[104:107]
	v_mfma_f32_16x16x32_bf16 v[108:111], v[152:155], v[176:179], v[108:111]
	v_mfma_f32_16x16x32_bf16 v[88:91], v[128:131], v[184:187], v[88:91]
	v_mfma_f32_16x16x32_bf16 v[92:95], v[152:155], v[184:187], v[92:95]
	v_mfma_f32_16x16x32_bf16 v[72:75], v[128:131], v[192:195], v[72:75]
	v_mfma_f32_16x16x32_bf16 v[76:79], v[152:155], v[192:195], v[76:79]
	v_mfma_f32_16x16x32_bf16 v[120:123], v[132:135], v[172:175], v[120:123]
	v_mfma_f32_16x16x32_bf16 v[124:127], v[156:159], v[172:175], v[124:127]
	v_mfma_f32_16x16x32_bf16 v[104:107], v[132:135], v[180:183], v[104:107]
	v_mfma_f32_16x16x32_bf16 v[108:111], v[156:159], v[180:183], v[108:111]
	v_mfma_f32_16x16x32_bf16 v[88:91], v[132:135], v[188:191], v[88:91]
	v_mfma_f32_16x16x32_bf16 v[92:95], v[156:159], v[188:191], v[92:95]
	v_mfma_f32_16x16x32_bf16 v[72:75], v[132:135], v[196:199], v[72:75]
	v_mfma_f32_16x16x32_bf16 v[76:79], v[156:159], v[196:199], v[76:79]
	s_setprio 0
	s_barrier
	s_add_i32 s64, s57, s49
	s_add_u32 s98, s38, s22
	s_addc_u32 s99, s39, s23
	s_mov_b32 m0, s64
	ds_read_b128 v[200:203], v166
	ds_read_b128 v[204:207], v166 offset:1024
	ds_read_b128 v[208:211], v166 offset:2048
	ds_read_b128 v[212:215], v166 offset:3072
	global_load_lds_dwordx4 v138, s[38:39]
	s_add_i32 m0, s64, 0x2000
	s_nop 0
	global_load_lds_dwordx4 v142, s[38:39]
	s_barrier
	s_waitcnt lgkmcnt(0)
	s_setprio 1
	v_mfma_f32_16x16x32_bf16 v[112:115], v[200:203], v[168:171], v[112:115]
	v_mfma_f32_16x16x32_bf16 v[116:119], v[208:211], v[168:171], v[116:119]
	v_mfma_f32_16x16x32_bf16 v[96:99], v[200:203], v[176:179], v[96:99]
	v_mfma_f32_16x16x32_bf16 v[100:103], v[208:211], v[176:179], v[100:103]
	v_mfma_f32_16x16x32_bf16 v[80:83], v[200:203], v[184:187], v[80:83]
	v_mfma_f32_16x16x32_bf16 v[84:87], v[208:211], v[184:187], v[84:87]
	v_mfma_f32_16x16x32_bf16 v[64:67], v[200:203], v[192:195], v[64:67]
	v_mfma_f32_16x16x32_bf16 v[68:71], v[208:211], v[192:195], v[68:71]
	v_mfma_f32_16x16x32_bf16 v[112:115], v[204:207], v[172:175], v[112:115]
	v_mfma_f32_16x16x32_bf16 v[116:119], v[212:215], v[172:175], v[116:119]
	v_mfma_f32_16x16x32_bf16 v[96:99], v[204:207], v[180:183], v[96:99]
	v_mfma_f32_16x16x32_bf16 v[100:103], v[212:215], v[180:183], v[100:103]
	v_mfma_f32_16x16x32_bf16 v[80:83], v[204:207], v[188:191], v[80:83]
	v_mfma_f32_16x16x32_bf16 v[84:87], v[212:215], v[188:191], v[84:87]
	v_mfma_f32_16x16x32_bf16 v[64:67], v[204:207], v[196:199], v[64:67]
	v_mfma_f32_16x16x32_bf16 v[68:71], v[212:215], v[196:199], v[68:71]
	s_setprio 0
	s_mov_b32 m0, s50
	s_add_u32 s100, s40, s22
	s_addc_u32 s101, s41, s23
	s_barrier
	ds_read_b128 v[168:171], v165 offset:16384
	ds_read_b128 v[172:175], v165 offset:17408
	ds_read_b128 v[176:179], v165 offset:18432
	ds_read_b128 v[180:183], v165 offset:19456
	ds_read_b128 v[184:187], v165 offset:20480
	ds_read_b128 v[188:191], v165 offset:21504
	ds_read_b128 v[192:195], v165 offset:22528
	ds_read_b128 v[196:199], v165 offset:23552
	global_load_lds_dwordx4 v136, s[40:41]
	s_mov_b32 m0, s51
	s_nop 0
	global_load_lds_dwordx4 v140, s[40:41]
	s_barrier
	s_waitcnt lgkmcnt(0)
	s_setprio 1
	v_mfma_f32_16x16x32_bf16 v[56:59], v[128:131], v[168:171], v[56:59]
	v_mfma_f32_16x16x32_bf16 v[60:63], v[152:155], v[168:171], v[60:63]
	v_mfma_f32_16x16x32_bf16 v[40:43], v[128:131], v[176:179], v[40:43]
	v_mfma_f32_16x16x32_bf16 v[44:47], v[152:155], v[176:179], v[44:47]
	v_mfma_f32_16x16x32_bf16 v[24:27], v[128:131], v[184:187], v[24:27]
	v_mfma_f32_16x16x32_bf16 v[28:31], v[152:155], v[184:187], v[28:31]
	v_mfma_f32_16x16x32_bf16 v[8:11], v[128:131], v[192:195], v[8:11]
	v_mfma_f32_16x16x32_bf16 v[12:15], v[152:155], v[192:195], v[12:15]
	v_mfma_f32_16x16x32_bf16 v[56:59], v[132:135], v[172:175], v[56:59]
	v_mfma_f32_16x16x32_bf16 v[60:63], v[156:159], v[172:175], v[60:63]
	v_mfma_f32_16x16x32_bf16 v[40:43], v[132:135], v[180:183], v[40:43]
	v_mfma_f32_16x16x32_bf16 v[44:47], v[156:159], v[180:183], v[44:47]
	v_mfma_f32_16x16x32_bf16 v[24:27], v[132:135], v[188:191], v[24:27]
	v_mfma_f32_16x16x32_bf16 v[28:31], v[156:159], v[188:191], v[28:31]
	v_mfma_f32_16x16x32_bf16 v[8:11], v[132:135], v[196:199], v[8:11]
	v_mfma_f32_16x16x32_bf16 v[12:15], v[156:159], v[196:199], v[12:15]
	s_setprio 0
	s_barrier
	s_add_u32 s64, s38, 0x40000
	s_addc_u32 s65, s39, 0
	s_add_i32 s66, s58, s49
	s_mov_b32 m0, s66
	s_nop 0
	global_load_lds_dwordx4 v138, s[64:65]
	s_add_i32 m0, s66, 0x2000
	s_nop 0
	global_load_lds_dwordx4 v142, s[64:65]
	s_waitcnt vmcnt(6)
	s_barrier
	s_setprio 1
	v_mfma_f32_16x16x32_bf16 v[48:51], v[200:203], v[168:171], v[48:51]
	v_mfma_f32_16x16x32_bf16 v[52:55], v[208:211], v[168:171], v[52:55]
	v_mfma_f32_16x16x32_bf16 v[32:35], v[200:203], v[176:179], v[32:35]
	v_mfma_f32_16x16x32_bf16 v[36:39], v[208:211], v[176:179], v[36:39]
	v_mfma_f32_16x16x32_bf16 v[16:19], v[200:203], v[184:187], v[16:19]
	v_mfma_f32_16x16x32_bf16 v[20:23], v[208:211], v[184:187], v[20:23]
	v_mfma_f32_16x16x32_bf16 v[4:7], v[200:203], v[192:195], v[4:7]
	v_mfma_f32_16x16x32_bf16 v[0:3], v[208:211], v[192:195], v[0:3]
	v_mfma_f32_16x16x32_bf16 v[48:51], v[204:207], v[172:175], v[48:51]
	v_mfma_f32_16x16x32_bf16 v[52:55], v[212:215], v[172:175], v[52:55]
	v_mfma_f32_16x16x32_bf16 v[32:35], v[204:207], v[180:183], v[32:35]
	v_mfma_f32_16x16x32_bf16 v[36:39], v[212:215], v[180:183], v[36:39]
	v_mfma_f32_16x16x32_bf16 v[16:19], v[204:207], v[188:191], v[16:19]
	v_mfma_f32_16x16x32_bf16 v[20:23], v[212:215], v[188:191], v[20:23]
	v_mfma_f32_16x16x32_bf16 v[4:7], v[204:207], v[196:199], v[4:7]
	v_mfma_f32_16x16x32_bf16 v[0:3], v[212:215], v[196:199], v[0:3]
	s_setprio 0
	s_add_i32 s64, 0, 0x18000
	v_add_u32_e32 v156, s64, v162
	s_barrier
	ds_read_b128 v[128:131], v156
	ds_read_b128 v[132:135], v156 offset:1024
	ds_read_b128 v[152:155], v156 offset:2048
	ds_read_b128 v[156:159], v156 offset:3072
	s_add_u32 s40, s40, 0x40000
	s_addc_u32 s41, s41, 0
	s_mov_b32 m0, s52
	ds_read_b128 v[168:171], v165 offset:32768
	ds_read_b128 v[172:175], v165 offset:33792
	ds_read_b128 v[176:179], v165 offset:34816
	ds_read_b128 v[180:183], v165 offset:35840
	ds_read_b128 v[184:187], v165 offset:36864
	ds_read_b128 v[188:191], v165 offset:37888
	ds_read_b128 v[192:195], v165 offset:38912
	ds_read_b128 v[196:199], v165 offset:39936
	global_load_lds_dwordx4 v136, s[40:41]
	s_mov_b32 m0, s53
	s_nop 0
	global_load_lds_dwordx4 v140, s[40:41]
	s_waitcnt lgkmcnt(8)
	s_barrier
	s_waitcnt lgkmcnt(0)
	s_setprio 1
	v_mfma_f32_16x16x32_bf16 v[120:123], v[128:131], v[168:171], v[120:123]
	v_mfma_f32_16x16x32_bf16 v[124:127], v[152:155], v[168:171], v[124:127]
	v_mfma_f32_16x16x32_bf16 v[104:107], v[128:131], v[176:179], v[104:107]
	v_mfma_f32_16x16x32_bf16 v[108:111], v[152:155], v[176:179], v[108:111]
	v_mfma_f32_16x16x32_bf16 v[88:91], v[128:131], v[184:187], v[88:91]
	v_mfma_f32_16x16x32_bf16 v[92:95], v[152:155], v[184:187], v[92:95]
	v_mfma_f32_16x16x32_bf16 v[72:75], v[128:131], v[192:195], v[72:75]
	v_mfma_f32_16x16x32_bf16 v[76:79], v[152:155], v[192:195], v[76:79]
	v_mfma_f32_16x16x32_bf16 v[120:123], v[132:135], v[172:175], v[120:123]
	v_mfma_f32_16x16x32_bf16 v[124:127], v[156:159], v[172:175], v[124:127]
	v_mfma_f32_16x16x32_bf16 v[104:107], v[132:135], v[180:183], v[104:107]
	v_mfma_f32_16x16x32_bf16 v[108:111], v[156:159], v[180:183], v[108:111]
	v_mfma_f32_16x16x32_bf16 v[88:91], v[132:135], v[188:191], v[88:91]
	v_mfma_f32_16x16x32_bf16 v[92:95], v[156:159], v[188:191], v[92:95]
	v_mfma_f32_16x16x32_bf16 v[72:75], v[132:135], v[196:199], v[72:75]
	v_mfma_f32_16x16x32_bf16 v[76:79], v[156:159], v[196:199], v[76:79]
	s_setprio 0
	s_barrier
	s_add_i32 s40, 0, 0x1c000
	s_add_i32 s41, s64, s49
	v_add_u32_e32 v212, s40, v162
	s_mov_b32 m0, s41
	ds_read_b128 v[200:203], v212
	ds_read_b128 v[204:207], v212 offset:1024
	ds_read_b128 v[208:211], v212 offset:2048
	ds_read_b128 v[212:215], v212 offset:3072
	global_load_lds_dwordx4 v138, s[98:99]
	s_add_i32 m0, s41, 0x2000
	s_nop 0
	global_load_lds_dwordx4 v142, s[98:99]
	s_barrier
	s_waitcnt lgkmcnt(0)
	s_setprio 1
	v_mfma_f32_16x16x32_bf16 v[112:115], v[200:203], v[168:171], v[112:115]
	v_mfma_f32_16x16x32_bf16 v[116:119], v[208:211], v[168:171], v[116:119]
	v_mfma_f32_16x16x32_bf16 v[96:99], v[200:203], v[176:179], v[96:99]
	v_mfma_f32_16x16x32_bf16 v[100:103], v[208:211], v[176:179], v[100:103]
	v_mfma_f32_16x16x32_bf16 v[80:83], v[200:203], v[184:187], v[80:83]
	v_mfma_f32_16x16x32_bf16 v[84:87], v[208:211], v[184:187], v[84:87]
	v_mfma_f32_16x16x32_bf16 v[64:67], v[200:203], v[192:195], v[64:67]
	v_mfma_f32_16x16x32_bf16 v[68:71], v[208:211], v[192:195], v[68:71]
	v_mfma_f32_16x16x32_bf16 v[112:115], v[204:207], v[172:175], v[112:115]
	v_mfma_f32_16x16x32_bf16 v[116:119], v[212:215], v[172:175], v[116:119]
	v_mfma_f32_16x16x32_bf16 v[96:99], v[204:207], v[180:183], v[96:99]
	v_mfma_f32_16x16x32_bf16 v[100:103], v[212:215], v[180:183], v[100:103]
	v_mfma_f32_16x16x32_bf16 v[80:83], v[204:207], v[188:191], v[80:83]
	v_mfma_f32_16x16x32_bf16 v[84:87], v[212:215], v[188:191], v[84:87]
	v_mfma_f32_16x16x32_bf16 v[64:67], v[204:207], v[196:199], v[64:67]
	v_mfma_f32_16x16x32_bf16 v[68:71], v[212:215], v[196:199], v[68:71]
	s_setprio 0
	s_mov_b32 m0, s55
	s_barrier
	ds_read_b128 v[168:171], v165 offset:49152
	ds_read_b128 v[172:175], v165 offset:50176
	ds_read_b128 v[176:179], v165 offset:51200
	ds_read_b128 v[180:183], v165 offset:52224
	ds_read_b128 v[184:187], v165 offset:53248
	ds_read_b128 v[188:191], v165 offset:54272
	ds_read_b128 v[192:195], v165 offset:55296
	ds_read_b128 v[196:199], v165 offset:56320
	global_load_lds_dwordx4 v136, s[100:101]
	s_mov_b32 m0, s56
	s_nop 0
	global_load_lds_dwordx4 v140, s[100:101]
	s_barrier
	s_waitcnt lgkmcnt(0)
	s_setprio 1
	v_mfma_f32_16x16x32_bf16 v[56:59], v[128:131], v[168:171], v[56:59]
	v_mfma_f32_16x16x32_bf16 v[60:63], v[152:155], v[168:171], v[60:63]
	v_mfma_f32_16x16x32_bf16 v[40:43], v[128:131], v[176:179], v[40:43]
	v_mfma_f32_16x16x32_bf16 v[44:47], v[152:155], v[176:179], v[44:47]
	v_mfma_f32_16x16x32_bf16 v[24:27], v[128:131], v[184:187], v[24:27]
	v_mfma_f32_16x16x32_bf16 v[28:31], v[152:155], v[184:187], v[28:31]
	v_mfma_f32_16x16x32_bf16 v[8:11], v[128:131], v[192:195], v[8:11]
	v_mfma_f32_16x16x32_bf16 v[12:15], v[152:155], v[192:195], v[12:15]
	v_mfma_f32_16x16x32_bf16 v[56:59], v[132:135], v[172:175], v[56:59]
	v_mfma_f32_16x16x32_bf16 v[60:63], v[156:159], v[172:175], v[60:63]
	v_mfma_f32_16x16x32_bf16 v[40:43], v[132:135], v[180:183], v[40:43]
	v_mfma_f32_16x16x32_bf16 v[44:47], v[156:159], v[180:183], v[44:47]
	v_mfma_f32_16x16x32_bf16 v[24:27], v[132:135], v[188:191], v[24:27]
	v_mfma_f32_16x16x32_bf16 v[28:31], v[156:159], v[188:191], v[28:31]
	v_mfma_f32_16x16x32_bf16 v[8:11], v[132:135], v[196:199], v[8:11]
	v_mfma_f32_16x16x32_bf16 v[12:15], v[156:159], v[196:199], v[12:15]
	s_setprio 0
	s_barrier
	s_add_u32 s38, s38, 0x40080
	s_addc_u32 s39, s39, 0
	s_add_i32 s40, s40, s49
	s_mov_b32 m0, s40
	s_nop 0
	global_load_lds_dwordx4 v138, s[38:39]
	s_add_i32 m0, s40, 0x2000
	s_nop 0
	global_load_lds_dwordx4 v142, s[38:39]
	s_waitcnt vmcnt(6)
	s_barrier
	s_setprio 1
	v_mfma_f32_16x16x32_bf16 v[48:51], v[200:203], v[168:171], v[48:51]
	v_mfma_f32_16x16x32_bf16 v[52:55], v[208:211], v[168:171], v[52:55]
	v_mfma_f32_16x16x32_bf16 v[32:35], v[200:203], v[176:179], v[32:35]
	v_mfma_f32_16x16x32_bf16 v[36:39], v[208:211], v[176:179], v[36:39]
	v_mfma_f32_16x16x32_bf16 v[16:19], v[200:203], v[184:187], v[16:19]
	v_mfma_f32_16x16x32_bf16 v[20:23], v[208:211], v[184:187], v[20:23]
	v_mfma_f32_16x16x32_bf16 v[4:7], v[200:203], v[192:195], v[4:7]
	v_mfma_f32_16x16x32_bf16 v[0:3], v[208:211], v[192:195], v[0:3]
	v_mfma_f32_16x16x32_bf16 v[48:51], v[204:207], v[172:175], v[48:51]
	v_mfma_f32_16x16x32_bf16 v[52:55], v[212:215], v[172:175], v[52:55]
	v_mfma_f32_16x16x32_bf16 v[32:35], v[204:207], v[180:183], v[32:35]
	v_mfma_f32_16x16x32_bf16 v[36:39], v[212:215], v[180:183], v[36:39]
	v_mfma_f32_16x16x32_bf16 v[16:19], v[204:207], v[188:191], v[16:19]
	v_mfma_f32_16x16x32_bf16 v[20:23], v[212:215], v[188:191], v[20:23]
	v_mfma_f32_16x16x32_bf16 v[4:7], v[204:207], v[196:199], v[4:7]
	v_mfma_f32_16x16x32_bf16 v[0:3], v[212:215], v[196:199], v[0:3]
	s_setprio 0
	s_add_i32 s63, s63, 2
	s_add_u32 s36, s36, 0x100
	s_addc_u32 s37, s37, 0
	s_add_u32 s61, s61, 0x100
	s_addc_u32 s62, s62, 0
	s_cmp_gt_u32 s63, 13
	s_barrier
	s_cbranch_scc0 .LBB0_583
	v_lshl_add_u32 v152, s8, 8, v161
	v_lshl_or_b32 v153, s16, 8, v163
	s_lshl_b32 s36, s16, 2
	s_ashr_i32 s37, s36, 31
	s_lshl_b32 s16, s54, 2
	v_lshl_add_u32 v154, v152, 10, v153
	v_lshl_add_u32 v156, v152, 6, s16
	v_lshl_add_u32 v156, s36, 2, v156
	v_lshlrev_b32_e32 v155, 1, v154
	v_lshlrev_b32_e32 v154, 2, v154
	global_load_dwordx4 v[168:171], v154, s[14:15]
	global_load_dwordx4 v[172:175], v154, s[14:15] offset:16
	global_load_dwordx4 v[176:179], v154, s[14:15] offset:512
	global_load_dwordx4 v[180:183], v154, s[14:15] offset:528
	v_add_u32_e32 v154, 0x10000, v154
	global_load_dwordx4 v[184:187], v154, s[14:15]
	global_load_dwordx4 v[188:191], v154, s[14:15] offset:16
	global_load_dwordx4 v[192:195], v154, s[14:15] offset:512
	global_load_dwordx4 v[196:199], v154, s[14:15] offset:528
	v_add_u32_e32 v154, 0x10000, v154
	global_load_dwordx4 v[200:203], v154, s[14:15]
	global_load_dwordx4 v[204:207], v154, s[14:15] offset:16
	global_load_dwordx4 v[208:211], v154, s[14:15] offset:512
	global_load_dwordx4 v[212:215], v154, s[14:15] offset:528
	v_add_u32_e32 v154, 0x10000, v154
	global_load_dwordx4 v[216:219], v154, s[14:15]
	global_load_dwordx4 v[220:223], v154, s[14:15] offset:16
	global_load_dwordx4 v[128:131], v154, s[14:15] offset:512
	global_load_dwordx4 v[132:135], v154, s[14:15] offset:528
	v_add_u32_e32 v154, 0x50000, v154
	s_waitcnt vmcnt(12)
	v_pk_add_f32 v[120:121], v[120:121], v[168:169]
	v_pk_add_f32 v[122:123], v[122:123], v[170:171]
	v_pk_add_f32 v[124:125], v[124:125], v[172:173]
	v_pk_add_f32 v[126:127], v[126:127], v[174:175]
	v_cvt_pk_bf16_f32 v168, v120, v121
	v_cvt_pk_bf16_f32 v169, v122, v123
	v_cvt_pk_bf16_f32 v170, v124, v125
	v_cvt_pk_bf16_f32 v171, v126, v127
	v_pk_mul_f32 v[172:173], v[120:121], v[120:121]
	global_store_dwordx4 v155, v[168:171], s[18:19]
	v_pk_fma_f32 v[172:173], v[122:123], v[122:123], v[172:173]
	v_pk_fma_f32 v[172:173], v[124:125], v[124:125], v[172:173]
	v_pk_fma_f32 v[172:173], v[126:127], v[126:127], v[172:173]
	v_pk_add_f32 v[112:113], v[112:113], v[176:177]
	v_pk_add_f32 v[114:115], v[114:115], v[178:179]
	v_pk_add_f32 v[116:117], v[116:117], v[180:181]
	v_pk_add_f32 v[118:119], v[118:119], v[182:183]
	v_cvt_pk_bf16_f32 v176, v112, v113
	v_cvt_pk_bf16_f32 v177, v114, v115
	v_cvt_pk_bf16_f32 v178, v116, v117
	v_cvt_pk_bf16_f32 v179, v118, v119
	v_pk_fma_f32 v[172:173], v[112:113], v[112:113], v[172:173]
	global_store_dwordx4 v155, v[176:179], s[18:19] offset:256
	v_pk_fma_f32 v[172:173], v[114:115], v[114:115], v[172:173]
	v_pk_fma_f32 v[172:173], v[116:117], v[116:117], v[172:173]
	v_pk_fma_f32 v[172:173], v[118:119], v[118:119], v[172:173]
	v_add_f32_e32 v157, v172, v173
	v_add_u32_e32 v155, 0x8000, v155
	v_mov_b32_e32 v158, v157
	s_nop 1
	v_permlane16_swap_b32_e32 v157, v158
	s_nop 0
	v_add_f32_e32 v157, v157, v158
	v_mov_b32_e32 v158, v157
	s_nop 1
	v_permlane32_swap_b32_e32 v157, v158
	s_nop 0
	v_add_f32_e32 v157, v157, v158
	s_and_saveexec_b64 s[38:39], s[4:5]
	global_store_dword v156, v157, s[20:21]
	s_mov_b64 exec, s[38:39]
	global_load_dwordx4 v[168:171], v154, s[14:15]
	global_load_dwordx4 v[172:175], v154, s[14:15] offset:16
	global_load_dwordx4 v[176:179], v154, s[14:15] offset:512
	global_load_dwordx4 v[180:183], v154, s[14:15] offset:528
	v_add_u32_e32 v154, 0x10000, v154
	s_waitcnt vmcnt(15)
	v_pk_add_f32 v[104:105], v[104:105], v[184:185]
	v_pk_add_f32 v[106:107], v[106:107], v[186:187]
	v_pk_add_f32 v[108:109], v[108:109], v[188:189]
	v_pk_add_f32 v[110:111], v[110:111], v[190:191]
	v_cvt_pk_bf16_f32 v184, v104, v105
	v_cvt_pk_bf16_f32 v185, v106, v107
	v_cvt_pk_bf16_f32 v186, v108, v109
	v_cvt_pk_bf16_f32 v187, v110, v111
	v_pk_mul_f32 v[188:189], v[104:105], v[104:105]
	global_store_dwordx4 v155, v[184:187], s[18:19]
	v_pk_fma_f32 v[188:189], v[106:107], v[106:107], v[188:189]
	v_pk_fma_f32 v[188:189], v[108:109], v[108:109], v[188:189]
	v_pk_fma_f32 v[188:189], v[110:111], v[110:111], v[188:189]
	v_pk_add_f32 v[96:97], v[96:97], v[192:193]
	v_pk_add_f32 v[98:99], v[98:99], v[194:195]
	v_pk_add_f32 v[100:101], v[100:101], v[196:197]
	v_pk_add_f32 v[102:103], v[102:103], v[198:199]
	v_cvt_pk_bf16_f32 v192, v96, v97
	v_cvt_pk_bf16_f32 v193, v98, v99
	v_cvt_pk_bf16_f32 v194, v100, v101
	v_cvt_pk_bf16_f32 v195, v102, v103
	v_pk_fma_f32 v[188:189], v[96:97], v[96:97], v[188:189]
	global_store_dwordx4 v155, v[192:195], s[18:19] offset:256
	v_pk_fma_f32 v[188:189], v[98:99], v[98:99], v[188:189]
	v_pk_fma_f32 v[188:189], v[100:101], v[100:101], v[188:189]
	v_pk_fma_f32 v[188:189], v[102:103], v[102:103], v[188:189]
	v_add_f32_e32 v157, v188, v189
	v_add_u32_e32 v155, 0x8000, v155
	v_mov_b32_e32 v158, v157
	s_nop 1
	v_permlane16_swap_b32_e32 v157, v158
	s_nop 0
	v_add_f32_e32 v157, v157, v158
	v_mov_b32_e32 v158, v157
	s_nop 1
	v_permlane32_swap_b32_e32 v157, v158
	s_nop 0
	v_add_f32_e32 v157, v157, v158
	s_and_saveexec_b64 s[38:39], s[4:5]
	global_store_dword v156, v157, s[20:21] offset:1024
	s_mov_b64 exec, s[38:39]
	global_load_dwordx4 v[184:187], v154, s[14:15]
	global_load_dwordx4 v[188:191], v154, s[14:15] offset:16
	global_load_dwordx4 v[192:195], v154, s[14:15] offset:512
	global_load_dwordx4 v[196:199], v154, s[14:15] offset:528
	v_add_u32_e32 v154, 0x10000, v154
	s_waitcnt vmcnt(18)
	v_pk_add_f32 v[88:89], v[88:89], v[200:201]
	v_pk_add_f32 v[90:91], v[90:91], v[202:203]
	v_pk_add_f32 v[92:93], v[92:93], v[204:205]
	v_pk_add_f32 v[94:95], v[94:95], v[206:207]
	v_cvt_pk_bf16_f32 v200, v88, v89
	v_cvt_pk_bf16_f32 v201, v90, v91
	v_cvt_pk_bf16_f32 v202, v92, v93
	v_cvt_pk_bf16_f32 v203, v94, v95
	v_pk_mul_f32 v[204:205], v[88:89], v[88:89]
	global_store_dwordx4 v155, v[200:203], s[18:19]
	v_pk_fma_f32 v[204:205], v[90:91], v[90:91], v[204:205]
	v_pk_fma_f32 v[204:205], v[92:93], v[92:93], v[204:205]
	v_pk_fma_f32 v[204:205], v[94:95], v[94:95], v[204:205]
	v_pk_add_f32 v[80:81], v[80:81], v[208:209]
	v_pk_add_f32 v[82:83], v[82:83], v[210:211]
	v_pk_add_f32 v[84:85], v[84:85], v[212:213]
	v_pk_add_f32 v[86:87], v[86:87], v[214:215]
	v_cvt_pk_bf16_f32 v208, v80, v81
	v_cvt_pk_bf16_f32 v209, v82, v83
	v_cvt_pk_bf16_f32 v210, v84, v85
	v_cvt_pk_bf16_f32 v211, v86, v87
	v_pk_fma_f32 v[204:205], v[80:81], v[80:81], v[204:205]
	global_store_dwordx4 v155, v[208:211], s[18:19] offset:256
	v_pk_fma_f32 v[204:205], v[82:83], v[82:83], v[204:205]
	v_pk_fma_f32 v[204:205], v[84:85], v[84:85], v[204:205]
	v_pk_fma_f32 v[204:205], v[86:87], v[86:87], v[204:205]
	v_add_f32_e32 v157, v204, v205
	v_add_u32_e32 v155, 0x8000, v155
	v_mov_b32_e32 v158, v157
	s_nop 1
	v_permlane16_swap_b32_e32 v157, v158
	s_nop 0
	v_add_f32_e32 v157, v157, v158
	v_mov_b32_e32 v158, v157
	s_nop 1
	v_permlane32_swap_b32_e32 v157, v158
	s_nop 0
	v_add_f32_e32 v157, v157, v158
	s_and_saveexec_b64 s[38:39], s[4:5]
	global_store_dword v156, v157, s[20:21] offset:2048
	s_mov_b64 exec, s[38:39]
	global_load_dwordx4 v[200:203], v154, s[14:15]
	global_load_dwordx4 v[204:207], v154, s[14:15] offset:16
	global_load_dwordx4 v[208:211], v154, s[14:15] offset:512
	global_load_dwordx4 v[212:215], v154, s[14:15] offset:528
	v_add_u32_e32 v154, 0x10000, v154
	s_waitcnt vmcnt(21)
	v_pk_add_f32 v[72:73], v[72:73], v[216:217]
	v_pk_add_f32 v[74:75], v[74:75], v[218:219]
	v_pk_add_f32 v[76:77], v[76:77], v[220:221]
	v_pk_add_f32 v[78:79], v[78:79], v[222:223]
	v_cvt_pk_bf16_f32 v216, v72, v73
	v_cvt_pk_bf16_f32 v217, v74, v75
	v_cvt_pk_bf16_f32 v218, v76, v77
	v_cvt_pk_bf16_f32 v219, v78, v79
	v_pk_mul_f32 v[220:221], v[72:73], v[72:73]
	global_store_dwordx4 v155, v[216:219], s[18:19]
	v_pk_fma_f32 v[220:221], v[74:75], v[74:75], v[220:221]
	v_pk_fma_f32 v[220:221], v[76:77], v[76:77], v[220:221]
	v_pk_fma_f32 v[220:221], v[78:79], v[78:79], v[220:221]
	v_pk_add_f32 v[64:65], v[64:65], v[128:129]
	v_pk_add_f32 v[66:67], v[66:67], v[130:131]
	v_pk_add_f32 v[68:69], v[68:69], v[132:133]
	v_pk_add_f32 v[70:71], v[70:71], v[134:135]
	v_cvt_pk_bf16_f32 v128, v64, v65
	v_cvt_pk_bf16_f32 v129, v66, v67
	v_cvt_pk_bf16_f32 v130, v68, v69
	v_cvt_pk_bf16_f32 v131, v70, v71
	v_pk_fma_f32 v[220:221], v[64:65], v[64:65], v[220:221]
	global_store_dwordx4 v155, v[128:131], s[18:19] offset:256
	v_pk_fma_f32 v[220:221], v[66:67], v[66:67], v[220:221]
	v_pk_fma_f32 v[220:221], v[68:69], v[68:69], v[220:221]
	v_pk_fma_f32 v[220:221], v[70:71], v[70:71], v[220:221]
	v_add_f32_e32 v157, v220, v221
	v_add_u32_e32 v155, 0x28000, v155
	v_mov_b32_e32 v158, v157
	s_nop 1
	v_permlane16_swap_b32_e32 v157, v158
	s_nop 0
	v_add_f32_e32 v157, v157, v158
	v_mov_b32_e32 v158, v157
	s_nop 1
	v_permlane32_swap_b32_e32 v157, v158
	s_nop 0
	v_add_f32_e32 v157, v157, v158
	s_and_saveexec_b64 s[38:39], s[4:5]
	global_store_dword v156, v157, s[20:21] offset:3072
	s_mov_b64 exec, s[38:39]
	v_add_u32_e32 v156, 0x2000, v156
	global_load_dwordx4 v[216:219], v154, s[14:15]
	global_load_dwordx4 v[220:223], v154, s[14:15] offset:16
	global_load_dwordx4 v[128:131], v154, s[14:15] offset:512
	global_load_dwordx4 v[132:135], v154, s[14:15] offset:528
	s_waitcnt vmcnt(21)
	v_pk_add_f32 v[56:57], v[56:57], v[168:169]
	v_pk_add_f32 v[58:59], v[58:59], v[170:171]
	v_pk_add_f32 v[60:61], v[60:61], v[172:173]
	v_pk_add_f32 v[62:63], v[62:63], v[174:175]
	v_cvt_pk_bf16_f32 v168, v56, v57
	v_cvt_pk_bf16_f32 v169, v58, v59
	v_cvt_pk_bf16_f32 v170, v60, v61
	v_cvt_pk_bf16_f32 v171, v62, v63
	v_pk_mul_f32 v[172:173], v[56:57], v[56:57]
	global_store_dwordx4 v155, v[168:171], s[18:19]
	v_pk_fma_f32 v[172:173], v[58:59], v[58:59], v[172:173]
	v_pk_fma_f32 v[172:173], v[60:61], v[60:61], v[172:173]
	v_pk_fma_f32 v[172:173], v[62:63], v[62:63], v[172:173]
	v_pk_add_f32 v[48:49], v[48:49], v[176:177]
	v_pk_add_f32 v[50:51], v[50:51], v[178:179]
	v_pk_add_f32 v[52:53], v[52:53], v[180:181]
	v_pk_add_f32 v[54:55], v[54:55], v[182:183]
	v_cvt_pk_bf16_f32 v176, v48, v49
	v_cvt_pk_bf16_f32 v177, v50, v51
	v_cvt_pk_bf16_f32 v178, v52, v53
	v_cvt_pk_bf16_f32 v179, v54, v55
	v_pk_fma_f32 v[172:173], v[48:49], v[48:49], v[172:173]
	global_store_dwordx4 v155, v[176:179], s[18:19] offset:256
	v_pk_fma_f32 v[172:173], v[50:51], v[50:51], v[172:173]
	v_pk_fma_f32 v[172:173], v[52:53], v[52:53], v[172:173]
	v_pk_fma_f32 v[172:173], v[54:55], v[54:55], v[172:173]
	v_add_f32_e32 v157, v172, v173
	v_add_u32_e32 v155, 0x8000, v155
	v_mov_b32_e32 v158, v157
	s_nop 1
	v_permlane16_swap_b32_e32 v157, v158
	s_nop 0
	v_add_f32_e32 v157, v157, v158
	v_mov_b32_e32 v158, v157
	s_nop 1
	v_permlane32_swap_b32_e32 v157, v158
	s_nop 0
	v_add_f32_e32 v157, v157, v158
	s_and_saveexec_b64 s[38:39], s[4:5]
	global_store_dword v156, v157, s[20:21]
	s_mov_b64 exec, s[38:39]
	s_waitcnt vmcnt(17)
	v_pk_add_f32 v[40:41], v[40:41], v[184:185]
	v_pk_add_f32 v[42:43], v[42:43], v[186:187]
	v_pk_add_f32 v[44:45], v[44:45], v[188:189]
	v_pk_add_f32 v[46:47], v[46:47], v[190:191]
	v_cvt_pk_bf16_f32 v184, v40, v41
	v_cvt_pk_bf16_f32 v185, v42, v43
	v_cvt_pk_bf16_f32 v186, v44, v45
	v_cvt_pk_bf16_f32 v187, v46, v47
	v_pk_mul_f32 v[188:189], v[40:41], v[40:41]
	global_store_dwordx4 v155, v[184:187], s[18:19]
	v_pk_fma_f32 v[188:189], v[42:43], v[42:43], v[188:189]
	v_pk_fma_f32 v[188:189], v[44:45], v[44:45], v[188:189]
	v_pk_fma_f32 v[188:189], v[46:47], v[46:47], v[188:189]
	v_pk_add_f32 v[32:33], v[32:33], v[192:193]
	v_pk_add_f32 v[34:35], v[34:35], v[194:195]
	v_pk_add_f32 v[36:37], v[36:37], v[196:197]
	v_pk_add_f32 v[38:39], v[38:39], v[198:199]
	v_cvt_pk_bf16_f32 v192, v32, v33
	v_cvt_pk_bf16_f32 v193, v34, v35
	v_cvt_pk_bf16_f32 v194, v36, v37
	v_cvt_pk_bf16_f32 v195, v38, v39
	v_pk_fma_f32 v[188:189], v[32:33], v[32:33], v[188:189]
	global_store_dwordx4 v155, v[192:195], s[18:19] offset:256
	v_pk_fma_f32 v[188:189], v[34:35], v[34:35], v[188:189]
	v_pk_fma_f32 v[188:189], v[36:37], v[36:37], v[188:189]
	v_pk_fma_f32 v[188:189], v[38:39], v[38:39], v[188:189]
	v_add_f32_e32 v157, v188, v189
	v_add_u32_e32 v155, 0x8000, v155
	v_mov_b32_e32 v158, v157
	s_nop 1
	v_permlane16_swap_b32_e32 v157, v158
	s_nop 0
	v_add_f32_e32 v157, v157, v158
	v_mov_b32_e32 v158, v157
	s_nop 1
	v_permlane32_swap_b32_e32 v157, v158
	s_nop 0
	v_add_f32_e32 v157, v157, v158
	s_and_saveexec_b64 s[38:39], s[4:5]
	global_store_dword v156, v157, s[20:21] offset:1024
	s_mov_b64 exec, s[38:39]
	s_waitcnt vmcnt(13)
	v_pk_add_f32 v[24:25], v[24:25], v[200:201]
	v_pk_add_f32 v[26:27], v[26:27], v[202:203]
	v_pk_add_f32 v[28:29], v[28:29], v[204:205]
	v_pk_add_f32 v[30:31], v[30:31], v[206:207]
	v_cvt_pk_bf16_f32 v200, v24, v25
	v_cvt_pk_bf16_f32 v201, v26, v27
	v_cvt_pk_bf16_f32 v202, v28, v29
	v_cvt_pk_bf16_f32 v203, v30, v31
	v_pk_mul_f32 v[204:205], v[24:25], v[24:25]
	global_store_dwordx4 v155, v[200:203], s[18:19]
	v_pk_fma_f32 v[204:205], v[26:27], v[26:27], v[204:205]
	v_pk_fma_f32 v[204:205], v[28:29], v[28:29], v[204:205]
	v_pk_fma_f32 v[204:205], v[30:31], v[30:31], v[204:205]
	v_pk_add_f32 v[16:17], v[16:17], v[208:209]
	v_pk_add_f32 v[18:19], v[18:19], v[210:211]
	v_pk_add_f32 v[20:21], v[20:21], v[212:213]
	v_pk_add_f32 v[22:23], v[22:23], v[214:215]
	v_cvt_pk_bf16_f32 v208, v16, v17
	v_cvt_pk_bf16_f32 v209, v18, v19
	v_cvt_pk_bf16_f32 v210, v20, v21
	v_cvt_pk_bf16_f32 v211, v22, v23
	v_pk_fma_f32 v[204:205], v[16:17], v[16:17], v[204:205]
	global_store_dwordx4 v155, v[208:211], s[18:19] offset:256
	v_pk_fma_f32 v[204:205], v[18:19], v[18:19], v[204:205]
	v_pk_fma_f32 v[204:205], v[20:21], v[20:21], v[204:205]
	v_pk_fma_f32 v[204:205], v[22:23], v[22:23], v[204:205]
	v_add_f32_e32 v157, v204, v205
	v_add_u32_e32 v155, 0x8000, v155
	v_mov_b32_e32 v158, v157
	s_nop 1
	v_permlane16_swap_b32_e32 v157, v158
	s_nop 0
	v_add_f32_e32 v157, v157, v158
	v_mov_b32_e32 v158, v157
	s_nop 1
	v_permlane32_swap_b32_e32 v157, v158
	s_nop 0
	v_add_f32_e32 v157, v157, v158
	s_and_saveexec_b64 s[38:39], s[4:5]
	global_store_dword v156, v157, s[20:21] offset:2048
	s_mov_b64 exec, s[38:39]
	s_waitcnt vmcnt(9)
	v_pk_add_f32 v[8:9], v[8:9], v[216:217]
	v_pk_add_f32 v[10:11], v[10:11], v[218:219]
	v_pk_add_f32 v[12:13], v[12:13], v[220:221]
	v_pk_add_f32 v[14:15], v[14:15], v[222:223]
	v_cvt_pk_bf16_f32 v216, v8, v9
	v_cvt_pk_bf16_f32 v217, v10, v11
	v_cvt_pk_bf16_f32 v218, v12, v13
	v_cvt_pk_bf16_f32 v219, v14, v15
	v_pk_mul_f32 v[220:221], v[8:9], v[8:9]
	global_store_dwordx4 v155, v[216:219], s[18:19]
	v_pk_fma_f32 v[220:221], v[10:11], v[10:11], v[220:221]
	v_pk_fma_f32 v[220:221], v[12:13], v[12:13], v[220:221]
	v_pk_fma_f32 v[220:221], v[14:15], v[14:15], v[220:221]
	v_pk_add_f32 v[4:5], v[4:5], v[128:129]
	v_pk_add_f32 v[6:7], v[6:7], v[130:131]
	v_pk_add_f32 v[0:1], v[0:1], v[132:133]
	v_pk_add_f32 v[2:3], v[2:3], v[134:135]
	v_cvt_pk_bf16_f32 v128, v4, v5
	v_cvt_pk_bf16_f32 v129, v6, v7
	v_cvt_pk_bf16_f32 v130, v0, v1
	v_cvt_pk_bf16_f32 v131, v2, v3
	v_pk_fma_f32 v[220:221], v[4:5], v[4:5], v[220:221]
	global_store_dwordx4 v155, v[128:131], s[18:19] offset:256
	v_pk_fma_f32 v[220:221], v[6:7], v[6:7], v[220:221]
	v_pk_fma_f32 v[220:221], v[0:1], v[0:1], v[220:221]
	v_pk_fma_f32 v[220:221], v[2:3], v[2:3], v[220:221]
	v_add_f32_e32 v157, v220, v221
	v_add_u32_e32 v155, 0x8000, v155
	v_mov_b32_e32 v158, v157
	s_nop 1
	v_permlane16_swap_b32_e32 v157, v158
	s_nop 0
	v_add_f32_e32 v157, v157, v158
	v_mov_b32_e32 v158, v157
	s_nop 1
	v_permlane32_swap_b32_e32 v157, v158
	s_nop 0
	v_add_f32_e32 v157, v157, v158
	s_and_saveexec_b64 s[38:39], s[4:5]
	global_store_dword v156, v157, s[20:21] offset:3072
	s_mov_b64 exec, s[38:39]
	s_branch .LBB0_575

.LBB0_698:
	s_add_u32 s28, s26, 0xfffc0080
	s_addc_u32 s29, s27, -1
	s_add_i32 s68, 0, 0x10000
	v_add_u32_e32 v155, s68, v153
	ds_read_b128 v[138:141], v155
	ds_read_b128 v[142:145], v155 offset:1024
	ds_read_b128 v[146:149], v155 offset:2048
	ds_read_b128 v[156:159], v155 offset:3072
	s_cmp_eq_u32 s51, 12
	s_cselect_b32 s31, s21, s29
	s_cselect_b32 s30, s38, s28
	s_cselect_b32 s29, s7, s50
	s_cselect_b32 s28, s39, s46
	s_add_i32 m0, s58, 0xc000
	ds_read_b128 v[160:163], v154
	ds_read_b128 v[164:167], v154 offset:1024
	ds_read_b128 v[168:171], v154 offset:2048
	ds_read_b128 v[172:175], v154 offset:3072
	ds_read_b128 v[176:179], v154 offset:4096
	ds_read_b128 v[180:183], v154 offset:5120
	ds_read_b128 v[184:187], v154 offset:6144
	ds_read_b128 v[188:191], v154 offset:7168
	global_load_lds_dwordx4 v134, s[26:27]
	s_add_i32 m0, s58, 0xe000
	s_nop 0
	global_load_lds_dwordx4 v136, s[26:27]
	s_waitcnt lgkmcnt(8)
	s_barrier
	s_waitcnt lgkmcnt(0)
	s_setprio 1
	v_mfma_f32_16x16x32_bf16 v[124:127], v[138:141], v[160:163], v[124:127]
	v_mfma_f32_16x16x32_bf16 v[120:123], v[146:149], v[160:163], v[120:123]
	v_mfma_f32_16x16x32_bf16 v[108:111], v[138:141], v[168:171], v[108:111]
	v_mfma_f32_16x16x32_bf16 v[104:107], v[146:149], v[168:171], v[104:107]
	v_mfma_f32_16x16x32_bf16 v[92:95], v[138:141], v[176:179], v[92:95]
	v_mfma_f32_16x16x32_bf16 v[88:91], v[146:149], v[176:179], v[88:91]
	v_mfma_f32_16x16x32_bf16 v[76:79], v[138:141], v[184:187], v[76:79]
	v_mfma_f32_16x16x32_bf16 v[72:75], v[146:149], v[184:187], v[72:75]
	v_mfma_f32_16x16x32_bf16 v[124:127], v[142:145], v[164:167], v[124:127]
	v_mfma_f32_16x16x32_bf16 v[120:123], v[156:159], v[164:167], v[120:123]
	v_mfma_f32_16x16x32_bf16 v[108:111], v[142:145], v[172:175], v[108:111]
	v_mfma_f32_16x16x32_bf16 v[104:107], v[156:159], v[172:175], v[104:107]
	v_mfma_f32_16x16x32_bf16 v[92:95], v[142:145], v[180:183], v[92:95]
	v_mfma_f32_16x16x32_bf16 v[88:91], v[156:159], v[180:183], v[88:91]
	v_mfma_f32_16x16x32_bf16 v[76:79], v[142:145], v[188:191], v[76:79]
	v_mfma_f32_16x16x32_bf16 v[72:75], v[156:159], v[188:191], v[72:75]
	s_setprio 0
	s_barrier
	s_add_i32 s70, 0, 0x14000
	s_add_i32 s68, s68, s57
	v_add_u32_e32 v155, s70, v153
	s_add_u32 s98, s28, s40
	s_addc_u32 s99, s29, s41
	s_mov_b32 m0, s68
	ds_read_b128 v[192:195], v155
	ds_read_b128 v[196:199], v155 offset:1024
	ds_read_b128 v[200:203], v155 offset:2048
	ds_read_b128 v[204:207], v155 offset:3072
	global_load_lds_dwordx4 v208, s[28:29]
	s_add_i32 m0, s68, 0x2000
	s_nop 0
	global_load_lds_dwordx4 v128, s[28:29]
	s_barrier
	s_waitcnt lgkmcnt(0)
	s_setprio 1
	v_mfma_f32_16x16x32_bf16 v[116:119], v[192:195], v[160:163], v[116:119]
	v_mfma_f32_16x16x32_bf16 v[112:115], v[200:203], v[160:163], v[112:115]
	v_mfma_f32_16x16x32_bf16 v[100:103], v[192:195], v[168:171], v[100:103]
	v_mfma_f32_16x16x32_bf16 v[96:99], v[200:203], v[168:171], v[96:99]
	v_mfma_f32_16x16x32_bf16 v[84:87], v[192:195], v[176:179], v[84:87]
	v_mfma_f32_16x16x32_bf16 v[80:83], v[200:203], v[176:179], v[80:83]
	v_mfma_f32_16x16x32_bf16 v[68:71], v[192:195], v[184:187], v[68:71]
	v_mfma_f32_16x16x32_bf16 v[64:67], v[200:203], v[184:187], v[64:67]
	v_mfma_f32_16x16x32_bf16 v[116:119], v[196:199], v[164:167], v[116:119]
	v_mfma_f32_16x16x32_bf16 v[112:115], v[204:207], v[164:167], v[112:115]
	v_mfma_f32_16x16x32_bf16 v[100:103], v[196:199], v[172:175], v[100:103]
	v_mfma_f32_16x16x32_bf16 v[96:99], v[204:207], v[172:175], v[96:99]
	v_mfma_f32_16x16x32_bf16 v[84:87], v[196:199], v[180:183], v[84:87]
	v_mfma_f32_16x16x32_bf16 v[80:83], v[204:207], v[180:183], v[80:83]
	v_mfma_f32_16x16x32_bf16 v[68:71], v[196:199], v[188:191], v[68:71]
	v_mfma_f32_16x16x32_bf16 v[64:67], v[204:207], v[188:191], v[64:67]
	s_setprio 0
	s_mov_b32 m0, s58
	s_add_u32 s100, s30, s40
	s_addc_u32 s101, s31, s41
	s_barrier
	ds_read_b128 v[160:163], v154 offset:16384
	ds_read_b128 v[164:167], v154 offset:17408
	ds_read_b128 v[168:171], v154 offset:18432
	ds_read_b128 v[172:175], v154 offset:19456
	ds_read_b128 v[176:179], v154 offset:20480
	ds_read_b128 v[180:183], v154 offset:21504
	ds_read_b128 v[184:187], v154 offset:22528
	ds_read_b128 v[188:191], v154 offset:23552
	global_load_lds_dwordx4 v132, s[30:31]
	s_mov_b32 m0, s59
	s_nop 0
	global_load_lds_dwordx4 v130, s[30:31]
	s_barrier
	s_waitcnt lgkmcnt(0)
	s_setprio 1
	v_mfma_f32_16x16x32_bf16 v[60:63], v[138:141], v[160:163], v[60:63]
	v_mfma_f32_16x16x32_bf16 v[56:59], v[146:149], v[160:163], v[56:59]
	v_mfma_f32_16x16x32_bf16 v[44:47], v[138:141], v[168:171], v[44:47]
	v_mfma_f32_16x16x32_bf16 v[40:43], v[146:149], v[168:171], v[40:43]
	v_mfma_f32_16x16x32_bf16 v[28:31], v[138:141], v[176:179], v[28:31]
	v_mfma_f32_16x16x32_bf16 v[24:27], v[146:149], v[176:179], v[24:27]
	v_mfma_f32_16x16x32_bf16 v[12:15], v[138:141], v[184:187], v[12:15]
	v_mfma_f32_16x16x32_bf16 v[8:11], v[146:149], v[184:187], v[8:11]
	v_mfma_f32_16x16x32_bf16 v[60:63], v[142:145], v[164:167], v[60:63]
	v_mfma_f32_16x16x32_bf16 v[56:59], v[156:159], v[164:167], v[56:59]
	v_mfma_f32_16x16x32_bf16 v[44:47], v[142:145], v[172:175], v[44:47]
	v_mfma_f32_16x16x32_bf16 v[40:43], v[156:159], v[172:175], v[40:43]
	v_mfma_f32_16x16x32_bf16 v[28:31], v[142:145], v[180:183], v[28:31]
	v_mfma_f32_16x16x32_bf16 v[24:27], v[156:159], v[180:183], v[24:27]
	v_mfma_f32_16x16x32_bf16 v[12:15], v[142:145], v[188:191], v[12:15]
	v_mfma_f32_16x16x32_bf16 v[8:11], v[156:159], v[188:191], v[8:11]
	s_setprio 0
	s_barrier
	s_add_u32 s68, s28, 0x40000
	s_addc_u32 s69, s29, 0
	s_add_i32 s70, s70, s57
	s_mov_b32 m0, s70
	s_nop 0
	global_load_lds_dwordx4 v208, s[68:69]
	s_add_i32 m0, s70, 0x2000
	s_nop 0
	global_load_lds_dwordx4 v128, s[68:69]
	s_waitcnt vmcnt(6)
	s_barrier
	s_setprio 1
	v_mfma_f32_16x16x32_bf16 v[52:55], v[192:195], v[160:163], v[52:55]
	v_mfma_f32_16x16x32_bf16 v[48:51], v[200:203], v[160:163], v[48:51]
	v_mfma_f32_16x16x32_bf16 v[36:39], v[192:195], v[168:171], v[36:39]
	v_mfma_f32_16x16x32_bf16 v[32:35], v[200:203], v[168:171], v[32:35]
	v_mfma_f32_16x16x32_bf16 v[20:23], v[192:195], v[176:179], v[20:23]
	v_mfma_f32_16x16x32_bf16 v[16:19], v[200:203], v[176:179], v[16:19]
	v_mfma_f32_16x16x32_bf16 v[4:7], v[192:195], v[184:187], v[4:7]
	v_mfma_f32_16x16x32_bf16 v[0:3], v[200:203], v[184:187], v[0:3]
	v_mfma_f32_16x16x32_bf16 v[52:55], v[196:199], v[164:167], v[52:55]
	v_mfma_f32_16x16x32_bf16 v[48:51], v[204:207], v[164:167], v[48:51]
	v_mfma_f32_16x16x32_bf16 v[36:39], v[196:199], v[172:175], v[36:39]
	v_mfma_f32_16x16x32_bf16 v[32:35], v[204:207], v[172:175], v[32:35]
	v_mfma_f32_16x16x32_bf16 v[20:23], v[196:199], v[180:183], v[20:23]
	v_mfma_f32_16x16x32_bf16 v[16:19], v[204:207], v[180:183], v[16:19]
	v_mfma_f32_16x16x32_bf16 v[4:7], v[196:199], v[188:191], v[4:7]
	v_mfma_f32_16x16x32_bf16 v[0:3], v[204:207], v[188:191], v[0:3]
	s_setprio 0
	s_add_i32 s68, 0, 0x18000
	v_add_u32_e32 v155, s68, v153
	s_barrier
	ds_read_b128 v[138:141], v155
	ds_read_b128 v[142:145], v155 offset:1024
	ds_read_b128 v[146:149], v155 offset:2048
	ds_read_b128 v[156:159], v155 offset:3072
	s_add_u32 s30, s30, 0x40000
	s_addc_u32 s31, s31, 0
	s_mov_b32 m0, s60
	ds_read_b128 v[160:163], v154 offset:32768
	ds_read_b128 v[164:167], v154 offset:33792
	ds_read_b128 v[168:171], v154 offset:34816
	ds_read_b128 v[172:175], v154 offset:35840
	ds_read_b128 v[176:179], v154 offset:36864
	ds_read_b128 v[180:183], v154 offset:37888
	ds_read_b128 v[184:187], v154 offset:38912
	ds_read_b128 v[188:191], v154 offset:39936
	global_load_lds_dwordx4 v132, s[30:31]
	s_mov_b32 m0, s61
	s_nop 0
	global_load_lds_dwordx4 v130, s[30:31]
	s_waitcnt lgkmcnt(8)
	s_barrier
	s_waitcnt lgkmcnt(0)
	s_setprio 1
	v_mfma_f32_16x16x32_bf16 v[124:127], v[138:141], v[160:163], v[124:127]
	v_mfma_f32_16x16x32_bf16 v[120:123], v[146:149], v[160:163], v[120:123]
	v_mfma_f32_16x16x32_bf16 v[108:111], v[138:141], v[168:171], v[108:111]
	v_mfma_f32_16x16x32_bf16 v[104:107], v[146:149], v[168:171], v[104:107]
	v_mfma_f32_16x16x32_bf16 v[92:95], v[138:141], v[176:179], v[92:95]
	v_mfma_f32_16x16x32_bf16 v[88:91], v[146:149], v[176:179], v[88:91]
	v_mfma_f32_16x16x32_bf16 v[76:79], v[138:141], v[184:187], v[76:79]
	v_mfma_f32_16x16x32_bf16 v[72:75], v[146:149], v[184:187], v[72:75]
	v_mfma_f32_16x16x32_bf16 v[124:127], v[142:145], v[164:167], v[124:127]
	v_mfma_f32_16x16x32_bf16 v[120:123], v[156:159], v[164:167], v[120:123]
	v_mfma_f32_16x16x32_bf16 v[108:111], v[142:145], v[172:175], v[108:111]
	v_mfma_f32_16x16x32_bf16 v[104:107], v[156:159], v[172:175], v[104:107]
	v_mfma_f32_16x16x32_bf16 v[92:95], v[142:145], v[180:183], v[92:95]
	v_mfma_f32_16x16x32_bf16 v[88:91], v[156:159], v[180:183], v[88:91]
	v_mfma_f32_16x16x32_bf16 v[76:79], v[142:145], v[188:191], v[76:79]
	v_mfma_f32_16x16x32_bf16 v[72:75], v[156:159], v[188:191], v[72:75]
	s_setprio 0
	s_barrier
	s_add_i32 s30, 0, 0x1c000
	s_add_i32 s31, s68, s57
	v_add_u32_e32 v155, s30, v153
	s_mov_b32 m0, s31
	ds_read_b128 v[192:195], v155
	ds_read_b128 v[196:199], v155 offset:1024
	ds_read_b128 v[200:203], v155 offset:2048
	ds_read_b128 v[204:207], v155 offset:3072
	global_load_lds_dwordx4 v208, s[98:99]
	s_add_i32 m0, s31, 0x2000
	s_nop 0
	global_load_lds_dwordx4 v128, s[98:99]
	s_barrier
	s_waitcnt lgkmcnt(0)
	s_setprio 1
	v_mfma_f32_16x16x32_bf16 v[116:119], v[192:195], v[160:163], v[116:119]
	v_mfma_f32_16x16x32_bf16 v[112:115], v[200:203], v[160:163], v[112:115]
	v_mfma_f32_16x16x32_bf16 v[100:103], v[192:195], v[168:171], v[100:103]
	v_mfma_f32_16x16x32_bf16 v[96:99], v[200:203], v[168:171], v[96:99]
	v_mfma_f32_16x16x32_bf16 v[84:87], v[192:195], v[176:179], v[84:87]
	v_mfma_f32_16x16x32_bf16 v[80:83], v[200:203], v[176:179], v[80:83]
	v_mfma_f32_16x16x32_bf16 v[68:71], v[192:195], v[184:187], v[68:71]
	v_mfma_f32_16x16x32_bf16 v[64:67], v[200:203], v[184:187], v[64:67]
	v_mfma_f32_16x16x32_bf16 v[116:119], v[196:199], v[164:167], v[116:119]
	v_mfma_f32_16x16x32_bf16 v[112:115], v[204:207], v[164:167], v[112:115]
	v_mfma_f32_16x16x32_bf16 v[100:103], v[196:199], v[172:175], v[100:103]
	v_mfma_f32_16x16x32_bf16 v[96:99], v[204:207], v[172:175], v[96:99]
	v_mfma_f32_16x16x32_bf16 v[84:87], v[196:199], v[180:183], v[84:87]
	v_mfma_f32_16x16x32_bf16 v[80:83], v[204:207], v[180:183], v[80:83]
	v_mfma_f32_16x16x32_bf16 v[68:71], v[196:199], v[188:191], v[68:71]
	v_mfma_f32_16x16x32_bf16 v[64:67], v[204:207], v[188:191], v[64:67]
	s_setprio 0
	s_mov_b32 m0, s64
	s_barrier
	ds_read_b128 v[160:163], v154 offset:49152
	ds_read_b128 v[164:167], v154 offset:50176
	ds_read_b128 v[168:171], v154 offset:51200
	ds_read_b128 v[172:175], v154 offset:52224
	ds_read_b128 v[176:179], v154 offset:53248
	ds_read_b128 v[180:183], v154 offset:54272
	ds_read_b128 v[184:187], v154 offset:55296
	ds_read_b128 v[188:191], v154 offset:56320
	global_load_lds_dwordx4 v132, s[100:101]
	s_mov_b32 m0, s65
	s_nop 0
	global_load_lds_dwordx4 v130, s[100:101]
	s_barrier
	s_waitcnt lgkmcnt(0)
	s_setprio 1
	v_mfma_f32_16x16x32_bf16 v[60:63], v[138:141], v[160:163], v[60:63]
	v_mfma_f32_16x16x32_bf16 v[56:59], v[146:149], v[160:163], v[56:59]
	v_mfma_f32_16x16x32_bf16 v[44:47], v[138:141], v[168:171], v[44:47]
	v_mfma_f32_16x16x32_bf16 v[40:43], v[146:149], v[168:171], v[40:43]
	v_mfma_f32_16x16x32_bf16 v[28:31], v[138:141], v[176:179], v[28:31]
	v_mfma_f32_16x16x32_bf16 v[24:27], v[146:149], v[176:179], v[24:27]
	v_mfma_f32_16x16x32_bf16 v[12:15], v[138:141], v[184:187], v[12:15]
	v_mfma_f32_16x16x32_bf16 v[8:11], v[146:149], v[184:187], v[8:11]
	v_mfma_f32_16x16x32_bf16 v[60:63], v[142:145], v[164:167], v[60:63]
	v_mfma_f32_16x16x32_bf16 v[56:59], v[156:159], v[164:167], v[56:59]
	v_mfma_f32_16x16x32_bf16 v[44:47], v[142:145], v[172:175], v[44:47]
	v_mfma_f32_16x16x32_bf16 v[40:43], v[156:159], v[172:175], v[40:43]
	v_mfma_f32_16x16x32_bf16 v[28:31], v[142:145], v[180:183], v[28:31]
	v_mfma_f32_16x16x32_bf16 v[24:27], v[156:159], v[180:183], v[24:27]
	v_mfma_f32_16x16x32_bf16 v[12:15], v[142:145], v[188:191], v[12:15]
	v_mfma_f32_16x16x32_bf16 v[8:11], v[156:159], v[188:191], v[8:11]
	s_setprio 0
	s_barrier
	s_add_u32 s28, s28, 0x40080
	s_addc_u32 s29, s29, 0
	s_add_i32 s30, s30, s57
	s_mov_b32 m0, s30
	s_nop 0
	global_load_lds_dwordx4 v208, s[28:29]
	s_add_i32 m0, s30, 0x2000
	s_nop 0
	global_load_lds_dwordx4 v128, s[28:29]
	s_waitcnt vmcnt(6)
	s_barrier
	s_setprio 1
	v_mfma_f32_16x16x32_bf16 v[52:55], v[192:195], v[160:163], v[52:55]
	v_mfma_f32_16x16x32_bf16 v[48:51], v[200:203], v[160:163], v[48:51]
	v_mfma_f32_16x16x32_bf16 v[36:39], v[192:195], v[168:171], v[36:39]
	v_mfma_f32_16x16x32_bf16 v[32:35], v[200:203], v[168:171], v[32:35]
	v_mfma_f32_16x16x32_bf16 v[20:23], v[192:195], v[176:179], v[20:23]
	v_mfma_f32_16x16x32_bf16 v[16:19], v[200:203], v[176:179], v[16:19]
	v_mfma_f32_16x16x32_bf16 v[4:7], v[192:195], v[184:187], v[4:7]
	v_mfma_f32_16x16x32_bf16 v[0:3], v[200:203], v[184:187], v[0:3]
	v_mfma_f32_16x16x32_bf16 v[52:55], v[196:199], v[164:167], v[52:55]
	v_mfma_f32_16x16x32_bf16 v[48:51], v[204:207], v[164:167], v[48:51]
	v_mfma_f32_16x16x32_bf16 v[36:39], v[196:199], v[172:175], v[36:39]
	v_mfma_f32_16x16x32_bf16 v[32:35], v[204:207], v[172:175], v[32:35]
	v_mfma_f32_16x16x32_bf16 v[20:23], v[196:199], v[180:183], v[20:23]
	v_mfma_f32_16x16x32_bf16 v[16:19], v[204:207], v[180:183], v[16:19]
	v_mfma_f32_16x16x32_bf16 v[4:7], v[196:199], v[188:191], v[4:7]
	v_mfma_f32_16x16x32_bf16 v[0:3], v[204:207], v[188:191], v[0:3]
	s_setprio 0
	s_add_i32 s51, s51, 2
	s_add_u32 s26, s26, 0x100
	s_addc_u32 s27, s27, 0
	s_add_u32 s46, s46, 0x100
	s_addc_u32 s50, s50, 0
	s_cmp_gt_u32 s51, 13
	s_barrier
	s_cbranch_scc0 .LBB0_698
	s_cmp_lt_i32 s34, 4
	s_cselect_b64 vcc, -1, 0
	v_mov_b32_e32 v138, 0x3e38aa3b
	s_nop 0
	v_cndmask_b32_e32 v155, 1.0, v138, vcc
	s_and_b64 s[26:27], vcc, exec
	v_lshl_add_u32 v140, s35, 8, v152
	s_cselect_b32 s7, s9, s11
	s_cselect_b32 s21, s8, s10
	v_mov_b32_e32 v138, s21
	v_mov_b32_e32 v139, s7
	v_lshlrev_b32_e32 v142, 3, v151
	v_mov_b32_e32 v143, 0
	v_lshl_add_u64 v[138:139], v[142:143], 2, v[138:139]
	global_load_dwordx4 v[188:191], v[138:139], off
	global_load_dwordx4 v[192:195], v[138:139], off offset:16
	global_load_dwordx4 v[196:199], v[138:139], off offset:128
	global_load_dwordx4 v[200:203], v[138:139], off offset:144
	s_lshl_b32 s7, s34, 8
	s_or_b32 s26, s7, s66
	s_ashr_i32 s27, s26, 31
	s_lshl_b64 s[26:27], s[26:27], 1
	s_add_u32 s26, s62, s26
	s_addc_u32 s27, s63, s27
	s_mov_b32 s34, s6
	s_mov_b32 s35, s20
	s_mov_b64 s[28:29], s[24:25]
	v_mbcnt_lo_u32_b32 v210, -1, 0
	v_mbcnt_hi_u32_b32 v210, -1, v210
	v_and_b32_e32 v210, 48, v210
	v_lshl_add_u32 v210, v140, 6, v210
	v_lshlrev_b32_e32 v211, 12, v140
	v_lshl_add_u32 v211, v151, 4, v211
	global_load_dwordx4 v[156:159], v210, s[18:19]
	global_load_dwordx4 v[160:163], v210, s[18:19] offset:1024
	global_load_dwordx4 v[164:167], v210, s[18:19] offset:2048
	global_load_dwordx4 v[168:171], v210, s[18:19] offset:3072
	v_add_u32_e32 v210, 0x2000, v210
	global_load_dwordx4 v[172:175], v210, s[18:19]
	global_load_dwordx4 v[176:179], v210, s[18:19] offset:1024
	global_load_dwordx4 v[180:183], v210, s[18:19] offset:2048
	global_load_dwordx4 v[184:187], v210, s[18:19] offset:3072
	s_waitcnt vmcnt(7)
	v_pk_add_f32 v[156:157], v[156:157], v[158:159]
	s_nop 0
	v_add_f32_e32 v214, v156, v157
	v_mov_b32_e32 v215, v214
	s_nop 1
	v_permlane16_swap_b32_e32 v214, v215
	s_nop 0
	v_add_f32_e32 v214, v214, v215
	v_mov_b32_e32 v215, v214
	s_nop 1
	v_permlane32_swap_b32_e32 v214, v215
	s_nop 0
	v_add_f32_e32 v214, v214, v215
	v_fmamk_f32 v214, v214, 0x3a800000, v248
	v_rsq_f32_e32 v216, v214
	s_nop 0
	v_pk_mul_f32 v[124:125], v[124:125], v[216:217] op_sel_hi:[1,0]
	v_pk_mul_f32 v[126:127], v[126:127], v[216:217] op_sel_hi:[1,0]
	v_pk_mul_f32 v[120:121], v[120:121], v[216:217] op_sel_hi:[1,0]
	v_pk_mul_f32 v[122:123], v[122:123], v[216:217] op_sel_hi:[1,0]
	v_pk_mul_f32 v[116:117], v[116:117], v[216:217] op_sel_hi:[1,0]
	v_pk_mul_f32 v[118:119], v[118:119], v[216:217] op_sel_hi:[1,0]
	v_pk_mul_f32 v[112:113], v[112:113], v[216:217] op_sel_hi:[1,0]
	v_pk_mul_f32 v[114:115], v[114:115], v[216:217] op_sel_hi:[1,0]
	v_pk_mul_f32 v[148:149], v[124:125], v[124:125]
	v_pk_fma_f32 v[148:149], v[126:127], v[126:127], v[148:149]
	v_pk_fma_f32 v[148:149], v[120:121], v[120:121], v[148:149]
	v_pk_fma_f32 v[148:149], v[122:123], v[122:123], v[148:149]
	v_pk_fma_f32 v[148:149], v[116:117], v[116:117], v[148:149]
	v_pk_fma_f32 v[148:149], v[118:119], v[118:119], v[148:149]
	v_pk_fma_f32 v[148:149], v[112:113], v[112:113], v[148:149]
	v_pk_fma_f32 v[148:149], v[114:115], v[114:115], v[148:149]
	v_add_f32_e32 v214, v148, v149
	v_mov_b32_e32 v215, v214
	s_nop 1
	v_permlane16_swap_b32_e32 v214, v215
	s_nop 0
	v_add_f32_e32 v214, v214, v215
	v_mov_b32_e32 v215, v214
	s_nop 1
	v_permlane32_swap_b32_e32 v214, v215
	s_nop 0
	v_add_f32_e32 v214, v214, v215
	v_fmamk_f32 v214, v214, 0x3c800000, v248
	v_rsq_f32_e32 v214, v214
	s_nop 0
	v_mul_f32_e32 v218, v155, v214
	v_pk_mul_f32 v[156:157], v[188:189], v[218:219] op_sel_hi:[1,0]
	v_pk_mul_f32 v[124:125], v[124:125], v[156:157]
	v_pk_mul_f32 v[156:157], v[190:191], v[218:219] op_sel_hi:[1,0]
	v_pk_mul_f32 v[126:127], v[126:127], v[156:157]
	v_pk_mul_f32 v[156:157], v[192:193], v[218:219] op_sel_hi:[1,0]
	v_pk_mul_f32 v[120:121], v[120:121], v[156:157]
	v_pk_mul_f32 v[156:157], v[194:195], v[218:219] op_sel_hi:[1,0]
	v_pk_mul_f32 v[122:123], v[122:123], v[156:157]
	v_cvt_pk_bf16_f32 v204, v124, v125
	v_cvt_pk_bf16_f32 v205, v126, v127
	v_cvt_pk_bf16_f32 v206, v120, v121
	v_cvt_pk_bf16_f32 v207, v122, v123
	global_store_dwordx4 v211, v[204:207], s[26:27]
	v_pk_mul_f32 v[156:157], v[196:197], v[218:219] op_sel_hi:[1,0]
	v_pk_mul_f32 v[116:117], v[116:117], v[156:157]
	v_pk_mul_f32 v[156:157], v[198:199], v[218:219] op_sel_hi:[1,0]
	v_pk_mul_f32 v[118:119], v[118:119], v[156:157]
	v_pk_mul_f32 v[156:157], v[200:201], v[218:219] op_sel_hi:[1,0]
	v_pk_mul_f32 v[112:113], v[112:113], v[156:157]
	v_pk_mul_f32 v[156:157], v[202:203], v[218:219] op_sel_hi:[1,0]
	v_pk_mul_f32 v[114:115], v[114:115], v[156:157]
	v_cvt_pk_bf16_f32 v144, v116, v117
	v_cvt_pk_bf16_f32 v145, v118, v119
	v_cvt_pk_bf16_f32 v146, v112, v113
	v_cvt_pk_bf16_f32 v147, v114, v115
	global_store_dwordx4 v211, v[144:147], s[26:27] offset:64
	v_add_u32_e32 v211, 0x10000, v211
	s_waitcnt vmcnt(8)
	v_pk_add_f32 v[160:161], v[160:161], v[162:163]
	s_nop 0
	v_add_f32_e32 v214, v160, v161
	v_mov_b32_e32 v215, v214
	s_nop 1
	v_permlane16_swap_b32_e32 v214, v215
	s_nop 0
	v_add_f32_e32 v214, v214, v215
	v_mov_b32_e32 v215, v214
	s_nop 1
	v_permlane32_swap_b32_e32 v214, v215
	s_nop 0
	v_add_f32_e32 v214, v214, v215
	v_fmamk_f32 v214, v214, 0x3a800000, v248
	v_rsq_f32_e32 v216, v214
	s_nop 0
	v_pk_mul_f32 v[108:109], v[108:109], v[216:217] op_sel_hi:[1,0]
	v_pk_mul_f32 v[110:111], v[110:111], v[216:217] op_sel_hi:[1,0]
	v_pk_mul_f32 v[104:105], v[104:105], v[216:217] op_sel_hi:[1,0]
	v_pk_mul_f32 v[106:107], v[106:107], v[216:217] op_sel_hi:[1,0]
	v_pk_mul_f32 v[100:101], v[100:101], v[216:217] op_sel_hi:[1,0]
	v_pk_mul_f32 v[102:103], v[102:103], v[216:217] op_sel_hi:[1,0]
	v_pk_mul_f32 v[96:97], v[96:97], v[216:217] op_sel_hi:[1,0]
	v_pk_mul_f32 v[98:99], v[98:99], v[216:217] op_sel_hi:[1,0]
	v_pk_mul_f32 v[148:149], v[108:109], v[108:109]
	v_pk_fma_f32 v[148:149], v[110:111], v[110:111], v[148:149]
	v_pk_fma_f32 v[148:149], v[104:105], v[104:105], v[148:149]
	v_pk_fma_f32 v[148:149], v[106:107], v[106:107], v[148:149]
	v_pk_fma_f32 v[148:149], v[100:101], v[100:101], v[148:149]
	v_pk_fma_f32 v[148:149], v[102:103], v[102:103], v[148:149]
	v_pk_fma_f32 v[148:149], v[96:97], v[96:97], v[148:149]
	v_pk_fma_f32 v[148:149], v[98:99], v[98:99], v[148:149]
	v_add_f32_e32 v214, v148, v149
	v_mov_b32_e32 v215, v214
	s_nop 1
	v_permlane16_swap_b32_e32 v214, v215
	s_nop 0
	v_add_f32_e32 v214, v214, v215
	v_mov_b32_e32 v215, v214
	s_nop 1
	v_permlane32_swap_b32_e32 v214, v215
	s_nop 0
	v_add_f32_e32 v214, v214, v215
	v_fmamk_f32 v214, v214, 0x3c800000, v248
	v_rsq_f32_e32 v214, v214
	s_nop 0
	v_mul_f32_e32 v218, v155, v214
	v_pk_mul_f32 v[160:161], v[188:189], v[218:219] op_sel_hi:[1,0]
	v_pk_mul_f32 v[108:109], v[108:109], v[160:161]
	v_pk_mul_f32 v[160:161], v[190:191], v[218:219] op_sel_hi:[1,0]
	v_pk_mul_f32 v[110:111], v[110:111], v[160:161]
	v_pk_mul_f32 v[160:161], v[192:193], v[218:219] op_sel_hi:[1,0]
	v_pk_mul_f32 v[104:105], v[104:105], v[160:161]
	v_pk_mul_f32 v[160:161], v[194:195], v[218:219] op_sel_hi:[1,0]
	v_pk_mul_f32 v[106:107], v[106:107], v[160:161]
	v_cvt_pk_bf16_f32 v204, v108, v109
	v_cvt_pk_bf16_f32 v205, v110, v111
	v_cvt_pk_bf16_f32 v206, v104, v105
	v_cvt_pk_bf16_f32 v207, v106, v107
	global_store_dwordx4 v211, v[204:207], s[26:27]
	v_pk_mul_f32 v[160:161], v[196:197], v[218:219] op_sel_hi:[1,0]
	v_pk_mul_f32 v[100:101], v[100:101], v[160:161]
	v_pk_mul_f32 v[160:161], v[198:199], v[218:219] op_sel_hi:[1,0]
	v_pk_mul_f32 v[102:103], v[102:103], v[160:161]
	v_pk_mul_f32 v[160:161], v[200:201], v[218:219] op_sel_hi:[1,0]
	v_pk_mul_f32 v[96:97], v[96:97], v[160:161]
	v_pk_mul_f32 v[160:161], v[202:203], v[218:219] op_sel_hi:[1,0]
	v_pk_mul_f32 v[98:99], v[98:99], v[160:161]
	v_cvt_pk_bf16_f32 v144, v100, v101
	v_cvt_pk_bf16_f32 v145, v102, v103
	v_cvt_pk_bf16_f32 v146, v96, v97
	v_cvt_pk_bf16_f32 v147, v98, v99
	global_store_dwordx4 v211, v[144:147], s[26:27] offset:64
	v_add_u32_e32 v211, 0x10000, v211
	s_waitcnt vmcnt(9)
	v_pk_add_f32 v[164:165], v[164:165], v[166:167]
	s_nop 0
	v_add_f32_e32 v214, v164, v165
	v_mov_b32_e32 v215, v214
	s_nop 1
	v_permlane16_swap_b32_e32 v214, v215
	s_nop 0
	v_add_f32_e32 v214, v214, v215
	v_mov_b32_e32 v215, v214
	s_nop 1
	v_permlane32_swap_b32_e32 v214, v215
	s_nop 0
	v_add_f32_e32 v214, v214, v215
	v_fmamk_f32 v214, v214, 0x3a800000, v248
	v_rsq_f32_e32 v216, v214
	s_nop 0
	v_pk_mul_f32 v[92:93], v[92:93], v[216:217] op_sel_hi:[1,0]
	v_pk_mul_f32 v[94:95], v[94:95], v[216:217] op_sel_hi:[1,0]
	v_pk_mul_f32 v[88:89], v[88:89], v[216:217] op_sel_hi:[1,0]
	v_pk_mul_f32 v[90:91], v[90:91], v[216:217] op_sel_hi:[1,0]
	v_pk_mul_f32 v[84:85], v[84:85], v[216:217] op_sel_hi:[1,0]
	v_pk_mul_f32 v[86:87], v[86:87], v[216:217] op_sel_hi:[1,0]
	v_pk_mul_f32 v[80:81], v[80:81], v[216:217] op_sel_hi:[1,0]
	v_pk_mul_f32 v[82:83], v[82:83], v[216:217] op_sel_hi:[1,0]
	v_pk_mul_f32 v[148:149], v[92:93], v[92:93]
	v_pk_fma_f32 v[148:149], v[94:95], v[94:95], v[148:149]
	v_pk_fma_f32 v[148:149], v[88:89], v[88:89], v[148:149]
	v_pk_fma_f32 v[148:149], v[90:91], v[90:91], v[148:149]
	v_pk_fma_f32 v[148:149], v[84:85], v[84:85], v[148:149]
	v_pk_fma_f32 v[148:149], v[86:87], v[86:87], v[148:149]
	v_pk_fma_f32 v[148:149], v[80:81], v[80:81], v[148:149]
	v_pk_fma_f32 v[148:149], v[82:83], v[82:83], v[148:149]
	v_add_f32_e32 v214, v148, v149
	v_mov_b32_e32 v215, v214
	s_nop 1
	v_permlane16_swap_b32_e32 v214, v215
	s_nop 0
	v_add_f32_e32 v214, v214, v215
	v_mov_b32_e32 v215, v214
	s_nop 1
	v_permlane32_swap_b32_e32 v214, v215
	s_nop 0
	v_add_f32_e32 v214, v214, v215
	v_fmamk_f32 v214, v214, 0x3c800000, v248
	v_rsq_f32_e32 v214, v214
	s_nop 0
	v_mul_f32_e32 v218, v155, v214
	v_pk_mul_f32 v[164:165], v[188:189], v[218:219] op_sel_hi:[1,0]
	v_pk_mul_f32 v[92:93], v[92:93], v[164:165]
	v_pk_mul_f32 v[164:165], v[190:191], v[218:219] op_sel_hi:[1,0]
	v_pk_mul_f32 v[94:95], v[94:95], v[164:165]
	v_pk_mul_f32 v[164:165], v[192:193], v[218:219] op_sel_hi:[1,0]
	v_pk_mul_f32 v[88:89], v[88:89], v[164:165]
	v_pk_mul_f32 v[164:165], v[194:195], v[218:219] op_sel_hi:[1,0]
	v_pk_mul_f32 v[90:91], v[90:91], v[164:165]
	v_cvt_pk_bf16_f32 v204, v92, v93
	v_cvt_pk_bf16_f32 v205, v94, v95
	v_cvt_pk_bf16_f32 v206, v88, v89
	v_cvt_pk_bf16_f32 v207, v90, v91
	global_store_dwordx4 v211, v[204:207], s[26:27]
	v_pk_mul_f32 v[164:165], v[196:197], v[218:219] op_sel_hi:[1,0]
	v_pk_mul_f32 v[84:85], v[84:85], v[164:165]
	v_pk_mul_f32 v[164:165], v[198:199], v[218:219] op_sel_hi:[1,0]
	v_pk_mul_f32 v[86:87], v[86:87], v[164:165]
	v_pk_mul_f32 v[164:165], v[200:201], v[218:219] op_sel_hi:[1,0]
	v_pk_mul_f32 v[80:81], v[80:81], v[164:165]
	v_pk_mul_f32 v[164:165], v[202:203], v[218:219] op_sel_hi:[1,0]
	v_pk_mul_f32 v[82:83], v[82:83], v[164:165]
	v_cvt_pk_bf16_f32 v144, v84, v85
	v_cvt_pk_bf16_f32 v145, v86, v87
	v_cvt_pk_bf16_f32 v146, v80, v81
	v_cvt_pk_bf16_f32 v147, v82, v83
	global_store_dwordx4 v211, v[144:147], s[26:27] offset:64
	v_add_u32_e32 v211, 0x10000, v211
	s_waitcnt vmcnt(10)
	v_pk_add_f32 v[168:169], v[168:169], v[170:171]
	s_nop 0
	v_add_f32_e32 v214, v168, v169
	v_mov_b32_e32 v215, v214
	s_nop 1
	v_permlane16_swap_b32_e32 v214, v215
	s_nop 0
	v_add_f32_e32 v214, v214, v215
	v_mov_b32_e32 v215, v214
	s_nop 1
	v_permlane32_swap_b32_e32 v214, v215
	s_nop 0
	v_add_f32_e32 v214, v214, v215
	v_fmamk_f32 v214, v214, 0x3a800000, v248
	v_rsq_f32_e32 v216, v214
	s_nop 0
	v_pk_mul_f32 v[76:77], v[76:77], v[216:217] op_sel_hi:[1,0]
	v_pk_mul_f32 v[78:79], v[78:79], v[216:217] op_sel_hi:[1,0]
	v_pk_mul_f32 v[72:73], v[72:73], v[216:217] op_sel_hi:[1,0]
	v_pk_mul_f32 v[74:75], v[74:75], v[216:217] op_sel_hi:[1,0]
	v_pk_mul_f32 v[68:69], v[68:69], v[216:217] op_sel_hi:[1,0]
	v_pk_mul_f32 v[70:71], v[70:71], v[216:217] op_sel_hi:[1,0]
	v_pk_mul_f32 v[64:65], v[64:65], v[216:217] op_sel_hi:[1,0]
	v_pk_mul_f32 v[66:67], v[66:67], v[216:217] op_sel_hi:[1,0]
	v_pk_mul_f32 v[148:149], v[76:77], v[76:77]
	v_pk_fma_f32 v[148:149], v[78:79], v[78:79], v[148:149]
	v_pk_fma_f32 v[148:149], v[72:73], v[72:73], v[148:149]
	v_pk_fma_f32 v[148:149], v[74:75], v[74:75], v[148:149]
	v_pk_fma_f32 v[148:149], v[68:69], v[68:69], v[148:149]
	v_pk_fma_f32 v[148:149], v[70:71], v[70:71], v[148:149]
	v_pk_fma_f32 v[148:149], v[64:65], v[64:65], v[148:149]
	v_pk_fma_f32 v[148:149], v[66:67], v[66:67], v[148:149]
	v_add_f32_e32 v214, v148, v149
	v_mov_b32_e32 v215, v214
	s_nop 1
	v_permlane16_swap_b32_e32 v214, v215
	s_nop 0
	v_add_f32_e32 v214, v214, v215
	v_mov_b32_e32 v215, v214
	s_nop 1
	v_permlane32_swap_b32_e32 v214, v215
	s_nop 0
	v_add_f32_e32 v214, v214, v215
	v_fmamk_f32 v214, v214, 0x3c800000, v248
	v_rsq_f32_e32 v214, v214
	s_nop 0
	v_mul_f32_e32 v218, v155, v214
	v_pk_mul_f32 v[168:169], v[188:189], v[218:219] op_sel_hi:[1,0]
	v_pk_mul_f32 v[76:77], v[76:77], v[168:169]
	v_pk_mul_f32 v[168:169], v[190:191], v[218:219] op_sel_hi:[1,0]
	v_pk_mul_f32 v[78:79], v[78:79], v[168:169]
	v_pk_mul_f32 v[168:169], v[192:193], v[218:219] op_sel_hi:[1,0]
	v_pk_mul_f32 v[72:73], v[72:73], v[168:169]
	v_pk_mul_f32 v[168:169], v[194:195], v[218:219] op_sel_hi:[1,0]
	v_pk_mul_f32 v[74:75], v[74:75], v[168:169]
	v_cvt_pk_bf16_f32 v204, v76, v77
	v_cvt_pk_bf16_f32 v205, v78, v79
	v_cvt_pk_bf16_f32 v206, v72, v73
	v_cvt_pk_bf16_f32 v207, v74, v75
	global_store_dwordx4 v211, v[204:207], s[26:27]
	v_pk_mul_f32 v[168:169], v[196:197], v[218:219] op_sel_hi:[1,0]
	v_pk_mul_f32 v[68:69], v[68:69], v[168:169]
	v_pk_mul_f32 v[168:169], v[198:199], v[218:219] op_sel_hi:[1,0]
	v_pk_mul_f32 v[70:71], v[70:71], v[168:169]
	v_pk_mul_f32 v[168:169], v[200:201], v[218:219] op_sel_hi:[1,0]
	v_pk_mul_f32 v[64:65], v[64:65], v[168:169]
	v_pk_mul_f32 v[168:169], v[202:203], v[218:219] op_sel_hi:[1,0]
	v_pk_mul_f32 v[66:67], v[66:67], v[168:169]
	v_cvt_pk_bf16_f32 v144, v68, v69
	v_cvt_pk_bf16_f32 v145, v70, v71
	v_cvt_pk_bf16_f32 v146, v64, v65
	v_cvt_pk_bf16_f32 v147, v66, v67
	global_store_dwordx4 v211, v[144:147], s[26:27] offset:64
	v_add_u32_e32 v211, 0x50000, v211
	s_waitcnt vmcnt(11)
	v_pk_add_f32 v[172:173], v[172:173], v[174:175]
	s_nop 0
	v_add_f32_e32 v214, v172, v173
	v_mov_b32_e32 v215, v214
	s_nop 1
	v_permlane16_swap_b32_e32 v214, v215
	s_nop 0
	v_add_f32_e32 v214, v214, v215
	v_mov_b32_e32 v215, v214
	s_nop 1
	v_permlane32_swap_b32_e32 v214, v215
	s_nop 0
	v_add_f32_e32 v214, v214, v215
	v_fmamk_f32 v214, v214, 0x3a800000, v248
	v_rsq_f32_e32 v216, v214
	s_nop 0
	v_pk_mul_f32 v[60:61], v[60:61], v[216:217] op_sel_hi:[1,0]
	v_pk_mul_f32 v[62:63], v[62:63], v[216:217] op_sel_hi:[1,0]
	v_pk_mul_f32 v[56:57], v[56:57], v[216:217] op_sel_hi:[1,0]
	v_pk_mul_f32 v[58:59], v[58:59], v[216:217] op_sel_hi:[1,0]
	v_pk_mul_f32 v[52:53], v[52:53], v[216:217] op_sel_hi:[1,0]
	v_pk_mul_f32 v[54:55], v[54:55], v[216:217] op_sel_hi:[1,0]
	v_pk_mul_f32 v[48:49], v[48:49], v[216:217] op_sel_hi:[1,0]
	v_pk_mul_f32 v[50:51], v[50:51], v[216:217] op_sel_hi:[1,0]
	v_pk_mul_f32 v[148:149], v[60:61], v[60:61]
	v_pk_fma_f32 v[148:149], v[62:63], v[62:63], v[148:149]
	v_pk_fma_f32 v[148:149], v[56:57], v[56:57], v[148:149]
	v_pk_fma_f32 v[148:149], v[58:59], v[58:59], v[148:149]
	v_pk_fma_f32 v[148:149], v[52:53], v[52:53], v[148:149]
	v_pk_fma_f32 v[148:149], v[54:55], v[54:55], v[148:149]
	v_pk_fma_f32 v[148:149], v[48:49], v[48:49], v[148:149]
	v_pk_fma_f32 v[148:149], v[50:51], v[50:51], v[148:149]
	v_add_f32_e32 v214, v148, v149
	v_mov_b32_e32 v215, v214
	s_nop 1
	v_permlane16_swap_b32_e32 v214, v215
	s_nop 0
	v_add_f32_e32 v214, v214, v215
	v_mov_b32_e32 v215, v214
	s_nop 1
	v_permlane32_swap_b32_e32 v214, v215
	s_nop 0
	v_add_f32_e32 v214, v214, v215
	v_fmamk_f32 v214, v214, 0x3c800000, v248
	v_rsq_f32_e32 v214, v214
	s_nop 0
	v_mul_f32_e32 v218, v155, v214
	v_pk_mul_f32 v[172:173], v[188:189], v[218:219] op_sel_hi:[1,0]
	v_pk_mul_f32 v[60:61], v[60:61], v[172:173]
	v_pk_mul_f32 v[172:173], v[190:191], v[218:219] op_sel_hi:[1,0]
	v_pk_mul_f32 v[62:63], v[62:63], v[172:173]
	v_pk_mul_f32 v[172:173], v[192:193], v[218:219] op_sel_hi:[1,0]
	v_pk_mul_f32 v[56:57], v[56:57], v[172:173]
	v_pk_mul_f32 v[172:173], v[194:195], v[218:219] op_sel_hi:[1,0]
	v_pk_mul_f32 v[58:59], v[58:59], v[172:173]
	v_cvt_pk_bf16_f32 v204, v60, v61
	v_cvt_pk_bf16_f32 v205, v62, v63
	v_cvt_pk_bf16_f32 v206, v56, v57
	v_cvt_pk_bf16_f32 v207, v58, v59
	global_store_dwordx4 v211, v[204:207], s[26:27]
	v_pk_mul_f32 v[172:173], v[196:197], v[218:219] op_sel_hi:[1,0]
	v_pk_mul_f32 v[52:53], v[52:53], v[172:173]
	v_pk_mul_f32 v[172:173], v[198:199], v[218:219] op_sel_hi:[1,0]
	v_pk_mul_f32 v[54:55], v[54:55], v[172:173]
	v_pk_mul_f32 v[172:173], v[200:201], v[218:219] op_sel_hi:[1,0]
	v_pk_mul_f32 v[48:49], v[48:49], v[172:173]
	v_pk_mul_f32 v[172:173], v[202:203], v[218:219] op_sel_hi:[1,0]
	v_pk_mul_f32 v[50:51], v[50:51], v[172:173]
	v_cvt_pk_bf16_f32 v144, v52, v53
	v_cvt_pk_bf16_f32 v145, v54, v55
	v_cvt_pk_bf16_f32 v146, v48, v49
	v_cvt_pk_bf16_f32 v147, v50, v51
	global_store_dwordx4 v211, v[144:147], s[26:27] offset:64
	v_add_u32_e32 v211, 0x10000, v211
	s_waitcnt vmcnt(12)
	v_pk_add_f32 v[176:177], v[176:177], v[178:179]
	s_nop 0
	v_add_f32_e32 v214, v176, v177
	v_mov_b32_e32 v215, v214
	s_nop 1
	v_permlane16_swap_b32_e32 v214, v215
	s_nop 0
	v_add_f32_e32 v214, v214, v215
	v_mov_b32_e32 v215, v214
	s_nop 1
	v_permlane32_swap_b32_e32 v214, v215
	s_nop 0
	v_add_f32_e32 v214, v214, v215
	v_fmamk_f32 v214, v214, 0x3a800000, v248
	v_rsq_f32_e32 v216, v214
	s_nop 0
	v_pk_mul_f32 v[44:45], v[44:45], v[216:217] op_sel_hi:[1,0]
	v_pk_mul_f32 v[46:47], v[46:47], v[216:217] op_sel_hi:[1,0]
	v_pk_mul_f32 v[40:41], v[40:41], v[216:217] op_sel_hi:[1,0]
	v_pk_mul_f32 v[42:43], v[42:43], v[216:217] op_sel_hi:[1,0]
	v_pk_mul_f32 v[36:37], v[36:37], v[216:217] op_sel_hi:[1,0]
	v_pk_mul_f32 v[38:39], v[38:39], v[216:217] op_sel_hi:[1,0]
	v_pk_mul_f32 v[32:33], v[32:33], v[216:217] op_sel_hi:[1,0]
	v_pk_mul_f32 v[34:35], v[34:35], v[216:217] op_sel_hi:[1,0]
	v_pk_mul_f32 v[148:149], v[44:45], v[44:45]
	v_pk_fma_f32 v[148:149], v[46:47], v[46:47], v[148:149]
	v_pk_fma_f32 v[148:149], v[40:41], v[40:41], v[148:149]
	v_pk_fma_f32 v[148:149], v[42:43], v[42:43], v[148:149]
	v_pk_fma_f32 v[148:149], v[36:37], v[36:37], v[148:149]
	v_pk_fma_f32 v[148:149], v[38:39], v[38:39], v[148:149]
	v_pk_fma_f32 v[148:149], v[32:33], v[32:33], v[148:149]
	v_pk_fma_f32 v[148:149], v[34:35], v[34:35], v[148:149]
	v_add_f32_e32 v214, v148, v149
	v_mov_b32_e32 v215, v214
	s_nop 1
	v_permlane16_swap_b32_e32 v214, v215
	s_nop 0
	v_add_f32_e32 v214, v214, v215
	v_mov_b32_e32 v215, v214
	s_nop 1
	v_permlane32_swap_b32_e32 v214, v215
	s_nop 0
	v_add_f32_e32 v214, v214, v215
	v_fmamk_f32 v214, v214, 0x3c800000, v248
	v_rsq_f32_e32 v214, v214
	s_nop 0
	v_mul_f32_e32 v218, v155, v214
	v_pk_mul_f32 v[176:177], v[188:189], v[218:219] op_sel_hi:[1,0]
	v_pk_mul_f32 v[44:45], v[44:45], v[176:177]
	v_pk_mul_f32 v[176:177], v[190:191], v[218:219] op_sel_hi:[1,0]
	v_pk_mul_f32 v[46:47], v[46:47], v[176:177]
	v_pk_mul_f32 v[176:177], v[192:193], v[218:219] op_sel_hi:[1,0]
	v_pk_mul_f32 v[40:41], v[40:41], v[176:177]
	v_pk_mul_f32 v[176:177], v[194:195], v[218:219] op_sel_hi:[1,0]
	v_pk_mul_f32 v[42:43], v[42:43], v[176:177]
	v_cvt_pk_bf16_f32 v204, v44, v45
	v_cvt_pk_bf16_f32 v205, v46, v47
	v_cvt_pk_bf16_f32 v206, v40, v41
	v_cvt_pk_bf16_f32 v207, v42, v43
	global_store_dwordx4 v211, v[204:207], s[26:27]
	v_pk_mul_f32 v[176:177], v[196:197], v[218:219] op_sel_hi:[1,0]
	v_pk_mul_f32 v[36:37], v[36:37], v[176:177]
	v_pk_mul_f32 v[176:177], v[198:199], v[218:219] op_sel_hi:[1,0]
	v_pk_mul_f32 v[38:39], v[38:39], v[176:177]
	v_pk_mul_f32 v[176:177], v[200:201], v[218:219] op_sel_hi:[1,0]
	v_pk_mul_f32 v[32:33], v[32:33], v[176:177]
	v_pk_mul_f32 v[176:177], v[202:203], v[218:219] op_sel_hi:[1,0]
	v_pk_mul_f32 v[34:35], v[34:35], v[176:177]
	v_cvt_pk_bf16_f32 v144, v36, v37
	v_cvt_pk_bf16_f32 v145, v38, v39
	v_cvt_pk_bf16_f32 v146, v32, v33
	v_cvt_pk_bf16_f32 v147, v34, v35
	global_store_dwordx4 v211, v[144:147], s[26:27] offset:64
	v_add_u32_e32 v211, 0x10000, v211
	s_waitcnt vmcnt(13)
	v_pk_add_f32 v[180:181], v[180:181], v[182:183]
	s_nop 0
	v_add_f32_e32 v214, v180, v181
	v_mov_b32_e32 v215, v214
	s_nop 1
	v_permlane16_swap_b32_e32 v214, v215
	s_nop 0
	v_add_f32_e32 v214, v214, v215
	v_mov_b32_e32 v215, v214
	s_nop 1
	v_permlane32_swap_b32_e32 v214, v215
	s_nop 0
	v_add_f32_e32 v214, v214, v215
	v_fmamk_f32 v214, v214, 0x3a800000, v248
	v_rsq_f32_e32 v216, v214
	s_nop 0
	v_pk_mul_f32 v[28:29], v[28:29], v[216:217] op_sel_hi:[1,0]
	v_pk_mul_f32 v[30:31], v[30:31], v[216:217] op_sel_hi:[1,0]
	v_pk_mul_f32 v[24:25], v[24:25], v[216:217] op_sel_hi:[1,0]
	v_pk_mul_f32 v[26:27], v[26:27], v[216:217] op_sel_hi:[1,0]
	v_pk_mul_f32 v[20:21], v[20:21], v[216:217] op_sel_hi:[1,0]
	v_pk_mul_f32 v[22:23], v[22:23], v[216:217] op_sel_hi:[1,0]
	v_pk_mul_f32 v[16:17], v[16:17], v[216:217] op_sel_hi:[1,0]
	v_pk_mul_f32 v[18:19], v[18:19], v[216:217] op_sel_hi:[1,0]
	v_pk_mul_f32 v[148:149], v[28:29], v[28:29]
	v_pk_fma_f32 v[148:149], v[30:31], v[30:31], v[148:149]
	v_pk_fma_f32 v[148:149], v[24:25], v[24:25], v[148:149]
	v_pk_fma_f32 v[148:149], v[26:27], v[26:27], v[148:149]
	v_pk_fma_f32 v[148:149], v[20:21], v[20:21], v[148:149]
	v_pk_fma_f32 v[148:149], v[22:23], v[22:23], v[148:149]
	v_pk_fma_f32 v[148:149], v[16:17], v[16:17], v[148:149]
	v_pk_fma_f32 v[148:149], v[18:19], v[18:19], v[148:149]
	v_add_f32_e32 v214, v148, v149
	v_mov_b32_e32 v215, v214
	s_nop 1
	v_permlane16_swap_b32_e32 v214, v215
	s_nop 0
	v_add_f32_e32 v214, v214, v215
	v_mov_b32_e32 v215, v214
	s_nop 1
	v_permlane32_swap_b32_e32 v214, v215
	s_nop 0
	v_add_f32_e32 v214, v214, v215
	v_fmamk_f32 v214, v214, 0x3c800000, v248
	v_rsq_f32_e32 v214, v214
	s_nop 0
	v_mul_f32_e32 v218, v155, v214
	v_pk_mul_f32 v[180:181], v[188:189], v[218:219] op_sel_hi:[1,0]
	v_pk_mul_f32 v[28:29], v[28:29], v[180:181]
	v_pk_mul_f32 v[180:181], v[190:191], v[218:219] op_sel_hi:[1,0]
	v_pk_mul_f32 v[30:31], v[30:31], v[180:181]
	v_pk_mul_f32 v[180:181], v[192:193], v[218:219] op_sel_hi:[1,0]
	v_pk_mul_f32 v[24:25], v[24:25], v[180:181]
	v_pk_mul_f32 v[180:181], v[194:195], v[218:219] op_sel_hi:[1,0]
	v_pk_mul_f32 v[26:27], v[26:27], v[180:181]
	v_cvt_pk_bf16_f32 v204, v28, v29
	v_cvt_pk_bf16_f32 v205, v30, v31
	v_cvt_pk_bf16_f32 v206, v24, v25
	v_cvt_pk_bf16_f32 v207, v26, v27
	global_store_dwordx4 v211, v[204:207], s[26:27]
	v_pk_mul_f32 v[180:181], v[196:197], v[218:219] op_sel_hi:[1,0]
	v_pk_mul_f32 v[20:21], v[20:21], v[180:181]
	v_pk_mul_f32 v[180:181], v[198:199], v[218:219] op_sel_hi:[1,0]
	v_pk_mul_f32 v[22:23], v[22:23], v[180:181]
	v_pk_mul_f32 v[180:181], v[200:201], v[218:219] op_sel_hi:[1,0]
	v_pk_mul_f32 v[16:17], v[16:17], v[180:181]
	v_pk_mul_f32 v[180:181], v[202:203], v[218:219] op_sel_hi:[1,0]
	v_pk_mul_f32 v[18:19], v[18:19], v[180:181]
	v_cvt_pk_bf16_f32 v144, v20, v21
	v_cvt_pk_bf16_f32 v145, v22, v23
	v_cvt_pk_bf16_f32 v146, v16, v17
	v_cvt_pk_bf16_f32 v147, v18, v19
	global_store_dwordx4 v211, v[144:147], s[26:27] offset:64
	v_add_u32_e32 v211, 0x10000, v211
	s_waitcnt vmcnt(14)
	v_pk_add_f32 v[184:185], v[184:185], v[186:187]
	s_nop 0
	v_add_f32_e32 v214, v184, v185
	v_mov_b32_e32 v215, v214
	s_nop 1
	v_permlane16_swap_b32_e32 v214, v215
	s_nop 0
	v_add_f32_e32 v214, v214, v215
	v_mov_b32_e32 v215, v214
	s_nop 1
	v_permlane32_swap_b32_e32 v214, v215
	s_nop 0
	v_add_f32_e32 v214, v214, v215
	v_fmamk_f32 v214, v214, 0x3a800000, v248
	v_rsq_f32_e32 v216, v214
	s_nop 0
	v_pk_mul_f32 v[12:13], v[12:13], v[216:217] op_sel_hi:[1,0]
	v_pk_mul_f32 v[14:15], v[14:15], v[216:217] op_sel_hi:[1,0]
	v_pk_mul_f32 v[8:9], v[8:9], v[216:217] op_sel_hi:[1,0]
	v_pk_mul_f32 v[10:11], v[10:11], v[216:217] op_sel_hi:[1,0]
	v_pk_mul_f32 v[4:5], v[4:5], v[216:217] op_sel_hi:[1,0]
	v_pk_mul_f32 v[6:7], v[6:7], v[216:217] op_sel_hi:[1,0]
	v_pk_mul_f32 v[0:1], v[0:1], v[216:217] op_sel_hi:[1,0]
	v_pk_mul_f32 v[2:3], v[2:3], v[216:217] op_sel_hi:[1,0]
	v_pk_mul_f32 v[148:149], v[12:13], v[12:13]
	v_pk_fma_f32 v[148:149], v[14:15], v[14:15], v[148:149]
	v_pk_fma_f32 v[148:149], v[8:9], v[8:9], v[148:149]
	v_pk_fma_f32 v[148:149], v[10:11], v[10:11], v[148:149]
	v_pk_fma_f32 v[148:149], v[4:5], v[4:5], v[148:149]
	v_pk_fma_f32 v[148:149], v[6:7], v[6:7], v[148:149]
	v_pk_fma_f32 v[148:149], v[0:1], v[0:1], v[148:149]
	v_pk_fma_f32 v[148:149], v[2:3], v[2:3], v[148:149]
	v_add_f32_e32 v214, v148, v149
	v_mov_b32_e32 v215, v214
	s_nop 1
	v_permlane16_swap_b32_e32 v214, v215
	s_nop 0
	v_add_f32_e32 v214, v214, v215
	v_mov_b32_e32 v215, v214
	s_nop 1
	v_permlane32_swap_b32_e32 v214, v215
	s_nop 0
	v_add_f32_e32 v214, v214, v215
	v_fmamk_f32 v214, v214, 0x3c800000, v248
	v_rsq_f32_e32 v214, v214
	s_nop 0
	v_mul_f32_e32 v218, v155, v214
	v_pk_mul_f32 v[184:185], v[188:189], v[218:219] op_sel_hi:[1,0]
	v_pk_mul_f32 v[12:13], v[12:13], v[184:185]
	v_pk_mul_f32 v[184:185], v[190:191], v[218:219] op_sel_hi:[1,0]
	v_pk_mul_f32 v[14:15], v[14:15], v[184:185]
	v_pk_mul_f32 v[184:185], v[192:193], v[218:219] op_sel_hi:[1,0]
	v_pk_mul_f32 v[8:9], v[8:9], v[184:185]
	v_pk_mul_f32 v[184:185], v[194:195], v[218:219] op_sel_hi:[1,0]
	v_pk_mul_f32 v[10:11], v[10:11], v[184:185]
	v_cvt_pk_bf16_f32 v204, v12, v13
	v_cvt_pk_bf16_f32 v205, v14, v15
	v_cvt_pk_bf16_f32 v206, v8, v9
	v_cvt_pk_bf16_f32 v207, v10, v11
	global_store_dwordx4 v211, v[204:207], s[26:27]
	v_pk_mul_f32 v[184:185], v[196:197], v[218:219] op_sel_hi:[1,0]
	v_pk_mul_f32 v[4:5], v[4:5], v[184:185]
	v_pk_mul_f32 v[184:185], v[198:199], v[218:219] op_sel_hi:[1,0]
	v_pk_mul_f32 v[6:7], v[6:7], v[184:185]
	v_pk_mul_f32 v[184:185], v[200:201], v[218:219] op_sel_hi:[1,0]
	v_pk_mul_f32 v[0:1], v[0:1], v[184:185]
	v_pk_mul_f32 v[184:185], v[202:203], v[218:219] op_sel_hi:[1,0]
	v_pk_mul_f32 v[2:3], v[2:3], v[184:185]
	v_cvt_pk_bf16_f32 v144, v4, v5
	v_cvt_pk_bf16_f32 v145, v6, v7
	v_cvt_pk_bf16_f32 v146, v0, v1
	v_cvt_pk_bf16_f32 v147, v2, v3
	global_store_dwordx4 v211, v[144:147], s[26:27] offset:64
	s_and_b64 vcc, exec, s[4:5]
	s_mov_b64 s[26:27], s[22:23]
	s_cbranch_vccz .LBB0_691
	s_waitcnt vmcnt(0)
	s_cmpk_gt_u32 s54, 0xff
	s_cbranch_scc1 .LBB0_702
	s_barrier

.LBB0_714:
	s_add_u32 s26, s6, 0xfffc0080
	s_addc_u32 s27, s7, -1
	s_add_i32 s63, 0, 0x10000
	v_add_u32_e32 v140, s63, v165
	ds_read_b128 v[128:131], v140
	ds_read_b128 v[132:135], v140 offset:1024
	ds_read_b128 v[136:139], v140 offset:2048
	ds_read_b128 v[140:143], v140 offset:3072
	s_cmp_eq_u32 s51, 12
	s_cselect_b32 s29, s21, s27
	s_cselect_b32 s28, s38, s26
	s_cselect_b32 s27, s11, s50
	s_cselect_b32 s26, s39, s46
	s_add_i32 m0, s56, 0xc000
	ds_read_b128 v[154:157], v167
	ds_read_b128 v[158:161], v167 offset:1024
	ds_read_b128 v[168:171], v167 offset:2048
	ds_read_b128 v[172:175], v167 offset:3072
	ds_read_b128 v[176:179], v167 offset:4096
	ds_read_b128 v[180:183], v167 offset:5120
	ds_read_b128 v[184:187], v167 offset:6144
	ds_read_b128 v[188:191], v167 offset:7168
	global_load_lds_dwordx4 v150, s[6:7]
	s_add_i32 m0, s56, 0xe000
	s_nop 0
	global_load_lds_dwordx4 v152, s[6:7]
	s_waitcnt lgkmcnt(8)
	s_barrier
	s_waitcnt lgkmcnt(0)
	s_setprio 1
	v_mfma_f32_16x16x32_bf16 v[124:127], v[128:131], v[154:157], v[124:127]
	v_mfma_f32_16x16x32_bf16 v[120:123], v[136:139], v[154:157], v[120:123]
	v_mfma_f32_16x16x32_bf16 v[116:119], v[128:131], v[168:171], v[116:119]
	v_mfma_f32_16x16x32_bf16 v[112:115], v[136:139], v[168:171], v[112:115]
	v_mfma_f32_16x16x32_bf16 v[108:111], v[128:131], v[176:179], v[108:111]
	v_mfma_f32_16x16x32_bf16 v[104:107], v[136:139], v[176:179], v[104:107]
	v_mfma_f32_16x16x32_bf16 v[100:103], v[128:131], v[184:187], v[100:103]
	v_mfma_f32_16x16x32_bf16 v[96:99], v[136:139], v[184:187], v[96:99]
	v_mfma_f32_16x16x32_bf16 v[124:127], v[132:135], v[158:161], v[124:127]
	v_mfma_f32_16x16x32_bf16 v[120:123], v[140:143], v[158:161], v[120:123]
	v_mfma_f32_16x16x32_bf16 v[116:119], v[132:135], v[172:175], v[116:119]
	v_mfma_f32_16x16x32_bf16 v[112:115], v[140:143], v[172:175], v[112:115]
	v_mfma_f32_16x16x32_bf16 v[108:111], v[132:135], v[180:183], v[108:111]
	v_mfma_f32_16x16x32_bf16 v[104:107], v[140:143], v[180:183], v[104:107]
	v_mfma_f32_16x16x32_bf16 v[100:103], v[132:135], v[188:191], v[100:103]
	v_mfma_f32_16x16x32_bf16 v[96:99], v[140:143], v[188:191], v[96:99]
	s_setprio 0
	s_barrier
	s_add_i32 s66, 0, 0x14000
	v_add_u32_e32 v162, s66, v165
	s_add_i32 s63, s63, s55
	ds_read_b128 v[192:195], v162
	ds_read_b128 v[196:199], v162 offset:1024
	ds_read_b128 v[200:203], v162 offset:2048
	ds_read_b128 v[204:207], v162 offset:3072
	s_add_u32 s98, s26, s40
	s_addc_u32 s99, s27, s41
	s_mov_b32 m0, s63
	s_nop 0
	global_load_lds_dwordx4 v208, s[26:27]
	s_add_i32 m0, s63, 0x2000
	s_nop 0
	global_load_lds_dwordx4 v144, s[26:27]
	s_barrier
	s_waitcnt lgkmcnt(0)
	s_setprio 1
	v_mfma_f32_16x16x32_bf16 v[60:63], v[192:195], v[154:157], v[60:63]
	v_mfma_f32_16x16x32_bf16 v[56:59], v[200:203], v[154:157], v[56:59]
	v_mfma_f32_16x16x32_bf16 v[52:55], v[192:195], v[168:171], v[52:55]
	v_mfma_f32_16x16x32_bf16 v[48:51], v[200:203], v[168:171], v[48:51]
	v_mfma_f32_16x16x32_bf16 v[44:47], v[192:195], v[176:179], v[44:47]
	v_mfma_f32_16x16x32_bf16 v[40:43], v[200:203], v[176:179], v[40:43]
	v_mfma_f32_16x16x32_bf16 v[36:39], v[192:195], v[184:187], v[36:39]
	v_mfma_f32_16x16x32_bf16 v[32:35], v[200:203], v[184:187], v[32:35]
	v_mfma_f32_16x16x32_bf16 v[60:63], v[196:199], v[158:161], v[60:63]
	v_mfma_f32_16x16x32_bf16 v[56:59], v[204:207], v[158:161], v[56:59]
	v_mfma_f32_16x16x32_bf16 v[52:55], v[196:199], v[172:175], v[52:55]
	v_mfma_f32_16x16x32_bf16 v[48:51], v[204:207], v[172:175], v[48:51]
	v_mfma_f32_16x16x32_bf16 v[44:47], v[196:199], v[180:183], v[44:47]
	v_mfma_f32_16x16x32_bf16 v[40:43], v[204:207], v[180:183], v[40:43]
	v_mfma_f32_16x16x32_bf16 v[36:39], v[196:199], v[188:191], v[36:39]
	v_mfma_f32_16x16x32_bf16 v[32:35], v[204:207], v[188:191], v[32:35]
	s_setprio 0
	s_mov_b32 m0, s56
	s_add_u32 s100, s28, s40
	s_addc_u32 s101, s29, s41
	s_barrier
	ds_read_b128 v[154:157], v167 offset:16384
	ds_read_b128 v[158:161], v167 offset:17408
	ds_read_b128 v[168:171], v167 offset:18432
	ds_read_b128 v[172:175], v167 offset:19456
	ds_read_b128 v[176:179], v167 offset:20480
	ds_read_b128 v[180:183], v167 offset:21504
	ds_read_b128 v[184:187], v167 offset:22528
	ds_read_b128 v[188:191], v167 offset:23552
	global_load_lds_dwordx4 v148, s[28:29]
	s_mov_b32 m0, s57
	s_nop 0
	global_load_lds_dwordx4 v146, s[28:29]
	s_barrier
	s_waitcnt lgkmcnt(0)
	s_setprio 1
	v_mfma_f32_16x16x32_bf16 v[92:95], v[128:131], v[154:157], v[92:95]
	v_mfma_f32_16x16x32_bf16 v[88:91], v[136:139], v[154:157], v[88:91]
	v_mfma_f32_16x16x32_bf16 v[84:87], v[128:131], v[168:171], v[84:87]
	v_mfma_f32_16x16x32_bf16 v[80:83], v[136:139], v[168:171], v[80:83]
	v_mfma_f32_16x16x32_bf16 v[76:79], v[128:131], v[176:179], v[76:79]
	v_mfma_f32_16x16x32_bf16 v[72:75], v[136:139], v[176:179], v[72:75]
	v_mfma_f32_16x16x32_bf16 v[68:71], v[128:131], v[184:187], v[68:71]
	v_mfma_f32_16x16x32_bf16 v[64:67], v[136:139], v[184:187], v[64:67]
	v_mfma_f32_16x16x32_bf16 v[92:95], v[132:135], v[158:161], v[92:95]
	v_mfma_f32_16x16x32_bf16 v[88:91], v[140:143], v[158:161], v[88:91]
	v_mfma_f32_16x16x32_bf16 v[84:87], v[132:135], v[172:175], v[84:87]
	v_mfma_f32_16x16x32_bf16 v[80:83], v[140:143], v[172:175], v[80:83]
	v_mfma_f32_16x16x32_bf16 v[76:79], v[132:135], v[180:183], v[76:79]
	v_mfma_f32_16x16x32_bf16 v[72:75], v[140:143], v[180:183], v[72:75]
	v_mfma_f32_16x16x32_bf16 v[68:71], v[132:135], v[188:191], v[68:71]
	v_mfma_f32_16x16x32_bf16 v[64:67], v[140:143], v[188:191], v[64:67]
	s_setprio 0
	s_barrier
	s_add_u32 s64, s26, 0x40000
	s_addc_u32 s65, s27, 0
	s_add_i32 s63, s66, s55
	s_mov_b32 m0, s63
	s_nop 0
	global_load_lds_dwordx4 v208, s[64:65]
	s_add_i32 m0, s63, 0x2000
	s_nop 0
	global_load_lds_dwordx4 v144, s[64:65]
	s_waitcnt vmcnt(6)
	s_barrier
	s_setprio 1
	v_mfma_f32_16x16x32_bf16 v[28:31], v[192:195], v[154:157], v[28:31]
	v_mfma_f32_16x16x32_bf16 v[24:27], v[200:203], v[154:157], v[24:27]
	v_mfma_f32_16x16x32_bf16 v[20:23], v[192:195], v[168:171], v[20:23]
	v_mfma_f32_16x16x32_bf16 v[16:19], v[200:203], v[168:171], v[16:19]
	v_mfma_f32_16x16x32_bf16 v[12:15], v[192:195], v[176:179], v[12:15]
	v_mfma_f32_16x16x32_bf16 v[8:11], v[200:203], v[176:179], v[8:11]
	v_mfma_f32_16x16x32_bf16 v[4:7], v[192:195], v[184:187], v[4:7]
	v_mfma_f32_16x16x32_bf16 v[0:3], v[200:203], v[184:187], v[0:3]
	v_mfma_f32_16x16x32_bf16 v[28:31], v[196:199], v[158:161], v[28:31]
	v_mfma_f32_16x16x32_bf16 v[24:27], v[204:207], v[158:161], v[24:27]
	v_mfma_f32_16x16x32_bf16 v[20:23], v[196:199], v[172:175], v[20:23]
	v_mfma_f32_16x16x32_bf16 v[16:19], v[204:207], v[172:175], v[16:19]
	v_mfma_f32_16x16x32_bf16 v[12:15], v[196:199], v[180:183], v[12:15]
	v_mfma_f32_16x16x32_bf16 v[8:11], v[204:207], v[180:183], v[8:11]
	v_mfma_f32_16x16x32_bf16 v[4:7], v[196:199], v[188:191], v[4:7]
	v_mfma_f32_16x16x32_bf16 v[0:3], v[204:207], v[188:191], v[0:3]
	s_setprio 0
	s_add_i32 s63, 0, 0x18000
	v_add_u32_e32 v140, s63, v165
	s_barrier
	ds_read_b128 v[128:131], v140
	ds_read_b128 v[132:135], v140 offset:1024
	ds_read_b128 v[136:139], v140 offset:2048
	ds_read_b128 v[140:143], v140 offset:3072
	s_add_u32 s28, s28, 0x40000
	s_addc_u32 s29, s29, 0
	s_mov_b32 m0, s58
	ds_read_b128 v[154:157], v167 offset:32768
	ds_read_b128 v[158:161], v167 offset:33792
	ds_read_b128 v[168:171], v167 offset:34816
	ds_read_b128 v[172:175], v167 offset:35840
	ds_read_b128 v[176:179], v167 offset:36864
	ds_read_b128 v[180:183], v167 offset:37888
	ds_read_b128 v[184:187], v167 offset:38912
	ds_read_b128 v[188:191], v167 offset:39936
	global_load_lds_dwordx4 v148, s[28:29]
	s_mov_b32 m0, s59
	s_nop 0
	global_load_lds_dwordx4 v146, s[28:29]
	s_waitcnt lgkmcnt(8)
	s_barrier
	s_waitcnt lgkmcnt(0)
	s_setprio 1
	v_mfma_f32_16x16x32_bf16 v[124:127], v[128:131], v[154:157], v[124:127]
	v_mfma_f32_16x16x32_bf16 v[120:123], v[136:139], v[154:157], v[120:123]
	v_mfma_f32_16x16x32_bf16 v[116:119], v[128:131], v[168:171], v[116:119]
	v_mfma_f32_16x16x32_bf16 v[112:115], v[136:139], v[168:171], v[112:115]
	v_mfma_f32_16x16x32_bf16 v[108:111], v[128:131], v[176:179], v[108:111]
	v_mfma_f32_16x16x32_bf16 v[104:107], v[136:139], v[176:179], v[104:107]
	v_mfma_f32_16x16x32_bf16 v[100:103], v[128:131], v[184:187], v[100:103]
	v_mfma_f32_16x16x32_bf16 v[96:99], v[136:139], v[184:187], v[96:99]
	v_mfma_f32_16x16x32_bf16 v[124:127], v[132:135], v[158:161], v[124:127]
	v_mfma_f32_16x16x32_bf16 v[120:123], v[140:143], v[158:161], v[120:123]
	v_mfma_f32_16x16x32_bf16 v[116:119], v[132:135], v[172:175], v[116:119]
	v_mfma_f32_16x16x32_bf16 v[112:115], v[140:143], v[172:175], v[112:115]
	v_mfma_f32_16x16x32_bf16 v[108:111], v[132:135], v[180:183], v[108:111]
	v_mfma_f32_16x16x32_bf16 v[104:107], v[140:143], v[180:183], v[104:107]
	v_mfma_f32_16x16x32_bf16 v[100:103], v[132:135], v[188:191], v[100:103]
	v_mfma_f32_16x16x32_bf16 v[96:99], v[140:143], v[188:191], v[96:99]
	s_setprio 0
	s_barrier
	s_add_i32 s28, 0, 0x1c000
	s_add_i32 s29, s63, s55
	v_add_u32_e32 v204, s28, v165
	s_mov_b32 m0, s29
	ds_read_b128 v[192:195], v204
	ds_read_b128 v[196:199], v204 offset:1024
	ds_read_b128 v[200:203], v204 offset:2048
	ds_read_b128 v[204:207], v204 offset:3072
	global_load_lds_dwordx4 v208, s[98:99]
	s_add_i32 m0, s29, 0x2000
	s_nop 0
	global_load_lds_dwordx4 v144, s[98:99]
	s_barrier
	s_waitcnt lgkmcnt(0)
	s_setprio 1
	v_mfma_f32_16x16x32_bf16 v[60:63], v[192:195], v[154:157], v[60:63]
	v_mfma_f32_16x16x32_bf16 v[56:59], v[200:203], v[154:157], v[56:59]
	v_mfma_f32_16x16x32_bf16 v[52:55], v[192:195], v[168:171], v[52:55]
	v_mfma_f32_16x16x32_bf16 v[48:51], v[200:203], v[168:171], v[48:51]
	v_mfma_f32_16x16x32_bf16 v[44:47], v[192:195], v[176:179], v[44:47]
	v_mfma_f32_16x16x32_bf16 v[40:43], v[200:203], v[176:179], v[40:43]
	v_mfma_f32_16x16x32_bf16 v[36:39], v[192:195], v[184:187], v[36:39]
	v_mfma_f32_16x16x32_bf16 v[32:35], v[200:203], v[184:187], v[32:35]
	v_mfma_f32_16x16x32_bf16 v[60:63], v[196:199], v[158:161], v[60:63]
	v_mfma_f32_16x16x32_bf16 v[56:59], v[204:207], v[158:161], v[56:59]
	v_mfma_f32_16x16x32_bf16 v[52:55], v[196:199], v[172:175], v[52:55]
	v_mfma_f32_16x16x32_bf16 v[48:51], v[204:207], v[172:175], v[48:51]
	v_mfma_f32_16x16x32_bf16 v[44:47], v[196:199], v[180:183], v[44:47]
	v_mfma_f32_16x16x32_bf16 v[40:43], v[204:207], v[180:183], v[40:43]
	v_mfma_f32_16x16x32_bf16 v[36:39], v[196:199], v[188:191], v[36:39]
	v_mfma_f32_16x16x32_bf16 v[32:35], v[204:207], v[188:191], v[32:35]
	s_setprio 0
	s_mov_b32 m0, s60
	s_barrier
	ds_read_b128 v[154:157], v167 offset:49152
	ds_read_b128 v[158:161], v167 offset:50176
	ds_read_b128 v[168:171], v167 offset:51200
	ds_read_b128 v[172:175], v167 offset:52224
	ds_read_b128 v[176:179], v167 offset:53248
	ds_read_b128 v[180:183], v167 offset:54272
	ds_read_b128 v[184:187], v167 offset:55296
	ds_read_b128 v[188:191], v167 offset:56320
	global_load_lds_dwordx4 v148, s[100:101]
	s_mov_b32 m0, s61
	s_nop 0
	global_load_lds_dwordx4 v146, s[100:101]
	s_barrier
	s_waitcnt lgkmcnt(0)
	s_setprio 1
	v_mfma_f32_16x16x32_bf16 v[92:95], v[128:131], v[154:157], v[92:95]
	v_mfma_f32_16x16x32_bf16 v[88:91], v[136:139], v[154:157], v[88:91]
	v_mfma_f32_16x16x32_bf16 v[84:87], v[128:131], v[168:171], v[84:87]
	v_mfma_f32_16x16x32_bf16 v[80:83], v[136:139], v[168:171], v[80:83]
	v_mfma_f32_16x16x32_bf16 v[76:79], v[128:131], v[176:179], v[76:79]
	v_mfma_f32_16x16x32_bf16 v[72:75], v[136:139], v[176:179], v[72:75]
	v_mfma_f32_16x16x32_bf16 v[68:71], v[128:131], v[184:187], v[68:71]
	v_mfma_f32_16x16x32_bf16 v[64:67], v[136:139], v[184:187], v[64:67]
	v_mfma_f32_16x16x32_bf16 v[92:95], v[132:135], v[158:161], v[92:95]
	v_mfma_f32_16x16x32_bf16 v[88:91], v[140:143], v[158:161], v[88:91]
	v_mfma_f32_16x16x32_bf16 v[84:87], v[132:135], v[172:175], v[84:87]
	v_mfma_f32_16x16x32_bf16 v[80:83], v[140:143], v[172:175], v[80:83]
	v_mfma_f32_16x16x32_bf16 v[76:79], v[132:135], v[180:183], v[76:79]
	v_mfma_f32_16x16x32_bf16 v[72:75], v[140:143], v[180:183], v[72:75]
	v_mfma_f32_16x16x32_bf16 v[68:71], v[132:135], v[188:191], v[68:71]
	v_mfma_f32_16x16x32_bf16 v[64:67], v[140:143], v[188:191], v[64:67]
	s_setprio 0
	s_barrier
	s_add_u32 s26, s26, 0x40080
	s_addc_u32 s27, s27, 0
	s_add_i32 s28, s28, s55
	s_mov_b32 m0, s28
	s_nop 0
	global_load_lds_dwordx4 v208, s[26:27]
	s_add_i32 m0, s28, 0x2000
	s_nop 0
	global_load_lds_dwordx4 v144, s[26:27]
	s_waitcnt vmcnt(6)
	s_barrier
	s_setprio 1
	v_mfma_f32_16x16x32_bf16 v[28:31], v[192:195], v[154:157], v[28:31]
	v_mfma_f32_16x16x32_bf16 v[24:27], v[200:203], v[154:157], v[24:27]
	v_mfma_f32_16x16x32_bf16 v[20:23], v[192:195], v[168:171], v[20:23]
	v_mfma_f32_16x16x32_bf16 v[16:19], v[200:203], v[168:171], v[16:19]
	v_mfma_f32_16x16x32_bf16 v[12:15], v[192:195], v[176:179], v[12:15]
	v_mfma_f32_16x16x32_bf16 v[8:11], v[200:203], v[176:179], v[8:11]
	v_mfma_f32_16x16x32_bf16 v[4:7], v[192:195], v[184:187], v[4:7]
	v_mfma_f32_16x16x32_bf16 v[0:3], v[200:203], v[184:187], v[0:3]
	v_mfma_f32_16x16x32_bf16 v[28:31], v[196:199], v[158:161], v[28:31]
	v_mfma_f32_16x16x32_bf16 v[24:27], v[204:207], v[158:161], v[24:27]
	v_mfma_f32_16x16x32_bf16 v[20:23], v[196:199], v[172:175], v[20:23]
	v_mfma_f32_16x16x32_bf16 v[16:19], v[204:207], v[172:175], v[16:19]
	v_mfma_f32_16x16x32_bf16 v[12:15], v[196:199], v[180:183], v[12:15]
	v_mfma_f32_16x16x32_bf16 v[8:11], v[204:207], v[180:183], v[8:11]
	v_mfma_f32_16x16x32_bf16 v[4:7], v[196:199], v[188:191], v[4:7]
	v_mfma_f32_16x16x32_bf16 v[0:3], v[204:207], v[188:191], v[0:3]
	s_setprio 0
	s_add_i32 s51, s51, 2
	s_add_u32 s6, s6, 0x100
	s_addc_u32 s7, s7, 0
	s_add_u32 s46, s46, 0x100
	s_addc_u32 s50, s50, 0
	s_cmp_gt_u32 s51, 13
	s_barrier
	s_cbranch_scc0 .LBB0_714
	v_lshl_or_b32 v158, s34, 8, v166
	v_lshl_add_u32 v159, s35, 8, v164
	s_mov_b32 s34, s10
	s_mov_b32 s35, s20
	s_mov_b64 s[26:27], s[24:25]
	v_mbcnt_lo_u32_b32 v160, -1, 0
	v_mbcnt_hi_u32_b32 v160, -1, v160
	v_and_b32_e32 v157, 7, v160
	v_and_b32_e32 v160, 8, v160
	v_add_u32_e32 v157, v158, v157
	v_lshlrev_b32_e32 v157, 6, v157
	v_lshl_add_u32 v157, v160, 2, v157
	v_add_u32_e32 v161, 0x2000, v157
	global_load_dwordx4 v[128:131], v157, s[18:19]
	global_load_dwordx4 v[132:135], v157, s[18:19] offset:16
	global_load_dwordx4 v[136:139], v161, s[18:19]
	global_load_dwordx4 v[140:143], v161, s[18:19] offset:16
	v_mov_b32_e32 v155, 0x358637bd
	v_lshlrev_b32_e32 v156, 17, v159
	v_lshl_add_u32 v156, v158, 1, v156
	s_waitcnt vmcnt(0)
	v_pk_add_f32 v[128:129], v[128:129], v[130:131]
	v_pk_add_f32 v[132:133], v[132:133], v[134:135]
	v_pk_add_f32 v[128:129], v[128:129], v[132:133]
	s_nop 0
	v_add_f32_e32 v154, v128, v129
	s_nop 1
	v_add_f32_dpp v154, v154, v154 row_ror:8 row_mask:0xf bank_mask:0xf
	s_nop 0
	v_fmamk_f32 v154, v154, 0x3a800000, v155
	v_rsq_f32_e32 v154, v154
	s_nop 1
	v_mov_b32_dpp v168, v154 row_newbcast:0 row_mask:0xf bank_mask:0xf
	v_mov_b32_dpp v169, v154 row_newbcast:1 row_mask:0xf bank_mask:0xf
	v_mov_b32_dpp v170, v154 row_newbcast:2 row_mask:0xf bank_mask:0xf
	v_mov_b32_dpp v171, v154 row_newbcast:3 row_mask:0xf bank_mask:0xf
	v_mov_b32_dpp v172, v154 row_newbcast:4 row_mask:0xf bank_mask:0xf
	v_mov_b32_dpp v173, v154 row_newbcast:5 row_mask:0xf bank_mask:0xf
	v_mov_b32_dpp v174, v154 row_newbcast:6 row_mask:0xf bank_mask:0xf
	v_mov_b32_dpp v175, v154 row_newbcast:7 row_mask:0xf bank_mask:0xf
	v_pk_add_f32 v[136:137], v[136:137], v[138:139]
	v_pk_add_f32 v[140:141], v[140:141], v[142:143]
	v_pk_add_f32 v[136:137], v[136:137], v[140:141]
	s_nop 0
	v_add_f32_e32 v154, v136, v137
	s_nop 1
	v_add_f32_dpp v154, v154, v154 row_ror:8 row_mask:0xf bank_mask:0xf
	s_nop 0
	v_fmamk_f32 v154, v154, 0x3a800000, v155
	v_rsq_f32_e32 v154, v154
	s_nop 1
	v_mov_b32_dpp v176, v154 row_newbcast:0 row_mask:0xf bank_mask:0xf
	v_mov_b32_dpp v177, v154 row_newbcast:1 row_mask:0xf bank_mask:0xf
	v_mov_b32_dpp v178, v154 row_newbcast:2 row_mask:0xf bank_mask:0xf
	v_mov_b32_dpp v179, v154 row_newbcast:3 row_mask:0xf bank_mask:0xf
	v_mov_b32_dpp v180, v154 row_newbcast:4 row_mask:0xf bank_mask:0xf
	v_mov_b32_dpp v181, v154 row_newbcast:5 row_mask:0xf bank_mask:0xf
	v_mov_b32_dpp v182, v154 row_newbcast:6 row_mask:0xf bank_mask:0xf
	v_mov_b32_dpp v183, v154 row_newbcast:7 row_mask:0xf bank_mask:0xf
	v_pk_mul_f32 v[124:125], v[124:125], v[168:169]
	v_pk_mul_f32 v[126:127], v[126:127], v[170:171]
	v_pk_mul_f32 v[120:121], v[120:121], v[172:173]
	v_pk_mul_f32 v[122:123], v[122:123], v[174:175]
	v_cvt_pk_bf16_f32 v184, v124, v125
	v_cvt_pk_bf16_f32 v185, v126, v127
	v_cvt_pk_bf16_f32 v186, v120, v121
	v_cvt_pk_bf16_f32 v187, v122, v123
	global_store_dwordx4 v156, v[184:187], s[8:9]
	v_pk_mul_f32 v[60:61], v[60:61], v[176:177]
	v_pk_mul_f32 v[62:63], v[62:63], v[178:179]
	v_pk_mul_f32 v[56:57], v[56:57], v[180:181]
	v_pk_mul_f32 v[58:59], v[58:59], v[182:183]
	v_cvt_pk_bf16_f32 v188, v60, v61
	v_cvt_pk_bf16_f32 v189, v62, v63
	v_cvt_pk_bf16_f32 v190, v56, v57
	v_cvt_pk_bf16_f32 v191, v58, v59
	global_store_dwordx4 v156, v[188:191], s[8:9] offset:256
	v_add_u32_e32 v156, 0x200000, v156
	v_pk_mul_f32 v[116:117], v[116:117], v[168:169]
	v_pk_mul_f32 v[118:119], v[118:119], v[170:171]
	v_pk_mul_f32 v[112:113], v[112:113], v[172:173]
	v_pk_mul_f32 v[114:115], v[114:115], v[174:175]
	v_cvt_pk_bf16_f32 v184, v116, v117
	v_cvt_pk_bf16_f32 v185, v118, v119
	v_cvt_pk_bf16_f32 v186, v112, v113
	v_cvt_pk_bf16_f32 v187, v114, v115
	global_store_dwordx4 v156, v[184:187], s[8:9]
	v_pk_mul_f32 v[52:53], v[52:53], v[176:177]
	v_pk_mul_f32 v[54:55], v[54:55], v[178:179]
	v_pk_mul_f32 v[48:49], v[48:49], v[180:181]
	v_pk_mul_f32 v[50:51], v[50:51], v[182:183]
	v_cvt_pk_bf16_f32 v188, v52, v53
	v_cvt_pk_bf16_f32 v189, v54, v55
	v_cvt_pk_bf16_f32 v190, v48, v49
	v_cvt_pk_bf16_f32 v191, v50, v51
	global_store_dwordx4 v156, v[188:191], s[8:9] offset:256
	v_add_u32_e32 v156, 0x200000, v156
	v_pk_mul_f32 v[108:109], v[108:109], v[168:169]
	v_pk_mul_f32 v[110:111], v[110:111], v[170:171]
	v_pk_mul_f32 v[104:105], v[104:105], v[172:173]
	v_pk_mul_f32 v[106:107], v[106:107], v[174:175]
	v_cvt_pk_bf16_f32 v184, v108, v109
	v_cvt_pk_bf16_f32 v185, v110, v111
	v_cvt_pk_bf16_f32 v186, v104, v105
	v_cvt_pk_bf16_f32 v187, v106, v107
	global_store_dwordx4 v156, v[184:187], s[8:9]
	v_pk_mul_f32 v[44:45], v[44:45], v[176:177]
	v_pk_mul_f32 v[46:47], v[46:47], v[178:179]
	v_pk_mul_f32 v[40:41], v[40:41], v[180:181]
	v_pk_mul_f32 v[42:43], v[42:43], v[182:183]
	v_cvt_pk_bf16_f32 v188, v44, v45
	v_cvt_pk_bf16_f32 v189, v46, v47
	v_cvt_pk_bf16_f32 v190, v40, v41
	v_cvt_pk_bf16_f32 v191, v42, v43
	global_store_dwordx4 v156, v[188:191], s[8:9] offset:256
	v_add_u32_e32 v156, 0x200000, v156
	v_pk_mul_f32 v[100:101], v[100:101], v[168:169]
	v_pk_mul_f32 v[102:103], v[102:103], v[170:171]
	v_pk_mul_f32 v[96:97], v[96:97], v[172:173]
	v_pk_mul_f32 v[98:99], v[98:99], v[174:175]
	v_cvt_pk_bf16_f32 v184, v100, v101
	v_cvt_pk_bf16_f32 v185, v102, v103
	v_cvt_pk_bf16_f32 v186, v96, v97
	v_cvt_pk_bf16_f32 v187, v98, v99
	global_store_dwordx4 v156, v[184:187], s[8:9]
	v_pk_mul_f32 v[36:37], v[36:37], v[176:177]
	v_pk_mul_f32 v[38:39], v[38:39], v[178:179]
	v_pk_mul_f32 v[32:33], v[32:33], v[180:181]
	v_pk_mul_f32 v[34:35], v[34:35], v[182:183]
	v_cvt_pk_bf16_f32 v188, v36, v37
	v_cvt_pk_bf16_f32 v189, v38, v39
	v_cvt_pk_bf16_f32 v190, v32, v33
	v_cvt_pk_bf16_f32 v191, v34, v35
	global_store_dwordx4 v156, v[188:191], s[8:9] offset:256
	v_add_u32_e32 v156, 0xa00000, v156
	v_pk_mul_f32 v[92:93], v[92:93], v[168:169]
	v_pk_mul_f32 v[94:95], v[94:95], v[170:171]
	v_pk_mul_f32 v[88:89], v[88:89], v[172:173]
	v_pk_mul_f32 v[90:91], v[90:91], v[174:175]
	v_cvt_pk_bf16_f32 v184, v92, v93
	v_cvt_pk_bf16_f32 v185, v94, v95
	v_cvt_pk_bf16_f32 v186, v88, v89
	v_cvt_pk_bf16_f32 v187, v90, v91
	global_store_dwordx4 v156, v[184:187], s[8:9]
	v_pk_mul_f32 v[28:29], v[28:29], v[176:177]
	v_pk_mul_f32 v[30:31], v[30:31], v[178:179]
	v_pk_mul_f32 v[24:25], v[24:25], v[180:181]
	v_pk_mul_f32 v[26:27], v[26:27], v[182:183]
	v_cvt_pk_bf16_f32 v188, v28, v29
	v_cvt_pk_bf16_f32 v189, v30, v31
	v_cvt_pk_bf16_f32 v190, v24, v25
	v_cvt_pk_bf16_f32 v191, v26, v27
	global_store_dwordx4 v156, v[188:191], s[8:9] offset:256
	v_add_u32_e32 v156, 0x200000, v156
	v_pk_mul_f32 v[84:85], v[84:85], v[168:169]
	v_pk_mul_f32 v[86:87], v[86:87], v[170:171]
	v_pk_mul_f32 v[80:81], v[80:81], v[172:173]
	v_pk_mul_f32 v[82:83], v[82:83], v[174:175]
	v_cvt_pk_bf16_f32 v184, v84, v85
	v_cvt_pk_bf16_f32 v185, v86, v87
	v_cvt_pk_bf16_f32 v186, v80, v81
	v_cvt_pk_bf16_f32 v187, v82, v83
	global_store_dwordx4 v156, v[184:187], s[8:9]
	v_pk_mul_f32 v[20:21], v[20:21], v[176:177]
	v_pk_mul_f32 v[22:23], v[22:23], v[178:179]
	v_pk_mul_f32 v[16:17], v[16:17], v[180:181]
	v_pk_mul_f32 v[18:19], v[18:19], v[182:183]
	v_cvt_pk_bf16_f32 v188, v20, v21
	v_cvt_pk_bf16_f32 v189, v22, v23
	v_cvt_pk_bf16_f32 v190, v16, v17
	v_cvt_pk_bf16_f32 v191, v18, v19
	global_store_dwordx4 v156, v[188:191], s[8:9] offset:256
	v_add_u32_e32 v156, 0x200000, v156
	v_pk_mul_f32 v[76:77], v[76:77], v[168:169]
	v_pk_mul_f32 v[78:79], v[78:79], v[170:171]
	v_pk_mul_f32 v[72:73], v[72:73], v[172:173]
	v_pk_mul_f32 v[74:75], v[74:75], v[174:175]
	v_cvt_pk_bf16_f32 v184, v76, v77
	v_cvt_pk_bf16_f32 v185, v78, v79
	v_cvt_pk_bf16_f32 v186, v72, v73
	v_cvt_pk_bf16_f32 v187, v74, v75
	global_store_dwordx4 v156, v[184:187], s[8:9]
	v_pk_mul_f32 v[12:13], v[12:13], v[176:177]
	v_pk_mul_f32 v[14:15], v[14:15], v[178:179]
	v_pk_mul_f32 v[8:9], v[8:9], v[180:181]
	v_pk_mul_f32 v[10:11], v[10:11], v[182:183]
	v_cvt_pk_bf16_f32 v188, v12, v13
	v_cvt_pk_bf16_f32 v189, v14, v15
	v_cvt_pk_bf16_f32 v190, v8, v9
	v_cvt_pk_bf16_f32 v191, v10, v11
	global_store_dwordx4 v156, v[188:191], s[8:9] offset:256
	v_add_u32_e32 v156, 0x200000, v156
	v_pk_mul_f32 v[68:69], v[68:69], v[168:169]
	v_pk_mul_f32 v[70:71], v[70:71], v[170:171]
	v_pk_mul_f32 v[64:65], v[64:65], v[172:173]
	v_pk_mul_f32 v[66:67], v[66:67], v[174:175]
	v_cvt_pk_bf16_f32 v184, v68, v69
	v_cvt_pk_bf16_f32 v185, v70, v71
	v_cvt_pk_bf16_f32 v186, v64, v65
	v_cvt_pk_bf16_f32 v187, v66, v67
	global_store_dwordx4 v156, v[184:187], s[8:9]
	v_pk_mul_f32 v[4:5], v[4:5], v[176:177]
	v_pk_mul_f32 v[6:7], v[6:7], v[178:179]
	v_pk_mul_f32 v[0:1], v[0:1], v[180:181]
	v_pk_mul_f32 v[2:3], v[2:3], v[182:183]
	v_cvt_pk_bf16_f32 v188, v4, v5
	v_cvt_pk_bf16_f32 v189, v6, v7
	v_cvt_pk_bf16_f32 v190, v0, v1
	v_cvt_pk_bf16_f32 v191, v2, v3
	global_store_dwordx4 v156, v[188:191], s[8:9] offset:256
	s_mov_b64 s[6:7], s[22:23]
	s_and_b64 vcc, exec, s[4:5]
	s_cbranch_vccz .LBB0_707
	s_waitcnt vmcnt(0)
	s_cmpk_gt_u32 s30, 0xff
	s_cbranch_scc1 .LBB0_718
	s_barrier

.LBB0_776:
	s_add_u32 s28, s26, 0xfffc0080
	s_addc_u32 s29, s27, -1
	s_add_i32 s66, 0, 0x10000
	v_add_u32_e32 v154, s66, v143
	ds_read_b128 v[138:141], v154
	ds_read_b128 v[146:149], v154 offset:1024
	ds_read_b128 v[150:153], v154 offset:2048
	ds_read_b128 v[154:157], v154 offset:3072
	s_cmp_eq_u32 s65, 12
	s_cselect_b32 s31, s21, s29
	s_cselect_b32 s30, s39, s28
	s_cselect_b32 s29, s19, s64
	s_cselect_b32 s28, s62, s63
	s_add_i32 m0, s54, 0xc000
	ds_read_b128 v[158:161], v145
	ds_read_b128 v[162:165], v145 offset:1024
	ds_read_b128 v[166:169], v145 offset:2048
	ds_read_b128 v[170:173], v145 offset:3072
	ds_read_b128 v[174:177], v145 offset:4096
	ds_read_b128 v[178:181], v145 offset:5120
	ds_read_b128 v[182:185], v145 offset:6144
	ds_read_b128 v[186:189], v145 offset:7168
	global_load_lds_dwordx4 v134, s[26:27]
	s_add_i32 m0, s54, 0xe000
	s_nop 0
	global_load_lds_dwordx4 v136, s[26:27]
	s_waitcnt lgkmcnt(8)
	s_barrier
	s_waitcnt lgkmcnt(0)
	s_setprio 1
	v_mfma_f32_16x16x32_bf16 v[124:127], v[138:141], v[158:161], v[124:127]
	v_mfma_f32_16x16x32_bf16 v[120:123], v[150:153], v[158:161], v[120:123]
	v_mfma_f32_16x16x32_bf16 v[108:111], v[138:141], v[166:169], v[108:111]
	v_mfma_f32_16x16x32_bf16 v[104:107], v[150:153], v[166:169], v[104:107]
	v_mfma_f32_16x16x32_bf16 v[92:95], v[138:141], v[174:177], v[92:95]
	v_mfma_f32_16x16x32_bf16 v[88:91], v[150:153], v[174:177], v[88:91]
	v_mfma_f32_16x16x32_bf16 v[76:79], v[138:141], v[182:185], v[76:79]
	v_mfma_f32_16x16x32_bf16 v[72:75], v[150:153], v[182:185], v[72:75]
	v_mfma_f32_16x16x32_bf16 v[124:127], v[146:149], v[162:165], v[124:127]
	v_mfma_f32_16x16x32_bf16 v[120:123], v[154:157], v[162:165], v[120:123]
	v_mfma_f32_16x16x32_bf16 v[108:111], v[146:149], v[170:173], v[108:111]
	v_mfma_f32_16x16x32_bf16 v[104:107], v[154:157], v[170:173], v[104:107]
	v_mfma_f32_16x16x32_bf16 v[92:95], v[146:149], v[178:181], v[92:95]
	v_mfma_f32_16x16x32_bf16 v[88:91], v[154:157], v[178:181], v[88:91]
	v_mfma_f32_16x16x32_bf16 v[76:79], v[146:149], v[186:189], v[76:79]
	v_mfma_f32_16x16x32_bf16 v[72:75], v[154:157], v[186:189], v[72:75]
	s_setprio 0
	s_barrier
	s_add_i32 s68, 0, 0x14000
	s_add_i32 s66, s66, s53
	v_add_u32_e32 v202, s68, v143
	s_add_u32 s98, s28, s40
	s_addc_u32 s99, s29, s41
	s_mov_b32 m0, s66
	ds_read_b128 v[190:193], v202
	ds_read_b128 v[194:197], v202 offset:1024
	ds_read_b128 v[198:201], v202 offset:2048
	ds_read_b128 v[202:205], v202 offset:3072
	global_load_lds_dwordx4 v208, s[28:29]
	s_add_i32 m0, s66, 0x2000
	s_nop 0
	global_load_lds_dwordx4 v128, s[28:29]
	s_barrier
	s_waitcnt lgkmcnt(0)
	s_setprio 1
	v_mfma_f32_16x16x32_bf16 v[116:119], v[190:193], v[158:161], v[116:119]
	v_mfma_f32_16x16x32_bf16 v[112:115], v[198:201], v[158:161], v[112:115]
	v_mfma_f32_16x16x32_bf16 v[100:103], v[190:193], v[166:169], v[100:103]
	v_mfma_f32_16x16x32_bf16 v[96:99], v[198:201], v[166:169], v[96:99]
	v_mfma_f32_16x16x32_bf16 v[84:87], v[190:193], v[174:177], v[84:87]
	v_mfma_f32_16x16x32_bf16 v[80:83], v[198:201], v[174:177], v[80:83]
	v_mfma_f32_16x16x32_bf16 v[68:71], v[190:193], v[182:185], v[68:71]
	v_mfma_f32_16x16x32_bf16 v[64:67], v[198:201], v[182:185], v[64:67]
	v_mfma_f32_16x16x32_bf16 v[116:119], v[194:197], v[162:165], v[116:119]
	v_mfma_f32_16x16x32_bf16 v[112:115], v[202:205], v[162:165], v[112:115]
	v_mfma_f32_16x16x32_bf16 v[100:103], v[194:197], v[170:173], v[100:103]
	v_mfma_f32_16x16x32_bf16 v[96:99], v[202:205], v[170:173], v[96:99]
	v_mfma_f32_16x16x32_bf16 v[84:87], v[194:197], v[178:181], v[84:87]
	v_mfma_f32_16x16x32_bf16 v[80:83], v[202:205], v[178:181], v[80:83]
	v_mfma_f32_16x16x32_bf16 v[68:71], v[194:197], v[186:189], v[68:71]
	v_mfma_f32_16x16x32_bf16 v[64:67], v[202:205], v[186:189], v[64:67]
	s_setprio 0
	s_mov_b32 m0, s54
	s_add_u32 s100, s30, s40
	s_addc_u32 s101, s31, s41
	s_barrier
	ds_read_b128 v[158:161], v145 offset:16384
	ds_read_b128 v[162:165], v145 offset:17408
	ds_read_b128 v[166:169], v145 offset:18432
	ds_read_b128 v[170:173], v145 offset:19456
	ds_read_b128 v[174:177], v145 offset:20480
	ds_read_b128 v[178:181], v145 offset:21504
	ds_read_b128 v[182:185], v145 offset:22528
	ds_read_b128 v[186:189], v145 offset:23552
	global_load_lds_dwordx4 v132, s[30:31]
	s_mov_b32 m0, s55
	s_nop 0
	global_load_lds_dwordx4 v130, s[30:31]
	s_barrier
	s_waitcnt lgkmcnt(0)
	s_setprio 1
	v_mfma_f32_16x16x32_bf16 v[60:63], v[138:141], v[158:161], v[60:63]
	v_mfma_f32_16x16x32_bf16 v[56:59], v[150:153], v[158:161], v[56:59]
	v_mfma_f32_16x16x32_bf16 v[44:47], v[138:141], v[166:169], v[44:47]
	v_mfma_f32_16x16x32_bf16 v[40:43], v[150:153], v[166:169], v[40:43]
	v_mfma_f32_16x16x32_bf16 v[28:31], v[138:141], v[174:177], v[28:31]
	v_mfma_f32_16x16x32_bf16 v[24:27], v[150:153], v[174:177], v[24:27]
	v_mfma_f32_16x16x32_bf16 v[12:15], v[138:141], v[182:185], v[12:15]
	v_mfma_f32_16x16x32_bf16 v[8:11], v[150:153], v[182:185], v[8:11]
	v_mfma_f32_16x16x32_bf16 v[60:63], v[146:149], v[162:165], v[60:63]
	v_mfma_f32_16x16x32_bf16 v[56:59], v[154:157], v[162:165], v[56:59]
	v_mfma_f32_16x16x32_bf16 v[44:47], v[146:149], v[170:173], v[44:47]
	v_mfma_f32_16x16x32_bf16 v[40:43], v[154:157], v[170:173], v[40:43]
	v_mfma_f32_16x16x32_bf16 v[28:31], v[146:149], v[178:181], v[28:31]
	v_mfma_f32_16x16x32_bf16 v[24:27], v[154:157], v[178:181], v[24:27]
	v_mfma_f32_16x16x32_bf16 v[12:15], v[146:149], v[186:189], v[12:15]
	v_mfma_f32_16x16x32_bf16 v[8:11], v[154:157], v[186:189], v[8:11]
	s_setprio 0
	s_barrier
	s_add_u32 s66, s28, 0x40000
	s_addc_u32 s67, s29, 0
	s_add_i32 s68, s68, s53
	s_mov_b32 m0, s68
	s_nop 0
	global_load_lds_dwordx4 v208, s[66:67]
	s_add_i32 m0, s68, 0x2000
	s_nop 0
	global_load_lds_dwordx4 v128, s[66:67]
	s_waitcnt vmcnt(6)
	s_barrier
	s_setprio 1
	v_mfma_f32_16x16x32_bf16 v[52:55], v[190:193], v[158:161], v[52:55]
	v_mfma_f32_16x16x32_bf16 v[48:51], v[198:201], v[158:161], v[48:51]
	v_mfma_f32_16x16x32_bf16 v[36:39], v[190:193], v[166:169], v[36:39]
	v_mfma_f32_16x16x32_bf16 v[32:35], v[198:201], v[166:169], v[32:35]
	v_mfma_f32_16x16x32_bf16 v[20:23], v[190:193], v[174:177], v[20:23]
	v_mfma_f32_16x16x32_bf16 v[16:19], v[198:201], v[174:177], v[16:19]
	v_mfma_f32_16x16x32_bf16 v[4:7], v[190:193], v[182:185], v[4:7]
	v_mfma_f32_16x16x32_bf16 v[0:3], v[198:201], v[182:185], v[0:3]
	v_mfma_f32_16x16x32_bf16 v[52:55], v[194:197], v[162:165], v[52:55]
	v_mfma_f32_16x16x32_bf16 v[48:51], v[202:205], v[162:165], v[48:51]
	v_mfma_f32_16x16x32_bf16 v[36:39], v[194:197], v[170:173], v[36:39]
	v_mfma_f32_16x16x32_bf16 v[32:35], v[202:205], v[170:173], v[32:35]
	v_mfma_f32_16x16x32_bf16 v[20:23], v[194:197], v[178:181], v[20:23]
	v_mfma_f32_16x16x32_bf16 v[16:19], v[202:205], v[178:181], v[16:19]
	v_mfma_f32_16x16x32_bf16 v[4:7], v[194:197], v[186:189], v[4:7]
	v_mfma_f32_16x16x32_bf16 v[0:3], v[202:205], v[186:189], v[0:3]
	s_setprio 0
	s_add_i32 s66, 0, 0x18000
	v_add_u32_e32 v154, s66, v143
	s_barrier
	ds_read_b128 v[138:141], v154
	ds_read_b128 v[146:149], v154 offset:1024
	ds_read_b128 v[150:153], v154 offset:2048
	ds_read_b128 v[154:157], v154 offset:3072
	s_add_u32 s30, s30, 0x40000
	s_addc_u32 s31, s31, 0
	s_mov_b32 m0, s56
	ds_read_b128 v[158:161], v145 offset:32768
	ds_read_b128 v[162:165], v145 offset:33792
	ds_read_b128 v[166:169], v145 offset:34816
	ds_read_b128 v[170:173], v145 offset:35840
	ds_read_b128 v[174:177], v145 offset:36864
	ds_read_b128 v[178:181], v145 offset:37888
	ds_read_b128 v[182:185], v145 offset:38912
	ds_read_b128 v[186:189], v145 offset:39936
	global_load_lds_dwordx4 v132, s[30:31]
	s_mov_b32 m0, s57
	s_nop 0
	global_load_lds_dwordx4 v130, s[30:31]
	s_waitcnt lgkmcnt(8)
	s_barrier
	s_waitcnt lgkmcnt(0)
	s_setprio 1
	v_mfma_f32_16x16x32_bf16 v[124:127], v[138:141], v[158:161], v[124:127]
	v_mfma_f32_16x16x32_bf16 v[120:123], v[150:153], v[158:161], v[120:123]
	v_mfma_f32_16x16x32_bf16 v[108:111], v[138:141], v[166:169], v[108:111]
	v_mfma_f32_16x16x32_bf16 v[104:107], v[150:153], v[166:169], v[104:107]
	v_mfma_f32_16x16x32_bf16 v[92:95], v[138:141], v[174:177], v[92:95]
	v_mfma_f32_16x16x32_bf16 v[88:91], v[150:153], v[174:177], v[88:91]
	v_mfma_f32_16x16x32_bf16 v[76:79], v[138:141], v[182:185], v[76:79]
	v_mfma_f32_16x16x32_bf16 v[72:75], v[150:153], v[182:185], v[72:75]
	v_mfma_f32_16x16x32_bf16 v[124:127], v[146:149], v[162:165], v[124:127]
	v_mfma_f32_16x16x32_bf16 v[120:123], v[154:157], v[162:165], v[120:123]
	v_mfma_f32_16x16x32_bf16 v[108:111], v[146:149], v[170:173], v[108:111]
	v_mfma_f32_16x16x32_bf16 v[104:107], v[154:157], v[170:173], v[104:107]
	v_mfma_f32_16x16x32_bf16 v[92:95], v[146:149], v[178:181], v[92:95]
	v_mfma_f32_16x16x32_bf16 v[88:91], v[154:157], v[178:181], v[88:91]
	v_mfma_f32_16x16x32_bf16 v[76:79], v[146:149], v[186:189], v[76:79]
	v_mfma_f32_16x16x32_bf16 v[72:75], v[154:157], v[186:189], v[72:75]
	s_setprio 0
	s_barrier
	s_add_i32 s30, 0, 0x1c000
	s_add_i32 s31, s66, s53
	v_add_u32_e32 v202, s30, v143
	s_mov_b32 m0, s31
	ds_read_b128 v[190:193], v202
	ds_read_b128 v[194:197], v202 offset:1024
	ds_read_b128 v[198:201], v202 offset:2048
	ds_read_b128 v[202:205], v202 offset:3072
	global_load_lds_dwordx4 v208, s[98:99]
	s_add_i32 m0, s31, 0x2000
	s_nop 0
	global_load_lds_dwordx4 v128, s[98:99]
	s_barrier
	s_waitcnt lgkmcnt(0)
	s_setprio 1
	v_mfma_f32_16x16x32_bf16 v[116:119], v[190:193], v[158:161], v[116:119]
	v_mfma_f32_16x16x32_bf16 v[112:115], v[198:201], v[158:161], v[112:115]
	v_mfma_f32_16x16x32_bf16 v[100:103], v[190:193], v[166:169], v[100:103]
	v_mfma_f32_16x16x32_bf16 v[96:99], v[198:201], v[166:169], v[96:99]
	v_mfma_f32_16x16x32_bf16 v[84:87], v[190:193], v[174:177], v[84:87]
	v_mfma_f32_16x16x32_bf16 v[80:83], v[198:201], v[174:177], v[80:83]
	v_mfma_f32_16x16x32_bf16 v[68:71], v[190:193], v[182:185], v[68:71]
	v_mfma_f32_16x16x32_bf16 v[64:67], v[198:201], v[182:185], v[64:67]
	v_mfma_f32_16x16x32_bf16 v[116:119], v[194:197], v[162:165], v[116:119]
	v_mfma_f32_16x16x32_bf16 v[112:115], v[202:205], v[162:165], v[112:115]
	v_mfma_f32_16x16x32_bf16 v[100:103], v[194:197], v[170:173], v[100:103]
	v_mfma_f32_16x16x32_bf16 v[96:99], v[202:205], v[170:173], v[96:99]
	v_mfma_f32_16x16x32_bf16 v[84:87], v[194:197], v[178:181], v[84:87]
	v_mfma_f32_16x16x32_bf16 v[80:83], v[202:205], v[178:181], v[80:83]
	v_mfma_f32_16x16x32_bf16 v[68:71], v[194:197], v[186:189], v[68:71]
	v_mfma_f32_16x16x32_bf16 v[64:67], v[202:205], v[186:189], v[64:67]
	s_setprio 0
	s_mov_b32 m0, s59
	s_barrier
	ds_read_b128 v[158:161], v145 offset:49152
	ds_read_b128 v[162:165], v145 offset:50176
	ds_read_b128 v[166:169], v145 offset:51200
	ds_read_b128 v[170:173], v145 offset:52224
	ds_read_b128 v[174:177], v145 offset:53248
	ds_read_b128 v[178:181], v145 offset:54272
	ds_read_b128 v[182:185], v145 offset:55296
	ds_read_b128 v[186:189], v145 offset:56320
	global_load_lds_dwordx4 v132, s[100:101]
	s_mov_b32 m0, s60
	s_nop 0
	global_load_lds_dwordx4 v130, s[100:101]
	s_barrier
	s_waitcnt lgkmcnt(0)
	s_setprio 1
	v_mfma_f32_16x16x32_bf16 v[60:63], v[138:141], v[158:161], v[60:63]
	v_mfma_f32_16x16x32_bf16 v[56:59], v[150:153], v[158:161], v[56:59]
	v_mfma_f32_16x16x32_bf16 v[44:47], v[138:141], v[166:169], v[44:47]
	v_mfma_f32_16x16x32_bf16 v[40:43], v[150:153], v[166:169], v[40:43]
	v_mfma_f32_16x16x32_bf16 v[28:31], v[138:141], v[174:177], v[28:31]
	v_mfma_f32_16x16x32_bf16 v[24:27], v[150:153], v[174:177], v[24:27]
	v_mfma_f32_16x16x32_bf16 v[12:15], v[138:141], v[182:185], v[12:15]
	v_mfma_f32_16x16x32_bf16 v[8:11], v[150:153], v[182:185], v[8:11]
	v_mfma_f32_16x16x32_bf16 v[60:63], v[146:149], v[162:165], v[60:63]
	v_mfma_f32_16x16x32_bf16 v[56:59], v[154:157], v[162:165], v[56:59]
	v_mfma_f32_16x16x32_bf16 v[44:47], v[146:149], v[170:173], v[44:47]
	v_mfma_f32_16x16x32_bf16 v[40:43], v[154:157], v[170:173], v[40:43]
	v_mfma_f32_16x16x32_bf16 v[28:31], v[146:149], v[178:181], v[28:31]
	v_mfma_f32_16x16x32_bf16 v[24:27], v[154:157], v[178:181], v[24:27]
	v_mfma_f32_16x16x32_bf16 v[12:15], v[146:149], v[186:189], v[12:15]
	v_mfma_f32_16x16x32_bf16 v[8:11], v[154:157], v[186:189], v[8:11]
	s_setprio 0
	s_barrier
	s_add_u32 s28, s28, 0x40080
	s_addc_u32 s29, s29, 0
	s_add_i32 s30, s30, s53
	s_mov_b32 m0, s30
	s_nop 0
	global_load_lds_dwordx4 v208, s[28:29]
	s_add_i32 m0, s30, 0x2000
	s_nop 0
	global_load_lds_dwordx4 v128, s[28:29]
	s_waitcnt vmcnt(6)
	s_barrier
	s_setprio 1
	v_mfma_f32_16x16x32_bf16 v[52:55], v[190:193], v[158:161], v[52:55]
	v_mfma_f32_16x16x32_bf16 v[48:51], v[198:201], v[158:161], v[48:51]
	v_mfma_f32_16x16x32_bf16 v[36:39], v[190:193], v[166:169], v[36:39]
	v_mfma_f32_16x16x32_bf16 v[32:35], v[198:201], v[166:169], v[32:35]
	v_mfma_f32_16x16x32_bf16 v[20:23], v[190:193], v[174:177], v[20:23]
	v_mfma_f32_16x16x32_bf16 v[16:19], v[198:201], v[174:177], v[16:19]
	v_mfma_f32_16x16x32_bf16 v[4:7], v[190:193], v[182:185], v[4:7]
	v_mfma_f32_16x16x32_bf16 v[0:3], v[198:201], v[182:185], v[0:3]
	v_mfma_f32_16x16x32_bf16 v[52:55], v[194:197], v[162:165], v[52:55]
	v_mfma_f32_16x16x32_bf16 v[48:51], v[202:205], v[162:165], v[48:51]
	v_mfma_f32_16x16x32_bf16 v[36:39], v[194:197], v[170:173], v[36:39]
	v_mfma_f32_16x16x32_bf16 v[32:35], v[202:205], v[170:173], v[32:35]
	v_mfma_f32_16x16x32_bf16 v[20:23], v[194:197], v[178:181], v[20:23]
	v_mfma_f32_16x16x32_bf16 v[16:19], v[202:205], v[178:181], v[16:19]
	v_mfma_f32_16x16x32_bf16 v[4:7], v[194:197], v[186:189], v[4:7]
	v_mfma_f32_16x16x32_bf16 v[0:3], v[202:205], v[186:189], v[0:3]
	s_setprio 0
	s_add_i32 s65, s65, 2
	s_add_u32 s26, s26, 0x100
	s_addc_u32 s27, s27, 0
	s_add_u32 s63, s63, 0x100
	s_addc_u32 s64, s64, 0
	s_cmp_gt_u32 s65, 13
	s_barrier
	s_cbranch_scc0 .LBB0_776
	v_lshl_add_u32 v140, s38, 8, v142
	v_lshl_or_b32 v141, s36, 8, v144
	s_lshl_b32 s26, s36, 2
	s_ashr_i32 s27, s26, 31
	s_lshl_b32 s36, s58, 2
	v_lshlrev_b32_e32 v206, 11, v140
	v_lshl_add_u32 v206, v141, 1, v206
	v_lshl_add_u32 v210, v140, 6, s36
	v_lshl_add_u32 v210, s26, 2, v210
	v_mov_b32_e32 v207, v206
	global_load_dwordx4 v[146:149], v206, s[10:11]
	global_load_dwordx4 v[150:153], v206, s[10:11] offset:256
	v_add_u32_e32 v206, 0x8000, v206
	global_load_dwordx4 v[154:157], v206, s[10:11]
	global_load_dwordx4 v[158:161], v206, s[10:11] offset:256
	v_add_u32_e32 v206, 0x8000, v206
	global_load_dwordx4 v[162:165], v206, s[10:11]
	global_load_dwordx4 v[166:169], v206, s[10:11] offset:256
	v_add_u32_e32 v206, 0x8000, v206
	global_load_dwordx4 v[170:173], v206, s[10:11]
	global_load_dwordx4 v[174:177], v206, s[10:11] offset:256
	v_add_u32_e32 v206, 0x28000, v206
	global_load_dwordx4 v[178:181], v206, s[10:11]
	global_load_dwordx4 v[182:185], v206, s[10:11] offset:256
	v_add_u32_e32 v206, 0x8000, v206
	global_load_dwordx4 v[186:189], v206, s[10:11]
	global_load_dwordx4 v[190:193], v206, s[10:11] offset:256
	v_add_u32_e32 v206, 0x8000, v206
	global_load_dwordx4 v[194:197], v206, s[10:11]
	global_load_dwordx4 v[198:201], v206, s[10:11] offset:256
	v_add_u32_e32 v206, 0x8000, v206
	s_waitcnt vmcnt(12)
	v_lshlrev_b32_e32 v202, 16, v146
	v_and_b32_e32 v203, 0xffff0000, v146
	v_lshlrev_b32_e32 v204, 16, v147
	v_and_b32_e32 v205, 0xffff0000, v147
	v_pk_add_f32 v[124:125], v[124:125], v[202:203]
	v_pk_add_f32 v[126:127], v[126:127], v[204:205]
	v_lshlrev_b32_e32 v202, 16, v148
	v_and_b32_e32 v203, 0xffff0000, v148
	v_lshlrev_b32_e32 v204, 16, v149
	v_and_b32_e32 v205, 0xffff0000, v149
	v_pk_add_f32 v[120:121], v[120:121], v[202:203]
	v_pk_add_f32 v[122:123], v[122:123], v[204:205]
	v_cvt_pk_bf16_f32 v146, v124, v125
	v_cvt_pk_bf16_f32 v147, v126, v127
	v_cvt_pk_bf16_f32 v148, v120, v121
	v_cvt_pk_bf16_f32 v149, v122, v123
	v_pk_mul_f32 v[138:139], v[124:125], v[124:125]
	global_store_dwordx4 v207, v[146:149], s[10:11]
	v_pk_fma_f32 v[138:139], v[126:127], v[126:127], v[138:139]
	v_pk_fma_f32 v[138:139], v[120:121], v[120:121], v[138:139]
	v_pk_fma_f32 v[138:139], v[122:123], v[122:123], v[138:139]
	v_lshlrev_b32_e32 v202, 16, v150
	v_and_b32_e32 v203, 0xffff0000, v150
	v_lshlrev_b32_e32 v204, 16, v151
	v_and_b32_e32 v205, 0xffff0000, v151
	v_pk_add_f32 v[116:117], v[116:117], v[202:203]
	v_pk_add_f32 v[118:119], v[118:119], v[204:205]
	v_lshlrev_b32_e32 v202, 16, v152
	v_and_b32_e32 v203, 0xffff0000, v152
	v_lshlrev_b32_e32 v204, 16, v153
	v_and_b32_e32 v205, 0xffff0000, v153
	v_pk_add_f32 v[112:113], v[112:113], v[202:203]
	v_pk_add_f32 v[114:115], v[114:115], v[204:205]
	v_cvt_pk_bf16_f32 v150, v116, v117
	v_cvt_pk_bf16_f32 v151, v118, v119
	v_cvt_pk_bf16_f32 v152, v112, v113
	v_cvt_pk_bf16_f32 v153, v114, v115
	v_pk_fma_f32 v[138:139], v[116:117], v[116:117], v[138:139]
	global_store_dwordx4 v207, v[150:153], s[10:11] offset:256
	v_pk_fma_f32 v[138:139], v[118:119], v[118:119], v[138:139]
	v_pk_fma_f32 v[138:139], v[112:113], v[112:113], v[138:139]
	v_pk_fma_f32 v[138:139], v[114:115], v[114:115], v[138:139]
	v_add_f32_e32 v214, v138, v139
	v_add_u32_e32 v207, 0x8000, v207
	v_mov_b32_e32 v215, v214
	s_nop 1
	v_permlane16_swap_b32_e32 v214, v215
	s_nop 0
	v_add_f32_e32 v214, v214, v215
	v_mov_b32_e32 v215, v214
	s_nop 1
	v_permlane32_swap_b32_e32 v214, v215
	s_nop 0
	v_add_f32_e32 v214, v214, v215
	s_and_saveexec_b64 s[28:29], s[4:5]
	global_store_dword v210, v214, s[16:17]
	s_mov_b64 exec, s[28:29]
	global_load_dwordx4 v[146:149], v206, s[10:11]
	global_load_dwordx4 v[150:153], v206, s[10:11] offset:256
	s_waitcnt vmcnt(15)
	v_lshlrev_b32_e32 v202, 16, v154
	v_and_b32_e32 v203, 0xffff0000, v154
	v_lshlrev_b32_e32 v204, 16, v155
	v_and_b32_e32 v205, 0xffff0000, v155
	v_pk_add_f32 v[108:109], v[108:109], v[202:203]
	v_pk_add_f32 v[110:111], v[110:111], v[204:205]
	v_lshlrev_b32_e32 v202, 16, v156
	v_and_b32_e32 v203, 0xffff0000, v156
	v_lshlrev_b32_e32 v204, 16, v157
	v_and_b32_e32 v205, 0xffff0000, v157
	v_pk_add_f32 v[104:105], v[104:105], v[202:203]
	v_pk_add_f32 v[106:107], v[106:107], v[204:205]
	v_cvt_pk_bf16_f32 v154, v108, v109
	v_cvt_pk_bf16_f32 v155, v110, v111
	v_cvt_pk_bf16_f32 v156, v104, v105
	v_cvt_pk_bf16_f32 v157, v106, v107
	v_pk_mul_f32 v[138:139], v[108:109], v[108:109]
	global_store_dwordx4 v207, v[154:157], s[10:11]
	v_pk_fma_f32 v[138:139], v[110:111], v[110:111], v[138:139]
	v_pk_fma_f32 v[138:139], v[104:105], v[104:105], v[138:139]
	v_pk_fma_f32 v[138:139], v[106:107], v[106:107], v[138:139]
	v_lshlrev_b32_e32 v202, 16, v158
	v_and_b32_e32 v203, 0xffff0000, v158
	v_lshlrev_b32_e32 v204, 16, v159
	v_and_b32_e32 v205, 0xffff0000, v159
	v_pk_add_f32 v[100:101], v[100:101], v[202:203]
	v_pk_add_f32 v[102:103], v[102:103], v[204:205]
	v_lshlrev_b32_e32 v202, 16, v160
	v_and_b32_e32 v203, 0xffff0000, v160
	v_lshlrev_b32_e32 v204, 16, v161
	v_and_b32_e32 v205, 0xffff0000, v161
	v_pk_add_f32 v[96:97], v[96:97], v[202:203]
	v_pk_add_f32 v[98:99], v[98:99], v[204:205]
	v_cvt_pk_bf16_f32 v158, v100, v101
	v_cvt_pk_bf16_f32 v159, v102, v103
	v_cvt_pk_bf16_f32 v160, v96, v97
	v_cvt_pk_bf16_f32 v161, v98, v99
	v_pk_fma_f32 v[138:139], v[100:101], v[100:101], v[138:139]
	global_store_dwordx4 v207, v[158:161], s[10:11] offset:256
	v_pk_fma_f32 v[138:139], v[102:103], v[102:103], v[138:139]
	v_pk_fma_f32 v[138:139], v[96:97], v[96:97], v[138:139]
	v_pk_fma_f32 v[138:139], v[98:99], v[98:99], v[138:139]
	v_add_f32_e32 v214, v138, v139
	v_add_u32_e32 v207, 0x8000, v207
	v_mov_b32_e32 v215, v214
	s_nop 1
	v_permlane16_swap_b32_e32 v214, v215
	s_nop 0
	v_add_f32_e32 v214, v214, v215
	v_mov_b32_e32 v215, v214
	s_nop 1
	v_permlane32_swap_b32_e32 v214, v215
	s_nop 0
	v_add_f32_e32 v214, v214, v215
	s_and_saveexec_b64 s[28:29], s[4:5]
	global_store_dword v210, v214, s[16:17] offset:1024
	s_mov_b64 exec, s[28:29]
	s_waitcnt vmcnt(16)
	v_lshlrev_b32_e32 v202, 16, v162
	v_and_b32_e32 v203, 0xffff0000, v162
	v_lshlrev_b32_e32 v204, 16, v163
	v_and_b32_e32 v205, 0xffff0000, v163
	v_pk_add_f32 v[92:93], v[92:93], v[202:203]
	v_pk_add_f32 v[94:95], v[94:95], v[204:205]
	v_lshlrev_b32_e32 v202, 16, v164
	v_and_b32_e32 v203, 0xffff0000, v164
	v_lshlrev_b32_e32 v204, 16, v165
	v_and_b32_e32 v205, 0xffff0000, v165
	v_pk_add_f32 v[88:89], v[88:89], v[202:203]
	v_pk_add_f32 v[90:91], v[90:91], v[204:205]
	v_cvt_pk_bf16_f32 v162, v92, v93
	v_cvt_pk_bf16_f32 v163, v94, v95
	v_cvt_pk_bf16_f32 v164, v88, v89
	v_cvt_pk_bf16_f32 v165, v90, v91
	v_pk_mul_f32 v[138:139], v[92:93], v[92:93]
	global_store_dwordx4 v207, v[162:165], s[10:11]
	v_pk_fma_f32 v[138:139], v[94:95], v[94:95], v[138:139]
	v_pk_fma_f32 v[138:139], v[88:89], v[88:89], v[138:139]
	v_pk_fma_f32 v[138:139], v[90:91], v[90:91], v[138:139]
	v_lshlrev_b32_e32 v202, 16, v166
	v_and_b32_e32 v203, 0xffff0000, v166
	v_lshlrev_b32_e32 v204, 16, v167
	v_and_b32_e32 v205, 0xffff0000, v167
	v_pk_add_f32 v[84:85], v[84:85], v[202:203]
	v_pk_add_f32 v[86:87], v[86:87], v[204:205]
	v_lshlrev_b32_e32 v202, 16, v168
	v_and_b32_e32 v203, 0xffff0000, v168
	v_lshlrev_b32_e32 v204, 16, v169
	v_and_b32_e32 v205, 0xffff0000, v169
	v_pk_add_f32 v[80:81], v[80:81], v[202:203]
	v_pk_add_f32 v[82:83], v[82:83], v[204:205]
	v_cvt_pk_bf16_f32 v166, v84, v85
	v_cvt_pk_bf16_f32 v167, v86, v87
	v_cvt_pk_bf16_f32 v168, v80, v81
	v_cvt_pk_bf16_f32 v169, v82, v83
	v_pk_fma_f32 v[138:139], v[84:85], v[84:85], v[138:139]
	global_store_dwordx4 v207, v[166:169], s[10:11] offset:256
	v_pk_fma_f32 v[138:139], v[86:87], v[86:87], v[138:139]
	v_pk_fma_f32 v[138:139], v[80:81], v[80:81], v[138:139]
	v_pk_fma_f32 v[138:139], v[82:83], v[82:83], v[138:139]
	v_add_f32_e32 v214, v138, v139
	v_add_u32_e32 v207, 0x8000, v207
	v_mov_b32_e32 v215, v214
	s_nop 1
	v_permlane16_swap_b32_e32 v214, v215
	s_nop 0
	v_add_f32_e32 v214, v214, v215
	v_mov_b32_e32 v215, v214
	s_nop 1
	v_permlane32_swap_b32_e32 v214, v215
	s_nop 0
	v_add_f32_e32 v214, v214, v215
	s_and_saveexec_b64 s[28:29], s[4:5]
	global_store_dword v210, v214, s[16:17] offset:2048
	s_mov_b64 exec, s[28:29]
	s_waitcnt vmcnt(17)
	v_lshlrev_b32_e32 v202, 16, v170
	v_and_b32_e32 v203, 0xffff0000, v170
	v_lshlrev_b32_e32 v204, 16, v171
	v_and_b32_e32 v205, 0xffff0000, v171
	v_pk_add_f32 v[76:77], v[76:77], v[202:203]
	v_pk_add_f32 v[78:79], v[78:79], v[204:205]
	v_lshlrev_b32_e32 v202, 16, v172
	v_and_b32_e32 v203, 0xffff0000, v172
	v_lshlrev_b32_e32 v204, 16, v173
	v_and_b32_e32 v205, 0xffff0000, v173
	v_pk_add_f32 v[72:73], v[72:73], v[202:203]
	v_pk_add_f32 v[74:75], v[74:75], v[204:205]
	v_cvt_pk_bf16_f32 v170, v76, v77
	v_cvt_pk_bf16_f32 v171, v78, v79
	v_cvt_pk_bf16_f32 v172, v72, v73
	v_cvt_pk_bf16_f32 v173, v74, v75
	v_pk_mul_f32 v[138:139], v[76:77], v[76:77]
	global_store_dwordx4 v207, v[170:173], s[10:11]
	v_pk_fma_f32 v[138:139], v[78:79], v[78:79], v[138:139]
	v_pk_fma_f32 v[138:139], v[72:73], v[72:73], v[138:139]
	v_pk_fma_f32 v[138:139], v[74:75], v[74:75], v[138:139]
	v_lshlrev_b32_e32 v202, 16, v174
	v_and_b32_e32 v203, 0xffff0000, v174
	v_lshlrev_b32_e32 v204, 16, v175
	v_and_b32_e32 v205, 0xffff0000, v175
	v_pk_add_f32 v[68:69], v[68:69], v[202:203]
	v_pk_add_f32 v[70:71], v[70:71], v[204:205]
	v_lshlrev_b32_e32 v202, 16, v176
	v_and_b32_e32 v203, 0xffff0000, v176
	v_lshlrev_b32_e32 v204, 16, v177
	v_and_b32_e32 v205, 0xffff0000, v177
	v_pk_add_f32 v[64:65], v[64:65], v[202:203]
	v_pk_add_f32 v[66:67], v[66:67], v[204:205]
	v_cvt_pk_bf16_f32 v174, v68, v69
	v_cvt_pk_bf16_f32 v175, v70, v71
	v_cvt_pk_bf16_f32 v176, v64, v65
	v_cvt_pk_bf16_f32 v177, v66, v67
	v_pk_fma_f32 v[138:139], v[68:69], v[68:69], v[138:139]
	global_store_dwordx4 v207, v[174:177], s[10:11] offset:256
	v_pk_fma_f32 v[138:139], v[70:71], v[70:71], v[138:139]
	v_pk_fma_f32 v[138:139], v[64:65], v[64:65], v[138:139]
	v_pk_fma_f32 v[138:139], v[66:67], v[66:67], v[138:139]
	v_add_f32_e32 v214, v138, v139
	v_add_u32_e32 v207, 0x28000, v207
	v_mov_b32_e32 v215, v214
	s_nop 1
	v_permlane16_swap_b32_e32 v214, v215
	s_nop 0
	v_add_f32_e32 v214, v214, v215
	v_mov_b32_e32 v215, v214
	s_nop 1
	v_permlane32_swap_b32_e32 v214, v215
	s_nop 0
	v_add_f32_e32 v214, v214, v215
	s_and_saveexec_b64 s[28:29], s[4:5]
	global_store_dword v210, v214, s[16:17] offset:3072
	s_mov_b64 exec, s[28:29]
	v_add_u32_e32 v210, 0x2000, v210
	s_waitcnt vmcnt(18)
	v_lshlrev_b32_e32 v202, 16, v178
	v_and_b32_e32 v203, 0xffff0000, v178
	v_lshlrev_b32_e32 v204, 16, v179
	v_and_b32_e32 v205, 0xffff0000, v179
	v_pk_add_f32 v[60:61], v[60:61], v[202:203]
	v_pk_add_f32 v[62:63], v[62:63], v[204:205]
	v_lshlrev_b32_e32 v202, 16, v180
	v_and_b32_e32 v203, 0xffff0000, v180
	v_lshlrev_b32_e32 v204, 16, v181
	v_and_b32_e32 v205, 0xffff0000, v181
	v_pk_add_f32 v[56:57], v[56:57], v[202:203]
	v_pk_add_f32 v[58:59], v[58:59], v[204:205]
	v_cvt_pk_bf16_f32 v178, v60, v61
	v_cvt_pk_bf16_f32 v179, v62, v63
	v_cvt_pk_bf16_f32 v180, v56, v57
	v_cvt_pk_bf16_f32 v181, v58, v59
	v_pk_mul_f32 v[138:139], v[60:61], v[60:61]
	global_store_dwordx4 v207, v[178:181], s[10:11]
	v_pk_fma_f32 v[138:139], v[62:63], v[62:63], v[138:139]
	v_pk_fma_f32 v[138:139], v[56:57], v[56:57], v[138:139]
	v_pk_fma_f32 v[138:139], v[58:59], v[58:59], v[138:139]
	v_lshlrev_b32_e32 v202, 16, v182
	v_and_b32_e32 v203, 0xffff0000, v182
	v_lshlrev_b32_e32 v204, 16, v183
	v_and_b32_e32 v205, 0xffff0000, v183
	v_pk_add_f32 v[52:53], v[52:53], v[202:203]
	v_pk_add_f32 v[54:55], v[54:55], v[204:205]
	v_lshlrev_b32_e32 v202, 16, v184
	v_and_b32_e32 v203, 0xffff0000, v184
	v_lshlrev_b32_e32 v204, 16, v185
	v_and_b32_e32 v205, 0xffff0000, v185
	v_pk_add_f32 v[48:49], v[48:49], v[202:203]
	v_pk_add_f32 v[50:51], v[50:51], v[204:205]
	v_cvt_pk_bf16_f32 v182, v52, v53
	v_cvt_pk_bf16_f32 v183, v54, v55
	v_cvt_pk_bf16_f32 v184, v48, v49
	v_cvt_pk_bf16_f32 v185, v50, v51
	v_pk_fma_f32 v[138:139], v[52:53], v[52:53], v[138:139]
	global_store_dwordx4 v207, v[182:185], s[10:11] offset:256
	v_pk_fma_f32 v[138:139], v[54:55], v[54:55], v[138:139]
	v_pk_fma_f32 v[138:139], v[48:49], v[48:49], v[138:139]
	v_pk_fma_f32 v[138:139], v[50:51], v[50:51], v[138:139]
	v_add_f32_e32 v214, v138, v139
	v_add_u32_e32 v207, 0x8000, v207
	v_mov_b32_e32 v215, v214
	s_nop 1
	v_permlane16_swap_b32_e32 v214, v215
	s_nop 0
	v_add_f32_e32 v214, v214, v215
	v_mov_b32_e32 v215, v214
	s_nop 1
	v_permlane32_swap_b32_e32 v214, v215
	s_nop 0
	v_add_f32_e32 v214, v214, v215
	s_and_saveexec_b64 s[28:29], s[4:5]
	global_store_dword v210, v214, s[16:17]
	s_mov_b64 exec, s[28:29]
	s_waitcnt vmcnt(19)
	v_lshlrev_b32_e32 v202, 16, v186
	v_and_b32_e32 v203, 0xffff0000, v186
	v_lshlrev_b32_e32 v204, 16, v187
	v_and_b32_e32 v205, 0xffff0000, v187
	v_pk_add_f32 v[44:45], v[44:45], v[202:203]
	v_pk_add_f32 v[46:47], v[46:47], v[204:205]
	v_lshlrev_b32_e32 v202, 16, v188
	v_and_b32_e32 v203, 0xffff0000, v188
	v_lshlrev_b32_e32 v204, 16, v189
	v_and_b32_e32 v205, 0xffff0000, v189
	v_pk_add_f32 v[40:41], v[40:41], v[202:203]
	v_pk_add_f32 v[42:43], v[42:43], v[204:205]
	v_cvt_pk_bf16_f32 v186, v44, v45
	v_cvt_pk_bf16_f32 v187, v46, v47
	v_cvt_pk_bf16_f32 v188, v40, v41
	v_cvt_pk_bf16_f32 v189, v42, v43
	v_pk_mul_f32 v[138:139], v[44:45], v[44:45]
	global_store_dwordx4 v207, v[186:189], s[10:11]
	v_pk_fma_f32 v[138:139], v[46:47], v[46:47], v[138:139]
	v_pk_fma_f32 v[138:139], v[40:41], v[40:41], v[138:139]
	v_pk_fma_f32 v[138:139], v[42:43], v[42:43], v[138:139]
	v_lshlrev_b32_e32 v202, 16, v190
	v_and_b32_e32 v203, 0xffff0000, v190
	v_lshlrev_b32_e32 v204, 16, v191
	v_and_b32_e32 v205, 0xffff0000, v191
	v_pk_add_f32 v[36:37], v[36:37], v[202:203]
	v_pk_add_f32 v[38:39], v[38:39], v[204:205]
	v_lshlrev_b32_e32 v202, 16, v192
	v_and_b32_e32 v203, 0xffff0000, v192
	v_lshlrev_b32_e32 v204, 16, v193
	v_and_b32_e32 v205, 0xffff0000, v193
	v_pk_add_f32 v[32:33], v[32:33], v[202:203]
	v_pk_add_f32 v[34:35], v[34:35], v[204:205]
	v_cvt_pk_bf16_f32 v190, v36, v37
	v_cvt_pk_bf16_f32 v191, v38, v39
	v_cvt_pk_bf16_f32 v192, v32, v33
	v_cvt_pk_bf16_f32 v193, v34, v35
	v_pk_fma_f32 v[138:139], v[36:37], v[36:37], v[138:139]
	global_store_dwordx4 v207, v[190:193], s[10:11] offset:256
	v_pk_fma_f32 v[138:139], v[38:39], v[38:39], v[138:139]
	v_pk_fma_f32 v[138:139], v[32:33], v[32:33], v[138:139]
	v_pk_fma_f32 v[138:139], v[34:35], v[34:35], v[138:139]
	v_add_f32_e32 v214, v138, v139
	v_add_u32_e32 v207, 0x8000, v207
	v_mov_b32_e32 v215, v214
	s_nop 1
	v_permlane16_swap_b32_e32 v214, v215
	s_nop 0
	v_add_f32_e32 v214, v214, v215
	v_mov_b32_e32 v215, v214
	s_nop 1
	v_permlane32_swap_b32_e32 v214, v215
	s_nop 0
	v_add_f32_e32 v214, v214, v215
	s_and_saveexec_b64 s[28:29], s[4:5]
	global_store_dword v210, v214, s[16:17] offset:1024
	s_mov_b64 exec, s[28:29]
	s_waitcnt vmcnt(20)
	v_lshlrev_b32_e32 v202, 16, v194
	v_and_b32_e32 v203, 0xffff0000, v194
	v_lshlrev_b32_e32 v204, 16, v195
	v_and_b32_e32 v205, 0xffff0000, v195
	v_pk_add_f32 v[28:29], v[28:29], v[202:203]
	v_pk_add_f32 v[30:31], v[30:31], v[204:205]
	v_lshlrev_b32_e32 v202, 16, v196
	v_and_b32_e32 v203, 0xffff0000, v196
	v_lshlrev_b32_e32 v204, 16, v197
	v_and_b32_e32 v205, 0xffff0000, v197
	v_pk_add_f32 v[24:25], v[24:25], v[202:203]
	v_pk_add_f32 v[26:27], v[26:27], v[204:205]
	v_cvt_pk_bf16_f32 v194, v28, v29
	v_cvt_pk_bf16_f32 v195, v30, v31
	v_cvt_pk_bf16_f32 v196, v24, v25
	v_cvt_pk_bf16_f32 v197, v26, v27
	v_pk_mul_f32 v[138:139], v[28:29], v[28:29]
	global_store_dwordx4 v207, v[194:197], s[10:11]
	v_pk_fma_f32 v[138:139], v[30:31], v[30:31], v[138:139]
	v_pk_fma_f32 v[138:139], v[24:25], v[24:25], v[138:139]
	v_pk_fma_f32 v[138:139], v[26:27], v[26:27], v[138:139]
	v_lshlrev_b32_e32 v202, 16, v198
	v_and_b32_e32 v203, 0xffff0000, v198
	v_lshlrev_b32_e32 v204, 16, v199
	v_and_b32_e32 v205, 0xffff0000, v199
	v_pk_add_f32 v[20:21], v[20:21], v[202:203]
	v_pk_add_f32 v[22:23], v[22:23], v[204:205]
	v_lshlrev_b32_e32 v202, 16, v200
	v_and_b32_e32 v203, 0xffff0000, v200
	v_lshlrev_b32_e32 v204, 16, v201
	v_and_b32_e32 v205, 0xffff0000, v201
	v_pk_add_f32 v[16:17], v[16:17], v[202:203]
	v_pk_add_f32 v[18:19], v[18:19], v[204:205]
	v_cvt_pk_bf16_f32 v198, v20, v21
	v_cvt_pk_bf16_f32 v199, v22, v23
	v_cvt_pk_bf16_f32 v200, v16, v17
	v_cvt_pk_bf16_f32 v201, v18, v19
	v_pk_fma_f32 v[138:139], v[20:21], v[20:21], v[138:139]
	global_store_dwordx4 v207, v[198:201], s[10:11] offset:256
	v_pk_fma_f32 v[138:139], v[22:23], v[22:23], v[138:139]
	v_pk_fma_f32 v[138:139], v[16:17], v[16:17], v[138:139]
	v_pk_fma_f32 v[138:139], v[18:19], v[18:19], v[138:139]
	v_add_f32_e32 v214, v138, v139
	v_add_u32_e32 v207, 0x8000, v207
	v_mov_b32_e32 v215, v214
	s_nop 1
	v_permlane16_swap_b32_e32 v214, v215
	s_nop 0
	v_add_f32_e32 v214, v214, v215
	v_mov_b32_e32 v215, v214
	s_nop 1
	v_permlane32_swap_b32_e32 v214, v215
	s_nop 0
	v_add_f32_e32 v214, v214, v215
	s_and_saveexec_b64 s[28:29], s[4:5]
	global_store_dword v210, v214, s[16:17] offset:2048
	s_mov_b64 exec, s[28:29]
	s_waitcnt vmcnt(18)
	v_lshlrev_b32_e32 v202, 16, v146
	v_and_b32_e32 v203, 0xffff0000, v146
	v_lshlrev_b32_e32 v204, 16, v147
	v_and_b32_e32 v205, 0xffff0000, v147
	v_pk_add_f32 v[12:13], v[12:13], v[202:203]
	v_pk_add_f32 v[14:15], v[14:15], v[204:205]
	v_lshlrev_b32_e32 v202, 16, v148
	v_and_b32_e32 v203, 0xffff0000, v148
	v_lshlrev_b32_e32 v204, 16, v149
	v_and_b32_e32 v205, 0xffff0000, v149
	v_pk_add_f32 v[8:9], v[8:9], v[202:203]
	v_pk_add_f32 v[10:11], v[10:11], v[204:205]
	v_cvt_pk_bf16_f32 v146, v12, v13
	v_cvt_pk_bf16_f32 v147, v14, v15
	v_cvt_pk_bf16_f32 v148, v8, v9
	v_cvt_pk_bf16_f32 v149, v10, v11
	v_pk_mul_f32 v[138:139], v[12:13], v[12:13]
	global_store_dwordx4 v207, v[146:149], s[10:11]
	v_pk_fma_f32 v[138:139], v[14:15], v[14:15], v[138:139]
	v_pk_fma_f32 v[138:139], v[8:9], v[8:9], v[138:139]
	v_pk_fma_f32 v[138:139], v[10:11], v[10:11], v[138:139]
	v_lshlrev_b32_e32 v202, 16, v150
	v_and_b32_e32 v203, 0xffff0000, v150
	v_lshlrev_b32_e32 v204, 16, v151
	v_and_b32_e32 v205, 0xffff0000, v151
	v_pk_add_f32 v[4:5], v[4:5], v[202:203]
	v_pk_add_f32 v[6:7], v[6:7], v[204:205]
	v_lshlrev_b32_e32 v202, 16, v152
	v_and_b32_e32 v203, 0xffff0000, v152
	v_lshlrev_b32_e32 v204, 16, v153
	v_and_b32_e32 v205, 0xffff0000, v153
	v_pk_add_f32 v[0:1], v[0:1], v[202:203]
	v_pk_add_f32 v[2:3], v[2:3], v[204:205]
	v_cvt_pk_bf16_f32 v150, v4, v5
	v_cvt_pk_bf16_f32 v151, v6, v7
	v_cvt_pk_bf16_f32 v152, v0, v1
	v_cvt_pk_bf16_f32 v153, v2, v3
	v_pk_fma_f32 v[138:139], v[4:5], v[4:5], v[138:139]
	global_store_dwordx4 v207, v[150:153], s[10:11] offset:256
	v_pk_fma_f32 v[138:139], v[6:7], v[6:7], v[138:139]
	v_pk_fma_f32 v[138:139], v[0:1], v[0:1], v[138:139]
	v_pk_fma_f32 v[138:139], v[2:3], v[2:3], v[138:139]
	v_add_f32_e32 v214, v138, v139
	v_add_u32_e32 v207, 0x8000, v207
	v_mov_b32_e32 v215, v214
	s_nop 1
	v_permlane16_swap_b32_e32 v214, v215
	s_nop 0
	v_add_f32_e32 v214, v214, v215
	v_mov_b32_e32 v215, v214
	s_nop 1
	v_permlane32_swap_b32_e32 v214, v215
	s_nop 0
	v_add_f32_e32 v214, v214, v215
	s_and_saveexec_b64 s[28:29], s[4:5]
	global_store_dword v210, v214, s[16:17] offset:3072
	s_mov_b64 exec, s[28:29]
	s_branch .LBB0_768

.LBB0_823:
	s_add_u32 s26, s24, 0xfffc0080
	s_addc_u32 s27, s25, -1
	s_add_i32 s65, 0, 0x10000
	v_add_u32_e32 v154, s65, v143
	ds_read_b128 v[138:141], v154
	ds_read_b128 v[146:149], v154 offset:1024
	ds_read_b128 v[150:153], v154 offset:2048
	ds_read_b128 v[154:157], v154 offset:3072
	s_cmp_eq_u32 s51, 12
	s_cselect_b32 s29, s19, s27
	s_cselect_b32 s28, s38, s26
	s_cselect_b32 s27, s17, s50
	s_cselect_b32 s26, s39, s46
	s_add_i32 m0, s58, 0xc000
	ds_read_b128 v[158:161], v145
	ds_read_b128 v[162:165], v145 offset:1024
	ds_read_b128 v[166:169], v145 offset:2048
	ds_read_b128 v[170:173], v145 offset:3072
	ds_read_b128 v[174:177], v145 offset:4096
	ds_read_b128 v[178:181], v145 offset:5120
	ds_read_b128 v[182:185], v145 offset:6144
	ds_read_b128 v[186:189], v145 offset:7168
	global_load_lds_dwordx4 v134, s[24:25]
	s_add_i32 m0, s58, 0xe000
	s_nop 0
	global_load_lds_dwordx4 v136, s[24:25]
	s_waitcnt lgkmcnt(8)
	s_barrier
	s_waitcnt lgkmcnt(0)
	s_setprio 1
	v_mfma_f32_16x16x32_bf16 v[124:127], v[138:141], v[158:161], v[124:127]
	v_mfma_f32_16x16x32_bf16 v[120:123], v[150:153], v[158:161], v[120:123]
	v_mfma_f32_16x16x32_bf16 v[108:111], v[138:141], v[166:169], v[108:111]
	v_mfma_f32_16x16x32_bf16 v[104:107], v[150:153], v[166:169], v[104:107]
	v_mfma_f32_16x16x32_bf16 v[92:95], v[138:141], v[174:177], v[92:95]
	v_mfma_f32_16x16x32_bf16 v[88:91], v[150:153], v[174:177], v[88:91]
	v_mfma_f32_16x16x32_bf16 v[76:79], v[138:141], v[182:185], v[76:79]
	v_mfma_f32_16x16x32_bf16 v[72:75], v[150:153], v[182:185], v[72:75]
	v_mfma_f32_16x16x32_bf16 v[124:127], v[146:149], v[162:165], v[124:127]
	v_mfma_f32_16x16x32_bf16 v[120:123], v[154:157], v[162:165], v[120:123]
	v_mfma_f32_16x16x32_bf16 v[108:111], v[146:149], v[170:173], v[108:111]
	v_mfma_f32_16x16x32_bf16 v[104:107], v[154:157], v[170:173], v[104:107]
	v_mfma_f32_16x16x32_bf16 v[92:95], v[146:149], v[178:181], v[92:95]
	v_mfma_f32_16x16x32_bf16 v[88:91], v[154:157], v[178:181], v[88:91]
	v_mfma_f32_16x16x32_bf16 v[76:79], v[146:149], v[186:189], v[76:79]
	v_mfma_f32_16x16x32_bf16 v[72:75], v[154:157], v[186:189], v[72:75]
	s_setprio 0
	s_barrier
	s_add_i32 s68, 0, 0x14000
	s_add_i32 s65, s65, s57
	v_add_u32_e32 v202, s68, v143
	s_add_u32 s98, s26, s40
	s_addc_u32 s99, s27, s41
	s_mov_b32 m0, s65
	ds_read_b128 v[190:193], v202
	ds_read_b128 v[194:197], v202 offset:1024
	ds_read_b128 v[198:201], v202 offset:2048
	ds_read_b128 v[202:205], v202 offset:3072
	global_load_lds_dwordx4 v208, s[26:27]
	s_add_i32 m0, s65, 0x2000
	s_nop 0
	global_load_lds_dwordx4 v128, s[26:27]
	s_barrier
	s_waitcnt lgkmcnt(0)
	s_setprio 1
	v_mfma_f32_16x16x32_bf16 v[116:119], v[190:193], v[158:161], v[116:119]
	v_mfma_f32_16x16x32_bf16 v[112:115], v[198:201], v[158:161], v[112:115]
	v_mfma_f32_16x16x32_bf16 v[100:103], v[190:193], v[166:169], v[100:103]
	v_mfma_f32_16x16x32_bf16 v[96:99], v[198:201], v[166:169], v[96:99]
	v_mfma_f32_16x16x32_bf16 v[84:87], v[190:193], v[174:177], v[84:87]
	v_mfma_f32_16x16x32_bf16 v[80:83], v[198:201], v[174:177], v[80:83]
	v_mfma_f32_16x16x32_bf16 v[68:71], v[190:193], v[182:185], v[68:71]
	v_mfma_f32_16x16x32_bf16 v[64:67], v[198:201], v[182:185], v[64:67]
	v_mfma_f32_16x16x32_bf16 v[116:119], v[194:197], v[162:165], v[116:119]
	v_mfma_f32_16x16x32_bf16 v[112:115], v[202:205], v[162:165], v[112:115]
	v_mfma_f32_16x16x32_bf16 v[100:103], v[194:197], v[170:173], v[100:103]
	v_mfma_f32_16x16x32_bf16 v[96:99], v[202:205], v[170:173], v[96:99]
	v_mfma_f32_16x16x32_bf16 v[84:87], v[194:197], v[178:181], v[84:87]
	v_mfma_f32_16x16x32_bf16 v[80:83], v[202:205], v[178:181], v[80:83]
	v_mfma_f32_16x16x32_bf16 v[68:71], v[194:197], v[186:189], v[68:71]
	v_mfma_f32_16x16x32_bf16 v[64:67], v[202:205], v[186:189], v[64:67]
	s_setprio 0
	s_mov_b32 m0, s58
	s_add_u32 s100, s28, s40
	s_addc_u32 s101, s29, s41
	s_barrier
	ds_read_b128 v[158:161], v145 offset:16384
	ds_read_b128 v[162:165], v145 offset:17408
	ds_read_b128 v[166:169], v145 offset:18432
	ds_read_b128 v[170:173], v145 offset:19456
	ds_read_b128 v[174:177], v145 offset:20480
	ds_read_b128 v[178:181], v145 offset:21504
	ds_read_b128 v[182:185], v145 offset:22528
	ds_read_b128 v[186:189], v145 offset:23552
	global_load_lds_dwordx4 v132, s[28:29]
	s_mov_b32 m0, s59
	s_nop 0
	global_load_lds_dwordx4 v130, s[28:29]
	s_barrier
	s_waitcnt lgkmcnt(0)
	s_setprio 1
	v_mfma_f32_16x16x32_bf16 v[60:63], v[138:141], v[158:161], v[60:63]
	v_mfma_f32_16x16x32_bf16 v[56:59], v[150:153], v[158:161], v[56:59]
	v_mfma_f32_16x16x32_bf16 v[44:47], v[138:141], v[166:169], v[44:47]
	v_mfma_f32_16x16x32_bf16 v[40:43], v[150:153], v[166:169], v[40:43]
	v_mfma_f32_16x16x32_bf16 v[28:31], v[138:141], v[174:177], v[28:31]
	v_mfma_f32_16x16x32_bf16 v[24:27], v[150:153], v[174:177], v[24:27]
	v_mfma_f32_16x16x32_bf16 v[12:15], v[138:141], v[182:185], v[12:15]
	v_mfma_f32_16x16x32_bf16 v[8:11], v[150:153], v[182:185], v[8:11]
	v_mfma_f32_16x16x32_bf16 v[60:63], v[146:149], v[162:165], v[60:63]
	v_mfma_f32_16x16x32_bf16 v[56:59], v[154:157], v[162:165], v[56:59]
	v_mfma_f32_16x16x32_bf16 v[44:47], v[146:149], v[170:173], v[44:47]
	v_mfma_f32_16x16x32_bf16 v[40:43], v[154:157], v[170:173], v[40:43]
	v_mfma_f32_16x16x32_bf16 v[28:31], v[146:149], v[178:181], v[28:31]
	v_mfma_f32_16x16x32_bf16 v[24:27], v[154:157], v[178:181], v[24:27]
	v_mfma_f32_16x16x32_bf16 v[12:15], v[146:149], v[186:189], v[12:15]
	v_mfma_f32_16x16x32_bf16 v[8:11], v[154:157], v[186:189], v[8:11]
	s_setprio 0
	s_barrier
	s_add_u32 s66, s26, 0x40000
	s_addc_u32 s67, s27, 0
	s_add_i32 s65, s68, s57
	s_mov_b32 m0, s65
	s_nop 0
	global_load_lds_dwordx4 v208, s[66:67]
	s_add_i32 m0, s65, 0x2000
	s_nop 0
	global_load_lds_dwordx4 v128, s[66:67]
	s_waitcnt vmcnt(6)
	s_barrier
	s_setprio 1
	v_mfma_f32_16x16x32_bf16 v[52:55], v[190:193], v[158:161], v[52:55]
	v_mfma_f32_16x16x32_bf16 v[48:51], v[198:201], v[158:161], v[48:51]
	v_mfma_f32_16x16x32_bf16 v[36:39], v[190:193], v[166:169], v[36:39]
	v_mfma_f32_16x16x32_bf16 v[32:35], v[198:201], v[166:169], v[32:35]
	v_mfma_f32_16x16x32_bf16 v[20:23], v[190:193], v[174:177], v[20:23]
	v_mfma_f32_16x16x32_bf16 v[16:19], v[198:201], v[174:177], v[16:19]
	v_mfma_f32_16x16x32_bf16 v[4:7], v[190:193], v[182:185], v[4:7]
	v_mfma_f32_16x16x32_bf16 v[0:3], v[198:201], v[182:185], v[0:3]
	v_mfma_f32_16x16x32_bf16 v[52:55], v[194:197], v[162:165], v[52:55]
	v_mfma_f32_16x16x32_bf16 v[48:51], v[202:205], v[162:165], v[48:51]
	v_mfma_f32_16x16x32_bf16 v[36:39], v[194:197], v[170:173], v[36:39]
	v_mfma_f32_16x16x32_bf16 v[32:35], v[202:205], v[170:173], v[32:35]
	v_mfma_f32_16x16x32_bf16 v[20:23], v[194:197], v[178:181], v[20:23]
	v_mfma_f32_16x16x32_bf16 v[16:19], v[202:205], v[178:181], v[16:19]
	v_mfma_f32_16x16x32_bf16 v[4:7], v[194:197], v[186:189], v[4:7]
	v_mfma_f32_16x16x32_bf16 v[0:3], v[202:205], v[186:189], v[0:3]
	s_setprio 0
	s_add_i32 s65, 0, 0x18000
	v_add_u32_e32 v154, s65, v143
	s_barrier
	ds_read_b128 v[138:141], v154
	ds_read_b128 v[146:149], v154 offset:1024
	ds_read_b128 v[150:153], v154 offset:2048
	ds_read_b128 v[154:157], v154 offset:3072
	s_add_u32 s28, s28, 0x40000
	s_addc_u32 s29, s29, 0
	s_mov_b32 m0, s60
	ds_read_b128 v[158:161], v145 offset:32768
	ds_read_b128 v[162:165], v145 offset:33792
	ds_read_b128 v[166:169], v145 offset:34816
	ds_read_b128 v[170:173], v145 offset:35840
	ds_read_b128 v[174:177], v145 offset:36864
	ds_read_b128 v[178:181], v145 offset:37888
	ds_read_b128 v[182:185], v145 offset:38912
	ds_read_b128 v[186:189], v145 offset:39936
	global_load_lds_dwordx4 v132, s[28:29]
	s_mov_b32 m0, s61
	s_nop 0
	global_load_lds_dwordx4 v130, s[28:29]
	s_waitcnt lgkmcnt(8)
	s_barrier
	s_waitcnt lgkmcnt(0)
	s_setprio 1
	v_mfma_f32_16x16x32_bf16 v[124:127], v[138:141], v[158:161], v[124:127]
	v_mfma_f32_16x16x32_bf16 v[120:123], v[150:153], v[158:161], v[120:123]
	v_mfma_f32_16x16x32_bf16 v[108:111], v[138:141], v[166:169], v[108:111]
	v_mfma_f32_16x16x32_bf16 v[104:107], v[150:153], v[166:169], v[104:107]
	v_mfma_f32_16x16x32_bf16 v[92:95], v[138:141], v[174:177], v[92:95]
	v_mfma_f32_16x16x32_bf16 v[88:91], v[150:153], v[174:177], v[88:91]
	v_mfma_f32_16x16x32_bf16 v[76:79], v[138:141], v[182:185], v[76:79]
	v_mfma_f32_16x16x32_bf16 v[72:75], v[150:153], v[182:185], v[72:75]
	v_mfma_f32_16x16x32_bf16 v[124:127], v[146:149], v[162:165], v[124:127]
	v_mfma_f32_16x16x32_bf16 v[120:123], v[154:157], v[162:165], v[120:123]
	v_mfma_f32_16x16x32_bf16 v[108:111], v[146:149], v[170:173], v[108:111]
	v_mfma_f32_16x16x32_bf16 v[104:107], v[154:157], v[170:173], v[104:107]
	v_mfma_f32_16x16x32_bf16 v[92:95], v[146:149], v[178:181], v[92:95]
	v_mfma_f32_16x16x32_bf16 v[88:91], v[154:157], v[178:181], v[88:91]
	v_mfma_f32_16x16x32_bf16 v[76:79], v[146:149], v[186:189], v[76:79]
	v_mfma_f32_16x16x32_bf16 v[72:75], v[154:157], v[186:189], v[72:75]
	s_setprio 0
	s_barrier
	s_add_i32 s28, 0, 0x1c000
	s_add_i32 s29, s65, s57
	v_add_u32_e32 v202, s28, v143
	s_mov_b32 m0, s29
	ds_read_b128 v[190:193], v202
	ds_read_b128 v[194:197], v202 offset:1024
	ds_read_b128 v[198:201], v202 offset:2048
	ds_read_b128 v[202:205], v202 offset:3072
	global_load_lds_dwordx4 v208, s[98:99]
	s_add_i32 m0, s29, 0x2000
	s_nop 0
	global_load_lds_dwordx4 v128, s[98:99]
	s_barrier
	s_waitcnt lgkmcnt(0)
	s_setprio 1
	v_mfma_f32_16x16x32_bf16 v[116:119], v[190:193], v[158:161], v[116:119]
	v_mfma_f32_16x16x32_bf16 v[112:115], v[198:201], v[158:161], v[112:115]
	v_mfma_f32_16x16x32_bf16 v[100:103], v[190:193], v[166:169], v[100:103]
	v_mfma_f32_16x16x32_bf16 v[96:99], v[198:201], v[166:169], v[96:99]
	v_mfma_f32_16x16x32_bf16 v[84:87], v[190:193], v[174:177], v[84:87]
	v_mfma_f32_16x16x32_bf16 v[80:83], v[198:201], v[174:177], v[80:83]
	v_mfma_f32_16x16x32_bf16 v[68:71], v[190:193], v[182:185], v[68:71]
	v_mfma_f32_16x16x32_bf16 v[64:67], v[198:201], v[182:185], v[64:67]
	v_mfma_f32_16x16x32_bf16 v[116:119], v[194:197], v[162:165], v[116:119]
	v_mfma_f32_16x16x32_bf16 v[112:115], v[202:205], v[162:165], v[112:115]
	v_mfma_f32_16x16x32_bf16 v[100:103], v[194:197], v[170:173], v[100:103]
	v_mfma_f32_16x16x32_bf16 v[96:99], v[202:205], v[170:173], v[96:99]
	v_mfma_f32_16x16x32_bf16 v[84:87], v[194:197], v[178:181], v[84:87]
	v_mfma_f32_16x16x32_bf16 v[80:83], v[202:205], v[178:181], v[80:83]
	v_mfma_f32_16x16x32_bf16 v[68:71], v[194:197], v[186:189], v[68:71]
	v_mfma_f32_16x16x32_bf16 v[64:67], v[202:205], v[186:189], v[64:67]
	s_setprio 0
	s_mov_b32 m0, s62
	s_barrier
	ds_read_b128 v[158:161], v145 offset:49152
	ds_read_b128 v[162:165], v145 offset:50176
	ds_read_b128 v[166:169], v145 offset:51200
	ds_read_b128 v[170:173], v145 offset:52224
	ds_read_b128 v[174:177], v145 offset:53248
	ds_read_b128 v[178:181], v145 offset:54272
	ds_read_b128 v[182:185], v145 offset:55296
	ds_read_b128 v[186:189], v145 offset:56320
	global_load_lds_dwordx4 v132, s[100:101]
	s_mov_b32 m0, s63
	s_nop 0
	global_load_lds_dwordx4 v130, s[100:101]
	s_barrier
	s_waitcnt lgkmcnt(0)
	s_setprio 1
	v_mfma_f32_16x16x32_bf16 v[60:63], v[138:141], v[158:161], v[60:63]
	v_mfma_f32_16x16x32_bf16 v[56:59], v[150:153], v[158:161], v[56:59]
	v_mfma_f32_16x16x32_bf16 v[44:47], v[138:141], v[166:169], v[44:47]
	v_mfma_f32_16x16x32_bf16 v[40:43], v[150:153], v[166:169], v[40:43]
	v_mfma_f32_16x16x32_bf16 v[28:31], v[138:141], v[174:177], v[28:31]
	v_mfma_f32_16x16x32_bf16 v[24:27], v[150:153], v[174:177], v[24:27]
	v_mfma_f32_16x16x32_bf16 v[12:15], v[138:141], v[182:185], v[12:15]
	v_mfma_f32_16x16x32_bf16 v[8:11], v[150:153], v[182:185], v[8:11]
	v_mfma_f32_16x16x32_bf16 v[60:63], v[146:149], v[162:165], v[60:63]
	v_mfma_f32_16x16x32_bf16 v[56:59], v[154:157], v[162:165], v[56:59]
	v_mfma_f32_16x16x32_bf16 v[44:47], v[146:149], v[170:173], v[44:47]
	v_mfma_f32_16x16x32_bf16 v[40:43], v[154:157], v[170:173], v[40:43]
	v_mfma_f32_16x16x32_bf16 v[28:31], v[146:149], v[178:181], v[28:31]
	v_mfma_f32_16x16x32_bf16 v[24:27], v[154:157], v[178:181], v[24:27]
	v_mfma_f32_16x16x32_bf16 v[12:15], v[146:149], v[186:189], v[12:15]
	v_mfma_f32_16x16x32_bf16 v[8:11], v[154:157], v[186:189], v[8:11]
	s_setprio 0
	s_barrier
	s_add_u32 s26, s26, 0x40080
	s_addc_u32 s27, s27, 0
	s_add_i32 s28, s28, s57
	s_mov_b32 m0, s28
	s_nop 0
	global_load_lds_dwordx4 v208, s[26:27]
	s_add_i32 m0, s28, 0x2000
	s_nop 0
	global_load_lds_dwordx4 v128, s[26:27]
	s_waitcnt vmcnt(6)
	s_barrier
	s_setprio 1
	v_mfma_f32_16x16x32_bf16 v[52:55], v[190:193], v[158:161], v[52:55]
	v_mfma_f32_16x16x32_bf16 v[48:51], v[198:201], v[158:161], v[48:51]
	v_mfma_f32_16x16x32_bf16 v[36:39], v[190:193], v[166:169], v[36:39]
	v_mfma_f32_16x16x32_bf16 v[32:35], v[198:201], v[166:169], v[32:35]
	v_mfma_f32_16x16x32_bf16 v[20:23], v[190:193], v[174:177], v[20:23]
	v_mfma_f32_16x16x32_bf16 v[16:19], v[198:201], v[174:177], v[16:19]
	v_mfma_f32_16x16x32_bf16 v[4:7], v[190:193], v[182:185], v[4:7]
	v_mfma_f32_16x16x32_bf16 v[0:3], v[198:201], v[182:185], v[0:3]
	v_mfma_f32_16x16x32_bf16 v[52:55], v[194:197], v[162:165], v[52:55]
	v_mfma_f32_16x16x32_bf16 v[48:51], v[202:205], v[162:165], v[48:51]
	v_mfma_f32_16x16x32_bf16 v[36:39], v[194:197], v[170:173], v[36:39]
	v_mfma_f32_16x16x32_bf16 v[32:35], v[202:205], v[170:173], v[32:35]
	v_mfma_f32_16x16x32_bf16 v[20:23], v[194:197], v[178:181], v[20:23]
	v_mfma_f32_16x16x32_bf16 v[16:19], v[202:205], v[178:181], v[16:19]
	v_mfma_f32_16x16x32_bf16 v[4:7], v[194:197], v[186:189], v[4:7]
	v_mfma_f32_16x16x32_bf16 v[0:3], v[202:205], v[186:189], v[0:3]
	s_setprio 0
	s_add_i32 s51, s51, 2
	s_add_u32 s24, s24, 0x100
	s_addc_u32 s25, s25, 0
	s_add_u32 s46, s46, 0x100
	s_addc_u32 s50, s50, 0
	s_cmp_gt_u32 s51, 13
	s_barrier
	s_cbranch_scc0 .LBB0_823
	v_lshl_add_u32 v140, s35, 8, v142
	v_lshl_or_b32 v141, s34, 8, v144
	s_mov_b32 s34, s16
	s_mov_b32 s35, s18
	s_mov_b64 s[26:27], s[22:23]
	s_mov_b64 s[24:25], s[20:21]
	v_mbcnt_lo_u32_b32 v206, -1, 0
	v_mbcnt_hi_u32_b32 v206, -1, v206
	v_and_b32_e32 v206, 48, v206
	v_lshl_add_u32 v206, v140, 6, v206
	v_lshlrev_b32_e32 v207, 11, v140
	v_lshl_add_u32 v207, v141, 1, v207
	global_load_dwordx4 v[146:149], v206, s[14:15]
	global_load_dwordx4 v[150:153], v206, s[14:15] offset:1024
	global_load_dwordx4 v[154:157], v206, s[14:15] offset:2048
	global_load_dwordx4 v[158:161], v206, s[14:15] offset:3072
	v_add_u32_e32 v206, 0x2000, v206
	global_load_dwordx4 v[162:165], v206, s[14:15]
	global_load_dwordx4 v[166:169], v206, s[14:15] offset:1024
	global_load_dwordx4 v[170:173], v206, s[14:15] offset:2048
	global_load_dwordx4 v[174:177], v206, s[14:15] offset:3072
	s_waitcnt vmcnt(7)
	v_pk_add_f32 v[146:147], v[146:147], v[148:149]
	s_nop 0
	v_add_f32_e32 v214, v146, v147
	v_mov_b32_e32 v215, v214
	s_nop 1
	v_permlane16_swap_b32_e32 v214, v215
	s_nop 0
	v_add_f32_e32 v214, v214, v215
	v_mov_b32_e32 v215, v214
	s_nop 1
	v_permlane32_swap_b32_e32 v214, v215
	s_nop 0
	v_add_f32_e32 v214, v214, v215
	v_fmamk_f32 v214, v214, 0x3a800000, v248
	v_rsq_f32_e32 v178, v214
	s_nop 0
	v_pk_mul_f32 v[124:125], v[124:125], v[178:179] op_sel_hi:[1,0]
	v_pk_mul_f32 v[126:127], v[126:127], v[178:179] op_sel_hi:[1,0]
	v_pk_mul_f32 v[120:121], v[120:121], v[178:179] op_sel_hi:[1,0]
	v_pk_mul_f32 v[122:123], v[122:123], v[178:179] op_sel_hi:[1,0]
	v_cvt_pk_bf16_f32 v198, v124, v125
	v_cvt_pk_bf16_f32 v199, v126, v127
	v_cvt_pk_bf16_f32 v200, v120, v121
	v_cvt_pk_bf16_f32 v201, v122, v123
	global_store_dwordx4 v207, v[198:201], s[10:11]
	v_pk_mul_f32 v[116:117], v[116:117], v[178:179] op_sel_hi:[1,0]
	v_pk_mul_f32 v[118:119], v[118:119], v[178:179] op_sel_hi:[1,0]
	v_pk_mul_f32 v[112:113], v[112:113], v[178:179] op_sel_hi:[1,0]
	v_pk_mul_f32 v[114:115], v[114:115], v[178:179] op_sel_hi:[1,0]
	v_cvt_pk_bf16_f32 v202, v116, v117
	v_cvt_pk_bf16_f32 v203, v118, v119
	v_cvt_pk_bf16_f32 v204, v112, v113
	v_cvt_pk_bf16_f32 v205, v114, v115
	global_store_dwordx4 v207, v[202:205], s[10:11] offset:256
	v_add_u32_e32 v207, 0x8000, v207
	s_waitcnt vmcnt(8)
	v_pk_add_f32 v[150:151], v[150:151], v[152:153]
	s_nop 0
	v_add_f32_e32 v214, v150, v151
	v_mov_b32_e32 v215, v214
	s_nop 1
	v_permlane16_swap_b32_e32 v214, v215
	s_nop 0
	v_add_f32_e32 v214, v214, v215
	v_mov_b32_e32 v215, v214
	s_nop 1
	v_permlane32_swap_b32_e32 v214, v215
	s_nop 0
	v_add_f32_e32 v214, v214, v215
	v_fmamk_f32 v214, v214, 0x3a800000, v248
	v_rsq_f32_e32 v180, v214
	s_nop 0
	v_pk_mul_f32 v[108:109], v[108:109], v[180:181] op_sel_hi:[1,0]
	v_pk_mul_f32 v[110:111], v[110:111], v[180:181] op_sel_hi:[1,0]
	v_pk_mul_f32 v[104:105], v[104:105], v[180:181] op_sel_hi:[1,0]
	v_pk_mul_f32 v[106:107], v[106:107], v[180:181] op_sel_hi:[1,0]
	v_cvt_pk_bf16_f32 v198, v108, v109
	v_cvt_pk_bf16_f32 v199, v110, v111
	v_cvt_pk_bf16_f32 v200, v104, v105
	v_cvt_pk_bf16_f32 v201, v106, v107
	global_store_dwordx4 v207, v[198:201], s[10:11]
	v_pk_mul_f32 v[100:101], v[100:101], v[180:181] op_sel_hi:[1,0]
	v_pk_mul_f32 v[102:103], v[102:103], v[180:181] op_sel_hi:[1,0]
	v_pk_mul_f32 v[96:97], v[96:97], v[180:181] op_sel_hi:[1,0]
	v_pk_mul_f32 v[98:99], v[98:99], v[180:181] op_sel_hi:[1,0]
	v_cvt_pk_bf16_f32 v202, v100, v101
	v_cvt_pk_bf16_f32 v203, v102, v103
	v_cvt_pk_bf16_f32 v204, v96, v97
	v_cvt_pk_bf16_f32 v205, v98, v99
	global_store_dwordx4 v207, v[202:205], s[10:11] offset:256
	v_add_u32_e32 v207, 0x8000, v207
	s_waitcnt vmcnt(9)
	v_pk_add_f32 v[154:155], v[154:155], v[156:157]
	s_nop 0
	v_add_f32_e32 v214, v154, v155
	v_mov_b32_e32 v215, v214
	s_nop 1
	v_permlane16_swap_b32_e32 v214, v215
	s_nop 0
	v_add_f32_e32 v214, v214, v215
	v_mov_b32_e32 v215, v214
	s_nop 1
	v_permlane32_swap_b32_e32 v214, v215
	s_nop 0
	v_add_f32_e32 v214, v214, v215
	v_fmamk_f32 v214, v214, 0x3a800000, v248
	v_rsq_f32_e32 v182, v214
	s_nop 0
	v_pk_mul_f32 v[92:93], v[92:93], v[182:183] op_sel_hi:[1,0]
	v_pk_mul_f32 v[94:95], v[94:95], v[182:183] op_sel_hi:[1,0]
	v_pk_mul_f32 v[88:89], v[88:89], v[182:183] op_sel_hi:[1,0]
	v_pk_mul_f32 v[90:91], v[90:91], v[182:183] op_sel_hi:[1,0]
	v_cvt_pk_bf16_f32 v198, v92, v93
	v_cvt_pk_bf16_f32 v199, v94, v95
	v_cvt_pk_bf16_f32 v200, v88, v89
	v_cvt_pk_bf16_f32 v201, v90, v91
	global_store_dwordx4 v207, v[198:201], s[10:11]
	v_pk_mul_f32 v[84:85], v[84:85], v[182:183] op_sel_hi:[1,0]
	v_pk_mul_f32 v[86:87], v[86:87], v[182:183] op_sel_hi:[1,0]
	v_pk_mul_f32 v[80:81], v[80:81], v[182:183] op_sel_hi:[1,0]
	v_pk_mul_f32 v[82:83], v[82:83], v[182:183] op_sel_hi:[1,0]
	v_cvt_pk_bf16_f32 v202, v84, v85
	v_cvt_pk_bf16_f32 v203, v86, v87
	v_cvt_pk_bf16_f32 v204, v80, v81
	v_cvt_pk_bf16_f32 v205, v82, v83
	global_store_dwordx4 v207, v[202:205], s[10:11] offset:256
	v_add_u32_e32 v207, 0x8000, v207
	s_waitcnt vmcnt(10)
	v_pk_add_f32 v[158:159], v[158:159], v[160:161]
	s_nop 0
	v_add_f32_e32 v214, v158, v159
	v_mov_b32_e32 v215, v214
	s_nop 1
	v_permlane16_swap_b32_e32 v214, v215
	s_nop 0
	v_add_f32_e32 v214, v214, v215
	v_mov_b32_e32 v215, v214
	s_nop 1
	v_permlane32_swap_b32_e32 v214, v215
	s_nop 0
	v_add_f32_e32 v214, v214, v215
	v_fmamk_f32 v214, v214, 0x3a800000, v248
	v_rsq_f32_e32 v184, v214
	s_nop 0
	v_pk_mul_f32 v[76:77], v[76:77], v[184:185] op_sel_hi:[1,0]
	v_pk_mul_f32 v[78:79], v[78:79], v[184:185] op_sel_hi:[1,0]
	v_pk_mul_f32 v[72:73], v[72:73], v[184:185] op_sel_hi:[1,0]
	v_pk_mul_f32 v[74:75], v[74:75], v[184:185] op_sel_hi:[1,0]
	v_cvt_pk_bf16_f32 v198, v76, v77
	v_cvt_pk_bf16_f32 v199, v78, v79
	v_cvt_pk_bf16_f32 v200, v72, v73
	v_cvt_pk_bf16_f32 v201, v74, v75
	global_store_dwordx4 v207, v[198:201], s[10:11]
	v_pk_mul_f32 v[68:69], v[68:69], v[184:185] op_sel_hi:[1,0]
	v_pk_mul_f32 v[70:71], v[70:71], v[184:185] op_sel_hi:[1,0]
	v_pk_mul_f32 v[64:65], v[64:65], v[184:185] op_sel_hi:[1,0]
	v_pk_mul_f32 v[66:67], v[66:67], v[184:185] op_sel_hi:[1,0]
	v_cvt_pk_bf16_f32 v202, v68, v69
	v_cvt_pk_bf16_f32 v203, v70, v71
	v_cvt_pk_bf16_f32 v204, v64, v65
	v_cvt_pk_bf16_f32 v205, v66, v67
	global_store_dwordx4 v207, v[202:205], s[10:11] offset:256
	v_add_u32_e32 v207, 0x28000, v207
	s_waitcnt vmcnt(11)
	v_pk_add_f32 v[162:163], v[162:163], v[164:165]
	s_nop 0
	v_add_f32_e32 v214, v162, v163
	v_mov_b32_e32 v215, v214
	s_nop 1
	v_permlane16_swap_b32_e32 v214, v215
	s_nop 0
	v_add_f32_e32 v214, v214, v215
	v_mov_b32_e32 v215, v214
	s_nop 1
	v_permlane32_swap_b32_e32 v214, v215
	s_nop 0
	v_add_f32_e32 v214, v214, v215
	v_fmamk_f32 v214, v214, 0x3a800000, v248
	v_rsq_f32_e32 v186, v214
	s_nop 0
	v_pk_mul_f32 v[60:61], v[60:61], v[186:187] op_sel_hi:[1,0]
	v_pk_mul_f32 v[62:63], v[62:63], v[186:187] op_sel_hi:[1,0]
	v_pk_mul_f32 v[56:57], v[56:57], v[186:187] op_sel_hi:[1,0]
	v_pk_mul_f32 v[58:59], v[58:59], v[186:187] op_sel_hi:[1,0]
	v_cvt_pk_bf16_f32 v198, v60, v61
	v_cvt_pk_bf16_f32 v199, v62, v63
	v_cvt_pk_bf16_f32 v200, v56, v57
	v_cvt_pk_bf16_f32 v201, v58, v59
	global_store_dwordx4 v207, v[198:201], s[10:11]
	v_pk_mul_f32 v[52:53], v[52:53], v[186:187] op_sel_hi:[1,0]
	v_pk_mul_f32 v[54:55], v[54:55], v[186:187] op_sel_hi:[1,0]
	v_pk_mul_f32 v[48:49], v[48:49], v[186:187] op_sel_hi:[1,0]
	v_pk_mul_f32 v[50:51], v[50:51], v[186:187] op_sel_hi:[1,0]
	v_cvt_pk_bf16_f32 v202, v52, v53
	v_cvt_pk_bf16_f32 v203, v54, v55
	v_cvt_pk_bf16_f32 v204, v48, v49
	v_cvt_pk_bf16_f32 v205, v50, v51
	global_store_dwordx4 v207, v[202:205], s[10:11] offset:256
	v_add_u32_e32 v207, 0x8000, v207
	s_waitcnt vmcnt(12)
	v_pk_add_f32 v[166:167], v[166:167], v[168:169]
	s_nop 0
	v_add_f32_e32 v214, v166, v167
	v_mov_b32_e32 v215, v214
	s_nop 1
	v_permlane16_swap_b32_e32 v214, v215
	s_nop 0
	v_add_f32_e32 v214, v214, v215
	v_mov_b32_e32 v215, v214
	s_nop 1
	v_permlane32_swap_b32_e32 v214, v215
	s_nop 0
	v_add_f32_e32 v214, v214, v215
	v_fmamk_f32 v214, v214, 0x3a800000, v248
	v_rsq_f32_e32 v188, v214
	s_nop 0
	v_pk_mul_f32 v[44:45], v[44:45], v[188:189] op_sel_hi:[1,0]
	v_pk_mul_f32 v[46:47], v[46:47], v[188:189] op_sel_hi:[1,0]
	v_pk_mul_f32 v[40:41], v[40:41], v[188:189] op_sel_hi:[1,0]
	v_pk_mul_f32 v[42:43], v[42:43], v[188:189] op_sel_hi:[1,0]
	v_cvt_pk_bf16_f32 v198, v44, v45
	v_cvt_pk_bf16_f32 v199, v46, v47
	v_cvt_pk_bf16_f32 v200, v40, v41
	v_cvt_pk_bf16_f32 v201, v42, v43
	global_store_dwordx4 v207, v[198:201], s[10:11]
	v_pk_mul_f32 v[36:37], v[36:37], v[188:189] op_sel_hi:[1,0]
	v_pk_mul_f32 v[38:39], v[38:39], v[188:189] op_sel_hi:[1,0]
	v_pk_mul_f32 v[32:33], v[32:33], v[188:189] op_sel_hi:[1,0]
	v_pk_mul_f32 v[34:35], v[34:35], v[188:189] op_sel_hi:[1,0]
	v_cvt_pk_bf16_f32 v202, v36, v37
	v_cvt_pk_bf16_f32 v203, v38, v39
	v_cvt_pk_bf16_f32 v204, v32, v33
	v_cvt_pk_bf16_f32 v205, v34, v35
	global_store_dwordx4 v207, v[202:205], s[10:11] offset:256
	v_add_u32_e32 v207, 0x8000, v207
	s_waitcnt vmcnt(13)
	v_pk_add_f32 v[170:171], v[170:171], v[172:173]
	s_nop 0
	v_add_f32_e32 v214, v170, v171
	v_mov_b32_e32 v215, v214
	s_nop 1
	v_permlane16_swap_b32_e32 v214, v215
	s_nop 0
	v_add_f32_e32 v214, v214, v215
	v_mov_b32_e32 v215, v214
	s_nop 1
	v_permlane32_swap_b32_e32 v214, v215
	s_nop 0
	v_add_f32_e32 v214, v214, v215
	v_fmamk_f32 v214, v214, 0x3a800000, v248
	v_rsq_f32_e32 v190, v214
	s_nop 0
	v_pk_mul_f32 v[28:29], v[28:29], v[190:191] op_sel_hi:[1,0]
	v_pk_mul_f32 v[30:31], v[30:31], v[190:191] op_sel_hi:[1,0]
	v_pk_mul_f32 v[24:25], v[24:25], v[190:191] op_sel_hi:[1,0]
	v_pk_mul_f32 v[26:27], v[26:27], v[190:191] op_sel_hi:[1,0]
	v_cvt_pk_bf16_f32 v198, v28, v29
	v_cvt_pk_bf16_f32 v199, v30, v31
	v_cvt_pk_bf16_f32 v200, v24, v25
	v_cvt_pk_bf16_f32 v201, v26, v27
	global_store_dwordx4 v207, v[198:201], s[10:11]
	v_pk_mul_f32 v[20:21], v[20:21], v[190:191] op_sel_hi:[1,0]
	v_pk_mul_f32 v[22:23], v[22:23], v[190:191] op_sel_hi:[1,0]
	v_pk_mul_f32 v[16:17], v[16:17], v[190:191] op_sel_hi:[1,0]
	v_pk_mul_f32 v[18:19], v[18:19], v[190:191] op_sel_hi:[1,0]
	v_cvt_pk_bf16_f32 v202, v20, v21
	v_cvt_pk_bf16_f32 v203, v22, v23
	v_cvt_pk_bf16_f32 v204, v16, v17
	v_cvt_pk_bf16_f32 v205, v18, v19
	global_store_dwordx4 v207, v[202:205], s[10:11] offset:256
	v_add_u32_e32 v207, 0x8000, v207
	s_waitcnt vmcnt(14)
	v_pk_add_f32 v[174:175], v[174:175], v[176:177]
	s_nop 0
	v_add_f32_e32 v214, v174, v175
	v_mov_b32_e32 v215, v214
	s_nop 1
	v_permlane16_swap_b32_e32 v214, v215
	s_nop 0
	v_add_f32_e32 v214, v214, v215
	v_mov_b32_e32 v215, v214
	s_nop 1
	v_permlane32_swap_b32_e32 v214, v215
	s_nop 0
	v_add_f32_e32 v214, v214, v215
	v_fmamk_f32 v214, v214, 0x3a800000, v248
	v_rsq_f32_e32 v192, v214
	s_nop 0
	v_pk_mul_f32 v[12:13], v[12:13], v[192:193] op_sel_hi:[1,0]
	v_pk_mul_f32 v[14:15], v[14:15], v[192:193] op_sel_hi:[1,0]
	v_pk_mul_f32 v[8:9], v[8:9], v[192:193] op_sel_hi:[1,0]
	v_pk_mul_f32 v[10:11], v[10:11], v[192:193] op_sel_hi:[1,0]
	v_cvt_pk_bf16_f32 v198, v12, v13
	v_cvt_pk_bf16_f32 v199, v14, v15
	v_cvt_pk_bf16_f32 v200, v8, v9
	v_cvt_pk_bf16_f32 v201, v10, v11
	global_store_dwordx4 v207, v[198:201], s[10:11]
	v_pk_mul_f32 v[4:5], v[4:5], v[192:193] op_sel_hi:[1,0]
	v_pk_mul_f32 v[6:7], v[6:7], v[192:193] op_sel_hi:[1,0]
	v_pk_mul_f32 v[0:1], v[0:1], v[192:193] op_sel_hi:[1,0]
	v_pk_mul_f32 v[2:3], v[2:3], v[192:193] op_sel_hi:[1,0]
	v_cvt_pk_bf16_f32 v202, v4, v5
	v_cvt_pk_bf16_f32 v203, v6, v7
	v_cvt_pk_bf16_f32 v204, v0, v1
	v_cvt_pk_bf16_f32 v205, v2, v3
	global_store_dwordx4 v207, v[202:205], s[10:11] offset:256
	s_and_b64 vcc, exec, s[4:5]
	s_cbranch_vccz .LBB0_816
	s_waitcnt vmcnt(0)
	s_cmpk_gt_u32 s30, 0xff
	s_cbranch_scc1 .LBB0_827
	s_barrier

.LBB0_878:
	s_add_u32 s26, s24, 0xfffc0080
	s_addc_u32 s27, s25, -1
	s_add_i32 s65, 0, 0x10000
	v_add_u32_e32 v154, s65, v143
	ds_read_b128 v[138:141], v154
	ds_read_b128 v[146:149], v154 offset:1024
	ds_read_b128 v[150:153], v154 offset:2048
	ds_read_b128 v[154:157], v154 offset:3072
	s_cmp_eq_u32 s64, 12
	s_cselect_b32 s29, s19, s27
	s_cselect_b32 s28, s39, s26
	s_cselect_b32 s27, s17, s63
	s_cselect_b32 s26, s61, s62
	s_add_i32 m0, s50, 0xc000
	ds_read_b128 v[158:161], v145
	ds_read_b128 v[162:165], v145 offset:1024
	ds_read_b128 v[166:169], v145 offset:2048
	ds_read_b128 v[170:173], v145 offset:3072
	ds_read_b128 v[174:177], v145 offset:4096
	ds_read_b128 v[178:181], v145 offset:5120
	ds_read_b128 v[182:185], v145 offset:6144
	ds_read_b128 v[186:189], v145 offset:7168
	global_load_lds_dwordx4 v134, s[24:25]
	s_add_i32 m0, s50, 0xe000
	s_nop 0
	global_load_lds_dwordx4 v136, s[24:25]
	s_waitcnt lgkmcnt(8)
	s_barrier
	s_waitcnt lgkmcnt(0)
	s_setprio 1
	v_mfma_f32_16x16x32_bf16 v[124:127], v[138:141], v[158:161], v[124:127]
	v_mfma_f32_16x16x32_bf16 v[120:123], v[150:153], v[158:161], v[120:123]
	v_mfma_f32_16x16x32_bf16 v[108:111], v[138:141], v[166:169], v[108:111]
	v_mfma_f32_16x16x32_bf16 v[104:107], v[150:153], v[166:169], v[104:107]
	v_mfma_f32_16x16x32_bf16 v[92:95], v[138:141], v[174:177], v[92:95]
	v_mfma_f32_16x16x32_bf16 v[88:91], v[150:153], v[174:177], v[88:91]
	v_mfma_f32_16x16x32_bf16 v[76:79], v[138:141], v[182:185], v[76:79]
	v_mfma_f32_16x16x32_bf16 v[72:75], v[150:153], v[182:185], v[72:75]
	v_mfma_f32_16x16x32_bf16 v[124:127], v[146:149], v[162:165], v[124:127]
	v_mfma_f32_16x16x32_bf16 v[120:123], v[154:157], v[162:165], v[120:123]
	v_mfma_f32_16x16x32_bf16 v[108:111], v[146:149], v[170:173], v[108:111]
	v_mfma_f32_16x16x32_bf16 v[104:107], v[154:157], v[170:173], v[104:107]
	v_mfma_f32_16x16x32_bf16 v[92:95], v[146:149], v[178:181], v[92:95]
	v_mfma_f32_16x16x32_bf16 v[88:91], v[154:157], v[178:181], v[88:91]
	v_mfma_f32_16x16x32_bf16 v[76:79], v[146:149], v[186:189], v[76:79]
	v_mfma_f32_16x16x32_bf16 v[72:75], v[154:157], v[186:189], v[72:75]
	s_setprio 0
	s_barrier
	s_add_i32 s68, 0, 0x14000
	s_add_i32 s65, s65, s47
	v_add_u32_e32 v202, s68, v143
	s_add_u32 s98, s26, s40
	s_addc_u32 s99, s27, s41
	s_mov_b32 m0, s65
	ds_read_b128 v[190:193], v202
	ds_read_b128 v[194:197], v202 offset:1024
	ds_read_b128 v[198:201], v202 offset:2048
	ds_read_b128 v[202:205], v202 offset:3072
	global_load_lds_dwordx4 v208, s[26:27]
	s_add_i32 m0, s65, 0x2000
	s_nop 0
	global_load_lds_dwordx4 v128, s[26:27]
	s_barrier
	s_waitcnt lgkmcnt(0)
	s_setprio 1
	v_mfma_f32_16x16x32_bf16 v[116:119], v[190:193], v[158:161], v[116:119]
	v_mfma_f32_16x16x32_bf16 v[112:115], v[198:201], v[158:161], v[112:115]
	v_mfma_f32_16x16x32_bf16 v[100:103], v[190:193], v[166:169], v[100:103]
	v_mfma_f32_16x16x32_bf16 v[96:99], v[198:201], v[166:169], v[96:99]
	v_mfma_f32_16x16x32_bf16 v[84:87], v[190:193], v[174:177], v[84:87]
	v_mfma_f32_16x16x32_bf16 v[80:83], v[198:201], v[174:177], v[80:83]
	v_mfma_f32_16x16x32_bf16 v[68:71], v[190:193], v[182:185], v[68:71]
	v_mfma_f32_16x16x32_bf16 v[64:67], v[198:201], v[182:185], v[64:67]
	v_mfma_f32_16x16x32_bf16 v[116:119], v[194:197], v[162:165], v[116:119]
	v_mfma_f32_16x16x32_bf16 v[112:115], v[202:205], v[162:165], v[112:115]
	v_mfma_f32_16x16x32_bf16 v[100:103], v[194:197], v[170:173], v[100:103]
	v_mfma_f32_16x16x32_bf16 v[96:99], v[202:205], v[170:173], v[96:99]
	v_mfma_f32_16x16x32_bf16 v[84:87], v[194:197], v[178:181], v[84:87]
	v_mfma_f32_16x16x32_bf16 v[80:83], v[202:205], v[178:181], v[80:83]
	v_mfma_f32_16x16x32_bf16 v[68:71], v[194:197], v[186:189], v[68:71]
	v_mfma_f32_16x16x32_bf16 v[64:67], v[202:205], v[186:189], v[64:67]
	s_setprio 0
	s_mov_b32 m0, s50
	s_add_u32 s100, s28, s40
	s_addc_u32 s101, s29, s41
	s_barrier
	ds_read_b128 v[158:161], v145 offset:16384
	ds_read_b128 v[162:165], v145 offset:17408
	ds_read_b128 v[166:169], v145 offset:18432
	ds_read_b128 v[170:173], v145 offset:19456
	ds_read_b128 v[174:177], v145 offset:20480
	ds_read_b128 v[178:181], v145 offset:21504
	ds_read_b128 v[182:185], v145 offset:22528
	ds_read_b128 v[186:189], v145 offset:23552
	global_load_lds_dwordx4 v132, s[28:29]
	s_mov_b32 m0, s51
	s_nop 0
	global_load_lds_dwordx4 v130, s[28:29]
	s_barrier
	s_waitcnt lgkmcnt(0)
	s_setprio 1
	v_mfma_f32_16x16x32_bf16 v[60:63], v[138:141], v[158:161], v[60:63]
	v_mfma_f32_16x16x32_bf16 v[56:59], v[150:153], v[158:161], v[56:59]
	v_mfma_f32_16x16x32_bf16 v[44:47], v[138:141], v[166:169], v[44:47]
	v_mfma_f32_16x16x32_bf16 v[40:43], v[150:153], v[166:169], v[40:43]
	v_mfma_f32_16x16x32_bf16 v[28:31], v[138:141], v[174:177], v[28:31]
	v_mfma_f32_16x16x32_bf16 v[24:27], v[150:153], v[174:177], v[24:27]
	v_mfma_f32_16x16x32_bf16 v[12:15], v[138:141], v[182:185], v[12:15]
	v_mfma_f32_16x16x32_bf16 v[8:11], v[150:153], v[182:185], v[8:11]
	v_mfma_f32_16x16x32_bf16 v[60:63], v[146:149], v[162:165], v[60:63]
	v_mfma_f32_16x16x32_bf16 v[56:59], v[154:157], v[162:165], v[56:59]
	v_mfma_f32_16x16x32_bf16 v[44:47], v[146:149], v[170:173], v[44:47]
	v_mfma_f32_16x16x32_bf16 v[40:43], v[154:157], v[170:173], v[40:43]
	v_mfma_f32_16x16x32_bf16 v[28:31], v[146:149], v[178:181], v[28:31]
	v_mfma_f32_16x16x32_bf16 v[24:27], v[154:157], v[178:181], v[24:27]
	v_mfma_f32_16x16x32_bf16 v[12:15], v[146:149], v[186:189], v[12:15]
	v_mfma_f32_16x16x32_bf16 v[8:11], v[154:157], v[186:189], v[8:11]
	s_setprio 0
	s_barrier
	s_add_u32 s66, s26, 0x40000
	s_addc_u32 s67, s27, 0
	s_add_i32 s65, s68, s47
	s_mov_b32 m0, s65
	s_nop 0
	global_load_lds_dwordx4 v208, s[66:67]
	s_add_i32 m0, s65, 0x2000
	s_nop 0
	global_load_lds_dwordx4 v128, s[66:67]
	s_waitcnt vmcnt(6)
	s_barrier
	s_setprio 1
	v_mfma_f32_16x16x32_bf16 v[52:55], v[190:193], v[158:161], v[52:55]
	v_mfma_f32_16x16x32_bf16 v[48:51], v[198:201], v[158:161], v[48:51]
	v_mfma_f32_16x16x32_bf16 v[36:39], v[190:193], v[166:169], v[36:39]
	v_mfma_f32_16x16x32_bf16 v[32:35], v[198:201], v[166:169], v[32:35]
	v_mfma_f32_16x16x32_bf16 v[20:23], v[190:193], v[174:177], v[20:23]
	v_mfma_f32_16x16x32_bf16 v[16:19], v[198:201], v[174:177], v[16:19]
	v_mfma_f32_16x16x32_bf16 v[4:7], v[190:193], v[182:185], v[4:7]
	v_mfma_f32_16x16x32_bf16 v[0:3], v[198:201], v[182:185], v[0:3]
	v_mfma_f32_16x16x32_bf16 v[52:55], v[194:197], v[162:165], v[52:55]
	v_mfma_f32_16x16x32_bf16 v[48:51], v[202:205], v[162:165], v[48:51]
	v_mfma_f32_16x16x32_bf16 v[36:39], v[194:197], v[170:173], v[36:39]
	v_mfma_f32_16x16x32_bf16 v[32:35], v[202:205], v[170:173], v[32:35]
	v_mfma_f32_16x16x32_bf16 v[20:23], v[194:197], v[178:181], v[20:23]
	v_mfma_f32_16x16x32_bf16 v[16:19], v[202:205], v[178:181], v[16:19]
	v_mfma_f32_16x16x32_bf16 v[4:7], v[194:197], v[186:189], v[4:7]
	v_mfma_f32_16x16x32_bf16 v[0:3], v[202:205], v[186:189], v[0:3]
	s_setprio 0
	s_add_i32 s65, 0, 0x18000
	v_add_u32_e32 v154, s65, v143
	s_barrier
	ds_read_b128 v[138:141], v154
	ds_read_b128 v[146:149], v154 offset:1024
	ds_read_b128 v[150:153], v154 offset:2048
	ds_read_b128 v[154:157], v154 offset:3072
	s_add_u32 s28, s28, 0x40000
	s_addc_u32 s29, s29, 0
	s_mov_b32 m0, s53
	ds_read_b128 v[158:161], v145 offset:32768
	ds_read_b128 v[162:165], v145 offset:33792
	ds_read_b128 v[166:169], v145 offset:34816
	ds_read_b128 v[170:173], v145 offset:35840
	ds_read_b128 v[174:177], v145 offset:36864
	ds_read_b128 v[178:181], v145 offset:37888
	ds_read_b128 v[182:185], v145 offset:38912
	ds_read_b128 v[186:189], v145 offset:39936
	global_load_lds_dwordx4 v132, s[28:29]
	s_mov_b32 m0, s56
	s_nop 0
	global_load_lds_dwordx4 v130, s[28:29]
	s_waitcnt lgkmcnt(8)
	s_barrier
	s_waitcnt lgkmcnt(0)
	s_setprio 1
	v_mfma_f32_16x16x32_bf16 v[124:127], v[138:141], v[158:161], v[124:127]
	v_mfma_f32_16x16x32_bf16 v[120:123], v[150:153], v[158:161], v[120:123]
	v_mfma_f32_16x16x32_bf16 v[108:111], v[138:141], v[166:169], v[108:111]
	v_mfma_f32_16x16x32_bf16 v[104:107], v[150:153], v[166:169], v[104:107]
	v_mfma_f32_16x16x32_bf16 v[92:95], v[138:141], v[174:177], v[92:95]
	v_mfma_f32_16x16x32_bf16 v[88:91], v[150:153], v[174:177], v[88:91]
	v_mfma_f32_16x16x32_bf16 v[76:79], v[138:141], v[182:185], v[76:79]
	v_mfma_f32_16x16x32_bf16 v[72:75], v[150:153], v[182:185], v[72:75]
	v_mfma_f32_16x16x32_bf16 v[124:127], v[146:149], v[162:165], v[124:127]
	v_mfma_f32_16x16x32_bf16 v[120:123], v[154:157], v[162:165], v[120:123]
	v_mfma_f32_16x16x32_bf16 v[108:111], v[146:149], v[170:173], v[108:111]
	v_mfma_f32_16x16x32_bf16 v[104:107], v[154:157], v[170:173], v[104:107]
	v_mfma_f32_16x16x32_bf16 v[92:95], v[146:149], v[178:181], v[92:95]
	v_mfma_f32_16x16x32_bf16 v[88:91], v[154:157], v[178:181], v[88:91]
	v_mfma_f32_16x16x32_bf16 v[76:79], v[146:149], v[186:189], v[76:79]
	v_mfma_f32_16x16x32_bf16 v[72:75], v[154:157], v[186:189], v[72:75]
	s_setprio 0
	s_barrier
	s_add_i32 s28, 0, 0x1c000
	s_add_i32 s29, s65, s47
	v_add_u32_e32 v202, s28, v143
	s_mov_b32 m0, s29
	ds_read_b128 v[190:193], v202
	ds_read_b128 v[194:197], v202 offset:1024
	ds_read_b128 v[198:201], v202 offset:2048
	ds_read_b128 v[202:205], v202 offset:3072
	global_load_lds_dwordx4 v208, s[98:99]
	s_add_i32 m0, s29, 0x2000
	s_nop 0
	global_load_lds_dwordx4 v128, s[98:99]
	s_barrier
	s_waitcnt lgkmcnt(0)
	s_setprio 1
	v_mfma_f32_16x16x32_bf16 v[116:119], v[190:193], v[158:161], v[116:119]
	v_mfma_f32_16x16x32_bf16 v[112:115], v[198:201], v[158:161], v[112:115]
	v_mfma_f32_16x16x32_bf16 v[100:103], v[190:193], v[166:169], v[100:103]
	v_mfma_f32_16x16x32_bf16 v[96:99], v[198:201], v[166:169], v[96:99]
	v_mfma_f32_16x16x32_bf16 v[84:87], v[190:193], v[174:177], v[84:87]
	v_mfma_f32_16x16x32_bf16 v[80:83], v[198:201], v[174:177], v[80:83]
	v_mfma_f32_16x16x32_bf16 v[68:71], v[190:193], v[182:185], v[68:71]
	v_mfma_f32_16x16x32_bf16 v[64:67], v[198:201], v[182:185], v[64:67]
	v_mfma_f32_16x16x32_bf16 v[116:119], v[194:197], v[162:165], v[116:119]
	v_mfma_f32_16x16x32_bf16 v[112:115], v[202:205], v[162:165], v[112:115]
	v_mfma_f32_16x16x32_bf16 v[100:103], v[194:197], v[170:173], v[100:103]
	v_mfma_f32_16x16x32_bf16 v[96:99], v[202:205], v[170:173], v[96:99]
	v_mfma_f32_16x16x32_bf16 v[84:87], v[194:197], v[178:181], v[84:87]
	v_mfma_f32_16x16x32_bf16 v[80:83], v[202:205], v[178:181], v[80:83]
	v_mfma_f32_16x16x32_bf16 v[68:71], v[194:197], v[186:189], v[68:71]
	v_mfma_f32_16x16x32_bf16 v[64:67], v[202:205], v[186:189], v[64:67]
	s_setprio 0
	s_mov_b32 m0, s58
	s_barrier
	ds_read_b128 v[158:161], v145 offset:49152
	ds_read_b128 v[162:165], v145 offset:50176
	ds_read_b128 v[166:169], v145 offset:51200
	ds_read_b128 v[170:173], v145 offset:52224
	ds_read_b128 v[174:177], v145 offset:53248
	ds_read_b128 v[178:181], v145 offset:54272
	ds_read_b128 v[182:185], v145 offset:55296
	ds_read_b128 v[186:189], v145 offset:56320
	global_load_lds_dwordx4 v132, s[100:101]
	s_mov_b32 m0, s59
	s_nop 0
	global_load_lds_dwordx4 v130, s[100:101]
	s_barrier
	s_waitcnt lgkmcnt(0)
	s_setprio 1
	v_mfma_f32_16x16x32_bf16 v[60:63], v[138:141], v[158:161], v[60:63]
	v_mfma_f32_16x16x32_bf16 v[56:59], v[150:153], v[158:161], v[56:59]
	v_mfma_f32_16x16x32_bf16 v[44:47], v[138:141], v[166:169], v[44:47]
	v_mfma_f32_16x16x32_bf16 v[40:43], v[150:153], v[166:169], v[40:43]
	v_mfma_f32_16x16x32_bf16 v[28:31], v[138:141], v[174:177], v[28:31]
	v_mfma_f32_16x16x32_bf16 v[24:27], v[150:153], v[174:177], v[24:27]
	v_mfma_f32_16x16x32_bf16 v[12:15], v[138:141], v[182:185], v[12:15]
	v_mfma_f32_16x16x32_bf16 v[8:11], v[150:153], v[182:185], v[8:11]
	v_mfma_f32_16x16x32_bf16 v[60:63], v[146:149], v[162:165], v[60:63]
	v_mfma_f32_16x16x32_bf16 v[56:59], v[154:157], v[162:165], v[56:59]
	v_mfma_f32_16x16x32_bf16 v[44:47], v[146:149], v[170:173], v[44:47]
	v_mfma_f32_16x16x32_bf16 v[40:43], v[154:157], v[170:173], v[40:43]
	v_mfma_f32_16x16x32_bf16 v[28:31], v[146:149], v[178:181], v[28:31]
	v_mfma_f32_16x16x32_bf16 v[24:27], v[154:157], v[178:181], v[24:27]
	v_mfma_f32_16x16x32_bf16 v[12:15], v[146:149], v[186:189], v[12:15]
	v_mfma_f32_16x16x32_bf16 v[8:11], v[154:157], v[186:189], v[8:11]
	s_setprio 0
	s_barrier
	s_add_u32 s26, s26, 0x40080
	s_addc_u32 s27, s27, 0
	s_add_i32 s28, s28, s47
	s_mov_b32 m0, s28
	s_nop 0
	global_load_lds_dwordx4 v208, s[26:27]
	s_add_i32 m0, s28, 0x2000
	s_nop 0
	global_load_lds_dwordx4 v128, s[26:27]
	s_waitcnt vmcnt(6)
	s_barrier
	s_setprio 1
	v_mfma_f32_16x16x32_bf16 v[52:55], v[190:193], v[158:161], v[52:55]
	v_mfma_f32_16x16x32_bf16 v[48:51], v[198:201], v[158:161], v[48:51]
	v_mfma_f32_16x16x32_bf16 v[36:39], v[190:193], v[166:169], v[36:39]
	v_mfma_f32_16x16x32_bf16 v[32:35], v[198:201], v[166:169], v[32:35]
	v_mfma_f32_16x16x32_bf16 v[20:23], v[190:193], v[174:177], v[20:23]
	v_mfma_f32_16x16x32_bf16 v[16:19], v[198:201], v[174:177], v[16:19]
	v_mfma_f32_16x16x32_bf16 v[4:7], v[190:193], v[182:185], v[4:7]
	v_mfma_f32_16x16x32_bf16 v[0:3], v[198:201], v[182:185], v[0:3]
	v_mfma_f32_16x16x32_bf16 v[52:55], v[194:197], v[162:165], v[52:55]
	v_mfma_f32_16x16x32_bf16 v[48:51], v[202:205], v[162:165], v[48:51]
	v_mfma_f32_16x16x32_bf16 v[36:39], v[194:197], v[170:173], v[36:39]
	v_mfma_f32_16x16x32_bf16 v[32:35], v[202:205], v[170:173], v[32:35]
	v_mfma_f32_16x16x32_bf16 v[20:23], v[194:197], v[178:181], v[20:23]
	v_mfma_f32_16x16x32_bf16 v[16:19], v[202:205], v[178:181], v[16:19]
	v_mfma_f32_16x16x32_bf16 v[4:7], v[194:197], v[186:189], v[4:7]
	v_mfma_f32_16x16x32_bf16 v[0:3], v[202:205], v[186:189], v[0:3]
	s_setprio 0
	s_add_i32 s64, s64, 2
	s_add_u32 s24, s24, 0x100
	s_addc_u32 s25, s25, 0
	s_add_u32 s62, s62, 0x100
	s_addc_u32 s63, s63, 0
	s_cmp_gt_u32 s64, 13
	s_barrier
	s_cbranch_scc0 .LBB0_878
	v_lshl_add_u32 v140, s38, 8, v142
	v_lshl_or_b32 v141, s36, 8, v144
	s_lshl_b32 s24, s36, 2
	s_ashr_i32 s25, s24, 31
	s_lshl_b32 s36, s57, 2
	v_lshlrev_b32_e32 v206, 11, v140
	v_lshl_add_u32 v206, v141, 1, v206
	v_lshl_add_u32 v210, v140, 6, s36
	v_lshl_add_u32 v210, s24, 2, v210
	v_mov_b32_e32 v207, v206
	global_load_dwordx4 v[146:149], v206, s[8:9]
	global_load_dwordx4 v[150:153], v206, s[8:9] offset:256
	v_add_u32_e32 v206, 0x8000, v206
	global_load_dwordx4 v[154:157], v206, s[8:9]
	global_load_dwordx4 v[158:161], v206, s[8:9] offset:256
	v_add_u32_e32 v206, 0x8000, v206
	global_load_dwordx4 v[162:165], v206, s[8:9]
	global_load_dwordx4 v[166:169], v206, s[8:9] offset:256
	v_add_u32_e32 v206, 0x8000, v206
	global_load_dwordx4 v[170:173], v206, s[8:9]
	global_load_dwordx4 v[174:177], v206, s[8:9] offset:256
	v_add_u32_e32 v206, 0x28000, v206
	global_load_dwordx4 v[178:181], v206, s[8:9]
	global_load_dwordx4 v[182:185], v206, s[8:9] offset:256
	v_add_u32_e32 v206, 0x8000, v206
	global_load_dwordx4 v[186:189], v206, s[8:9]
	global_load_dwordx4 v[190:193], v206, s[8:9] offset:256
	v_add_u32_e32 v206, 0x8000, v206
	global_load_dwordx4 v[194:197], v206, s[8:9]
	global_load_dwordx4 v[198:201], v206, s[8:9] offset:256
	v_add_u32_e32 v206, 0x8000, v206
	s_waitcnt vmcnt(12)
	v_lshlrev_b32_e32 v202, 16, v146
	v_and_b32_e32 v203, 0xffff0000, v146
	v_lshlrev_b32_e32 v204, 16, v147
	v_and_b32_e32 v205, 0xffff0000, v147
	v_pk_add_f32 v[124:125], v[124:125], v[202:203]
	v_pk_add_f32 v[126:127], v[126:127], v[204:205]
	v_lshlrev_b32_e32 v202, 16, v148
	v_and_b32_e32 v203, 0xffff0000, v148
	v_lshlrev_b32_e32 v204, 16, v149
	v_and_b32_e32 v205, 0xffff0000, v149
	v_pk_add_f32 v[120:121], v[120:121], v[202:203]
	v_pk_add_f32 v[122:123], v[122:123], v[204:205]
	v_cvt_pk_bf16_f32 v146, v124, v125
	v_cvt_pk_bf16_f32 v147, v126, v127
	v_cvt_pk_bf16_f32 v148, v120, v121
	v_cvt_pk_bf16_f32 v149, v122, v123
	v_pk_mul_f32 v[138:139], v[124:125], v[124:125]
	global_store_dwordx4 v207, v[146:149], s[8:9]
	v_pk_fma_f32 v[138:139], v[126:127], v[126:127], v[138:139]
	v_pk_fma_f32 v[138:139], v[120:121], v[120:121], v[138:139]
	v_pk_fma_f32 v[138:139], v[122:123], v[122:123], v[138:139]
	v_lshlrev_b32_e32 v202, 16, v150
	v_and_b32_e32 v203, 0xffff0000, v150
	v_lshlrev_b32_e32 v204, 16, v151
	v_and_b32_e32 v205, 0xffff0000, v151
	v_pk_add_f32 v[116:117], v[116:117], v[202:203]
	v_pk_add_f32 v[118:119], v[118:119], v[204:205]
	v_lshlrev_b32_e32 v202, 16, v152
	v_and_b32_e32 v203, 0xffff0000, v152
	v_lshlrev_b32_e32 v204, 16, v153
	v_and_b32_e32 v205, 0xffff0000, v153
	v_pk_add_f32 v[112:113], v[112:113], v[202:203]
	v_pk_add_f32 v[114:115], v[114:115], v[204:205]
	v_cvt_pk_bf16_f32 v150, v116, v117
	v_cvt_pk_bf16_f32 v151, v118, v119
	v_cvt_pk_bf16_f32 v152, v112, v113
	v_cvt_pk_bf16_f32 v153, v114, v115
	v_pk_fma_f32 v[138:139], v[116:117], v[116:117], v[138:139]
	global_store_dwordx4 v207, v[150:153], s[8:9] offset:256
	v_pk_fma_f32 v[138:139], v[118:119], v[118:119], v[138:139]
	v_pk_fma_f32 v[138:139], v[112:113], v[112:113], v[138:139]
	v_pk_fma_f32 v[138:139], v[114:115], v[114:115], v[138:139]
	v_add_f32_e32 v214, v138, v139
	v_add_u32_e32 v207, 0x8000, v207
	v_mov_b32_e32 v215, v214
	s_nop 1
	v_permlane16_swap_b32_e32 v214, v215
	s_nop 0
	v_add_f32_e32 v214, v214, v215
	v_mov_b32_e32 v215, v214
	s_nop 1
	v_permlane32_swap_b32_e32 v214, v215
	s_nop 0
	v_add_f32_e32 v214, v214, v215
	s_and_saveexec_b64 s[26:27], s[4:5]
	global_store_dword v210, v214, s[14:15]
	s_mov_b64 exec, s[26:27]
	global_load_dwordx4 v[146:149], v206, s[8:9]
	global_load_dwordx4 v[150:153], v206, s[8:9] offset:256
	s_waitcnt vmcnt(15)
	v_lshlrev_b32_e32 v202, 16, v154
	v_and_b32_e32 v203, 0xffff0000, v154
	v_lshlrev_b32_e32 v204, 16, v155
	v_and_b32_e32 v205, 0xffff0000, v155
	v_pk_add_f32 v[108:109], v[108:109], v[202:203]
	v_pk_add_f32 v[110:111], v[110:111], v[204:205]
	v_lshlrev_b32_e32 v202, 16, v156
	v_and_b32_e32 v203, 0xffff0000, v156
	v_lshlrev_b32_e32 v204, 16, v157
	v_and_b32_e32 v205, 0xffff0000, v157
	v_pk_add_f32 v[104:105], v[104:105], v[202:203]
	v_pk_add_f32 v[106:107], v[106:107], v[204:205]
	v_cvt_pk_bf16_f32 v154, v108, v109
	v_cvt_pk_bf16_f32 v155, v110, v111
	v_cvt_pk_bf16_f32 v156, v104, v105
	v_cvt_pk_bf16_f32 v157, v106, v107
	v_pk_mul_f32 v[138:139], v[108:109], v[108:109]
	global_store_dwordx4 v207, v[154:157], s[8:9]
	v_pk_fma_f32 v[138:139], v[110:111], v[110:111], v[138:139]
	v_pk_fma_f32 v[138:139], v[104:105], v[104:105], v[138:139]
	v_pk_fma_f32 v[138:139], v[106:107], v[106:107], v[138:139]
	v_lshlrev_b32_e32 v202, 16, v158
	v_and_b32_e32 v203, 0xffff0000, v158
	v_lshlrev_b32_e32 v204, 16, v159
	v_and_b32_e32 v205, 0xffff0000, v159
	v_pk_add_f32 v[100:101], v[100:101], v[202:203]
	v_pk_add_f32 v[102:103], v[102:103], v[204:205]
	v_lshlrev_b32_e32 v202, 16, v160
	v_and_b32_e32 v203, 0xffff0000, v160
	v_lshlrev_b32_e32 v204, 16, v161
	v_and_b32_e32 v205, 0xffff0000, v161
	v_pk_add_f32 v[96:97], v[96:97], v[202:203]
	v_pk_add_f32 v[98:99], v[98:99], v[204:205]
	v_cvt_pk_bf16_f32 v158, v100, v101
	v_cvt_pk_bf16_f32 v159, v102, v103
	v_cvt_pk_bf16_f32 v160, v96, v97
	v_cvt_pk_bf16_f32 v161, v98, v99
	v_pk_fma_f32 v[138:139], v[100:101], v[100:101], v[138:139]
	global_store_dwordx4 v207, v[158:161], s[8:9] offset:256
	v_pk_fma_f32 v[138:139], v[102:103], v[102:103], v[138:139]
	v_pk_fma_f32 v[138:139], v[96:97], v[96:97], v[138:139]
	v_pk_fma_f32 v[138:139], v[98:99], v[98:99], v[138:139]
	v_add_f32_e32 v214, v138, v139
	v_add_u32_e32 v207, 0x8000, v207
	v_mov_b32_e32 v215, v214
	s_nop 1
	v_permlane16_swap_b32_e32 v214, v215
	s_nop 0
	v_add_f32_e32 v214, v214, v215
	v_mov_b32_e32 v215, v214
	s_nop 1
	v_permlane32_swap_b32_e32 v214, v215
	s_nop 0
	v_add_f32_e32 v214, v214, v215
	s_and_saveexec_b64 s[26:27], s[4:5]
	global_store_dword v210, v214, s[14:15] offset:1024
	s_mov_b64 exec, s[26:27]
	s_waitcnt vmcnt(16)
	v_lshlrev_b32_e32 v202, 16, v162
	v_and_b32_e32 v203, 0xffff0000, v162
	v_lshlrev_b32_e32 v204, 16, v163
	v_and_b32_e32 v205, 0xffff0000, v163
	v_pk_add_f32 v[92:93], v[92:93], v[202:203]
	v_pk_add_f32 v[94:95], v[94:95], v[204:205]
	v_lshlrev_b32_e32 v202, 16, v164
	v_and_b32_e32 v203, 0xffff0000, v164
	v_lshlrev_b32_e32 v204, 16, v165
	v_and_b32_e32 v205, 0xffff0000, v165
	v_pk_add_f32 v[88:89], v[88:89], v[202:203]
	v_pk_add_f32 v[90:91], v[90:91], v[204:205]
	v_cvt_pk_bf16_f32 v162, v92, v93
	v_cvt_pk_bf16_f32 v163, v94, v95
	v_cvt_pk_bf16_f32 v164, v88, v89
	v_cvt_pk_bf16_f32 v165, v90, v91
	v_pk_mul_f32 v[138:139], v[92:93], v[92:93]
	global_store_dwordx4 v207, v[162:165], s[8:9]
	v_pk_fma_f32 v[138:139], v[94:95], v[94:95], v[138:139]
	v_pk_fma_f32 v[138:139], v[88:89], v[88:89], v[138:139]
	v_pk_fma_f32 v[138:139], v[90:91], v[90:91], v[138:139]
	v_lshlrev_b32_e32 v202, 16, v166
	v_and_b32_e32 v203, 0xffff0000, v166
	v_lshlrev_b32_e32 v204, 16, v167
	v_and_b32_e32 v205, 0xffff0000, v167
	v_pk_add_f32 v[84:85], v[84:85], v[202:203]
	v_pk_add_f32 v[86:87], v[86:87], v[204:205]
	v_lshlrev_b32_e32 v202, 16, v168
	v_and_b32_e32 v203, 0xffff0000, v168
	v_lshlrev_b32_e32 v204, 16, v169
	v_and_b32_e32 v205, 0xffff0000, v169
	v_pk_add_f32 v[80:81], v[80:81], v[202:203]
	v_pk_add_f32 v[82:83], v[82:83], v[204:205]
	v_cvt_pk_bf16_f32 v166, v84, v85
	v_cvt_pk_bf16_f32 v167, v86, v87
	v_cvt_pk_bf16_f32 v168, v80, v81
	v_cvt_pk_bf16_f32 v169, v82, v83
	v_pk_fma_f32 v[138:139], v[84:85], v[84:85], v[138:139]
	global_store_dwordx4 v207, v[166:169], s[8:9] offset:256
	v_pk_fma_f32 v[138:139], v[86:87], v[86:87], v[138:139]
	v_pk_fma_f32 v[138:139], v[80:81], v[80:81], v[138:139]
	v_pk_fma_f32 v[138:139], v[82:83], v[82:83], v[138:139]
	v_add_f32_e32 v214, v138, v139
	v_add_u32_e32 v207, 0x8000, v207
	v_mov_b32_e32 v215, v214
	s_nop 1
	v_permlane16_swap_b32_e32 v214, v215
	s_nop 0
	v_add_f32_e32 v214, v214, v215
	v_mov_b32_e32 v215, v214
	s_nop 1
	v_permlane32_swap_b32_e32 v214, v215
	s_nop 0
	v_add_f32_e32 v214, v214, v215
	s_and_saveexec_b64 s[26:27], s[4:5]
	global_store_dword v210, v214, s[14:15] offset:2048
	s_mov_b64 exec, s[26:27]
	s_waitcnt vmcnt(17)
	v_lshlrev_b32_e32 v202, 16, v170
	v_and_b32_e32 v203, 0xffff0000, v170
	v_lshlrev_b32_e32 v204, 16, v171
	v_and_b32_e32 v205, 0xffff0000, v171
	v_pk_add_f32 v[76:77], v[76:77], v[202:203]
	v_pk_add_f32 v[78:79], v[78:79], v[204:205]
	v_lshlrev_b32_e32 v202, 16, v172
	v_and_b32_e32 v203, 0xffff0000, v172
	v_lshlrev_b32_e32 v204, 16, v173
	v_and_b32_e32 v205, 0xffff0000, v173
	v_pk_add_f32 v[72:73], v[72:73], v[202:203]
	v_pk_add_f32 v[74:75], v[74:75], v[204:205]
	v_cvt_pk_bf16_f32 v170, v76, v77
	v_cvt_pk_bf16_f32 v171, v78, v79
	v_cvt_pk_bf16_f32 v172, v72, v73
	v_cvt_pk_bf16_f32 v173, v74, v75
	v_pk_mul_f32 v[138:139], v[76:77], v[76:77]
	global_store_dwordx4 v207, v[170:173], s[8:9]
	v_pk_fma_f32 v[138:139], v[78:79], v[78:79], v[138:139]
	v_pk_fma_f32 v[138:139], v[72:73], v[72:73], v[138:139]
	v_pk_fma_f32 v[138:139], v[74:75], v[74:75], v[138:139]
	v_lshlrev_b32_e32 v202, 16, v174
	v_and_b32_e32 v203, 0xffff0000, v174
	v_lshlrev_b32_e32 v204, 16, v175
	v_and_b32_e32 v205, 0xffff0000, v175
	v_pk_add_f32 v[68:69], v[68:69], v[202:203]
	v_pk_add_f32 v[70:71], v[70:71], v[204:205]
	v_lshlrev_b32_e32 v202, 16, v176
	v_and_b32_e32 v203, 0xffff0000, v176
	v_lshlrev_b32_e32 v204, 16, v177
	v_and_b32_e32 v205, 0xffff0000, v177
	v_pk_add_f32 v[64:65], v[64:65], v[202:203]
	v_pk_add_f32 v[66:67], v[66:67], v[204:205]
	v_cvt_pk_bf16_f32 v174, v68, v69
	v_cvt_pk_bf16_f32 v175, v70, v71
	v_cvt_pk_bf16_f32 v176, v64, v65
	v_cvt_pk_bf16_f32 v177, v66, v67
	v_pk_fma_f32 v[138:139], v[68:69], v[68:69], v[138:139]
	global_store_dwordx4 v207, v[174:177], s[8:9] offset:256
	v_pk_fma_f32 v[138:139], v[70:71], v[70:71], v[138:139]
	v_pk_fma_f32 v[138:139], v[64:65], v[64:65], v[138:139]
	v_pk_fma_f32 v[138:139], v[66:67], v[66:67], v[138:139]
	v_add_f32_e32 v214, v138, v139
	v_add_u32_e32 v207, 0x28000, v207
	v_mov_b32_e32 v215, v214
	s_nop 1
	v_permlane16_swap_b32_e32 v214, v215
	s_nop 0
	v_add_f32_e32 v214, v214, v215
	v_mov_b32_e32 v215, v214
	s_nop 1
	v_permlane32_swap_b32_e32 v214, v215
	s_nop 0
	v_add_f32_e32 v214, v214, v215
	s_and_saveexec_b64 s[26:27], s[4:5]
	global_store_dword v210, v214, s[14:15] offset:3072
	s_mov_b64 exec, s[26:27]
	v_add_u32_e32 v210, 0x2000, v210
	s_waitcnt vmcnt(18)
	v_lshlrev_b32_e32 v202, 16, v178
	v_and_b32_e32 v203, 0xffff0000, v178
	v_lshlrev_b32_e32 v204, 16, v179
	v_and_b32_e32 v205, 0xffff0000, v179
	v_pk_add_f32 v[60:61], v[60:61], v[202:203]
	v_pk_add_f32 v[62:63], v[62:63], v[204:205]
	v_lshlrev_b32_e32 v202, 16, v180
	v_and_b32_e32 v203, 0xffff0000, v180
	v_lshlrev_b32_e32 v204, 16, v181
	v_and_b32_e32 v205, 0xffff0000, v181
	v_pk_add_f32 v[56:57], v[56:57], v[202:203]
	v_pk_add_f32 v[58:59], v[58:59], v[204:205]
	v_cvt_pk_bf16_f32 v178, v60, v61
	v_cvt_pk_bf16_f32 v179, v62, v63
	v_cvt_pk_bf16_f32 v180, v56, v57
	v_cvt_pk_bf16_f32 v181, v58, v59
	v_pk_mul_f32 v[138:139], v[60:61], v[60:61]
	global_store_dwordx4 v207, v[178:181], s[8:9]
	v_pk_fma_f32 v[138:139], v[62:63], v[62:63], v[138:139]
	v_pk_fma_f32 v[138:139], v[56:57], v[56:57], v[138:139]
	v_pk_fma_f32 v[138:139], v[58:59], v[58:59], v[138:139]
	v_lshlrev_b32_e32 v202, 16, v182
	v_and_b32_e32 v203, 0xffff0000, v182
	v_lshlrev_b32_e32 v204, 16, v183
	v_and_b32_e32 v205, 0xffff0000, v183
	v_pk_add_f32 v[52:53], v[52:53], v[202:203]
	v_pk_add_f32 v[54:55], v[54:55], v[204:205]
	v_lshlrev_b32_e32 v202, 16, v184
	v_and_b32_e32 v203, 0xffff0000, v184
	v_lshlrev_b32_e32 v204, 16, v185
	v_and_b32_e32 v205, 0xffff0000, v185
	v_pk_add_f32 v[48:49], v[48:49], v[202:203]
	v_pk_add_f32 v[50:51], v[50:51], v[204:205]
	v_cvt_pk_bf16_f32 v182, v52, v53
	v_cvt_pk_bf16_f32 v183, v54, v55
	v_cvt_pk_bf16_f32 v184, v48, v49
	v_cvt_pk_bf16_f32 v185, v50, v51
	v_pk_fma_f32 v[138:139], v[52:53], v[52:53], v[138:139]
	global_store_dwordx4 v207, v[182:185], s[8:9] offset:256
	v_pk_fma_f32 v[138:139], v[54:55], v[54:55], v[138:139]
	v_pk_fma_f32 v[138:139], v[48:49], v[48:49], v[138:139]
	v_pk_fma_f32 v[138:139], v[50:51], v[50:51], v[138:139]
	v_add_f32_e32 v214, v138, v139
	v_add_u32_e32 v207, 0x8000, v207
	v_mov_b32_e32 v215, v214
	s_nop 1
	v_permlane16_swap_b32_e32 v214, v215
	s_nop 0
	v_add_f32_e32 v214, v214, v215
	v_mov_b32_e32 v215, v214
	s_nop 1
	v_permlane32_swap_b32_e32 v214, v215
	s_nop 0
	v_add_f32_e32 v214, v214, v215
	s_and_saveexec_b64 s[26:27], s[4:5]
	global_store_dword v210, v214, s[14:15]
	s_mov_b64 exec, s[26:27]
	s_waitcnt vmcnt(19)
	v_lshlrev_b32_e32 v202, 16, v186
	v_and_b32_e32 v203, 0xffff0000, v186
	v_lshlrev_b32_e32 v204, 16, v187
	v_and_b32_e32 v205, 0xffff0000, v187
	v_pk_add_f32 v[44:45], v[44:45], v[202:203]
	v_pk_add_f32 v[46:47], v[46:47], v[204:205]
	v_lshlrev_b32_e32 v202, 16, v188
	v_and_b32_e32 v203, 0xffff0000, v188
	v_lshlrev_b32_e32 v204, 16, v189
	v_and_b32_e32 v205, 0xffff0000, v189
	v_pk_add_f32 v[40:41], v[40:41], v[202:203]
	v_pk_add_f32 v[42:43], v[42:43], v[204:205]
	v_cvt_pk_bf16_f32 v186, v44, v45
	v_cvt_pk_bf16_f32 v187, v46, v47
	v_cvt_pk_bf16_f32 v188, v40, v41
	v_cvt_pk_bf16_f32 v189, v42, v43
	v_pk_mul_f32 v[138:139], v[44:45], v[44:45]
	global_store_dwordx4 v207, v[186:189], s[8:9]
	v_pk_fma_f32 v[138:139], v[46:47], v[46:47], v[138:139]
	v_pk_fma_f32 v[138:139], v[40:41], v[40:41], v[138:139]
	v_pk_fma_f32 v[138:139], v[42:43], v[42:43], v[138:139]
	v_lshlrev_b32_e32 v202, 16, v190
	v_and_b32_e32 v203, 0xffff0000, v190
	v_lshlrev_b32_e32 v204, 16, v191
	v_and_b32_e32 v205, 0xffff0000, v191
	v_pk_add_f32 v[36:37], v[36:37], v[202:203]
	v_pk_add_f32 v[38:39], v[38:39], v[204:205]
	v_lshlrev_b32_e32 v202, 16, v192
	v_and_b32_e32 v203, 0xffff0000, v192
	v_lshlrev_b32_e32 v204, 16, v193
	v_and_b32_e32 v205, 0xffff0000, v193
	v_pk_add_f32 v[32:33], v[32:33], v[202:203]
	v_pk_add_f32 v[34:35], v[34:35], v[204:205]
	v_cvt_pk_bf16_f32 v190, v36, v37
	v_cvt_pk_bf16_f32 v191, v38, v39
	v_cvt_pk_bf16_f32 v192, v32, v33
	v_cvt_pk_bf16_f32 v193, v34, v35
	v_pk_fma_f32 v[138:139], v[36:37], v[36:37], v[138:139]
	global_store_dwordx4 v207, v[190:193], s[8:9] offset:256
	v_pk_fma_f32 v[138:139], v[38:39], v[38:39], v[138:139]
	v_pk_fma_f32 v[138:139], v[32:33], v[32:33], v[138:139]
	v_pk_fma_f32 v[138:139], v[34:35], v[34:35], v[138:139]
	v_add_f32_e32 v214, v138, v139
	v_add_u32_e32 v207, 0x8000, v207
	v_mov_b32_e32 v215, v214
	s_nop 1
	v_permlane16_swap_b32_e32 v214, v215
	s_nop 0
	v_add_f32_e32 v214, v214, v215
	v_mov_b32_e32 v215, v214
	s_nop 1
	v_permlane32_swap_b32_e32 v214, v215
	s_nop 0
	v_add_f32_e32 v214, v214, v215
	s_and_saveexec_b64 s[26:27], s[4:5]
	global_store_dword v210, v214, s[14:15] offset:1024
	s_mov_b64 exec, s[26:27]
	s_waitcnt vmcnt(20)
	v_lshlrev_b32_e32 v202, 16, v194
	v_and_b32_e32 v203, 0xffff0000, v194
	v_lshlrev_b32_e32 v204, 16, v195
	v_and_b32_e32 v205, 0xffff0000, v195
	v_pk_add_f32 v[28:29], v[28:29], v[202:203]
	v_pk_add_f32 v[30:31], v[30:31], v[204:205]
	v_lshlrev_b32_e32 v202, 16, v196
	v_and_b32_e32 v203, 0xffff0000, v196
	v_lshlrev_b32_e32 v204, 16, v197
	v_and_b32_e32 v205, 0xffff0000, v197
	v_pk_add_f32 v[24:25], v[24:25], v[202:203]
	v_pk_add_f32 v[26:27], v[26:27], v[204:205]
	v_cvt_pk_bf16_f32 v194, v28, v29
	v_cvt_pk_bf16_f32 v195, v30, v31
	v_cvt_pk_bf16_f32 v196, v24, v25
	v_cvt_pk_bf16_f32 v197, v26, v27
	v_pk_mul_f32 v[138:139], v[28:29], v[28:29]
	global_store_dwordx4 v207, v[194:197], s[8:9]
	v_pk_fma_f32 v[138:139], v[30:31], v[30:31], v[138:139]
	v_pk_fma_f32 v[138:139], v[24:25], v[24:25], v[138:139]
	v_pk_fma_f32 v[138:139], v[26:27], v[26:27], v[138:139]
	v_lshlrev_b32_e32 v202, 16, v198
	v_and_b32_e32 v203, 0xffff0000, v198
	v_lshlrev_b32_e32 v204, 16, v199
	v_and_b32_e32 v205, 0xffff0000, v199
	v_pk_add_f32 v[20:21], v[20:21], v[202:203]
	v_pk_add_f32 v[22:23], v[22:23], v[204:205]
	v_lshlrev_b32_e32 v202, 16, v200
	v_and_b32_e32 v203, 0xffff0000, v200
	v_lshlrev_b32_e32 v204, 16, v201
	v_and_b32_e32 v205, 0xffff0000, v201
	v_pk_add_f32 v[16:17], v[16:17], v[202:203]
	v_pk_add_f32 v[18:19], v[18:19], v[204:205]
	v_cvt_pk_bf16_f32 v198, v20, v21
	v_cvt_pk_bf16_f32 v199, v22, v23
	v_cvt_pk_bf16_f32 v200, v16, v17
	v_cvt_pk_bf16_f32 v201, v18, v19
	v_pk_fma_f32 v[138:139], v[20:21], v[20:21], v[138:139]
	global_store_dwordx4 v207, v[198:201], s[8:9] offset:256
	v_pk_fma_f32 v[138:139], v[22:23], v[22:23], v[138:139]
	v_pk_fma_f32 v[138:139], v[16:17], v[16:17], v[138:139]
	v_pk_fma_f32 v[138:139], v[18:19], v[18:19], v[138:139]
	v_add_f32_e32 v214, v138, v139
	v_add_u32_e32 v207, 0x8000, v207
	v_mov_b32_e32 v215, v214
	s_nop 1
	v_permlane16_swap_b32_e32 v214, v215
	s_nop 0
	v_add_f32_e32 v214, v214, v215
	v_mov_b32_e32 v215, v214
	s_nop 1
	v_permlane32_swap_b32_e32 v214, v215
	s_nop 0
	v_add_f32_e32 v214, v214, v215
	s_and_saveexec_b64 s[26:27], s[4:5]
	global_store_dword v210, v214, s[14:15] offset:2048
	s_mov_b64 exec, s[26:27]
	s_waitcnt vmcnt(18)
	v_lshlrev_b32_e32 v202, 16, v146
	v_and_b32_e32 v203, 0xffff0000, v146
	v_lshlrev_b32_e32 v204, 16, v147
	v_and_b32_e32 v205, 0xffff0000, v147
	v_pk_add_f32 v[12:13], v[12:13], v[202:203]
	v_pk_add_f32 v[14:15], v[14:15], v[204:205]
	v_lshlrev_b32_e32 v202, 16, v148
	v_and_b32_e32 v203, 0xffff0000, v148
	v_lshlrev_b32_e32 v204, 16, v149
	v_and_b32_e32 v205, 0xffff0000, v149
	v_pk_add_f32 v[8:9], v[8:9], v[202:203]
	v_pk_add_f32 v[10:11], v[10:11], v[204:205]
	v_cvt_pk_bf16_f32 v146, v12, v13
	v_cvt_pk_bf16_f32 v147, v14, v15
	v_cvt_pk_bf16_f32 v148, v8, v9
	v_cvt_pk_bf16_f32 v149, v10, v11
	v_pk_mul_f32 v[138:139], v[12:13], v[12:13]
	global_store_dwordx4 v207, v[146:149], s[8:9]
	v_pk_fma_f32 v[138:139], v[14:15], v[14:15], v[138:139]
	v_pk_fma_f32 v[138:139], v[8:9], v[8:9], v[138:139]
	v_pk_fma_f32 v[138:139], v[10:11], v[10:11], v[138:139]
	v_lshlrev_b32_e32 v202, 16, v150
	v_and_b32_e32 v203, 0xffff0000, v150
	v_lshlrev_b32_e32 v204, 16, v151
	v_and_b32_e32 v205, 0xffff0000, v151
	v_pk_add_f32 v[4:5], v[4:5], v[202:203]
	v_pk_add_f32 v[6:7], v[6:7], v[204:205]
	v_lshlrev_b32_e32 v202, 16, v152
	v_and_b32_e32 v203, 0xffff0000, v152
	v_lshlrev_b32_e32 v204, 16, v153
	v_and_b32_e32 v205, 0xffff0000, v153
	v_pk_add_f32 v[0:1], v[0:1], v[202:203]
	v_pk_add_f32 v[2:3], v[2:3], v[204:205]
	v_cvt_pk_bf16_f32 v150, v4, v5
	v_cvt_pk_bf16_f32 v151, v6, v7
	v_cvt_pk_bf16_f32 v152, v0, v1
	v_cvt_pk_bf16_f32 v153, v2, v3
	v_pk_fma_f32 v[138:139], v[4:5], v[4:5], v[138:139]
	global_store_dwordx4 v207, v[150:153], s[8:9] offset:256
	v_pk_fma_f32 v[138:139], v[6:7], v[6:7], v[138:139]
	v_pk_fma_f32 v[138:139], v[0:1], v[0:1], v[138:139]
	v_pk_fma_f32 v[138:139], v[2:3], v[2:3], v[138:139]
	v_add_f32_e32 v214, v138, v139
	v_add_u32_e32 v207, 0x8000, v207
	v_mov_b32_e32 v215, v214
	s_nop 1
	v_permlane16_swap_b32_e32 v214, v215
	s_nop 0
	v_add_f32_e32 v214, v214, v215
	v_mov_b32_e32 v215, v214
	s_nop 1
	v_permlane32_swap_b32_e32 v214, v215
	s_nop 0
	v_add_f32_e32 v214, v214, v215
	s_and_saveexec_b64 s[26:27], s[4:5]
	global_store_dword v210, v214, s[14:15] offset:3072
	s_mov_b64 exec, s[26:27]
	s_branch .LBB0_870

.LBB0_921:
	s_add_u32 s8, s6, 0xfffe0080
	s_addc_u32 s9, s7, -1
	s_add_i32 s84, 0, 0x10000
	v_add_u32_e32 v140, s84, v253
	ds_read_b128 v[128:131], v140
	ds_read_b128 v[132:135], v140 offset:1024
	ds_read_b128 v[136:139], v140 offset:2048
	ds_read_b128 v[140:143], v140 offset:3072
	s_cmp_eq_u32 s73, 12
	s_cselect_b32 s11, s15, s9
	s_cselect_b32 s10, s39, s8
	s_cselect_b32 s9, s65, vcc_hi
	s_cselect_b32 s8, s67, vcc_lo
	s_add_i32 m0, s46, 0xc000
	ds_read_b128 v[144:147], v251
	ds_read_b128 v[148:151], v251 offset:1024
	ds_read_b128 v[152:155], v251 offset:2048
	ds_read_b128 v[156:159], v251 offset:3072
	ds_read_b128 v[160:163], v251 offset:4096
	ds_read_b128 v[164:167], v251 offset:5120
	ds_read_b128 v[168:171], v251 offset:6144
	ds_read_b128 v[172:175], v251 offset:7168
	global_load_lds_dwordx4 v220, s[6:7]
	s_add_i32 m0, s46, 0xe000
	s_nop 0
	global_load_lds_dwordx4 v222, s[6:7]
	s_waitcnt lgkmcnt(8)
	s_barrier
	s_waitcnt lgkmcnt(0)
	s_setprio 1
	v_mfma_f32_16x16x32_bf16 v[124:127], v[128:131], v[144:147], v[124:127]
	v_mfma_f32_16x16x32_bf16 v[120:123], v[136:139], v[144:147], v[120:123]
	v_mfma_f32_16x16x32_bf16 v[92:95], v[128:131], v[152:155], v[92:95]
	v_mfma_f32_16x16x32_bf16 v[44:47], v[136:139], v[152:155], v[44:47]
	v_mfma_f32_16x16x32_bf16 v[84:87], v[128:131], v[160:163], v[84:87]
	v_mfma_f32_16x16x32_bf16 v[40:43], v[136:139], v[160:163], v[40:43]
	v_mfma_f32_16x16x32_bf16 v[76:79], v[128:131], v[168:171], v[76:79]
	v_mfma_f32_16x16x32_bf16 v[36:39], v[136:139], v[168:171], v[36:39]
	v_mfma_f32_16x16x32_bf16 v[124:127], v[132:135], v[148:151], v[124:127]
	v_mfma_f32_16x16x32_bf16 v[120:123], v[140:143], v[148:151], v[120:123]
	v_mfma_f32_16x16x32_bf16 v[92:95], v[132:135], v[156:159], v[92:95]
	v_mfma_f32_16x16x32_bf16 v[44:47], v[140:143], v[156:159], v[44:47]
	v_mfma_f32_16x16x32_bf16 v[84:87], v[132:135], v[164:167], v[84:87]
	v_mfma_f32_16x16x32_bf16 v[40:43], v[140:143], v[164:167], v[40:43]
	v_mfma_f32_16x16x32_bf16 v[76:79], v[132:135], v[172:175], v[76:79]
	v_mfma_f32_16x16x32_bf16 v[36:39], v[140:143], v[172:175], v[36:39]
	s_setprio 0
	s_barrier
	s_add_i32 s86, 0, 0x14000
	s_add_i32 s84, s84, s88
	v_add_u32_e32 v188, s86, v253
	s_add_u32 s98, s8, s40
	s_addc_u32 s99, s9, s41
	s_mov_b32 m0, s84
	ds_read_b128 v[176:179], v188
	ds_read_b128 v[180:183], v188 offset:1024
	ds_read_b128 v[184:187], v188 offset:2048
	ds_read_b128 v[188:191], v188 offset:3072
	global_load_lds_dwordx4 v208, s[8:9]
	s_add_i32 m0, s84, 0x2000
	s_nop 0
	global_load_lds_dwordx4 v214, s[8:9]
	s_barrier
	s_waitcnt lgkmcnt(0)
	s_setprio 1
	v_mfma_f32_16x16x32_bf16 v[116:119], v[176:179], v[144:147], v[116:119]
	v_mfma_f32_16x16x32_bf16 v[112:115], v[184:187], v[144:147], v[112:115]
	v_mfma_f32_16x16x32_bf16 v[88:91], v[176:179], v[152:155], v[88:91]
	v_mfma_f32_16x16x32_bf16 v[32:35], v[184:187], v[152:155], v[32:35]
	v_mfma_f32_16x16x32_bf16 v[80:83], v[176:179], v[160:163], v[80:83]
	v_mfma_f32_16x16x32_bf16 v[28:31], v[184:187], v[160:163], v[28:31]
	v_mfma_f32_16x16x32_bf16 v[72:75], v[176:179], v[168:171], v[72:75]
	v_mfma_f32_16x16x32_bf16 v[24:27], v[184:187], v[168:171], v[24:27]
	v_mfma_f32_16x16x32_bf16 v[116:119], v[180:183], v[148:151], v[116:119]
	v_mfma_f32_16x16x32_bf16 v[112:115], v[188:191], v[148:151], v[112:115]
	v_mfma_f32_16x16x32_bf16 v[88:91], v[180:183], v[156:159], v[88:91]
	v_mfma_f32_16x16x32_bf16 v[32:35], v[188:191], v[156:159], v[32:35]
	v_mfma_f32_16x16x32_bf16 v[80:83], v[180:183], v[164:167], v[80:83]
	v_mfma_f32_16x16x32_bf16 v[28:31], v[188:191], v[164:167], v[28:31]
	v_mfma_f32_16x16x32_bf16 v[72:75], v[180:183], v[172:175], v[72:75]
	v_mfma_f32_16x16x32_bf16 v[24:27], v[188:191], v[172:175], v[24:27]
	s_setprio 0
	s_mov_b32 m0, s46
	s_add_u32 s100, s10, s40
	s_addc_u32 s101, s11, s41
	s_barrier
	ds_read_b128 v[144:147], v251 offset:16384
	ds_read_b128 v[148:151], v251 offset:17408
	ds_read_b128 v[152:155], v251 offset:18432
	ds_read_b128 v[156:159], v251 offset:19456
	ds_read_b128 v[160:163], v251 offset:20480
	ds_read_b128 v[164:167], v251 offset:21504
	ds_read_b128 v[168:171], v251 offset:22528
	ds_read_b128 v[172:175], v251 offset:23552
	global_load_lds_dwordx4 v218, s[10:11]
	s_mov_b32 m0, s50
	s_nop 0
	global_load_lds_dwordx4 v216, s[10:11]
	s_barrier
	s_waitcnt lgkmcnt(0)
	s_setprio 1
	v_mfma_f32_16x16x32_bf16 v[68:71], v[128:131], v[144:147], v[68:71]
	v_mfma_f32_16x16x32_bf16 v[20:23], v[136:139], v[144:147], v[20:23]
	v_mfma_f32_16x16x32_bf16 v[64:67], v[128:131], v[152:155], v[64:67]
	v_mfma_f32_16x16x32_bf16 v[16:19], v[136:139], v[152:155], v[16:19]
	v_mfma_f32_16x16x32_bf16 v[60:63], v[128:131], v[160:163], v[60:63]
	v_mfma_f32_16x16x32_bf16 v[12:15], v[136:139], v[160:163], v[12:15]
	v_mfma_f32_16x16x32_bf16 v[108:111], v[128:131], v[168:171], v[108:111]
	v_mfma_f32_16x16x32_bf16 v[104:107], v[136:139], v[168:171], v[104:107]
	v_mfma_f32_16x16x32_bf16 v[68:71], v[132:135], v[148:151], v[68:71]
	v_mfma_f32_16x16x32_bf16 v[20:23], v[140:143], v[148:151], v[20:23]
	v_mfma_f32_16x16x32_bf16 v[64:67], v[132:135], v[156:159], v[64:67]
	v_mfma_f32_16x16x32_bf16 v[16:19], v[140:143], v[156:159], v[16:19]
	v_mfma_f32_16x16x32_bf16 v[60:63], v[132:135], v[164:167], v[60:63]
	v_mfma_f32_16x16x32_bf16 v[12:15], v[140:143], v[164:167], v[12:15]
	v_mfma_f32_16x16x32_bf16 v[108:111], v[132:135], v[172:175], v[108:111]
	v_mfma_f32_16x16x32_bf16 v[104:107], v[140:143], v[172:175], v[104:107]
	s_setprio 0
	s_barrier
	s_add_u32 s84, s8, 0x40000
	s_addc_u32 s85, s9, 0
	s_add_i32 s86, s86, s88
	s_mov_b32 m0, s86
	s_nop 0
	global_load_lds_dwordx4 v208, s[84:85]
	s_add_i32 m0, s86, 0x2000
	s_nop 0
	global_load_lds_dwordx4 v214, s[84:85]
	s_waitcnt vmcnt(6)
	s_barrier
	s_setprio 1
	v_mfma_f32_16x16x32_bf16 v[56:59], v[176:179], v[144:147], v[56:59]
	v_mfma_f32_16x16x32_bf16 v[8:11], v[184:187], v[144:147], v[8:11]
	v_mfma_f32_16x16x32_bf16 v[52:55], v[176:179], v[152:155], v[52:55]
	v_mfma_f32_16x16x32_bf16 v[4:7], v[184:187], v[152:155], v[4:7]
	v_mfma_f32_16x16x32_bf16 v[48:51], v[176:179], v[160:163], v[48:51]
	v_mfma_f32_16x16x32_bf16 v[0:3], v[184:187], v[160:163], v[0:3]
	v_mfma_f32_16x16x32_bf16 v[100:103], v[176:179], v[168:171], v[100:103]
	v_mfma_f32_16x16x32_bf16 v[96:99], v[184:187], v[168:171], v[96:99]
	v_mfma_f32_16x16x32_bf16 v[56:59], v[180:183], v[148:151], v[56:59]
	v_mfma_f32_16x16x32_bf16 v[8:11], v[188:191], v[148:151], v[8:11]
	v_mfma_f32_16x16x32_bf16 v[52:55], v[180:183], v[156:159], v[52:55]
	v_mfma_f32_16x16x32_bf16 v[4:7], v[188:191], v[156:159], v[4:7]
	v_mfma_f32_16x16x32_bf16 v[48:51], v[180:183], v[164:167], v[48:51]
	v_mfma_f32_16x16x32_bf16 v[0:3], v[188:191], v[164:167], v[0:3]
	v_mfma_f32_16x16x32_bf16 v[100:103], v[180:183], v[172:175], v[100:103]
	v_mfma_f32_16x16x32_bf16 v[96:99], v[188:191], v[172:175], v[96:99]
	s_setprio 0
	s_add_i32 s84, 0, 0x18000
	v_add_u32_e32 v140, s84, v253
	s_barrier
	ds_read_b128 v[128:131], v140
	ds_read_b128 v[132:135], v140 offset:1024
	ds_read_b128 v[136:139], v140 offset:2048
	ds_read_b128 v[140:143], v140 offset:3072
	s_add_u32 s10, s10, 0x20000
	s_addc_u32 s11, s11, 0
	s_mov_b32 m0, s51
	ds_read_b128 v[144:147], v251 offset:32768
	ds_read_b128 v[148:151], v251 offset:33792
	ds_read_b128 v[152:155], v251 offset:34816
	ds_read_b128 v[156:159], v251 offset:35840
	ds_read_b128 v[160:163], v251 offset:36864
	ds_read_b128 v[164:167], v251 offset:37888
	ds_read_b128 v[168:171], v251 offset:38912
	ds_read_b128 v[172:175], v251 offset:39936
	global_load_lds_dwordx4 v218, s[10:11]
	s_mov_b32 m0, s34
	s_nop 0
	global_load_lds_dwordx4 v216, s[10:11]
	s_waitcnt lgkmcnt(8)
	s_barrier
	s_waitcnt lgkmcnt(0)
	s_setprio 1
	v_mfma_f32_16x16x32_bf16 v[124:127], v[128:131], v[144:147], v[124:127]
	v_mfma_f32_16x16x32_bf16 v[120:123], v[136:139], v[144:147], v[120:123]
	v_mfma_f32_16x16x32_bf16 v[92:95], v[128:131], v[152:155], v[92:95]
	v_mfma_f32_16x16x32_bf16 v[44:47], v[136:139], v[152:155], v[44:47]
	v_mfma_f32_16x16x32_bf16 v[84:87], v[128:131], v[160:163], v[84:87]
	v_mfma_f32_16x16x32_bf16 v[40:43], v[136:139], v[160:163], v[40:43]
	v_mfma_f32_16x16x32_bf16 v[76:79], v[128:131], v[168:171], v[76:79]
	v_mfma_f32_16x16x32_bf16 v[36:39], v[136:139], v[168:171], v[36:39]
	v_mfma_f32_16x16x32_bf16 v[124:127], v[132:135], v[148:151], v[124:127]
	v_mfma_f32_16x16x32_bf16 v[120:123], v[140:143], v[148:151], v[120:123]
	v_mfma_f32_16x16x32_bf16 v[92:95], v[132:135], v[156:159], v[92:95]
	v_mfma_f32_16x16x32_bf16 v[44:47], v[140:143], v[156:159], v[44:47]
	v_mfma_f32_16x16x32_bf16 v[84:87], v[132:135], v[164:167], v[84:87]
	v_mfma_f32_16x16x32_bf16 v[40:43], v[140:143], v[164:167], v[40:43]
	v_mfma_f32_16x16x32_bf16 v[76:79], v[132:135], v[172:175], v[76:79]
	v_mfma_f32_16x16x32_bf16 v[36:39], v[140:143], v[172:175], v[36:39]
	s_setprio 0
	s_barrier
	s_add_i32 s10, 0, 0x1c000
	s_add_i32 s11, s84, s88
	v_add_u32_e32 v188, s10, v253
	s_mov_b32 m0, s11
	ds_read_b128 v[176:179], v188
	ds_read_b128 v[180:183], v188 offset:1024
	ds_read_b128 v[184:187], v188 offset:2048
	ds_read_b128 v[188:191], v188 offset:3072
	global_load_lds_dwordx4 v208, s[98:99]
	s_add_i32 m0, s11, 0x2000
	s_nop 0
	global_load_lds_dwordx4 v214, s[98:99]
	s_barrier
	s_waitcnt lgkmcnt(0)
	s_setprio 1
	v_mfma_f32_16x16x32_bf16 v[116:119], v[176:179], v[144:147], v[116:119]
	v_mfma_f32_16x16x32_bf16 v[112:115], v[184:187], v[144:147], v[112:115]
	v_mfma_f32_16x16x32_bf16 v[88:91], v[176:179], v[152:155], v[88:91]
	v_mfma_f32_16x16x32_bf16 v[32:35], v[184:187], v[152:155], v[32:35]
	v_mfma_f32_16x16x32_bf16 v[80:83], v[176:179], v[160:163], v[80:83]
	v_mfma_f32_16x16x32_bf16 v[28:31], v[184:187], v[160:163], v[28:31]
	v_mfma_f32_16x16x32_bf16 v[72:75], v[176:179], v[168:171], v[72:75]
	v_mfma_f32_16x16x32_bf16 v[24:27], v[184:187], v[168:171], v[24:27]
	v_mfma_f32_16x16x32_bf16 v[116:119], v[180:183], v[148:151], v[116:119]
	v_mfma_f32_16x16x32_bf16 v[112:115], v[188:191], v[148:151], v[112:115]
	v_mfma_f32_16x16x32_bf16 v[88:91], v[180:183], v[156:159], v[88:91]
	v_mfma_f32_16x16x32_bf16 v[32:35], v[188:191], v[156:159], v[32:35]
	v_mfma_f32_16x16x32_bf16 v[80:83], v[180:183], v[164:167], v[80:83]
	v_mfma_f32_16x16x32_bf16 v[28:31], v[188:191], v[164:167], v[28:31]
	v_mfma_f32_16x16x32_bf16 v[72:75], v[180:183], v[172:175], v[72:75]
	v_mfma_f32_16x16x32_bf16 v[24:27], v[188:191], v[172:175], v[24:27]
	s_setprio 0
	s_mov_b32 m0, s92
	s_barrier
	ds_read_b128 v[144:147], v251 offset:49152
	ds_read_b128 v[148:151], v251 offset:50176
	ds_read_b128 v[152:155], v251 offset:51200
	ds_read_b128 v[156:159], v251 offset:52224
	ds_read_b128 v[160:163], v251 offset:53248
	ds_read_b128 v[164:167], v251 offset:54272
	ds_read_b128 v[168:171], v251 offset:55296
	ds_read_b128 v[172:175], v251 offset:56320
	global_load_lds_dwordx4 v218, s[100:101]
	s_mov_b32 m0, s93
	s_nop 0
	global_load_lds_dwordx4 v216, s[100:101]
	s_barrier
	s_waitcnt lgkmcnt(0)
	s_setprio 1
	v_mfma_f32_16x16x32_bf16 v[68:71], v[128:131], v[144:147], v[68:71]
	v_mfma_f32_16x16x32_bf16 v[20:23], v[136:139], v[144:147], v[20:23]
	v_mfma_f32_16x16x32_bf16 v[64:67], v[128:131], v[152:155], v[64:67]
	v_mfma_f32_16x16x32_bf16 v[16:19], v[136:139], v[152:155], v[16:19]
	v_mfma_f32_16x16x32_bf16 v[60:63], v[128:131], v[160:163], v[60:63]
	v_mfma_f32_16x16x32_bf16 v[12:15], v[136:139], v[160:163], v[12:15]
	v_mfma_f32_16x16x32_bf16 v[108:111], v[128:131], v[168:171], v[108:111]
	v_mfma_f32_16x16x32_bf16 v[104:107], v[136:139], v[168:171], v[104:107]
	v_mfma_f32_16x16x32_bf16 v[68:71], v[132:135], v[148:151], v[68:71]
	v_mfma_f32_16x16x32_bf16 v[20:23], v[140:143], v[148:151], v[20:23]
	v_mfma_f32_16x16x32_bf16 v[64:67], v[132:135], v[156:159], v[64:67]
	v_mfma_f32_16x16x32_bf16 v[16:19], v[140:143], v[156:159], v[16:19]
	v_mfma_f32_16x16x32_bf16 v[60:63], v[132:135], v[164:167], v[60:63]
	v_mfma_f32_16x16x32_bf16 v[12:15], v[140:143], v[164:167], v[12:15]
	v_mfma_f32_16x16x32_bf16 v[108:111], v[132:135], v[172:175], v[108:111]
	v_mfma_f32_16x16x32_bf16 v[104:107], v[140:143], v[172:175], v[104:107]
	s_setprio 0
	s_barrier
	s_add_u32 s8, s8, 0x40080
	s_addc_u32 s9, s9, 0
	s_add_i32 s10, s10, s88
	s_mov_b32 m0, s10
	s_nop 0
	global_load_lds_dwordx4 v208, s[8:9]
	s_add_i32 m0, s10, 0x2000
	s_nop 0
	global_load_lds_dwordx4 v214, s[8:9]
	s_waitcnt vmcnt(6)
	s_barrier
	s_setprio 1
	v_mfma_f32_16x16x32_bf16 v[56:59], v[176:179], v[144:147], v[56:59]
	v_mfma_f32_16x16x32_bf16 v[8:11], v[184:187], v[144:147], v[8:11]
	v_mfma_f32_16x16x32_bf16 v[52:55], v[176:179], v[152:155], v[52:55]
	v_mfma_f32_16x16x32_bf16 v[4:7], v[184:187], v[152:155], v[4:7]
	v_mfma_f32_16x16x32_bf16 v[48:51], v[176:179], v[160:163], v[48:51]
	v_mfma_f32_16x16x32_bf16 v[0:3], v[184:187], v[160:163], v[0:3]
	v_mfma_f32_16x16x32_bf16 v[100:103], v[176:179], v[168:171], v[100:103]
	v_mfma_f32_16x16x32_bf16 v[96:99], v[184:187], v[168:171], v[96:99]
	v_mfma_f32_16x16x32_bf16 v[56:59], v[180:183], v[148:151], v[56:59]
	v_mfma_f32_16x16x32_bf16 v[8:11], v[188:191], v[148:151], v[8:11]
	v_mfma_f32_16x16x32_bf16 v[52:55], v[180:183], v[156:159], v[52:55]
	v_mfma_f32_16x16x32_bf16 v[4:7], v[188:191], v[156:159], v[4:7]
	v_mfma_f32_16x16x32_bf16 v[48:51], v[180:183], v[164:167], v[48:51]
	v_mfma_f32_16x16x32_bf16 v[0:3], v[188:191], v[164:167], v[0:3]
	v_mfma_f32_16x16x32_bf16 v[100:103], v[180:183], v[172:175], v[100:103]
	v_mfma_f32_16x16x32_bf16 v[96:99], v[188:191], v[172:175], v[96:99]
	s_setprio 0
	s_add_i32 s73, s73, 2
	s_add_u32 s6, s6, 0x100
	s_addc_u32 s7, s7, 0
	s_add_u32 vcc_lo, vcc_lo, 0x100
	s_addc_u32 vcc_hi, vcc_hi, 0
	s_cmp_gt_u32 s73, 13
	s_barrier
	s_cbranch_scc0 .LBB0_921
	s_lshl_b32 s6, s38, 8
	v_mov_b32_e32 v250, v210
	v_mov_b32_e32 v254, v249
	s_add_i32 s6, s6, s90
	v_mov_b64_e32 v[242:243], s[44:45]
	v_add_u32_e32 v234, s6, v254
	v_ashrrev_i32_e32 v235, 31, v234
	v_mbcnt_lo_u32_b32 v212, -1, 0
	v_mbcnt_hi_u32_b32 v212, -1, v212
	v_lshlrev_b32_e32 v244, 6, v234
	v_and_b32_e32 v212, 48, v212
	v_add_u32_e32 v212, v244, v212
	v_add_u32_e32 v213, 0x1000, v212
	v_add_u32_e32 v245, 0x1000, v244
	global_load_dwordx4 v[192:195], v212, s[20:21]
	global_load_dwordx4 v[196:199], v212, s[20:21] offset:1024
	global_load_dwordx4 v[200:203], v213, s[20:21] offset:2048
	global_load_dwordx4 v[204:207], v213, s[20:21] offset:3072
	global_load_dwordx4 v[160:163], v244, s[20:21] offset:2096
	global_load_dwordx4 v[164:167], v244, s[20:21] offset:2080
	global_load_dwordx4 v[176:179], v244, s[20:21] offset:2064
	global_load_dwordx4 v[180:183], v244, s[20:21] offset:2048
	global_load_dwordx4 v[168:171], v244, s[20:21] offset:3120
	global_load_dwordx4 v[172:175], v244, s[20:21] offset:3104
	global_load_dwordx4 v[184:187], v244, s[20:21] offset:3088
	global_load_dwordx4 v[188:191], v244, s[20:21] offset:3072
	global_load_dwordx4 v[144:147], v245, s[20:21] offset:48
	global_load_dwordx4 v[148:151], v245, s[20:21] offset:32
	global_load_dwordx4 v[152:155], v245, s[20:21] offset:16
	global_load_dwordx4 v[156:159], v245, s[20:21]
	global_load_dwordx4 v[128:131], v245, s[20:21] offset:1072
	global_load_dwordx4 v[132:135], v245, s[20:21] offset:1056
	global_load_dwordx4 v[136:139], v245, s[20:21] offset:1040
	global_load_dwordx4 v[140:143], v245, s[20:21] offset:1024
	v_add_u32_e32 v236, 16, v234
	v_ashrrev_i32_e32 v237, 31, v236
	v_add_u32_e32 v238, 32, v234
	v_ashrrev_i32_e32 v239, 31, v238
	v_add_u32_e32 v232, 48, v234
	v_ashrrev_i32_e32 v233, 31, v232
	v_add_u32_e32 v230, 64, v234
	v_ashrrev_i32_e32 v231, 31, v230
	v_add_u32_e32 v228, 0x50, v234
	v_ashrrev_i32_e32 v229, 31, v228
	v_add_u32_e32 v224, 0x60, v234
	v_ashrrev_i32_e32 v225, 31, v224
	v_add_u32_e32 v226, 0x70, v234
	v_ashrrev_i32_e32 v227, 31, v226
	s_lshl_b32 s14, s14, 7
	s_or_b32 s14, s14, s35
	s_waitcnt vmcnt(16)
	v_pk_add_f32 v[192:193], v[192:193], v[194:195]
	s_nop 0
	v_add_f32_e32 v246, v192, v193
	v_mov_b32_e32 v247, v246
	s_nop 1
	v_permlane16_swap_b32_e32 v246, v247
	s_nop 0
	v_add_f32_e32 v246, v246, v247
	v_mov_b32_e32 v247, v246
	s_nop 1
	v_permlane32_swap_b32_e32 v246, v247
	s_nop 0
	v_add_f32_e32 v193, v246, v247
	v_pk_add_f32 v[196:197], v[196:197], v[198:199]
	s_nop 0
	v_add_f32_e32 v246, v196, v197
	v_mov_b32_e32 v247, v246
	s_nop 1
	v_permlane16_swap_b32_e32 v246, v247
	s_nop 0
	v_add_f32_e32 v246, v246, v247
	v_mov_b32_e32 v247, v246
	s_nop 1
	v_permlane32_swap_b32_e32 v246, v247
	s_nop 0
	v_add_f32_e32 v192, v246, v247
	v_pk_add_f32 v[200:201], v[200:201], v[202:203]
	s_nop 0
	v_add_f32_e32 v246, v200, v201
	v_mov_b32_e32 v247, v246
	s_nop 1
	v_permlane16_swap_b32_e32 v246, v247
	s_nop 0
	v_add_f32_e32 v246, v246, v247
	v_mov_b32_e32 v247, v246
	s_nop 1
	v_permlane32_swap_b32_e32 v246, v247
	s_nop 0
	v_add_f32_e32 v197, v246, v247
	v_pk_add_f32 v[204:205], v[204:205], v[206:207]
	s_nop 0
	v_add_f32_e32 v246, v204, v205
	v_mov_b32_e32 v247, v246
	s_nop 1
	v_permlane16_swap_b32_e32 v246, v247
	s_nop 0
	v_add_f32_e32 v246, v246, v247
	v_mov_b32_e32 v247, v246
	s_nop 1
	v_permlane32_swap_b32_e32 v246, v247
	s_nop 0
	v_add_f32_e32 v196, v246, v247
	s_nop 0
	v_pk_fma_f32 v[240:241], v[192:193], s[42:43], v[242:243] op_sel_hi:[1,0,0]
	v_pk_fma_f32 v[202:203], v[196:197], s[42:43], v[242:243] op_sel_hi:[1,0,0]
	v_cmp_gt_f32_e64 s[6:7], s97, v240
	v_cmp_gt_f32_e32 vcc, s97, v241
	s_waitcnt vmcnt(0)
	v_lshl_add_u32 v192, v250, 3, s14
	v_add_u32_e32 v193, -14, v254
	v_cmp_gt_f32_e64 s[8:9], s97, v203
	v_cmp_gt_f32_e64 s[10:11], s97, v202
	v_cmp_lt_u32_e64 s[14:15], -13, v193
	v_ashrrev_i32_e32 v193, 31, v192
	s_and_saveexec_b64 s[86:87], s[14:15]
	s_xor_b64 s[14:15], exec, s[86:87]
	s_or_saveexec_b64 s[14:15], s[14:15]
	v_mul_f32_e32 v194, 0x4b800000, v241
	v_cndmask_b32_e32 v194, v241, v194, vcc
	v_rsq_f32_e32 v194, v194
	s_nop 0
	v_mul_f32_e32 v195, 0x45800000, v194
	v_cndmask_b32_e32 v204, v194, v195, vcc
	v_pk_mul_f32 v[196:197], v[118:119], v[204:205] op_sel_hi:[1,0]
	v_mul_f32_e32 v118, 0x4b800000, v202
	v_cndmask_b32_e64 v118, v202, v118, s[10:11]
	v_rsq_f32_e32 v118, v118
	v_pk_mul_f32 v[200:201], v[116:117], v[204:205] op_sel_hi:[1,0]
	v_pk_mul_f32 v[194:195], v[126:127], v[204:205] op_sel_hi:[1,0]
	v_pk_mul_f32 v[198:199], v[124:125], v[204:205] op_sel_hi:[1,0]
	v_mul_f32_e32 v116, 0x45800000, v118
	v_cndmask_b32_e64 v116, v118, v116, s[10:11]
	v_pk_mul_f32 v[122:123], v[122:123], v[204:205] op_sel_hi:[1,0]
	v_pk_mul_f32 v[120:121], v[120:121], v[204:205] op_sel_hi:[1,0]
	v_pk_mul_f32 v[114:115], v[114:115], v[204:205] op_sel_hi:[1,0]
	v_pk_mul_f32 v[112:113], v[112:113], v[204:205] op_sel_hi:[1,0]
	v_pk_mul_f32 v[110:111], v[110:111], v[116:117] op_sel_hi:[1,0]
	v_pk_mul_f32 v[108:109], v[108:109], v[116:117] op_sel_hi:[1,0]
	v_pk_mul_f32 v[106:107], v[106:107], v[116:117] op_sel_hi:[1,0]
	v_pk_mul_f32 v[104:105], v[104:105], v[116:117] op_sel_hi:[1,0]
	v_pk_mul_f32 v[102:103], v[102:103], v[116:117] op_sel_hi:[1,0]
	v_pk_mul_f32 v[100:101], v[100:101], v[116:117] op_sel_hi:[1,0]
	v_pk_mul_f32 v[98:99], v[98:99], v[116:117] op_sel_hi:[1,0]
	v_pk_mul_f32 v[96:97], v[96:97], v[116:117] op_sel_hi:[1,0]
	s_xor_b64 exec, exec, s[14:15]
	s_cbranch_execz .LBB0_917
	v_add_u32_e32 v116, -12, v254
	v_cmp_gt_i32_e64 s[10:11], 2, v254
	s_lshl_b32 s38, s38, 3
	s_add_i32 s38, s38, s91
	v_cndmask_b32_e64 v116, v116, v254, s[10:11]
	v_add_u32_e32 v126, s38, v116
	v_mov_b64_e32 v[124:125], s[22:23]
	s_movk_i32 s38, 0x5800
	v_mad_i64_i32 v[124:125], s[38:39], v126, s38, v[124:125]
	v_cndmask_b32_e64 v119, v111, v195, s[10:11]
	v_cndmask_b32_e64 v118, v110, v194, s[10:11]
	v_cndmask_b32_e64 v117, v109, v199, s[10:11]
	v_cndmask_b32_e64 v116, v108, v198, s[10:11]
	v_lshl_add_u64 v[124:125], v[192:193], 2, v[124:125]
	s_mov_b64 s[38:39], 0x2c00
	global_store_dwordx4 v[124:125], v[116:119], off
	v_lshl_add_u64 v[126:127], v[124:125], 0, s[38:39]
	s_movk_i32 s38, 0x2000
	v_cndmask_b32_e64 v119, v107, v123, s[10:11]
	v_cndmask_b32_e64 v118, v106, v122, s[10:11]
	v_cndmask_b32_e64 v117, v105, v121, s[10:11]
	v_cndmask_b32_e64 v116, v104, v120, s[10:11]
	global_store_dwordx4 v[124:125], v[116:119], off offset:16
	v_add_co_u32_e32 v124, vcc, s38, v124
	s_nop 0
	v_cndmask_b32_e64 v119, v103, v197, s[10:11]
	v_cndmask_b32_e64 v118, v102, v196, s[10:11]
	v_cndmask_b32_e64 v117, v101, v201, s[10:11]
	v_cndmask_b32_e64 v116, v100, v200, s[10:11]
	v_addc_co_u32_e32 v125, vcc, 0, v125, vcc
	global_store_dwordx4 v[124:125], v[116:119], off offset:3072
	s_nop 1
	v_cndmask_b32_e64 v119, v99, v115, s[10:11]
	v_cndmask_b32_e64 v118, v98, v114, s[10:11]
	v_cndmask_b32_e64 v117, v97, v113, s[10:11]
	v_cndmask_b32_e64 v116, v96, v112, s[10:11]
	global_store_dwordx4 v[126:127], v[116:119], off offset:16
	s_branch .LBB0_917

.LBB0_998:
	s_add_u32 s20, s10, 0x100
	s_addc_u32 s21, s11, 0
	s_add_i32 s60, 0, 0x10000
	v_add_u32_e32 v142, s60, v145
	ds_read_b128 v[138:141], v142
	ds_read_b128 v[148:151], v142 offset:1024
	ds_read_b128 v[152:155], v142 offset:2048
	ds_read_b128 v[156:159], v142 offset:3072
	s_cmp_eq_u32 s59, 40
	s_cselect_b32 s25, s7, s21
	s_cselect_b32 s24, s6, s20
	s_cselect_b32 s23, s9, s58
	s_cselect_b32 s22, s8, s57
	v_lshl_add_u64 v[142:143], s[10:11], 0, v[134:135]
	s_add_i32 m0, s34, 0xc000
	ds_read_b128 v[160:163], v147
	ds_read_b128 v[164:167], v147 offset:1024
	ds_read_b128 v[168:171], v147 offset:2048
	ds_read_b128 v[172:175], v147 offset:3072
	ds_read_b128 v[176:179], v147 offset:4096
	ds_read_b128 v[180:183], v147 offset:5120
	ds_read_b128 v[184:187], v147 offset:6144
	ds_read_b128 v[188:191], v147 offset:7168
	global_load_lds_dwordx4 v[142:143], off
	v_lshl_add_u64 v[142:143], s[10:11], 0, v[136:137]
	s_add_i32 m0, s34, 0xe000
	s_nop 0
	global_load_lds_dwordx4 v[142:143], off
	s_waitcnt lgkmcnt(8)
	s_barrier
	s_waitcnt lgkmcnt(0)
	s_setprio 1
	v_mfma_f32_16x16x32_bf16 v[124:127], v[138:141], v[160:163], v[124:127]
	v_mfma_f32_16x16x32_bf16 v[120:123], v[152:155], v[160:163], v[120:123]
	v_mfma_f32_16x16x32_bf16 v[108:111], v[138:141], v[168:171], v[108:111]
	v_mfma_f32_16x16x32_bf16 v[104:107], v[152:155], v[168:171], v[104:107]
	v_mfma_f32_16x16x32_bf16 v[92:95], v[138:141], v[176:179], v[92:95]
	v_mfma_f32_16x16x32_bf16 v[88:91], v[152:155], v[176:179], v[88:91]
	v_mfma_f32_16x16x32_bf16 v[76:79], v[138:141], v[184:187], v[76:79]
	v_mfma_f32_16x16x32_bf16 v[72:75], v[152:155], v[184:187], v[72:75]
	v_mfma_f32_16x16x32_bf16 v[124:127], v[148:151], v[164:167], v[124:127]
	v_mfma_f32_16x16x32_bf16 v[120:123], v[156:159], v[164:167], v[120:123]
	v_mfma_f32_16x16x32_bf16 v[108:111], v[148:151], v[172:175], v[108:111]
	v_mfma_f32_16x16x32_bf16 v[104:107], v[156:159], v[172:175], v[104:107]
	v_mfma_f32_16x16x32_bf16 v[92:95], v[148:151], v[180:183], v[92:95]
	v_mfma_f32_16x16x32_bf16 v[88:91], v[156:159], v[180:183], v[88:91]
	v_mfma_f32_16x16x32_bf16 v[76:79], v[148:151], v[188:191], v[76:79]
	v_mfma_f32_16x16x32_bf16 v[72:75], v[156:159], v[188:191], v[72:75]
	s_setprio 0
	s_barrier
	s_add_i32 s61, 0, 0x14000
	v_add_u32_e32 v142, s61, v145
	s_add_i32 s10, s60, s27
	ds_read_b128 v[192:195], v142
	ds_read_b128 v[196:199], v142 offset:1024
	ds_read_b128 v[200:203], v142 offset:2048
	ds_read_b128 v[204:207], v142 offset:3072
	s_add_u32 s98, s22, s40
	s_addc_u32 s99, s23, s41
	s_mov_b32 m0, s10
	s_nop 0
	global_load_lds_dwordx4 v208, s[22:23]
	s_add_i32 m0, s10, 0x2000
	s_nop 0
	global_load_lds_dwordx4 v128, s[22:23]
	s_barrier
	s_waitcnt lgkmcnt(0)
	s_setprio 1
	v_mfma_f32_16x16x32_bf16 v[116:119], v[192:195], v[160:163], v[116:119]
	v_mfma_f32_16x16x32_bf16 v[112:115], v[200:203], v[160:163], v[112:115]
	v_mfma_f32_16x16x32_bf16 v[100:103], v[192:195], v[168:171], v[100:103]
	v_mfma_f32_16x16x32_bf16 v[96:99], v[200:203], v[168:171], v[96:99]
	v_mfma_f32_16x16x32_bf16 v[84:87], v[192:195], v[176:179], v[84:87]
	v_mfma_f32_16x16x32_bf16 v[80:83], v[200:203], v[176:179], v[80:83]
	v_mfma_f32_16x16x32_bf16 v[68:71], v[192:195], v[184:187], v[68:71]
	v_mfma_f32_16x16x32_bf16 v[64:67], v[200:203], v[184:187], v[64:67]
	v_mfma_f32_16x16x32_bf16 v[116:119], v[196:199], v[164:167], v[116:119]
	v_mfma_f32_16x16x32_bf16 v[112:115], v[204:207], v[164:167], v[112:115]
	v_mfma_f32_16x16x32_bf16 v[100:103], v[196:199], v[172:175], v[100:103]
	v_mfma_f32_16x16x32_bf16 v[96:99], v[204:207], v[172:175], v[96:99]
	v_mfma_f32_16x16x32_bf16 v[84:87], v[196:199], v[180:183], v[84:87]
	v_mfma_f32_16x16x32_bf16 v[80:83], v[204:207], v[180:183], v[80:83]
	v_mfma_f32_16x16x32_bf16 v[68:71], v[196:199], v[188:191], v[68:71]
	v_mfma_f32_16x16x32_bf16 v[64:67], v[204:207], v[188:191], v[64:67]
	s_setprio 0
	s_mov_b32 m0, s34
	s_add_u32 s100, s24, s40
	s_addc_u32 s101, s25, s41
	s_barrier
	ds_read_b128 v[160:163], v147 offset:16384
	ds_read_b128 v[164:167], v147 offset:17408
	ds_read_b128 v[168:171], v147 offset:18432
	ds_read_b128 v[172:175], v147 offset:19456
	ds_read_b128 v[176:179], v147 offset:20480
	ds_read_b128 v[180:183], v147 offset:21504
	ds_read_b128 v[184:187], v147 offset:22528
	ds_read_b128 v[188:191], v147 offset:23552
	global_load_lds_dwordx4 v132, s[24:25]
	s_mov_b32 m0, s35
	s_nop 0
	global_load_lds_dwordx4 v130, s[24:25]
	s_barrier
	s_waitcnt lgkmcnt(0)
	s_setprio 1
	v_mfma_f32_16x16x32_bf16 v[60:63], v[138:141], v[160:163], v[60:63]
	v_mfma_f32_16x16x32_bf16 v[56:59], v[152:155], v[160:163], v[56:59]
	v_mfma_f32_16x16x32_bf16 v[44:47], v[138:141], v[168:171], v[44:47]
	v_mfma_f32_16x16x32_bf16 v[40:43], v[152:155], v[168:171], v[40:43]
	v_mfma_f32_16x16x32_bf16 v[28:31], v[138:141], v[176:179], v[28:31]
	v_mfma_f32_16x16x32_bf16 v[24:27], v[152:155], v[176:179], v[24:27]
	v_mfma_f32_16x16x32_bf16 v[12:15], v[138:141], v[184:187], v[12:15]
	v_mfma_f32_16x16x32_bf16 v[8:11], v[152:155], v[184:187], v[8:11]
	v_mfma_f32_16x16x32_bf16 v[60:63], v[148:151], v[164:167], v[60:63]
	v_mfma_f32_16x16x32_bf16 v[56:59], v[156:159], v[164:167], v[56:59]
	v_mfma_f32_16x16x32_bf16 v[44:47], v[148:151], v[172:175], v[44:47]
	v_mfma_f32_16x16x32_bf16 v[40:43], v[156:159], v[172:175], v[40:43]
	v_mfma_f32_16x16x32_bf16 v[28:31], v[148:151], v[180:183], v[28:31]
	v_mfma_f32_16x16x32_bf16 v[24:27], v[156:159], v[180:183], v[24:27]
	v_mfma_f32_16x16x32_bf16 v[12:15], v[148:151], v[188:191], v[12:15]
	v_mfma_f32_16x16x32_bf16 v[8:11], v[156:159], v[188:191], v[8:11]
	s_setprio 0
	s_barrier
	s_add_u32 s10, s22, 0xb0000
	s_addc_u32 s11, s23, 0
	s_add_i32 s60, s61, s27
	s_mov_b32 m0, s60
	s_nop 0
	global_load_lds_dwordx4 v208, s[10:11]
	s_add_i32 m0, s60, 0x2000
	s_nop 0
	global_load_lds_dwordx4 v128, s[10:11]
	s_waitcnt vmcnt(6)
	s_barrier
	s_setprio 1
	v_mfma_f32_16x16x32_bf16 v[52:55], v[192:195], v[160:163], v[52:55]
	v_mfma_f32_16x16x32_bf16 v[48:51], v[200:203], v[160:163], v[48:51]
	v_mfma_f32_16x16x32_bf16 v[36:39], v[192:195], v[168:171], v[36:39]
	v_mfma_f32_16x16x32_bf16 v[32:35], v[200:203], v[168:171], v[32:35]
	v_mfma_f32_16x16x32_bf16 v[20:23], v[192:195], v[176:179], v[20:23]
	v_mfma_f32_16x16x32_bf16 v[16:19], v[200:203], v[176:179], v[16:19]
	v_mfma_f32_16x16x32_bf16 v[4:7], v[192:195], v[184:187], v[4:7]
	v_mfma_f32_16x16x32_bf16 v[0:3], v[200:203], v[184:187], v[0:3]
	v_mfma_f32_16x16x32_bf16 v[52:55], v[196:199], v[164:167], v[52:55]
	v_mfma_f32_16x16x32_bf16 v[48:51], v[204:207], v[164:167], v[48:51]
	v_mfma_f32_16x16x32_bf16 v[36:39], v[196:199], v[172:175], v[36:39]
	v_mfma_f32_16x16x32_bf16 v[32:35], v[204:207], v[172:175], v[32:35]
	v_mfma_f32_16x16x32_bf16 v[20:23], v[196:199], v[180:183], v[20:23]
	v_mfma_f32_16x16x32_bf16 v[16:19], v[204:207], v[180:183], v[16:19]
	v_mfma_f32_16x16x32_bf16 v[4:7], v[196:199], v[188:191], v[4:7]
	v_mfma_f32_16x16x32_bf16 v[0:3], v[204:207], v[188:191], v[0:3]
	s_setprio 0
	s_add_i32 s60, 0, 0x18000
	v_add_u32_e32 v156, s60, v145
	s_barrier
	ds_read_b128 v[138:141], v156
	ds_read_b128 v[148:151], v156 offset:1024
	ds_read_b128 v[152:155], v156 offset:2048
	ds_read_b128 v[156:159], v156 offset:3072
	s_add_u32 s10, s24, 0xb0000
	s_addc_u32 s11, s25, 0
	s_mov_b32 m0, s36
	ds_read_b128 v[160:163], v147 offset:32768
	ds_read_b128 v[164:167], v147 offset:33792
	ds_read_b128 v[168:171], v147 offset:34816
	ds_read_b128 v[172:175], v147 offset:35840
	ds_read_b128 v[176:179], v147 offset:36864
	ds_read_b128 v[180:183], v147 offset:37888
	ds_read_b128 v[184:187], v147 offset:38912
	ds_read_b128 v[188:191], v147 offset:39936
	global_load_lds_dwordx4 v132, s[10:11]
	s_mov_b32 m0, s46
	s_nop 0
	global_load_lds_dwordx4 v130, s[10:11]
	s_waitcnt lgkmcnt(8)
	s_barrier
	s_waitcnt lgkmcnt(0)
	s_setprio 1
	v_mfma_f32_16x16x32_bf16 v[124:127], v[138:141], v[160:163], v[124:127]
	v_mfma_f32_16x16x32_bf16 v[120:123], v[152:155], v[160:163], v[120:123]
	v_mfma_f32_16x16x32_bf16 v[108:111], v[138:141], v[168:171], v[108:111]
	v_mfma_f32_16x16x32_bf16 v[104:107], v[152:155], v[168:171], v[104:107]
	v_mfma_f32_16x16x32_bf16 v[92:95], v[138:141], v[176:179], v[92:95]
	v_mfma_f32_16x16x32_bf16 v[88:91], v[152:155], v[176:179], v[88:91]
	v_mfma_f32_16x16x32_bf16 v[76:79], v[138:141], v[184:187], v[76:79]
	v_mfma_f32_16x16x32_bf16 v[72:75], v[152:155], v[184:187], v[72:75]
	v_mfma_f32_16x16x32_bf16 v[124:127], v[148:151], v[164:167], v[124:127]
	v_mfma_f32_16x16x32_bf16 v[120:123], v[156:159], v[164:167], v[120:123]
	v_mfma_f32_16x16x32_bf16 v[108:111], v[148:151], v[172:175], v[108:111]
	v_mfma_f32_16x16x32_bf16 v[104:107], v[156:159], v[172:175], v[104:107]
	v_mfma_f32_16x16x32_bf16 v[92:95], v[148:151], v[180:183], v[92:95]
	v_mfma_f32_16x16x32_bf16 v[88:91], v[156:159], v[180:183], v[88:91]
	v_mfma_f32_16x16x32_bf16 v[76:79], v[148:151], v[188:191], v[76:79]
	v_mfma_f32_16x16x32_bf16 v[72:75], v[156:159], v[188:191], v[72:75]
	s_setprio 0
	s_barrier
	s_add_i32 s24, 0, 0x1c000
	s_add_i32 s10, s60, s27
	v_add_u32_e32 v204, s24, v145
	s_mov_b32 m0, s10
	ds_read_b128 v[192:195], v204
	ds_read_b128 v[196:199], v204 offset:1024
	ds_read_b128 v[200:203], v204 offset:2048
	ds_read_b128 v[204:207], v204 offset:3072
	global_load_lds_dwordx4 v208, s[98:99]
	s_add_i32 m0, s10, 0x2000
	s_nop 0
	global_load_lds_dwordx4 v128, s[98:99]
	s_barrier
	s_waitcnt lgkmcnt(0)
	s_setprio 1
	v_mfma_f32_16x16x32_bf16 v[116:119], v[192:195], v[160:163], v[116:119]
	v_mfma_f32_16x16x32_bf16 v[112:115], v[200:203], v[160:163], v[112:115]
	v_mfma_f32_16x16x32_bf16 v[100:103], v[192:195], v[168:171], v[100:103]
	v_mfma_f32_16x16x32_bf16 v[96:99], v[200:203], v[168:171], v[96:99]
	v_mfma_f32_16x16x32_bf16 v[84:87], v[192:195], v[176:179], v[84:87]
	v_mfma_f32_16x16x32_bf16 v[80:83], v[200:203], v[176:179], v[80:83]
	v_mfma_f32_16x16x32_bf16 v[68:71], v[192:195], v[184:187], v[68:71]
	v_mfma_f32_16x16x32_bf16 v[64:67], v[200:203], v[184:187], v[64:67]
	v_mfma_f32_16x16x32_bf16 v[116:119], v[196:199], v[164:167], v[116:119]
	v_mfma_f32_16x16x32_bf16 v[112:115], v[204:207], v[164:167], v[112:115]
	v_mfma_f32_16x16x32_bf16 v[100:103], v[196:199], v[172:175], v[100:103]
	v_mfma_f32_16x16x32_bf16 v[96:99], v[204:207], v[172:175], v[96:99]
	v_mfma_f32_16x16x32_bf16 v[84:87], v[196:199], v[180:183], v[84:87]
	v_mfma_f32_16x16x32_bf16 v[80:83], v[204:207], v[180:183], v[80:83]
	v_mfma_f32_16x16x32_bf16 v[68:71], v[196:199], v[188:191], v[68:71]
	v_mfma_f32_16x16x32_bf16 v[64:67], v[204:207], v[188:191], v[64:67]
	s_setprio 0
	s_mov_b32 m0, s50
	s_barrier
	ds_read_b128 v[160:163], v147 offset:49152
	ds_read_b128 v[164:167], v147 offset:50176
	ds_read_b128 v[168:171], v147 offset:51200
	ds_read_b128 v[172:175], v147 offset:52224
	ds_read_b128 v[176:179], v147 offset:53248
	ds_read_b128 v[180:183], v147 offset:54272
	ds_read_b128 v[184:187], v147 offset:55296
	ds_read_b128 v[188:191], v147 offset:56320
	global_load_lds_dwordx4 v132, s[100:101]
	s_mov_b32 m0, s51
	s_nop 0
	global_load_lds_dwordx4 v130, s[100:101]
	s_barrier
	s_waitcnt lgkmcnt(0)
	s_setprio 1
	v_mfma_f32_16x16x32_bf16 v[60:63], v[138:141], v[160:163], v[60:63]
	v_mfma_f32_16x16x32_bf16 v[56:59], v[152:155], v[160:163], v[56:59]
	v_mfma_f32_16x16x32_bf16 v[44:47], v[138:141], v[168:171], v[44:47]
	v_mfma_f32_16x16x32_bf16 v[40:43], v[152:155], v[168:171], v[40:43]
	v_mfma_f32_16x16x32_bf16 v[28:31], v[138:141], v[176:179], v[28:31]
	v_mfma_f32_16x16x32_bf16 v[24:27], v[152:155], v[176:179], v[24:27]
	v_mfma_f32_16x16x32_bf16 v[12:15], v[138:141], v[184:187], v[12:15]
	v_mfma_f32_16x16x32_bf16 v[8:11], v[152:155], v[184:187], v[8:11]
	v_mfma_f32_16x16x32_bf16 v[60:63], v[148:151], v[164:167], v[60:63]
	v_mfma_f32_16x16x32_bf16 v[56:59], v[156:159], v[164:167], v[56:59]
	v_mfma_f32_16x16x32_bf16 v[44:47], v[148:151], v[172:175], v[44:47]
	v_mfma_f32_16x16x32_bf16 v[40:43], v[156:159], v[172:175], v[40:43]
	v_mfma_f32_16x16x32_bf16 v[28:31], v[148:151], v[180:183], v[28:31]
	v_mfma_f32_16x16x32_bf16 v[24:27], v[156:159], v[180:183], v[24:27]
	v_mfma_f32_16x16x32_bf16 v[12:15], v[148:151], v[188:191], v[12:15]
	v_mfma_f32_16x16x32_bf16 v[8:11], v[156:159], v[188:191], v[8:11]
	s_setprio 0
	s_barrier
	s_add_u32 s10, s22, 0xb0080
	s_addc_u32 s11, s23, 0
	s_add_i32 s22, s24, s27
	s_mov_b32 m0, s22
	s_nop 0
	global_load_lds_dwordx4 v208, s[10:11]
	s_add_i32 m0, s22, 0x2000
	s_nop 0
	global_load_lds_dwordx4 v128, s[10:11]
	s_waitcnt vmcnt(6)
	s_barrier
	s_setprio 1
	v_mfma_f32_16x16x32_bf16 v[52:55], v[192:195], v[160:163], v[52:55]
	v_mfma_f32_16x16x32_bf16 v[48:51], v[200:203], v[160:163], v[48:51]
	v_mfma_f32_16x16x32_bf16 v[36:39], v[192:195], v[168:171], v[36:39]
	v_mfma_f32_16x16x32_bf16 v[32:35], v[200:203], v[168:171], v[32:35]
	v_mfma_f32_16x16x32_bf16 v[20:23], v[192:195], v[176:179], v[20:23]
	v_mfma_f32_16x16x32_bf16 v[16:19], v[200:203], v[176:179], v[16:19]
	v_mfma_f32_16x16x32_bf16 v[4:7], v[192:195], v[184:187], v[4:7]
	v_mfma_f32_16x16x32_bf16 v[0:3], v[200:203], v[184:187], v[0:3]
	v_mfma_f32_16x16x32_bf16 v[52:55], v[196:199], v[164:167], v[52:55]
	v_mfma_f32_16x16x32_bf16 v[48:51], v[204:207], v[164:167], v[48:51]
	v_mfma_f32_16x16x32_bf16 v[36:39], v[196:199], v[172:175], v[36:39]
	v_mfma_f32_16x16x32_bf16 v[32:35], v[204:207], v[172:175], v[32:35]
	v_mfma_f32_16x16x32_bf16 v[20:23], v[196:199], v[180:183], v[20:23]
	v_mfma_f32_16x16x32_bf16 v[16:19], v[204:207], v[180:183], v[16:19]
	v_mfma_f32_16x16x32_bf16 v[4:7], v[196:199], v[188:191], v[4:7]
	v_mfma_f32_16x16x32_bf16 v[0:3], v[204:207], v[188:191], v[0:3]
	s_setprio 0
	s_add_i32 s59, s59, 2
	s_add_u32 s57, s57, 0x100
	s_addc_u32 s58, s58, 0
	s_cmp_gt_u32 s59, 41
	s_mov_b64 s[10:11], s[20:21]
	s_barrier
	s_cbranch_scc0 .LBB0_998
	v_lshl_add_u32 v142, s39, 8, v144
	v_lshl_or_b32 v143, s38, 8, v146
	s_and_b64 vcc, exec, s[4:5]
	s_mov_b32 s38, s53
	s_mov_b32 s39, s56
	s_mov_b64 s[20:21], s[8:9]
	s_mov_b64 s[10:11], s[6:7]
	v_lshl_add_u32 v210, v142, 10, v143
	v_lshlrev_b32_e32 v211, 2, v210
	v_lshlrev_b32_e32 v210, 1, v210
	global_load_dwordx4 v[148:151], v210, s[14:15]
	global_load_dwordx4 v[152:155], v210, s[14:15] offset:256
	v_add_u32_e32 v210, 0x8000, v210
	global_load_dwordx4 v[156:159], v210, s[14:15]
	global_load_dwordx4 v[160:163], v210, s[14:15] offset:256
	v_add_u32_e32 v210, 0x8000, v210
	global_load_dwordx4 v[164:167], v210, s[14:15]
	global_load_dwordx4 v[168:171], v210, s[14:15] offset:256
	v_add_u32_e32 v210, 0x8000, v210
	global_load_dwordx4 v[172:175], v210, s[14:15]
	global_load_dwordx4 v[176:179], v210, s[14:15] offset:256
	v_add_u32_e32 v210, 0x28000, v210
	global_load_dwordx4 v[180:183], v210, s[14:15]
	global_load_dwordx4 v[184:187], v210, s[14:15] offset:256
	v_add_u32_e32 v210, 0x8000, v210
	global_load_dwordx4 v[188:191], v210, s[14:15]
	global_load_dwordx4 v[192:195], v210, s[14:15] offset:256
	v_add_u32_e32 v210, 0x8000, v210
	global_load_dwordx4 v[196:199], v210, s[14:15]
	global_load_dwordx4 v[200:203], v210, s[14:15] offset:256
	v_add_u32_e32 v210, 0x8000, v210
	s_waitcnt vmcnt(12)
	v_lshlrev_b32_e32 v204, 16, v148
	v_and_b32_e32 v205, 0xffff0000, v148
	v_lshlrev_b32_e32 v206, 16, v149
	v_and_b32_e32 v207, 0xffff0000, v149
	v_pk_add_f32 v[124:125], v[124:125], v[204:205]
	v_pk_add_f32 v[126:127], v[126:127], v[206:207]
	v_lshlrev_b32_e32 v204, 16, v150
	v_and_b32_e32 v205, 0xffff0000, v150
	v_lshlrev_b32_e32 v206, 16, v151
	v_and_b32_e32 v207, 0xffff0000, v151
	v_pk_add_f32 v[120:121], v[120:121], v[204:205]
	v_pk_add_f32 v[122:123], v[122:123], v[206:207]
	global_store_dwordx4 v211, v[124:127], s[16:17]
	global_store_dwordx4 v211, v[120:123], s[16:17] offset:16
	v_lshlrev_b32_e32 v204, 16, v152
	v_and_b32_e32 v205, 0xffff0000, v152
	v_lshlrev_b32_e32 v206, 16, v153
	v_and_b32_e32 v207, 0xffff0000, v153
	v_pk_add_f32 v[116:117], v[116:117], v[204:205]
	v_pk_add_f32 v[118:119], v[118:119], v[206:207]
	v_lshlrev_b32_e32 v204, 16, v154
	v_and_b32_e32 v205, 0xffff0000, v154
	v_lshlrev_b32_e32 v206, 16, v155
	v_and_b32_e32 v207, 0xffff0000, v155
	v_pk_add_f32 v[112:113], v[112:113], v[204:205]
	v_pk_add_f32 v[114:115], v[114:115], v[206:207]
	global_store_dwordx4 v211, v[116:119], s[16:17] offset:512
	global_store_dwordx4 v211, v[112:115], s[16:17] offset:528
	v_add_u32_e32 v211, 0x10000, v211
	global_load_dwordx4 v[148:151], v210, s[14:15]
	global_load_dwordx4 v[152:155], v210, s[14:15] offset:256
	s_waitcnt vmcnt(16)
	v_lshlrev_b32_e32 v204, 16, v156
	v_and_b32_e32 v205, 0xffff0000, v156
	v_lshlrev_b32_e32 v206, 16, v157
	v_and_b32_e32 v207, 0xffff0000, v157
	v_pk_add_f32 v[108:109], v[108:109], v[204:205]
	v_pk_add_f32 v[110:111], v[110:111], v[206:207]
	v_lshlrev_b32_e32 v204, 16, v158
	v_and_b32_e32 v205, 0xffff0000, v158
	v_lshlrev_b32_e32 v206, 16, v159
	v_and_b32_e32 v207, 0xffff0000, v159
	v_pk_add_f32 v[104:105], v[104:105], v[204:205]
	v_pk_add_f32 v[106:107], v[106:107], v[206:207]
	global_store_dwordx4 v211, v[108:111], s[16:17]
	global_store_dwordx4 v211, v[104:107], s[16:17] offset:16
	v_lshlrev_b32_e32 v204, 16, v160
	v_and_b32_e32 v205, 0xffff0000, v160
	v_lshlrev_b32_e32 v206, 16, v161
	v_and_b32_e32 v207, 0xffff0000, v161
	v_pk_add_f32 v[100:101], v[100:101], v[204:205]
	v_pk_add_f32 v[102:103], v[102:103], v[206:207]
	v_lshlrev_b32_e32 v204, 16, v162
	v_and_b32_e32 v205, 0xffff0000, v162
	v_lshlrev_b32_e32 v206, 16, v163
	v_and_b32_e32 v207, 0xffff0000, v163
	v_pk_add_f32 v[96:97], v[96:97], v[204:205]
	v_pk_add_f32 v[98:99], v[98:99], v[206:207]
	global_store_dwordx4 v211, v[100:103], s[16:17] offset:512
	global_store_dwordx4 v211, v[96:99], s[16:17] offset:528
	v_add_u32_e32 v211, 0x10000, v211
	s_waitcnt vmcnt(18)
	v_lshlrev_b32_e32 v204, 16, v164
	v_and_b32_e32 v205, 0xffff0000, v164
	v_lshlrev_b32_e32 v206, 16, v165
	v_and_b32_e32 v207, 0xffff0000, v165
	v_pk_add_f32 v[92:93], v[92:93], v[204:205]
	v_pk_add_f32 v[94:95], v[94:95], v[206:207]
	v_lshlrev_b32_e32 v204, 16, v166
	v_and_b32_e32 v205, 0xffff0000, v166
	v_lshlrev_b32_e32 v206, 16, v167
	v_and_b32_e32 v207, 0xffff0000, v167
	v_pk_add_f32 v[88:89], v[88:89], v[204:205]
	v_pk_add_f32 v[90:91], v[90:91], v[206:207]
	global_store_dwordx4 v211, v[92:95], s[16:17]
	global_store_dwordx4 v211, v[88:91], s[16:17] offset:16
	v_lshlrev_b32_e32 v204, 16, v168
	v_and_b32_e32 v205, 0xffff0000, v168
	v_lshlrev_b32_e32 v206, 16, v169
	v_and_b32_e32 v207, 0xffff0000, v169
	v_pk_add_f32 v[84:85], v[84:85], v[204:205]
	v_pk_add_f32 v[86:87], v[86:87], v[206:207]
	v_lshlrev_b32_e32 v204, 16, v170
	v_and_b32_e32 v205, 0xffff0000, v170
	v_lshlrev_b32_e32 v206, 16, v171
	v_and_b32_e32 v207, 0xffff0000, v171
	v_pk_add_f32 v[80:81], v[80:81], v[204:205]
	v_pk_add_f32 v[82:83], v[82:83], v[206:207]
	global_store_dwordx4 v211, v[84:87], s[16:17] offset:512
	global_store_dwordx4 v211, v[80:83], s[16:17] offset:528
	v_add_u32_e32 v211, 0x10000, v211
	s_waitcnt vmcnt(20)
	v_lshlrev_b32_e32 v204, 16, v172
	v_and_b32_e32 v205, 0xffff0000, v172
	v_lshlrev_b32_e32 v206, 16, v173
	v_and_b32_e32 v207, 0xffff0000, v173
	v_pk_add_f32 v[76:77], v[76:77], v[204:205]
	v_pk_add_f32 v[78:79], v[78:79], v[206:207]
	v_lshlrev_b32_e32 v204, 16, v174
	v_and_b32_e32 v205, 0xffff0000, v174
	v_lshlrev_b32_e32 v206, 16, v175
	v_and_b32_e32 v207, 0xffff0000, v175
	v_pk_add_f32 v[72:73], v[72:73], v[204:205]
	v_pk_add_f32 v[74:75], v[74:75], v[206:207]
	global_store_dwordx4 v211, v[76:79], s[16:17]
	global_store_dwordx4 v211, v[72:75], s[16:17] offset:16
	v_lshlrev_b32_e32 v204, 16, v176
	v_and_b32_e32 v205, 0xffff0000, v176
	v_lshlrev_b32_e32 v206, 16, v177
	v_and_b32_e32 v207, 0xffff0000, v177
	v_pk_add_f32 v[68:69], v[68:69], v[204:205]
	v_pk_add_f32 v[70:71], v[70:71], v[206:207]
	v_lshlrev_b32_e32 v204, 16, v178
	v_and_b32_e32 v205, 0xffff0000, v178
	v_lshlrev_b32_e32 v206, 16, v179
	v_and_b32_e32 v207, 0xffff0000, v179
	v_pk_add_f32 v[64:65], v[64:65], v[204:205]
	v_pk_add_f32 v[66:67], v[66:67], v[206:207]
	global_store_dwordx4 v211, v[68:71], s[16:17] offset:512
	global_store_dwordx4 v211, v[64:67], s[16:17] offset:528
	v_add_u32_e32 v211, 0x50000, v211
	s_waitcnt vmcnt(22)
	v_lshlrev_b32_e32 v204, 16, v180
	v_and_b32_e32 v205, 0xffff0000, v180
	v_lshlrev_b32_e32 v206, 16, v181
	v_and_b32_e32 v207, 0xffff0000, v181
	v_pk_add_f32 v[60:61], v[60:61], v[204:205]
	v_pk_add_f32 v[62:63], v[62:63], v[206:207]
	v_lshlrev_b32_e32 v204, 16, v182
	v_and_b32_e32 v205, 0xffff0000, v182
	v_lshlrev_b32_e32 v206, 16, v183
	v_and_b32_e32 v207, 0xffff0000, v183
	v_pk_add_f32 v[56:57], v[56:57], v[204:205]
	v_pk_add_f32 v[58:59], v[58:59], v[206:207]
	global_store_dwordx4 v211, v[60:63], s[16:17]
	global_store_dwordx4 v211, v[56:59], s[16:17] offset:16
	v_lshlrev_b32_e32 v204, 16, v184
	v_and_b32_e32 v205, 0xffff0000, v184
	v_lshlrev_b32_e32 v206, 16, v185
	v_and_b32_e32 v207, 0xffff0000, v185
	v_pk_add_f32 v[52:53], v[52:53], v[204:205]
	v_pk_add_f32 v[54:55], v[54:55], v[206:207]
	v_lshlrev_b32_e32 v204, 16, v186
	v_and_b32_e32 v205, 0xffff0000, v186
	v_lshlrev_b32_e32 v206, 16, v187
	v_and_b32_e32 v207, 0xffff0000, v187
	v_pk_add_f32 v[48:49], v[48:49], v[204:205]
	v_pk_add_f32 v[50:51], v[50:51], v[206:207]
	global_store_dwordx4 v211, v[52:55], s[16:17] offset:512
	global_store_dwordx4 v211, v[48:51], s[16:17] offset:528
	v_add_u32_e32 v211, 0x10000, v211
	s_waitcnt vmcnt(24)
	v_lshlrev_b32_e32 v204, 16, v188
	v_and_b32_e32 v205, 0xffff0000, v188
	v_lshlrev_b32_e32 v206, 16, v189
	v_and_b32_e32 v207, 0xffff0000, v189
	v_pk_add_f32 v[44:45], v[44:45], v[204:205]
	v_pk_add_f32 v[46:47], v[46:47], v[206:207]
	v_lshlrev_b32_e32 v204, 16, v190
	v_and_b32_e32 v205, 0xffff0000, v190
	v_lshlrev_b32_e32 v206, 16, v191
	v_and_b32_e32 v207, 0xffff0000, v191
	v_pk_add_f32 v[40:41], v[40:41], v[204:205]
	v_pk_add_f32 v[42:43], v[42:43], v[206:207]
	global_store_dwordx4 v211, v[44:47], s[16:17]
	global_store_dwordx4 v211, v[40:43], s[16:17] offset:16
	v_lshlrev_b32_e32 v204, 16, v192
	v_and_b32_e32 v205, 0xffff0000, v192
	v_lshlrev_b32_e32 v206, 16, v193
	v_and_b32_e32 v207, 0xffff0000, v193
	v_pk_add_f32 v[36:37], v[36:37], v[204:205]
	v_pk_add_f32 v[38:39], v[38:39], v[206:207]
	v_lshlrev_b32_e32 v204, 16, v194
	v_and_b32_e32 v205, 0xffff0000, v194
	v_lshlrev_b32_e32 v206, 16, v195
	v_and_b32_e32 v207, 0xffff0000, v195
	v_pk_add_f32 v[32:33], v[32:33], v[204:205]
	v_pk_add_f32 v[34:35], v[34:35], v[206:207]
	global_store_dwordx4 v211, v[36:39], s[16:17] offset:512
	global_store_dwordx4 v211, v[32:35], s[16:17] offset:528
	v_add_u32_e32 v211, 0x10000, v211
	s_waitcnt vmcnt(26)
	v_lshlrev_b32_e32 v204, 16, v196
	v_and_b32_e32 v205, 0xffff0000, v196
	v_lshlrev_b32_e32 v206, 16, v197
	v_and_b32_e32 v207, 0xffff0000, v197
	v_pk_add_f32 v[28:29], v[28:29], v[204:205]
	v_pk_add_f32 v[30:31], v[30:31], v[206:207]
	v_lshlrev_b32_e32 v204, 16, v198
	v_and_b32_e32 v205, 0xffff0000, v198
	v_lshlrev_b32_e32 v206, 16, v199
	v_and_b32_e32 v207, 0xffff0000, v199
	v_pk_add_f32 v[24:25], v[24:25], v[204:205]
	v_pk_add_f32 v[26:27], v[26:27], v[206:207]
	global_store_dwordx4 v211, v[28:31], s[16:17]
	global_store_dwordx4 v211, v[24:27], s[16:17] offset:16
	v_lshlrev_b32_e32 v204, 16, v200
	v_and_b32_e32 v205, 0xffff0000, v200
	v_lshlrev_b32_e32 v206, 16, v201
	v_and_b32_e32 v207, 0xffff0000, v201
	v_pk_add_f32 v[20:21], v[20:21], v[204:205]
	v_pk_add_f32 v[22:23], v[22:23], v[206:207]
	v_lshlrev_b32_e32 v204, 16, v202
	v_and_b32_e32 v205, 0xffff0000, v202
	v_lshlrev_b32_e32 v206, 16, v203
	v_and_b32_e32 v207, 0xffff0000, v203
	v_pk_add_f32 v[16:17], v[16:17], v[204:205]
	v_pk_add_f32 v[18:19], v[18:19], v[206:207]
	global_store_dwordx4 v211, v[20:23], s[16:17] offset:512
	global_store_dwordx4 v211, v[16:19], s[16:17] offset:528
	v_add_u32_e32 v211, 0x10000, v211
	s_waitcnt vmcnt(24)
	v_lshlrev_b32_e32 v204, 16, v148
	v_and_b32_e32 v205, 0xffff0000, v148
	v_lshlrev_b32_e32 v206, 16, v149
	v_and_b32_e32 v207, 0xffff0000, v149
	v_pk_add_f32 v[12:13], v[12:13], v[204:205]
	v_pk_add_f32 v[14:15], v[14:15], v[206:207]
	v_lshlrev_b32_e32 v204, 16, v150
	v_and_b32_e32 v205, 0xffff0000, v150
	v_lshlrev_b32_e32 v206, 16, v151
	v_and_b32_e32 v207, 0xffff0000, v151
	v_pk_add_f32 v[8:9], v[8:9], v[204:205]
	v_pk_add_f32 v[10:11], v[10:11], v[206:207]
	global_store_dwordx4 v211, v[12:15], s[16:17]
	global_store_dwordx4 v211, v[8:11], s[16:17] offset:16
	v_lshlrev_b32_e32 v204, 16, v152
	v_and_b32_e32 v205, 0xffff0000, v152
	v_lshlrev_b32_e32 v206, 16, v153
	v_and_b32_e32 v207, 0xffff0000, v153
	v_pk_add_f32 v[4:5], v[4:5], v[204:205]
	v_pk_add_f32 v[6:7], v[6:7], v[206:207]
	v_lshlrev_b32_e32 v204, 16, v154
	v_and_b32_e32 v205, 0xffff0000, v154
	v_lshlrev_b32_e32 v206, 16, v155
	v_and_b32_e32 v207, 0xffff0000, v155
	v_pk_add_f32 v[0:1], v[0:1], v[204:205]
	v_pk_add_f32 v[2:3], v[2:3], v[206:207]
	global_store_dwordx4 v211, v[4:7], s[16:17] offset:512
	global_store_dwordx4 v211, v[0:3], s[16:17] offset:528
	v_add_u32_e32 v211, 0x10000, v211
	s_cbranch_vccz .LBB0_987
	s_waitcnt vmcnt(0)
	s_cmpk_gt_u32 s26, 0xff
	s_cbranch_scc1 .LBB0_1002
	s_barrier

.LBB0_1021:
	s_add_u32 s22, s20, 0x100
	s_addc_u32 s23, s21, 0
	s_add_i32 s62, 0, 0x10000
	v_add_u32_e32 v154, s62, v143
	ds_read_b128 v[138:141], v154
	ds_read_b128 v[146:149], v154 offset:1024
	ds_read_b128 v[150:153], v154 offset:2048
	ds_read_b128 v[154:157], v154 offset:3072
	s_cmp_eq_u32 s61, 40
	s_cselect_b32 s27, s9, s23
	s_cselect_b32 s26, s8, s22
	s_cselect_b32 s25, s11, s60
	s_cselect_b32 s24, s10, s39
	v_lshl_add_u64 v[190:191], s[20:21], 0, v[134:135]
	s_add_i32 m0, s46, 0xc000
	ds_read_b128 v[158:161], v145
	ds_read_b128 v[162:165], v145 offset:1024
	ds_read_b128 v[166:169], v145 offset:2048
	ds_read_b128 v[170:173], v145 offset:3072
	ds_read_b128 v[174:177], v145 offset:4096
	ds_read_b128 v[178:181], v145 offset:5120
	ds_read_b128 v[182:185], v145 offset:6144
	ds_read_b128 v[186:189], v145 offset:7168
	global_load_lds_dwordx4 v[190:191], off
	v_lshl_add_u64 v[190:191], s[20:21], 0, v[136:137]
	s_add_i32 m0, s46, 0xe000
	s_nop 0
	global_load_lds_dwordx4 v[190:191], off
	s_waitcnt lgkmcnt(8)
	s_barrier
	s_waitcnt lgkmcnt(0)
	s_setprio 1
	v_mfma_f32_16x16x32_bf16 v[124:127], v[138:141], v[158:161], v[124:127]
	v_mfma_f32_16x16x32_bf16 v[120:123], v[150:153], v[158:161], v[120:123]
	v_mfma_f32_16x16x32_bf16 v[108:111], v[138:141], v[166:169], v[108:111]
	v_mfma_f32_16x16x32_bf16 v[104:107], v[150:153], v[166:169], v[104:107]
	v_mfma_f32_16x16x32_bf16 v[92:95], v[138:141], v[174:177], v[92:95]
	v_mfma_f32_16x16x32_bf16 v[88:91], v[150:153], v[174:177], v[88:91]
	v_mfma_f32_16x16x32_bf16 v[76:79], v[138:141], v[182:185], v[76:79]
	v_mfma_f32_16x16x32_bf16 v[72:75], v[150:153], v[182:185], v[72:75]
	v_mfma_f32_16x16x32_bf16 v[124:127], v[146:149], v[162:165], v[124:127]
	v_mfma_f32_16x16x32_bf16 v[120:123], v[154:157], v[162:165], v[120:123]
	v_mfma_f32_16x16x32_bf16 v[108:111], v[146:149], v[170:173], v[108:111]
	v_mfma_f32_16x16x32_bf16 v[104:107], v[154:157], v[170:173], v[104:107]
	v_mfma_f32_16x16x32_bf16 v[92:95], v[146:149], v[178:181], v[92:95]
	v_mfma_f32_16x16x32_bf16 v[88:91], v[154:157], v[178:181], v[88:91]
	v_mfma_f32_16x16x32_bf16 v[76:79], v[146:149], v[186:189], v[76:79]
	v_mfma_f32_16x16x32_bf16 v[72:75], v[154:157], v[186:189], v[72:75]
	s_setprio 0
	s_barrier
	s_add_i32 s63, 0, 0x14000
	s_add_i32 s20, s62, s35
	v_add_u32_e32 v202, s63, v143
	s_add_u32 s98, s24, s40
	s_addc_u32 s99, s25, s41
	s_mov_b32 m0, s20
	ds_read_b128 v[190:193], v202
	ds_read_b128 v[194:197], v202 offset:1024
	ds_read_b128 v[198:201], v202 offset:2048
	ds_read_b128 v[202:205], v202 offset:3072
	global_load_lds_dwordx4 v208, s[24:25]
	s_add_i32 m0, s20, 0x2000
	s_nop 0
	global_load_lds_dwordx4 v128, s[24:25]
	s_barrier
	s_waitcnt lgkmcnt(0)
	s_setprio 1
	v_mfma_f32_16x16x32_bf16 v[116:119], v[190:193], v[158:161], v[116:119]
	v_mfma_f32_16x16x32_bf16 v[112:115], v[198:201], v[158:161], v[112:115]
	v_mfma_f32_16x16x32_bf16 v[100:103], v[190:193], v[166:169], v[100:103]
	v_mfma_f32_16x16x32_bf16 v[96:99], v[198:201], v[166:169], v[96:99]
	v_mfma_f32_16x16x32_bf16 v[84:87], v[190:193], v[174:177], v[84:87]
	v_mfma_f32_16x16x32_bf16 v[80:83], v[198:201], v[174:177], v[80:83]
	v_mfma_f32_16x16x32_bf16 v[68:71], v[190:193], v[182:185], v[68:71]
	v_mfma_f32_16x16x32_bf16 v[64:67], v[198:201], v[182:185], v[64:67]
	v_mfma_f32_16x16x32_bf16 v[116:119], v[194:197], v[162:165], v[116:119]
	v_mfma_f32_16x16x32_bf16 v[112:115], v[202:205], v[162:165], v[112:115]
	v_mfma_f32_16x16x32_bf16 v[100:103], v[194:197], v[170:173], v[100:103]
	v_mfma_f32_16x16x32_bf16 v[96:99], v[202:205], v[170:173], v[96:99]
	v_mfma_f32_16x16x32_bf16 v[84:87], v[194:197], v[178:181], v[84:87]
	v_mfma_f32_16x16x32_bf16 v[80:83], v[202:205], v[178:181], v[80:83]
	v_mfma_f32_16x16x32_bf16 v[68:71], v[194:197], v[186:189], v[68:71]
	v_mfma_f32_16x16x32_bf16 v[64:67], v[202:205], v[186:189], v[64:67]
	s_setprio 0
	s_mov_b32 m0, s46
	s_add_u32 s100, s26, s40
	s_addc_u32 s101, s27, s41
	s_barrier
	ds_read_b128 v[158:161], v145 offset:16384
	ds_read_b128 v[162:165], v145 offset:17408
	ds_read_b128 v[166:169], v145 offset:18432
	ds_read_b128 v[170:173], v145 offset:19456
	ds_read_b128 v[174:177], v145 offset:20480
	ds_read_b128 v[178:181], v145 offset:21504
	ds_read_b128 v[182:185], v145 offset:22528
	ds_read_b128 v[186:189], v145 offset:23552
	global_load_lds_dwordx4 v132, s[26:27]
	s_mov_b32 m0, s47
	s_nop 0
	global_load_lds_dwordx4 v130, s[26:27]
	s_barrier
	s_waitcnt lgkmcnt(0)
	s_setprio 1
	v_mfma_f32_16x16x32_bf16 v[60:63], v[138:141], v[158:161], v[60:63]
	v_mfma_f32_16x16x32_bf16 v[56:59], v[150:153], v[158:161], v[56:59]
	v_mfma_f32_16x16x32_bf16 v[44:47], v[138:141], v[166:169], v[44:47]
	v_mfma_f32_16x16x32_bf16 v[40:43], v[150:153], v[166:169], v[40:43]
	v_mfma_f32_16x16x32_bf16 v[28:31], v[138:141], v[174:177], v[28:31]
	v_mfma_f32_16x16x32_bf16 v[24:27], v[150:153], v[174:177], v[24:27]
	v_mfma_f32_16x16x32_bf16 v[12:15], v[138:141], v[182:185], v[12:15]
	v_mfma_f32_16x16x32_bf16 v[8:11], v[150:153], v[182:185], v[8:11]
	v_mfma_f32_16x16x32_bf16 v[60:63], v[146:149], v[162:165], v[60:63]
	v_mfma_f32_16x16x32_bf16 v[56:59], v[154:157], v[162:165], v[56:59]
	v_mfma_f32_16x16x32_bf16 v[44:47], v[146:149], v[170:173], v[44:47]
	v_mfma_f32_16x16x32_bf16 v[40:43], v[154:157], v[170:173], v[40:43]
	v_mfma_f32_16x16x32_bf16 v[28:31], v[146:149], v[178:181], v[28:31]
	v_mfma_f32_16x16x32_bf16 v[24:27], v[154:157], v[178:181], v[24:27]
	v_mfma_f32_16x16x32_bf16 v[12:15], v[146:149], v[186:189], v[12:15]
	v_mfma_f32_16x16x32_bf16 v[8:11], v[154:157], v[186:189], v[8:11]
	s_setprio 0
	s_barrier
	s_add_u32 s20, s24, 0xb0000
	s_addc_u32 s21, s25, 0
	s_add_i32 s62, s63, s35
	s_mov_b32 m0, s62
	s_nop 0
	global_load_lds_dwordx4 v208, s[20:21]
	s_add_i32 m0, s62, 0x2000
	s_nop 0
	global_load_lds_dwordx4 v128, s[20:21]
	s_waitcnt vmcnt(6)
	s_barrier
	s_setprio 1
	v_mfma_f32_16x16x32_bf16 v[52:55], v[190:193], v[158:161], v[52:55]
	v_mfma_f32_16x16x32_bf16 v[48:51], v[198:201], v[158:161], v[48:51]
	v_mfma_f32_16x16x32_bf16 v[36:39], v[190:193], v[166:169], v[36:39]
	v_mfma_f32_16x16x32_bf16 v[32:35], v[198:201], v[166:169], v[32:35]
	v_mfma_f32_16x16x32_bf16 v[20:23], v[190:193], v[174:177], v[20:23]
	v_mfma_f32_16x16x32_bf16 v[16:19], v[198:201], v[174:177], v[16:19]
	v_mfma_f32_16x16x32_bf16 v[4:7], v[190:193], v[182:185], v[4:7]
	v_mfma_f32_16x16x32_bf16 v[0:3], v[198:201], v[182:185], v[0:3]
	v_mfma_f32_16x16x32_bf16 v[52:55], v[194:197], v[162:165], v[52:55]
	v_mfma_f32_16x16x32_bf16 v[48:51], v[202:205], v[162:165], v[48:51]
	v_mfma_f32_16x16x32_bf16 v[36:39], v[194:197], v[170:173], v[36:39]
	v_mfma_f32_16x16x32_bf16 v[32:35], v[202:205], v[170:173], v[32:35]
	v_mfma_f32_16x16x32_bf16 v[20:23], v[194:197], v[178:181], v[20:23]
	v_mfma_f32_16x16x32_bf16 v[16:19], v[202:205], v[178:181], v[16:19]
	v_mfma_f32_16x16x32_bf16 v[4:7], v[194:197], v[186:189], v[4:7]
	v_mfma_f32_16x16x32_bf16 v[0:3], v[202:205], v[186:189], v[0:3]
	s_setprio 0
	s_add_i32 s62, 0, 0x18000
	v_add_u32_e32 v154, s62, v143
	s_barrier
	ds_read_b128 v[138:141], v154
	ds_read_b128 v[146:149], v154 offset:1024
	ds_read_b128 v[150:153], v154 offset:2048
	ds_read_b128 v[154:157], v154 offset:3072
	s_add_u32 s20, s26, 0xb0000
	s_addc_u32 s21, s27, 0
	s_mov_b32 m0, s50
	ds_read_b128 v[158:161], v145 offset:32768
	ds_read_b128 v[162:165], v145 offset:33792
	ds_read_b128 v[166:169], v145 offset:34816
	ds_read_b128 v[170:173], v145 offset:35840
	ds_read_b128 v[174:177], v145 offset:36864
	ds_read_b128 v[178:181], v145 offset:37888
	ds_read_b128 v[182:185], v145 offset:38912
	ds_read_b128 v[186:189], v145 offset:39936
	global_load_lds_dwordx4 v132, s[20:21]
	s_mov_b32 m0, s51
	s_nop 0
	global_load_lds_dwordx4 v130, s[20:21]
	s_waitcnt lgkmcnt(8)
	s_barrier
	s_waitcnt lgkmcnt(0)
	s_setprio 1
	v_mfma_f32_16x16x32_bf16 v[124:127], v[138:141], v[158:161], v[124:127]
	v_mfma_f32_16x16x32_bf16 v[120:123], v[150:153], v[158:161], v[120:123]
	v_mfma_f32_16x16x32_bf16 v[108:111], v[138:141], v[166:169], v[108:111]
	v_mfma_f32_16x16x32_bf16 v[104:107], v[150:153], v[166:169], v[104:107]
	v_mfma_f32_16x16x32_bf16 v[92:95], v[138:141], v[174:177], v[92:95]
	v_mfma_f32_16x16x32_bf16 v[88:91], v[150:153], v[174:177], v[88:91]
	v_mfma_f32_16x16x32_bf16 v[76:79], v[138:141], v[182:185], v[76:79]
	v_mfma_f32_16x16x32_bf16 v[72:75], v[150:153], v[182:185], v[72:75]
	v_mfma_f32_16x16x32_bf16 v[124:127], v[146:149], v[162:165], v[124:127]
	v_mfma_f32_16x16x32_bf16 v[120:123], v[154:157], v[162:165], v[120:123]
	v_mfma_f32_16x16x32_bf16 v[108:111], v[146:149], v[170:173], v[108:111]
	v_mfma_f32_16x16x32_bf16 v[104:107], v[154:157], v[170:173], v[104:107]
	v_mfma_f32_16x16x32_bf16 v[92:95], v[146:149], v[178:181], v[92:95]
	v_mfma_f32_16x16x32_bf16 v[88:91], v[154:157], v[178:181], v[88:91]
	v_mfma_f32_16x16x32_bf16 v[76:79], v[146:149], v[186:189], v[76:79]
	v_mfma_f32_16x16x32_bf16 v[72:75], v[154:157], v[186:189], v[72:75]
	s_setprio 0
	s_barrier
	s_add_i32 s26, 0, 0x1c000
	s_add_i32 s20, s62, s35
	v_add_u32_e32 v202, s26, v143
	s_mov_b32 m0, s20
	ds_read_b128 v[190:193], v202
	ds_read_b128 v[194:197], v202 offset:1024
	ds_read_b128 v[198:201], v202 offset:2048
	ds_read_b128 v[202:205], v202 offset:3072
	global_load_lds_dwordx4 v208, s[98:99]
	s_add_i32 m0, s20, 0x2000
	s_nop 0
	global_load_lds_dwordx4 v128, s[98:99]
	s_barrier
	s_waitcnt lgkmcnt(0)
	s_setprio 1
	v_mfma_f32_16x16x32_bf16 v[116:119], v[190:193], v[158:161], v[116:119]
	v_mfma_f32_16x16x32_bf16 v[112:115], v[198:201], v[158:161], v[112:115]
	v_mfma_f32_16x16x32_bf16 v[100:103], v[190:193], v[166:169], v[100:103]
	v_mfma_f32_16x16x32_bf16 v[96:99], v[198:201], v[166:169], v[96:99]
	v_mfma_f32_16x16x32_bf16 v[84:87], v[190:193], v[174:177], v[84:87]
	v_mfma_f32_16x16x32_bf16 v[80:83], v[198:201], v[174:177], v[80:83]
	v_mfma_f32_16x16x32_bf16 v[68:71], v[190:193], v[182:185], v[68:71]
	v_mfma_f32_16x16x32_bf16 v[64:67], v[198:201], v[182:185], v[64:67]
	v_mfma_f32_16x16x32_bf16 v[116:119], v[194:197], v[162:165], v[116:119]
	v_mfma_f32_16x16x32_bf16 v[112:115], v[202:205], v[162:165], v[112:115]
	v_mfma_f32_16x16x32_bf16 v[100:103], v[194:197], v[170:173], v[100:103]
	v_mfma_f32_16x16x32_bf16 v[96:99], v[202:205], v[170:173], v[96:99]
	v_mfma_f32_16x16x32_bf16 v[84:87], v[194:197], v[178:181], v[84:87]
	v_mfma_f32_16x16x32_bf16 v[80:83], v[202:205], v[178:181], v[80:83]
	v_mfma_f32_16x16x32_bf16 v[68:71], v[194:197], v[186:189], v[68:71]
	v_mfma_f32_16x16x32_bf16 v[64:67], v[202:205], v[186:189], v[64:67]
	s_setprio 0
	s_mov_b32 m0, s53
	s_barrier
	ds_read_b128 v[158:161], v145 offset:49152
	ds_read_b128 v[162:165], v145 offset:50176
	ds_read_b128 v[166:169], v145 offset:51200
	ds_read_b128 v[170:173], v145 offset:52224
	ds_read_b128 v[174:177], v145 offset:53248
	ds_read_b128 v[178:181], v145 offset:54272
	ds_read_b128 v[182:185], v145 offset:55296
	ds_read_b128 v[186:189], v145 offset:56320
	global_load_lds_dwordx4 v132, s[100:101]
	s_mov_b32 m0, s56
	s_nop 0
	global_load_lds_dwordx4 v130, s[100:101]
	s_barrier
	s_waitcnt lgkmcnt(0)
	s_setprio 1
	v_mfma_f32_16x16x32_bf16 v[60:63], v[138:141], v[158:161], v[60:63]
	v_mfma_f32_16x16x32_bf16 v[56:59], v[150:153], v[158:161], v[56:59]
	v_mfma_f32_16x16x32_bf16 v[44:47], v[138:141], v[166:169], v[44:47]
	v_mfma_f32_16x16x32_bf16 v[40:43], v[150:153], v[166:169], v[40:43]
	v_mfma_f32_16x16x32_bf16 v[28:31], v[138:141], v[174:177], v[28:31]
	v_mfma_f32_16x16x32_bf16 v[24:27], v[150:153], v[174:177], v[24:27]
	v_mfma_f32_16x16x32_bf16 v[12:15], v[138:141], v[182:185], v[12:15]
	v_mfma_f32_16x16x32_bf16 v[8:11], v[150:153], v[182:185], v[8:11]
	v_mfma_f32_16x16x32_bf16 v[60:63], v[146:149], v[162:165], v[60:63]
	v_mfma_f32_16x16x32_bf16 v[56:59], v[154:157], v[162:165], v[56:59]
	v_mfma_f32_16x16x32_bf16 v[44:47], v[146:149], v[170:173], v[44:47]
	v_mfma_f32_16x16x32_bf16 v[40:43], v[154:157], v[170:173], v[40:43]
	v_mfma_f32_16x16x32_bf16 v[28:31], v[146:149], v[178:181], v[28:31]
	v_mfma_f32_16x16x32_bf16 v[24:27], v[154:157], v[178:181], v[24:27]
	v_mfma_f32_16x16x32_bf16 v[12:15], v[146:149], v[186:189], v[12:15]
	v_mfma_f32_16x16x32_bf16 v[8:11], v[154:157], v[186:189], v[8:11]
	s_setprio 0
	s_barrier
	s_add_u32 s20, s24, 0xb0080
	s_addc_u32 s21, s25, 0
	s_add_i32 s24, s26, s35
	s_mov_b32 m0, s24
	s_nop 0
	global_load_lds_dwordx4 v208, s[20:21]
	s_add_i32 m0, s24, 0x2000
	s_nop 0
	global_load_lds_dwordx4 v128, s[20:21]
	s_waitcnt vmcnt(6)
	s_barrier
	s_setprio 1
	v_mfma_f32_16x16x32_bf16 v[52:55], v[190:193], v[158:161], v[52:55]
	v_mfma_f32_16x16x32_bf16 v[48:51], v[198:201], v[158:161], v[48:51]
	v_mfma_f32_16x16x32_bf16 v[36:39], v[190:193], v[166:169], v[36:39]
	v_mfma_f32_16x16x32_bf16 v[32:35], v[198:201], v[166:169], v[32:35]
	v_mfma_f32_16x16x32_bf16 v[20:23], v[190:193], v[174:177], v[20:23]
	v_mfma_f32_16x16x32_bf16 v[16:19], v[198:201], v[174:177], v[16:19]
	v_mfma_f32_16x16x32_bf16 v[4:7], v[190:193], v[182:185], v[4:7]
	v_mfma_f32_16x16x32_bf16 v[0:3], v[198:201], v[182:185], v[0:3]
	v_mfma_f32_16x16x32_bf16 v[52:55], v[194:197], v[162:165], v[52:55]
	v_mfma_f32_16x16x32_bf16 v[48:51], v[202:205], v[162:165], v[48:51]
	v_mfma_f32_16x16x32_bf16 v[36:39], v[194:197], v[170:173], v[36:39]
	v_mfma_f32_16x16x32_bf16 v[32:35], v[202:205], v[170:173], v[32:35]
	v_mfma_f32_16x16x32_bf16 v[20:23], v[194:197], v[178:181], v[20:23]
	v_mfma_f32_16x16x32_bf16 v[16:19], v[202:205], v[178:181], v[16:19]
	v_mfma_f32_16x16x32_bf16 v[4:7], v[194:197], v[186:189], v[4:7]
	v_mfma_f32_16x16x32_bf16 v[0:3], v[202:205], v[186:189], v[0:3]
	s_setprio 0
	s_add_i32 s61, s61, 2
	s_add_u32 s39, s39, 0x100
	s_addc_u32 s60, s60, 0
	s_cmp_gt_u32 s61, 41
	s_mov_b64 s[20:21], s[22:23]
	s_barrier
	s_cbranch_scc0 .LBB0_1021
	v_lshl_add_u32 v140, s38, 8, v142
	v_lshl_or_b32 v141, s36, 8, v144
	s_lshl_b32 s20, s36, 2
	s_ashr_i32 s21, s20, 31
	s_lshl_b32 s36, s52, 2
	v_lshlrev_b32_e32 v206, 11, v140
	v_lshl_add_u32 v206, v141, 1, v206
	v_lshl_add_u32 v210, v140, 6, s36
	v_lshl_add_u32 v210, s20, 2, v210
	v_mov_b32_e32 v207, v206
	global_load_dwordx4 v[146:149], v206, s[14:15]
	global_load_dwordx4 v[150:153], v206, s[14:15] offset:256
	v_add_u32_e32 v206, 0x8000, v206
	global_load_dwordx4 v[154:157], v206, s[14:15]
	global_load_dwordx4 v[158:161], v206, s[14:15] offset:256
	v_add_u32_e32 v206, 0x8000, v206
	global_load_dwordx4 v[162:165], v206, s[14:15]
	global_load_dwordx4 v[166:169], v206, s[14:15] offset:256
	v_add_u32_e32 v206, 0x8000, v206
	global_load_dwordx4 v[170:173], v206, s[14:15]
	global_load_dwordx4 v[174:177], v206, s[14:15] offset:256
	v_add_u32_e32 v206, 0x28000, v206
	global_load_dwordx4 v[178:181], v206, s[14:15]
	global_load_dwordx4 v[182:185], v206, s[14:15] offset:256
	v_add_u32_e32 v206, 0x8000, v206
	global_load_dwordx4 v[186:189], v206, s[14:15]
	global_load_dwordx4 v[190:193], v206, s[14:15] offset:256
	v_add_u32_e32 v206, 0x8000, v206
	global_load_dwordx4 v[194:197], v206, s[14:15]
	global_load_dwordx4 v[198:201], v206, s[14:15] offset:256
	v_add_u32_e32 v206, 0x8000, v206
	s_waitcnt vmcnt(12)
	v_lshlrev_b32_e32 v202, 16, v146
	v_and_b32_e32 v203, 0xffff0000, v146
	v_lshlrev_b32_e32 v204, 16, v147
	v_and_b32_e32 v205, 0xffff0000, v147
	v_pk_add_f32 v[124:125], v[124:125], v[202:203]
	v_pk_add_f32 v[126:127], v[126:127], v[204:205]
	v_lshlrev_b32_e32 v202, 16, v148
	v_and_b32_e32 v203, 0xffff0000, v148
	v_lshlrev_b32_e32 v204, 16, v149
	v_and_b32_e32 v205, 0xffff0000, v149
	v_pk_add_f32 v[120:121], v[120:121], v[202:203]
	v_pk_add_f32 v[122:123], v[122:123], v[204:205]
	v_cvt_pk_bf16_f32 v146, v124, v125
	v_cvt_pk_bf16_f32 v147, v126, v127
	v_cvt_pk_bf16_f32 v148, v120, v121
	v_cvt_pk_bf16_f32 v149, v122, v123
	v_pk_mul_f32 v[138:139], v[124:125], v[124:125]
	global_store_dwordx4 v207, v[146:149], s[14:15]
	v_pk_fma_f32 v[138:139], v[126:127], v[126:127], v[138:139]
	v_pk_fma_f32 v[138:139], v[120:121], v[120:121], v[138:139]
	v_pk_fma_f32 v[138:139], v[122:123], v[122:123], v[138:139]
	v_lshlrev_b32_e32 v202, 16, v150
	v_and_b32_e32 v203, 0xffff0000, v150
	v_lshlrev_b32_e32 v204, 16, v151
	v_and_b32_e32 v205, 0xffff0000, v151
	v_pk_add_f32 v[116:117], v[116:117], v[202:203]
	v_pk_add_f32 v[118:119], v[118:119], v[204:205]
	v_lshlrev_b32_e32 v202, 16, v152
	v_and_b32_e32 v203, 0xffff0000, v152
	v_lshlrev_b32_e32 v204, 16, v153
	v_and_b32_e32 v205, 0xffff0000, v153
	v_pk_add_f32 v[112:113], v[112:113], v[202:203]
	v_pk_add_f32 v[114:115], v[114:115], v[204:205]
	v_cvt_pk_bf16_f32 v150, v116, v117
	v_cvt_pk_bf16_f32 v151, v118, v119
	v_cvt_pk_bf16_f32 v152, v112, v113
	v_cvt_pk_bf16_f32 v153, v114, v115
	v_pk_fma_f32 v[138:139], v[116:117], v[116:117], v[138:139]
	global_store_dwordx4 v207, v[150:153], s[14:15] offset:256
	v_pk_fma_f32 v[138:139], v[118:119], v[118:119], v[138:139]
	v_pk_fma_f32 v[138:139], v[112:113], v[112:113], v[138:139]
	v_pk_fma_f32 v[138:139], v[114:115], v[114:115], v[138:139]
	v_add_f32_e32 v214, v138, v139
	v_add_u32_e32 v207, 0x8000, v207
	v_mov_b32_e32 v215, v214
	s_nop 1
	v_permlane16_swap_b32_e32 v214, v215
	s_nop 0
	v_add_f32_e32 v214, v214, v215
	v_mov_b32_e32 v215, v214
	s_nop 1
	v_permlane32_swap_b32_e32 v214, v215
	s_nop 0
	v_add_f32_e32 v214, v214, v215
	s_and_saveexec_b64 s[22:23], s[4:5]
	global_store_dword v210, v214, s[16:17]
	s_mov_b64 exec, s[22:23]
	global_load_dwordx4 v[146:149], v206, s[14:15]
	global_load_dwordx4 v[150:153], v206, s[14:15] offset:256
	s_waitcnt vmcnt(15)
	v_lshlrev_b32_e32 v202, 16, v154
	v_and_b32_e32 v203, 0xffff0000, v154
	v_lshlrev_b32_e32 v204, 16, v155
	v_and_b32_e32 v205, 0xffff0000, v155
	v_pk_add_f32 v[108:109], v[108:109], v[202:203]
	v_pk_add_f32 v[110:111], v[110:111], v[204:205]
	v_lshlrev_b32_e32 v202, 16, v156
	v_and_b32_e32 v203, 0xffff0000, v156
	v_lshlrev_b32_e32 v204, 16, v157
	v_and_b32_e32 v205, 0xffff0000, v157
	v_pk_add_f32 v[104:105], v[104:105], v[202:203]
	v_pk_add_f32 v[106:107], v[106:107], v[204:205]
	v_cvt_pk_bf16_f32 v154, v108, v109
	v_cvt_pk_bf16_f32 v155, v110, v111
	v_cvt_pk_bf16_f32 v156, v104, v105
	v_cvt_pk_bf16_f32 v157, v106, v107
	v_pk_mul_f32 v[138:139], v[108:109], v[108:109]
	global_store_dwordx4 v207, v[154:157], s[14:15]
	v_pk_fma_f32 v[138:139], v[110:111], v[110:111], v[138:139]
	v_pk_fma_f32 v[138:139], v[104:105], v[104:105], v[138:139]
	v_pk_fma_f32 v[138:139], v[106:107], v[106:107], v[138:139]
	v_lshlrev_b32_e32 v202, 16, v158
	v_and_b32_e32 v203, 0xffff0000, v158
	v_lshlrev_b32_e32 v204, 16, v159
	v_and_b32_e32 v205, 0xffff0000, v159
	v_pk_add_f32 v[100:101], v[100:101], v[202:203]
	v_pk_add_f32 v[102:103], v[102:103], v[204:205]
	v_lshlrev_b32_e32 v202, 16, v160
	v_and_b32_e32 v203, 0xffff0000, v160
	v_lshlrev_b32_e32 v204, 16, v161
	v_and_b32_e32 v205, 0xffff0000, v161
	v_pk_add_f32 v[96:97], v[96:97], v[202:203]
	v_pk_add_f32 v[98:99], v[98:99], v[204:205]
	v_cvt_pk_bf16_f32 v158, v100, v101
	v_cvt_pk_bf16_f32 v159, v102, v103
	v_cvt_pk_bf16_f32 v160, v96, v97
	v_cvt_pk_bf16_f32 v161, v98, v99
	v_pk_fma_f32 v[138:139], v[100:101], v[100:101], v[138:139]
	global_store_dwordx4 v207, v[158:161], s[14:15] offset:256
	v_pk_fma_f32 v[138:139], v[102:103], v[102:103], v[138:139]
	v_pk_fma_f32 v[138:139], v[96:97], v[96:97], v[138:139]
	v_pk_fma_f32 v[138:139], v[98:99], v[98:99], v[138:139]
	v_add_f32_e32 v214, v138, v139
	v_add_u32_e32 v207, 0x8000, v207
	v_mov_b32_e32 v215, v214
	s_nop 1
	v_permlane16_swap_b32_e32 v214, v215
	s_nop 0
	v_add_f32_e32 v214, v214, v215
	v_mov_b32_e32 v215, v214
	s_nop 1
	v_permlane32_swap_b32_e32 v214, v215
	s_nop 0
	v_add_f32_e32 v214, v214, v215
	s_and_saveexec_b64 s[22:23], s[4:5]
	global_store_dword v210, v214, s[16:17] offset:1024
	s_mov_b64 exec, s[22:23]
	s_waitcnt vmcnt(16)
	v_lshlrev_b32_e32 v202, 16, v162
	v_and_b32_e32 v203, 0xffff0000, v162
	v_lshlrev_b32_e32 v204, 16, v163
	v_and_b32_e32 v205, 0xffff0000, v163
	v_pk_add_f32 v[92:93], v[92:93], v[202:203]
	v_pk_add_f32 v[94:95], v[94:95], v[204:205]
	v_lshlrev_b32_e32 v202, 16, v164
	v_and_b32_e32 v203, 0xffff0000, v164
	v_lshlrev_b32_e32 v204, 16, v165
	v_and_b32_e32 v205, 0xffff0000, v165
	v_pk_add_f32 v[88:89], v[88:89], v[202:203]
	v_pk_add_f32 v[90:91], v[90:91], v[204:205]
	v_cvt_pk_bf16_f32 v162, v92, v93
	v_cvt_pk_bf16_f32 v163, v94, v95
	v_cvt_pk_bf16_f32 v164, v88, v89
	v_cvt_pk_bf16_f32 v165, v90, v91
	v_pk_mul_f32 v[138:139], v[92:93], v[92:93]
	global_store_dwordx4 v207, v[162:165], s[14:15]
	v_pk_fma_f32 v[138:139], v[94:95], v[94:95], v[138:139]
	v_pk_fma_f32 v[138:139], v[88:89], v[88:89], v[138:139]
	v_pk_fma_f32 v[138:139], v[90:91], v[90:91], v[138:139]
	v_lshlrev_b32_e32 v202, 16, v166
	v_and_b32_e32 v203, 0xffff0000, v166
	v_lshlrev_b32_e32 v204, 16, v167
	v_and_b32_e32 v205, 0xffff0000, v167
	v_pk_add_f32 v[84:85], v[84:85], v[202:203]
	v_pk_add_f32 v[86:87], v[86:87], v[204:205]
	v_lshlrev_b32_e32 v202, 16, v168
	v_and_b32_e32 v203, 0xffff0000, v168
	v_lshlrev_b32_e32 v204, 16, v169
	v_and_b32_e32 v205, 0xffff0000, v169
	v_pk_add_f32 v[80:81], v[80:81], v[202:203]
	v_pk_add_f32 v[82:83], v[82:83], v[204:205]
	v_cvt_pk_bf16_f32 v166, v84, v85
	v_cvt_pk_bf16_f32 v167, v86, v87
	v_cvt_pk_bf16_f32 v168, v80, v81
	v_cvt_pk_bf16_f32 v169, v82, v83
	v_pk_fma_f32 v[138:139], v[84:85], v[84:85], v[138:139]
	global_store_dwordx4 v207, v[166:169], s[14:15] offset:256
	v_pk_fma_f32 v[138:139], v[86:87], v[86:87], v[138:139]
	v_pk_fma_f32 v[138:139], v[80:81], v[80:81], v[138:139]
	v_pk_fma_f32 v[138:139], v[82:83], v[82:83], v[138:139]
	v_add_f32_e32 v214, v138, v139
	v_add_u32_e32 v207, 0x8000, v207
	v_mov_b32_e32 v215, v214
	s_nop 1
	v_permlane16_swap_b32_e32 v214, v215
	s_nop 0
	v_add_f32_e32 v214, v214, v215
	v_mov_b32_e32 v215, v214
	s_nop 1
	v_permlane32_swap_b32_e32 v214, v215
	s_nop 0
	v_add_f32_e32 v214, v214, v215
	s_and_saveexec_b64 s[22:23], s[4:5]
	global_store_dword v210, v214, s[16:17] offset:2048
	s_mov_b64 exec, s[22:23]
	s_waitcnt vmcnt(17)
	v_lshlrev_b32_e32 v202, 16, v170
	v_and_b32_e32 v203, 0xffff0000, v170
	v_lshlrev_b32_e32 v204, 16, v171
	v_and_b32_e32 v205, 0xffff0000, v171
	v_pk_add_f32 v[76:77], v[76:77], v[202:203]
	v_pk_add_f32 v[78:79], v[78:79], v[204:205]
	v_lshlrev_b32_e32 v202, 16, v172
	v_and_b32_e32 v203, 0xffff0000, v172
	v_lshlrev_b32_e32 v204, 16, v173
	v_and_b32_e32 v205, 0xffff0000, v173
	v_pk_add_f32 v[72:73], v[72:73], v[202:203]
	v_pk_add_f32 v[74:75], v[74:75], v[204:205]
	v_cvt_pk_bf16_f32 v170, v76, v77
	v_cvt_pk_bf16_f32 v171, v78, v79
	v_cvt_pk_bf16_f32 v172, v72, v73
	v_cvt_pk_bf16_f32 v173, v74, v75
	v_pk_mul_f32 v[138:139], v[76:77], v[76:77]
	global_store_dwordx4 v207, v[170:173], s[14:15]
	v_pk_fma_f32 v[138:139], v[78:79], v[78:79], v[138:139]
	v_pk_fma_f32 v[138:139], v[72:73], v[72:73], v[138:139]
	v_pk_fma_f32 v[138:139], v[74:75], v[74:75], v[138:139]
	v_lshlrev_b32_e32 v202, 16, v174
	v_and_b32_e32 v203, 0xffff0000, v174
	v_lshlrev_b32_e32 v204, 16, v175
	v_and_b32_e32 v205, 0xffff0000, v175
	v_pk_add_f32 v[68:69], v[68:69], v[202:203]
	v_pk_add_f32 v[70:71], v[70:71], v[204:205]
	v_lshlrev_b32_e32 v202, 16, v176
	v_and_b32_e32 v203, 0xffff0000, v176
	v_lshlrev_b32_e32 v204, 16, v177
	v_and_b32_e32 v205, 0xffff0000, v177
	v_pk_add_f32 v[64:65], v[64:65], v[202:203]
	v_pk_add_f32 v[66:67], v[66:67], v[204:205]
	v_cvt_pk_bf16_f32 v174, v68, v69
	v_cvt_pk_bf16_f32 v175, v70, v71
	v_cvt_pk_bf16_f32 v176, v64, v65
	v_cvt_pk_bf16_f32 v177, v66, v67
	v_pk_fma_f32 v[138:139], v[68:69], v[68:69], v[138:139]
	global_store_dwordx4 v207, v[174:177], s[14:15] offset:256
	v_pk_fma_f32 v[138:139], v[70:71], v[70:71], v[138:139]
	v_pk_fma_f32 v[138:139], v[64:65], v[64:65], v[138:139]
	v_pk_fma_f32 v[138:139], v[66:67], v[66:67], v[138:139]
	v_add_f32_e32 v214, v138, v139
	v_add_u32_e32 v207, 0x28000, v207
	v_mov_b32_e32 v215, v214
	s_nop 1
	v_permlane16_swap_b32_e32 v214, v215
	s_nop 0
	v_add_f32_e32 v214, v214, v215
	v_mov_b32_e32 v215, v214
	s_nop 1
	v_permlane32_swap_b32_e32 v214, v215
	s_nop 0
	v_add_f32_e32 v214, v214, v215
	s_and_saveexec_b64 s[22:23], s[4:5]
	global_store_dword v210, v214, s[16:17] offset:3072
	s_mov_b64 exec, s[22:23]
	v_add_u32_e32 v210, 0x2000, v210
	s_waitcnt vmcnt(18)
	v_lshlrev_b32_e32 v202, 16, v178
	v_and_b32_e32 v203, 0xffff0000, v178
	v_lshlrev_b32_e32 v204, 16, v179
	v_and_b32_e32 v205, 0xffff0000, v179
	v_pk_add_f32 v[60:61], v[60:61], v[202:203]
	v_pk_add_f32 v[62:63], v[62:63], v[204:205]
	v_lshlrev_b32_e32 v202, 16, v180
	v_and_b32_e32 v203, 0xffff0000, v180
	v_lshlrev_b32_e32 v204, 16, v181
	v_and_b32_e32 v205, 0xffff0000, v181
	v_pk_add_f32 v[56:57], v[56:57], v[202:203]
	v_pk_add_f32 v[58:59], v[58:59], v[204:205]
	v_cvt_pk_bf16_f32 v178, v60, v61
	v_cvt_pk_bf16_f32 v179, v62, v63
	v_cvt_pk_bf16_f32 v180, v56, v57
	v_cvt_pk_bf16_f32 v181, v58, v59
	v_pk_mul_f32 v[138:139], v[60:61], v[60:61]
	global_store_dwordx4 v207, v[178:181], s[14:15]
	v_pk_fma_f32 v[138:139], v[62:63], v[62:63], v[138:139]
	v_pk_fma_f32 v[138:139], v[56:57], v[56:57], v[138:139]
	v_pk_fma_f32 v[138:139], v[58:59], v[58:59], v[138:139]
	v_lshlrev_b32_e32 v202, 16, v182
	v_and_b32_e32 v203, 0xffff0000, v182
	v_lshlrev_b32_e32 v204, 16, v183
	v_and_b32_e32 v205, 0xffff0000, v183
	v_pk_add_f32 v[52:53], v[52:53], v[202:203]
	v_pk_add_f32 v[54:55], v[54:55], v[204:205]
	v_lshlrev_b32_e32 v202, 16, v184
	v_and_b32_e32 v203, 0xffff0000, v184
	v_lshlrev_b32_e32 v204, 16, v185
	v_and_b32_e32 v205, 0xffff0000, v185
	v_pk_add_f32 v[48:49], v[48:49], v[202:203]
	v_pk_add_f32 v[50:51], v[50:51], v[204:205]
	v_cvt_pk_bf16_f32 v182, v52, v53
	v_cvt_pk_bf16_f32 v183, v54, v55
	v_cvt_pk_bf16_f32 v184, v48, v49
	v_cvt_pk_bf16_f32 v185, v50, v51
	v_pk_fma_f32 v[138:139], v[52:53], v[52:53], v[138:139]
	global_store_dwordx4 v207, v[182:185], s[14:15] offset:256
	v_pk_fma_f32 v[138:139], v[54:55], v[54:55], v[138:139]
	v_pk_fma_f32 v[138:139], v[48:49], v[48:49], v[138:139]
	v_pk_fma_f32 v[138:139], v[50:51], v[50:51], v[138:139]
	v_add_f32_e32 v214, v138, v139
	v_add_u32_e32 v207, 0x8000, v207
	v_mov_b32_e32 v215, v214
	s_nop 1
	v_permlane16_swap_b32_e32 v214, v215
	s_nop 0
	v_add_f32_e32 v214, v214, v215
	v_mov_b32_e32 v215, v214
	s_nop 1
	v_permlane32_swap_b32_e32 v214, v215
	s_nop 0
	v_add_f32_e32 v214, v214, v215
	s_and_saveexec_b64 s[22:23], s[4:5]
	global_store_dword v210, v214, s[16:17]
	s_mov_b64 exec, s[22:23]
	s_waitcnt vmcnt(19)
	v_lshlrev_b32_e32 v202, 16, v186
	v_and_b32_e32 v203, 0xffff0000, v186
	v_lshlrev_b32_e32 v204, 16, v187
	v_and_b32_e32 v205, 0xffff0000, v187
	v_pk_add_f32 v[44:45], v[44:45], v[202:203]
	v_pk_add_f32 v[46:47], v[46:47], v[204:205]
	v_lshlrev_b32_e32 v202, 16, v188
	v_and_b32_e32 v203, 0xffff0000, v188
	v_lshlrev_b32_e32 v204, 16, v189
	v_and_b32_e32 v205, 0xffff0000, v189
	v_pk_add_f32 v[40:41], v[40:41], v[202:203]
	v_pk_add_f32 v[42:43], v[42:43], v[204:205]
	v_cvt_pk_bf16_f32 v186, v44, v45
	v_cvt_pk_bf16_f32 v187, v46, v47
	v_cvt_pk_bf16_f32 v188, v40, v41
	v_cvt_pk_bf16_f32 v189, v42, v43
	v_pk_mul_f32 v[138:139], v[44:45], v[44:45]
	global_store_dwordx4 v207, v[186:189], s[14:15]
	v_pk_fma_f32 v[138:139], v[46:47], v[46:47], v[138:139]
	v_pk_fma_f32 v[138:139], v[40:41], v[40:41], v[138:139]
	v_pk_fma_f32 v[138:139], v[42:43], v[42:43], v[138:139]
	v_lshlrev_b32_e32 v202, 16, v190
	v_and_b32_e32 v203, 0xffff0000, v190
	v_lshlrev_b32_e32 v204, 16, v191
	v_and_b32_e32 v205, 0xffff0000, v191
	v_pk_add_f32 v[36:37], v[36:37], v[202:203]
	v_pk_add_f32 v[38:39], v[38:39], v[204:205]
	v_lshlrev_b32_e32 v202, 16, v192
	v_and_b32_e32 v203, 0xffff0000, v192
	v_lshlrev_b32_e32 v204, 16, v193
	v_and_b32_e32 v205, 0xffff0000, v193
	v_pk_add_f32 v[32:33], v[32:33], v[202:203]
	v_pk_add_f32 v[34:35], v[34:35], v[204:205]
	v_cvt_pk_bf16_f32 v190, v36, v37
	v_cvt_pk_bf16_f32 v191, v38, v39
	v_cvt_pk_bf16_f32 v192, v32, v33
	v_cvt_pk_bf16_f32 v193, v34, v35
	v_pk_fma_f32 v[138:139], v[36:37], v[36:37], v[138:139]
	global_store_dwordx4 v207, v[190:193], s[14:15] offset:256
	v_pk_fma_f32 v[138:139], v[38:39], v[38:39], v[138:139]
	v_pk_fma_f32 v[138:139], v[32:33], v[32:33], v[138:139]
	v_pk_fma_f32 v[138:139], v[34:35], v[34:35], v[138:139]
	v_add_f32_e32 v214, v138, v139
	v_add_u32_e32 v207, 0x8000, v207
	v_mov_b32_e32 v215, v214
	s_nop 1
	v_permlane16_swap_b32_e32 v214, v215
	s_nop 0
	v_add_f32_e32 v214, v214, v215
	v_mov_b32_e32 v215, v214
	s_nop 1
	v_permlane32_swap_b32_e32 v214, v215
	s_nop 0
	v_add_f32_e32 v214, v214, v215
	s_and_saveexec_b64 s[22:23], s[4:5]
	global_store_dword v210, v214, s[16:17] offset:1024
	s_mov_b64 exec, s[22:23]
	s_waitcnt vmcnt(20)
	v_lshlrev_b32_e32 v202, 16, v194
	v_and_b32_e32 v203, 0xffff0000, v194
	v_lshlrev_b32_e32 v204, 16, v195
	v_and_b32_e32 v205, 0xffff0000, v195
	v_pk_add_f32 v[28:29], v[28:29], v[202:203]
	v_pk_add_f32 v[30:31], v[30:31], v[204:205]
	v_lshlrev_b32_e32 v202, 16, v196
	v_and_b32_e32 v203, 0xffff0000, v196
	v_lshlrev_b32_e32 v204, 16, v197
	v_and_b32_e32 v205, 0xffff0000, v197
	v_pk_add_f32 v[24:25], v[24:25], v[202:203]
	v_pk_add_f32 v[26:27], v[26:27], v[204:205]
	v_cvt_pk_bf16_f32 v194, v28, v29
	v_cvt_pk_bf16_f32 v195, v30, v31
	v_cvt_pk_bf16_f32 v196, v24, v25
	v_cvt_pk_bf16_f32 v197, v26, v27
	v_pk_mul_f32 v[138:139], v[28:29], v[28:29]
	global_store_dwordx4 v207, v[194:197], s[14:15]
	v_pk_fma_f32 v[138:139], v[30:31], v[30:31], v[138:139]
	v_pk_fma_f32 v[138:139], v[24:25], v[24:25], v[138:139]
	v_pk_fma_f32 v[138:139], v[26:27], v[26:27], v[138:139]
	v_lshlrev_b32_e32 v202, 16, v198
	v_and_b32_e32 v203, 0xffff0000, v198
	v_lshlrev_b32_e32 v204, 16, v199
	v_and_b32_e32 v205, 0xffff0000, v199
	v_pk_add_f32 v[20:21], v[20:21], v[202:203]
	v_pk_add_f32 v[22:23], v[22:23], v[204:205]
	v_lshlrev_b32_e32 v202, 16, v200
	v_and_b32_e32 v203, 0xffff0000, v200
	v_lshlrev_b32_e32 v204, 16, v201
	v_and_b32_e32 v205, 0xffff0000, v201
	v_pk_add_f32 v[16:17], v[16:17], v[202:203]
	v_pk_add_f32 v[18:19], v[18:19], v[204:205]
	v_cvt_pk_bf16_f32 v198, v20, v21
	v_cvt_pk_bf16_f32 v199, v22, v23
	v_cvt_pk_bf16_f32 v200, v16, v17
	v_cvt_pk_bf16_f32 v201, v18, v19
	v_pk_fma_f32 v[138:139], v[20:21], v[20:21], v[138:139]
	global_store_dwordx4 v207, v[198:201], s[14:15] offset:256
	v_pk_fma_f32 v[138:139], v[22:23], v[22:23], v[138:139]
	v_pk_fma_f32 v[138:139], v[16:17], v[16:17], v[138:139]
	v_pk_fma_f32 v[138:139], v[18:19], v[18:19], v[138:139]
	v_add_f32_e32 v214, v138, v139
	v_add_u32_e32 v207, 0x8000, v207
	v_mov_b32_e32 v215, v214
	s_nop 1
	v_permlane16_swap_b32_e32 v214, v215
	s_nop 0
	v_add_f32_e32 v214, v214, v215
	v_mov_b32_e32 v215, v214
	s_nop 1
	v_permlane32_swap_b32_e32 v214, v215
	s_nop 0
	v_add_f32_e32 v214, v214, v215
	s_and_saveexec_b64 s[22:23], s[4:5]
	global_store_dword v210, v214, s[16:17] offset:2048
	s_mov_b64 exec, s[22:23]
	s_waitcnt vmcnt(18)
	v_lshlrev_b32_e32 v202, 16, v146
	v_and_b32_e32 v203, 0xffff0000, v146
	v_lshlrev_b32_e32 v204, 16, v147
	v_and_b32_e32 v205, 0xffff0000, v147
	v_pk_add_f32 v[12:13], v[12:13], v[202:203]
	v_pk_add_f32 v[14:15], v[14:15], v[204:205]
	v_lshlrev_b32_e32 v202, 16, v148
	v_and_b32_e32 v203, 0xffff0000, v148
	v_lshlrev_b32_e32 v204, 16, v149
	v_and_b32_e32 v205, 0xffff0000, v149
	v_pk_add_f32 v[8:9], v[8:9], v[202:203]
	v_pk_add_f32 v[10:11], v[10:11], v[204:205]
	v_cvt_pk_bf16_f32 v146, v12, v13
	v_cvt_pk_bf16_f32 v147, v14, v15
	v_cvt_pk_bf16_f32 v148, v8, v9
	v_cvt_pk_bf16_f32 v149, v10, v11
	v_pk_mul_f32 v[138:139], v[12:13], v[12:13]
	global_store_dwordx4 v207, v[146:149], s[14:15]
	v_pk_fma_f32 v[138:139], v[14:15], v[14:15], v[138:139]
	v_pk_fma_f32 v[138:139], v[8:9], v[8:9], v[138:139]
	v_pk_fma_f32 v[138:139], v[10:11], v[10:11], v[138:139]
	v_lshlrev_b32_e32 v202, 16, v150
	v_and_b32_e32 v203, 0xffff0000, v150
	v_lshlrev_b32_e32 v204, 16, v151
	v_and_b32_e32 v205, 0xffff0000, v151
	v_pk_add_f32 v[4:5], v[4:5], v[202:203]
	v_pk_add_f32 v[6:7], v[6:7], v[204:205]
	v_lshlrev_b32_e32 v202, 16, v152
	v_and_b32_e32 v203, 0xffff0000, v152
	v_lshlrev_b32_e32 v204, 16, v153
	v_and_b32_e32 v205, 0xffff0000, v153
	v_pk_add_f32 v[0:1], v[0:1], v[202:203]
	v_pk_add_f32 v[2:3], v[2:3], v[204:205]
	v_cvt_pk_bf16_f32 v150, v4, v5
	v_cvt_pk_bf16_f32 v151, v6, v7
	v_cvt_pk_bf16_f32 v152, v0, v1
	v_cvt_pk_bf16_f32 v153, v2, v3
	v_pk_fma_f32 v[138:139], v[4:5], v[4:5], v[138:139]
	global_store_dwordx4 v207, v[150:153], s[14:15] offset:256
	v_pk_fma_f32 v[138:139], v[6:7], v[6:7], v[138:139]
	v_pk_fma_f32 v[138:139], v[0:1], v[0:1], v[138:139]
	v_pk_fma_f32 v[138:139], v[2:3], v[2:3], v[138:139]
	v_add_f32_e32 v214, v138, v139
	v_add_u32_e32 v207, 0x8000, v207
	v_mov_b32_e32 v215, v214
	s_nop 1
	v_permlane16_swap_b32_e32 v214, v215
	s_nop 0
	v_add_f32_e32 v214, v214, v215
	v_mov_b32_e32 v215, v214
	s_nop 1
	v_permlane32_swap_b32_e32 v214, v215
	s_nop 0
	v_add_f32_e32 v214, v214, v215
	s_and_saveexec_b64 s[22:23], s[4:5]
	global_store_dword v210, v214, s[16:17] offset:3072
	s_mov_b64 exec, s[22:23]
	s_branch .LBB0_1009

	.amdhsa_kernel _Z14fwd_megakernel6Params
		.amdhsa_group_segment_fixed_size 0
		.amdhsa_private_segment_fixed_size 0
		.amdhsa_kernarg_size 592
		.amdhsa_user_sgpr_count 2
		.amdhsa_user_sgpr_dispatch_ptr 0
		.amdhsa_user_sgpr_queue_ptr 0
		.amdhsa_user_sgpr_kernarg_segment_ptr 1
		.amdhsa_user_sgpr_dispatch_id 0
		.amdhsa_user_sgpr_kernarg_preload_length 0
		.amdhsa_user_sgpr_kernarg_preload_offset 0
		.amdhsa_user_sgpr_private_segment_size 0
		.amdhsa_uses_dynamic_stack 0
		.amdhsa_enable_private_segment 0
		.amdhsa_system_sgpr_workgroup_id_x 1
		.amdhsa_system_sgpr_workgroup_id_y 0
		.amdhsa_system_sgpr_workgroup_id_z 0
		.amdhsa_system_sgpr_workgroup_info 0
		.amdhsa_system_vgpr_workitem_id 2
		.amdhsa_next_free_vgpr 256
		.amdhsa_next_free_sgpr 102
		.amdhsa_accum_offset 256
		.amdhsa_reserve_vcc 1
		.amdhsa_float_round_mode_32 0
		.amdhsa_float_round_mode_16_64 0
		.amdhsa_float_denorm_mode_32 3
		.amdhsa_float_denorm_mode_16_64 3
		.amdhsa_dx10_clamp 1
		.amdhsa_ieee_mode 1
		.amdhsa_fp16_overflow 0
		.amdhsa_tg_split 0
		.amdhsa_exception_fp_ieee_invalid_op 0
		.amdhsa_exception_fp_denorm_src 0
		.amdhsa_exception_fp_ieee_div_zero 0
		.amdhsa_exception_fp_ieee_overflow 0
		.amdhsa_exception_fp_ieee_underflow 0
		.amdhsa_exception_fp_ieee_inexact 0
		.amdhsa_exception_int_div_zero 0
	.end_amdhsa_kernel

amdhsa.kernels:
  - .agpr_count:     0
    .args:
      - .offset:         0
        .size:           336
        .value_kind:     by_value
      - .offset:         336
        .size:           4
        .value_kind:     hidden_block_count_x
      - .offset:         340
        .size:           4
        .value_kind:     hidden_block_count_y
      - .offset:         344
        .size:           4
        .value_kind:     hidden_block_count_z
      - .offset:         348
        .size:           2
        .value_kind:     hidden_group_size_x
      - .offset:         350
        .size:           2
        .value_kind:     hidden_group_size_y
      - .offset:         352
        .size:           2
        .value_kind:     hidden_group_size_z
      - .offset:         354
        .size:           2
        .value_kind:     hidden_remainder_x
      - .offset:         356
        .size:           2
        .value_kind:     hidden_remainder_y
      - .offset:         358
        .size:           2
        .value_kind:     hidden_remainder_z
      - .offset:         376
        .size:           8
        .value_kind:     hidden_global_offset_x
      - .offset:         384
        .size:           8
        .value_kind:     hidden_global_offset_y
      - .offset:         392
        .size:           8
        .value_kind:     hidden_global_offset_z
      - .offset:         400
        .size:           2
        .value_kind:     hidden_grid_dims
      - .offset:         424
        .size:           8
        .value_kind:     hidden_multigrid_sync_arg
      - .offset:         456
        .size:           4
        .value_kind:     hidden_dynamic_lds_size
    .group_segment_fixed_size: 0
    .kernarg_segment_align: 8
    .kernarg_segment_size: 592
    .language:       OpenCL C
    .language_version:
      - 2
      - 0
    .max_flat_workgroup_size: 512
    .name:           _Z14fwd_megakernel6Params
    .private_segment_fixed_size: 0
    .sgpr_count:     108
    .sgpr_spill_count: 20
    .symbol:         _Z14fwd_megakernel6Params.kd
    .uniform_work_group_size: 1
    .uses_dynamic_stack: false
    .vgpr_count:     256
    .vgpr_spill_count: 0
    .wavefront_size: 64
